# v56 plus: GEMM MFMA segments drop their priority behind the segment-closing barrier instead of in front of it
# speedup vs baseline: 1.0132x; 1.0008x over previous
.LBB0_185:
	ds_read_b128 v[136:139], v149
	ds_read_b128 v[154:157], v149 offset:1024
	ds_read_b128 v[158:161], v149 offset:2048
	ds_read_b128 v[162:165], v149 offset:3072
	ds_read_b128 v[166:169], v150
	ds_read_b128 v[170:173], v150 offset:1024
	ds_read_b128 v[174:177], v150 offset:2048
	ds_read_b128 v[178:181], v150 offset:3072
	s_cmp_eq_u32 s86, 28
	s_cselect_b32 s54, s80, s84
	s_cselect_b32 s55, s25, s85
	s_cselect_b32 s46, s81, s82
	s_cselect_b32 s47, s19, s83
	s_add_u32 s44, s54, 0x80
	s_addc_u32 s45, s55, 0
	ds_read_b128 v[182:185], v151
	ds_read_b128 v[186:189], v151 offset:1024
	ds_read_b128 v[190:193], v151 offset:2048
	ds_read_b128 v[194:197], v151 offset:3072
	ds_read_b128 v[198:201], v151 offset:4096
	ds_read_b128 v[202:205], v151 offset:5120
	ds_read_b128 v[206:209], v151 offset:6144
	ds_read_b128 v[210:213], v151 offset:7168
	s_mov_b32 m0, s75
	s_nop 0
	global_load_lds_dwordx4 v1, s[40:41] offset:0
	s_nop 0
	s_mov_b32 m0, s76
	s_nop 0
	global_load_lds_dwordx4 v143, s[40:41] offset:0
	s_waitcnt vmcnt(8)
	s_waitcnt lgkmcnt(0)
	s_barrier
	s_setprio 1
	v_mfma_f32_16x16x32_bf16 v[126:129], v[136:139], v[182:185], v[126:129]
	v_mfma_f32_16x16x32_bf16 v[126:129], v[154:157], v[186:189], v[126:129]
	v_mfma_f32_16x16x32_bf16 v[122:125], v[158:161], v[182:185], v[122:125]
	v_mfma_f32_16x16x32_bf16 v[122:125], v[162:165], v[186:189], v[122:125]
	v_mfma_f32_16x16x32_bf16 v[114:117], v[136:139], v[190:193], v[114:117]
	v_mfma_f32_16x16x32_bf16 v[114:117], v[154:157], v[194:197], v[114:117]
	v_mfma_f32_16x16x32_bf16 v[106:109], v[158:161], v[190:193], v[106:109]
	v_mfma_f32_16x16x32_bf16 v[106:109], v[162:165], v[194:197], v[106:109]
	v_mfma_f32_16x16x32_bf16 v[98:101], v[136:139], v[198:201], v[98:101]
	v_mfma_f32_16x16x32_bf16 v[98:101], v[154:157], v[202:205], v[98:101]
	v_mfma_f32_16x16x32_bf16 v[90:93], v[158:161], v[198:201], v[90:93]
	v_mfma_f32_16x16x32_bf16 v[90:93], v[162:165], v[202:205], v[90:93]
	v_mfma_f32_16x16x32_bf16 v[82:85], v[136:139], v[206:209], v[82:85]
	v_mfma_f32_16x16x32_bf16 v[82:85], v[154:157], v[210:213], v[82:85]
	v_mfma_f32_16x16x32_bf16 v[74:77], v[158:161], v[206:209], v[74:77]
	v_mfma_f32_16x16x32_bf16 v[74:77], v[162:165], v[210:213], v[74:77]
	s_setprio 0
	s_setprio 1
	v_mfma_f32_16x16x32_bf16 v[118:121], v[166:169], v[182:185], v[118:121]
	v_mfma_f32_16x16x32_bf16 v[118:121], v[170:173], v[186:189], v[118:121]
	v_mfma_f32_16x16x32_bf16 v[110:113], v[174:177], v[182:185], v[110:113]
	v_mfma_f32_16x16x32_bf16 v[110:113], v[178:181], v[186:189], v[110:113]
	v_mfma_f32_16x16x32_bf16 v[102:105], v[166:169], v[190:193], v[102:105]
	v_mfma_f32_16x16x32_bf16 v[102:105], v[170:173], v[194:197], v[102:105]
	v_mfma_f32_16x16x32_bf16 v[94:97], v[174:177], v[190:193], v[94:97]
	v_mfma_f32_16x16x32_bf16 v[94:97], v[178:181], v[194:197], v[94:97]
	v_mfma_f32_16x16x32_bf16 v[86:89], v[166:169], v[198:201], v[86:89]
	v_mfma_f32_16x16x32_bf16 v[86:89], v[170:173], v[202:205], v[86:89]
	v_mfma_f32_16x16x32_bf16 v[78:81], v[174:177], v[198:201], v[78:81]
	v_mfma_f32_16x16x32_bf16 v[78:81], v[178:181], v[202:205], v[78:81]
	v_mfma_f32_16x16x32_bf16 v[70:73], v[166:169], v[206:209], v[70:73]
	v_mfma_f32_16x16x32_bf16 v[70:73], v[170:173], v[210:213], v[70:73]
	v_mfma_f32_16x16x32_bf16 v[66:69], v[174:177], v[206:209], v[66:69]
	v_mfma_f32_16x16x32_bf16 v[66:69], v[178:181], v[210:213], v[66:69]
	s_barrier
	s_setprio 0
	ds_read_b128 v[182:185], v151 offset:16384
	ds_read_b128 v[186:189], v151 offset:17408
	ds_read_b128 v[190:193], v151 offset:18432
	ds_read_b128 v[194:197], v151 offset:19456
	ds_read_b128 v[198:201], v151 offset:20480
	ds_read_b128 v[202:205], v151 offset:21504
	ds_read_b128 v[206:209], v151 offset:22528
	ds_read_b128 v[210:213], v151 offset:23552
	s_mov_b32 m0, s39
	s_nop 0
	global_load_lds_dwordx4 v135, s[46:47] offset:0
	s_add_u32 s30, s46, 0x80000
	s_mov_b32 m0, s58
	s_nop 0
	global_load_lds_dwordx4 v145, s[46:47] offset:0
	s_addc_u32 s31, s47, 0
	s_mov_b32 m0, s59
	s_nop 0
	global_load_lds_dwordx4 v135, s[30:31] offset:0
	s_nop 0
	s_mov_b32 m0, s64
	s_nop 0
	global_load_lds_dwordx4 v145, s[30:31] offset:0
	s_nop 0
	s_mov_b32 m0, s53
	s_nop 0
	global_load_lds_dwordx4 v1, s[54:55] offset:0
	s_nop 0
	s_mov_b32 m0, s65
	s_nop 0
	global_load_lds_dwordx4 v143, s[54:55] offset:0
	s_waitcnt vmcnt(8)
	s_waitcnt lgkmcnt(0)
	s_barrier
	s_setprio 1
	v_mfma_f32_16x16x32_bf16 v[62:65], v[136:139], v[182:185], v[62:65]
	v_mfma_f32_16x16x32_bf16 v[62:65], v[154:157], v[186:189], v[62:65]
	v_mfma_f32_16x16x32_bf16 v[58:61], v[158:161], v[182:185], v[58:61]
	v_mfma_f32_16x16x32_bf16 v[58:61], v[162:165], v[186:189], v[58:61]
	v_mfma_f32_16x16x32_bf16 v[50:53], v[136:139], v[190:193], v[50:53]
	v_mfma_f32_16x16x32_bf16 v[50:53], v[154:157], v[194:197], v[50:53]
	v_mfma_f32_16x16x32_bf16 v[42:45], v[158:161], v[190:193], v[42:45]
	v_mfma_f32_16x16x32_bf16 v[42:45], v[162:165], v[194:197], v[42:45]
	v_mfma_f32_16x16x32_bf16 v[34:37], v[136:139], v[198:201], v[34:37]
	v_mfma_f32_16x16x32_bf16 v[34:37], v[154:157], v[202:205], v[34:37]
	v_mfma_f32_16x16x32_bf16 v[26:29], v[158:161], v[198:201], v[26:29]
	v_mfma_f32_16x16x32_bf16 v[26:29], v[162:165], v[202:205], v[26:29]
	v_mfma_f32_16x16x32_bf16 v[18:21], v[136:139], v[206:209], v[18:21]
	v_mfma_f32_16x16x32_bf16 v[18:21], v[154:157], v[210:213], v[18:21]
	v_mfma_f32_16x16x32_bf16 v[10:13], v[158:161], v[206:209], v[10:13]
	v_mfma_f32_16x16x32_bf16 v[10:13], v[162:165], v[210:213], v[10:13]
	s_setprio 0
	s_setprio 1
	v_mfma_f32_16x16x32_bf16 v[54:57], v[166:169], v[182:185], v[54:57]
	v_mfma_f32_16x16x32_bf16 v[54:57], v[170:173], v[186:189], v[54:57]
	v_mfma_f32_16x16x32_bf16 v[46:49], v[174:177], v[182:185], v[46:49]
	v_mfma_f32_16x16x32_bf16 v[46:49], v[178:181], v[186:189], v[46:49]
	v_mfma_f32_16x16x32_bf16 v[38:41], v[166:169], v[190:193], v[38:41]
	v_mfma_f32_16x16x32_bf16 v[38:41], v[170:173], v[194:197], v[38:41]
	v_mfma_f32_16x16x32_bf16 v[30:33], v[174:177], v[190:193], v[30:33]
	v_mfma_f32_16x16x32_bf16 v[30:33], v[178:181], v[194:197], v[30:33]
	v_mfma_f32_16x16x32_bf16 v[22:25], v[166:169], v[198:201], v[22:25]
	v_mfma_f32_16x16x32_bf16 v[22:25], v[170:173], v[202:205], v[22:25]
	v_mfma_f32_16x16x32_bf16 v[14:17], v[174:177], v[198:201], v[14:17]
	v_mfma_f32_16x16x32_bf16 v[14:17], v[178:181], v[202:205], v[14:17]
	v_mfma_f32_16x16x32_bf16 v[6:9], v[166:169], v[206:209], v[6:9]
	v_mfma_f32_16x16x32_bf16 v[6:9], v[170:173], v[210:213], v[6:9]
	v_mfma_f32_16x16x32_bf16 v[2:5], v[174:177], v[206:209], v[2:5]
	v_mfma_f32_16x16x32_bf16 v[2:5], v[178:181], v[210:213], v[2:5]
	s_barrier
	s_setprio 0
	ds_read_b128 v[136:139], v152
	ds_read_b128 v[154:157], v152 offset:1024
	ds_read_b128 v[158:161], v152 offset:2048
	ds_read_b128 v[162:165], v152 offset:3072
	ds_read_b128 v[166:169], v153
	ds_read_b128 v[170:173], v153 offset:1024
	ds_read_b128 v[174:177], v153 offset:2048
	ds_read_b128 v[178:181], v153 offset:3072
	ds_read_b128 v[182:185], v151 offset:32768
	ds_read_b128 v[186:189], v151 offset:33792
	ds_read_b128 v[190:193], v151 offset:34816
	ds_read_b128 v[194:197], v151 offset:35840
	ds_read_b128 v[198:201], v151 offset:36864
	ds_read_b128 v[202:205], v151 offset:37888
	ds_read_b128 v[206:209], v151 offset:38912
	ds_read_b128 v[210:213], v151 offset:39936
	s_add_u32 s30, s54, 0x80000
	s_addc_u32 s31, s55, 0
	s_mov_b32 m0, s66
	s_nop 0
	global_load_lds_dwordx4 v1, s[30:31] offset:0
	s_nop 0
	s_mov_b32 m0, s67
	s_nop 0
	global_load_lds_dwordx4 v143, s[30:31] offset:0
	s_waitcnt vmcnt(8)
	s_waitcnt lgkmcnt(0)
	s_barrier
	s_setprio 1
	v_mfma_f32_16x16x32_bf16 v[126:129], v[136:139], v[182:185], v[126:129]
	v_mfma_f32_16x16x32_bf16 v[126:129], v[154:157], v[186:189], v[126:129]
	v_mfma_f32_16x16x32_bf16 v[122:125], v[158:161], v[182:185], v[122:125]
	v_mfma_f32_16x16x32_bf16 v[122:125], v[162:165], v[186:189], v[122:125]
	v_mfma_f32_16x16x32_bf16 v[114:117], v[136:139], v[190:193], v[114:117]
	v_mfma_f32_16x16x32_bf16 v[114:117], v[154:157], v[194:197], v[114:117]
	v_mfma_f32_16x16x32_bf16 v[106:109], v[158:161], v[190:193], v[106:109]
	v_mfma_f32_16x16x32_bf16 v[106:109], v[162:165], v[194:197], v[106:109]
	v_mfma_f32_16x16x32_bf16 v[98:101], v[136:139], v[198:201], v[98:101]
	v_mfma_f32_16x16x32_bf16 v[98:101], v[154:157], v[202:205], v[98:101]
	v_mfma_f32_16x16x32_bf16 v[90:93], v[158:161], v[198:201], v[90:93]
	v_mfma_f32_16x16x32_bf16 v[90:93], v[162:165], v[202:205], v[90:93]
	v_mfma_f32_16x16x32_bf16 v[82:85], v[136:139], v[206:209], v[82:85]
	v_mfma_f32_16x16x32_bf16 v[82:85], v[154:157], v[210:213], v[82:85]
	v_mfma_f32_16x16x32_bf16 v[74:77], v[158:161], v[206:209], v[74:77]
	v_mfma_f32_16x16x32_bf16 v[74:77], v[162:165], v[210:213], v[74:77]
	s_setprio 0
	s_setprio 1
	v_mfma_f32_16x16x32_bf16 v[118:121], v[166:169], v[182:185], v[118:121]
	v_mfma_f32_16x16x32_bf16 v[118:121], v[170:173], v[186:189], v[118:121]
	v_mfma_f32_16x16x32_bf16 v[110:113], v[174:177], v[182:185], v[110:113]
	v_mfma_f32_16x16x32_bf16 v[110:113], v[178:181], v[186:189], v[110:113]
	v_mfma_f32_16x16x32_bf16 v[102:105], v[166:169], v[190:193], v[102:105]
	v_mfma_f32_16x16x32_bf16 v[102:105], v[170:173], v[194:197], v[102:105]
	v_mfma_f32_16x16x32_bf16 v[94:97], v[174:177], v[190:193], v[94:97]
	v_mfma_f32_16x16x32_bf16 v[94:97], v[178:181], v[194:197], v[94:97]
	v_mfma_f32_16x16x32_bf16 v[86:89], v[166:169], v[198:201], v[86:89]
	v_mfma_f32_16x16x32_bf16 v[86:89], v[170:173], v[202:205], v[86:89]
	v_mfma_f32_16x16x32_bf16 v[78:81], v[174:177], v[198:201], v[78:81]
	v_mfma_f32_16x16x32_bf16 v[78:81], v[178:181], v[202:205], v[78:81]
	v_mfma_f32_16x16x32_bf16 v[70:73], v[166:169], v[206:209], v[70:73]
	v_mfma_f32_16x16x32_bf16 v[70:73], v[170:173], v[210:213], v[70:73]
	v_mfma_f32_16x16x32_bf16 v[66:69], v[174:177], v[206:209], v[66:69]
	v_mfma_f32_16x16x32_bf16 v[66:69], v[178:181], v[210:213], v[66:69]
	s_barrier
	s_setprio 0
	ds_read_b128 v[182:185], v151 offset:49152
	ds_read_b128 v[186:189], v151 offset:50176
	ds_read_b128 v[190:193], v151 offset:51200
	ds_read_b128 v[194:197], v151 offset:52224
	ds_read_b128 v[198:201], v151 offset:53248
	ds_read_b128 v[202:205], v151 offset:54272
	ds_read_b128 v[206:209], v151 offset:55296
	ds_read_b128 v[210:213], v151 offset:56320
	s_add_u32 s30, s46, 0x80
	s_addc_u32 s31, s47, 0
	s_mov_b32 m0, s69
	s_nop 0
	global_load_lds_dwordx4 v135, s[30:31] offset:0
	s_nop 0
	s_mov_b32 m0, s70
	s_nop 0
	global_load_lds_dwordx4 v145, s[30:31] offset:0
	s_add_u32 s30, s46, 0x80080
	s_addc_u32 s31, s47, 0
	s_mov_b32 m0, s73
	s_nop 0
	global_load_lds_dwordx4 v135, s[30:31] offset:0
	s_nop 0
	s_mov_b32 m0, s74
	s_nop 0
	global_load_lds_dwordx4 v145, s[30:31] offset:0
	s_nop 0
	s_mov_b32 m0, s71
	s_nop 0
	global_load_lds_dwordx4 v1, s[44:45] offset:0
	s_nop 0
	s_mov_b32 m0, s72
	s_nop 0
	global_load_lds_dwordx4 v143, s[44:45] offset:0
	s_waitcnt vmcnt(8)
	s_waitcnt lgkmcnt(0)
	s_barrier
	s_setprio 1
	v_mfma_f32_16x16x32_bf16 v[62:65], v[136:139], v[182:185], v[62:65]
	v_mfma_f32_16x16x32_bf16 v[62:65], v[154:157], v[186:189], v[62:65]
	v_mfma_f32_16x16x32_bf16 v[58:61], v[158:161], v[182:185], v[58:61]
	v_mfma_f32_16x16x32_bf16 v[58:61], v[162:165], v[186:189], v[58:61]
	v_mfma_f32_16x16x32_bf16 v[50:53], v[136:139], v[190:193], v[50:53]
	v_mfma_f32_16x16x32_bf16 v[50:53], v[154:157], v[194:197], v[50:53]
	v_mfma_f32_16x16x32_bf16 v[42:45], v[158:161], v[190:193], v[42:45]
	v_mfma_f32_16x16x32_bf16 v[42:45], v[162:165], v[194:197], v[42:45]
	v_mfma_f32_16x16x32_bf16 v[34:37], v[136:139], v[198:201], v[34:37]
	v_mfma_f32_16x16x32_bf16 v[34:37], v[154:157], v[202:205], v[34:37]
	v_mfma_f32_16x16x32_bf16 v[26:29], v[158:161], v[198:201], v[26:29]
	v_mfma_f32_16x16x32_bf16 v[26:29], v[162:165], v[202:205], v[26:29]
	v_mfma_f32_16x16x32_bf16 v[18:21], v[136:139], v[206:209], v[18:21]
	v_mfma_f32_16x16x32_bf16 v[18:21], v[154:157], v[210:213], v[18:21]
	v_mfma_f32_16x16x32_bf16 v[10:13], v[158:161], v[206:209], v[10:13]
	v_mfma_f32_16x16x32_bf16 v[10:13], v[162:165], v[210:213], v[10:13]
	s_setprio 0
	s_setprio 1
	v_mfma_f32_16x16x32_bf16 v[54:57], v[166:169], v[182:185], v[54:57]
	v_mfma_f32_16x16x32_bf16 v[54:57], v[170:173], v[186:189], v[54:57]
	v_mfma_f32_16x16x32_bf16 v[46:49], v[174:177], v[182:185], v[46:49]
	v_mfma_f32_16x16x32_bf16 v[46:49], v[178:181], v[186:189], v[46:49]
	v_mfma_f32_16x16x32_bf16 v[38:41], v[166:169], v[190:193], v[38:41]
	v_mfma_f32_16x16x32_bf16 v[38:41], v[170:173], v[194:197], v[38:41]
	v_mfma_f32_16x16x32_bf16 v[30:33], v[174:177], v[190:193], v[30:33]
	v_mfma_f32_16x16x32_bf16 v[30:33], v[178:181], v[194:197], v[30:33]
	v_mfma_f32_16x16x32_bf16 v[22:25], v[166:169], v[198:201], v[22:25]
	v_mfma_f32_16x16x32_bf16 v[22:25], v[170:173], v[202:205], v[22:25]
	v_mfma_f32_16x16x32_bf16 v[14:17], v[174:177], v[198:201], v[14:17]
	v_mfma_f32_16x16x32_bf16 v[14:17], v[178:181], v[202:205], v[14:17]
	v_mfma_f32_16x16x32_bf16 v[6:9], v[166:169], v[206:209], v[6:9]
	v_mfma_f32_16x16x32_bf16 v[6:9], v[170:173], v[210:213], v[6:9]
	v_mfma_f32_16x16x32_bf16 v[2:5], v[174:177], v[206:209], v[2:5]
	v_mfma_f32_16x16x32_bf16 v[2:5], v[178:181], v[210:213], v[2:5]
	s_barrier
	s_setprio 0
	s_add_i32 s86, s86, 2
	s_add_u32 s82, s82, 0x100
	s_addc_u32 s83, s83, 0
	s_add_u32 s84, s84, 0x100
	s_addc_u32 s85, s85, 0
	s_add_u32 s40, s40, 0x100
	s_addc_u32 s41, s41, 0
	s_cmp_gt_u32 s86, 29
	s_cbranch_scc0 .LBB0_185
	s_and_b64 vcc, exec, s[16:17]
	s_cbranch_vccz .LBB0_188
	s_barrier

.LBB0_624:
	s_cmp_eq_u32 s37, 0
	s_mov_b32 s64, 0
	s_cbranch_scc1 .LBB0_626
	ds_read_b128 v[4:7], v147
	ds_read_b128 v[8:11], v147 offset:1024
	ds_read_b128 v[12:15], v147 offset:2048
	ds_read_b128 v[16:19], v147 offset:3072
	ds_read_b128 v[20:23], v148
	ds_read_b128 v[24:27], v148 offset:1024
	ds_read_b128 v[28:31], v148 offset:2048
	ds_read_b128 v[32:35], v148 offset:3072
	s_add_u32 s44, s56, 0x100
	s_addc_u32 s45, s57, 0
	s_add_u32 s30, s58, 0x100
	s_addc_u32 s31, s59, 0
	s_add_u32 s40, s56, 0x180
	s_addc_u32 s41, s57, 0
	ds_read_b128 v[36:39], v149
	ds_read_b128 v[40:43], v149 offset:1024
	ds_read_b128 v[44:47], v149 offset:2048
	ds_read_b128 v[48:51], v149 offset:3072
	ds_read_b128 v[52:55], v149 offset:4096
	ds_read_b128 v[56:59], v149 offset:5120
	ds_read_b128 v[60:63], v149 offset:6144
	ds_read_b128 v[64:67], v149 offset:7168
	s_add_u32 s42, s56, 0x80080
	s_addc_u32 s43, s57, 0
	s_mov_b32 m0, s81
	s_nop 0
	global_load_lds_dwordx4 v1, s[42:43] offset:0
	s_nop 0
	s_mov_b32 m0, s82
	s_nop 0
	global_load_lds_dwordx4 v143, s[42:43] offset:0
	s_waitcnt vmcnt(24)
	s_waitcnt lgkmcnt(0)
	s_barrier
	s_setprio 1
	v_mfma_f32_16x16x32_bf16 v[92:95], v[4:7], v[60:63], 0
	v_mfma_f32_16x16x32_bf16 v[68:71], v[4:7], v[36:39], 0
	v_mfma_f32_16x16x32_bf16 v[72:75], v[12:15], v[36:39], 0
	v_mfma_f32_16x16x32_bf16 v[76:79], v[4:7], v[44:47], 0
	v_mfma_f32_16x16x32_bf16 v[80:83], v[12:15], v[44:47], 0
	v_mfma_f32_16x16x32_bf16 v[84:87], v[4:7], v[52:55], 0
	v_mfma_f32_16x16x32_bf16 v[88:91], v[12:15], v[52:55], 0
	v_mfma_f32_16x16x32_bf16 v[102:105], v[8:11], v[64:67], v[92:95]
	v_mfma_f32_16x16x32_bf16 v[92:95], v[12:15], v[60:63], 0
	v_mfma_f32_16x16x32_bf16 v[68:71], v[8:11], v[40:43], v[68:71]
	v_mfma_f32_16x16x32_bf16 v[72:75], v[16:19], v[40:43], v[72:75]
	v_mfma_f32_16x16x32_bf16 v[76:79], v[8:11], v[48:51], v[76:79]
	v_mfma_f32_16x16x32_bf16 v[80:83], v[16:19], v[48:51], v[80:83]
	v_mfma_f32_16x16x32_bf16 v[84:87], v[8:11], v[56:59], v[84:87]
	v_mfma_f32_16x16x32_bf16 v[88:91], v[16:19], v[56:59], v[88:91]
	v_mfma_f32_16x16x32_bf16 v[106:109], v[16:19], v[64:67], v[92:95]
	s_setprio 0
	s_setprio 1
	v_mfma_f32_16x16x32_bf16 v[92:95], v[20:23], v[36:39], 0
	v_mfma_f32_16x16x32_bf16 v[36:39], v[28:31], v[36:39], 0
	v_mfma_f32_16x16x32_bf16 v[118:121], v[24:27], v[40:43], v[92:95]
	v_mfma_f32_16x16x32_bf16 v[36:39], v[32:35], v[40:43], v[36:39]
	v_mfma_f32_16x16x32_bf16 v[40:43], v[20:23], v[44:47], 0
	v_mfma_f32_16x16x32_bf16 v[44:47], v[28:31], v[44:47], 0
	v_mfma_f32_16x16x32_bf16 v[40:43], v[24:27], v[48:51], v[40:43]
	v_mfma_f32_16x16x32_bf16 v[44:47], v[32:35], v[48:51], v[44:47]
	v_mfma_f32_16x16x32_bf16 v[48:51], v[20:23], v[52:55], 0
	v_mfma_f32_16x16x32_bf16 v[52:55], v[28:31], v[52:55], 0
	v_mfma_f32_16x16x32_bf16 v[48:51], v[24:27], v[56:59], v[48:51]
	v_mfma_f32_16x16x32_bf16 v[52:55], v[32:35], v[56:59], v[52:55]
	v_mfma_f32_16x16x32_bf16 v[56:59], v[20:23], v[60:63], 0
	v_mfma_f32_16x16x32_bf16 v[60:63], v[28:31], v[60:63], 0
	v_mfma_f32_16x16x32_bf16 v[56:59], v[24:27], v[64:67], v[56:59]
	v_mfma_f32_16x16x32_bf16 v[60:63], v[32:35], v[64:67], v[60:63]
	s_barrier
	s_setprio 0
	ds_read_b128 v[64:67], v149 offset:16384
	ds_read_b128 v[92:95], v149 offset:17408
	ds_read_b128 v[96:99], v149 offset:18432
	ds_read_b128 v[110:113], v149 offset:19456
	ds_read_b128 v[114:117], v149 offset:20480
	ds_read_b128 v[122:125], v149 offset:21504
	ds_read_b128 v[126:129], v149 offset:22528
	ds_read_b128 v[130:133], v149 offset:23552
	s_mov_b32 m0, s52
	s_nop 0
	global_load_lds_dwordx4 v142, s[30:31] offset:0
	s_nop 0
	s_mov_b32 m0, s53
	s_nop 0
	global_load_lds_dwordx4 v144, s[30:31] offset:0
	s_add_u32 s30, s58, 0x80100
	s_addc_u32 s31, s59, 0
	s_mov_b32 m0, s55
	s_nop 0
	global_load_lds_dwordx4 v142, s[30:31] offset:0
	s_nop 0
	s_mov_b32 m0, s68
	s_nop 0
	global_load_lds_dwordx4 v144, s[30:31] offset:0
	s_nop 0
	s_mov_b32 m0, s33
	s_nop 0
	global_load_lds_dwordx4 v1, s[44:45] offset:0
	s_nop 0
	s_mov_b32 m0, s69
	s_nop 0
	global_load_lds_dwordx4 v143, s[44:45] offset:0
	s_waitcnt vmcnt(24)
	s_waitcnt lgkmcnt(0)
	s_barrier
	s_setprio 1
	v_mfma_f32_16x16x32_bf16 v[138:141], v[4:7], v[64:67], 0
	v_mfma_f32_16x16x32_bf16 v[156:159], v[4:7], v[96:99], 0
	v_mfma_f32_16x16x32_bf16 v[164:167], v[4:7], v[114:117], 0
	v_mfma_f32_16x16x32_bf16 v[4:7], v[4:7], v[126:129], 0
	v_mfma_f32_16x16x32_bf16 v[138:141], v[8:11], v[92:95], v[138:141]
	v_mfma_f32_16x16x32_bf16 v[156:159], v[8:11], v[110:113], v[156:159]
	v_mfma_f32_16x16x32_bf16 v[164:167], v[8:11], v[122:125], v[164:167]
	v_mfma_f32_16x16x32_bf16 v[4:7], v[8:11], v[130:133], v[4:7]
	v_mfma_f32_16x16x32_bf16 v[8:11], v[12:15], v[126:129], 0
	v_mfma_f32_16x16x32_bf16 v[152:155], v[12:15], v[64:67], 0
	v_mfma_f32_16x16x32_bf16 v[160:163], v[12:15], v[96:99], 0
	v_mfma_f32_16x16x32_bf16 v[168:171], v[12:15], v[114:117], 0
	v_mfma_f32_16x16x32_bf16 v[8:11], v[16:19], v[130:133], v[8:11]
	v_mfma_f32_16x16x32_bf16 v[152:155], v[16:19], v[92:95], v[152:155]
	v_mfma_f32_16x16x32_bf16 v[160:163], v[16:19], v[110:113], v[160:163]
	v_mfma_f32_16x16x32_bf16 v[168:171], v[16:19], v[122:125], v[168:171]
	s_setprio 0
	s_setprio 1
	v_mfma_f32_16x16x32_bf16 v[12:15], v[20:23], v[64:67], 0
	v_mfma_f32_16x16x32_bf16 v[172:175], v[24:27], v[92:95], v[12:15]
	v_mfma_f32_16x16x32_bf16 v[12:15], v[28:31], v[64:67], 0
	v_mfma_f32_16x16x32_bf16 v[176:179], v[32:35], v[92:95], v[12:15]
	v_mfma_f32_16x16x32_bf16 v[12:15], v[20:23], v[96:99], 0
	v_mfma_f32_16x16x32_bf16 v[180:183], v[24:27], v[110:113], v[12:15]
	v_mfma_f32_16x16x32_bf16 v[12:15], v[28:31], v[96:99], 0
	v_mfma_f32_16x16x32_bf16 v[184:187], v[32:35], v[110:113], v[12:15]
	v_mfma_f32_16x16x32_bf16 v[12:15], v[20:23], v[114:117], 0
	v_mfma_f32_16x16x32_bf16 v[188:191], v[24:27], v[122:125], v[12:15]
	v_mfma_f32_16x16x32_bf16 v[12:15], v[28:31], v[114:117], 0
	v_mfma_f32_16x16x32_bf16 v[192:195], v[32:35], v[122:125], v[12:15]
	v_mfma_f32_16x16x32_bf16 v[12:15], v[20:23], v[126:129], 0
	v_mfma_f32_16x16x32_bf16 v[196:199], v[24:27], v[130:133], v[12:15]
	v_mfma_f32_16x16x32_bf16 v[12:15], v[28:31], v[126:129], 0
	v_mfma_f32_16x16x32_bf16 v[200:203], v[32:35], v[130:133], v[12:15]
	s_barrier
	s_setprio 0
	s_nop 4
	ds_read_b128 v[12:15], v150
	ds_read_b128 v[16:19], v150 offset:1024
	ds_read_b128 v[22:25], v150 offset:2048
	ds_read_b128 v[26:29], v150 offset:3072
	ds_read_b128 v[204:207], v151
	ds_read_b128 v[208:211], v151 offset:1024
	ds_read_b128 v[212:215], v151 offset:2048
	ds_read_b128 v[216:219], v151 offset:3072
	ds_read_b128 v[30:33], v149 offset:32768
	ds_read_b128 v[64:67], v149 offset:33792
	ds_read_b128 v[220:223], v149 offset:34816
	ds_read_b128 v[224:227], v149 offset:35840
	ds_read_b128 v[228:231], v149 offset:36864
	ds_read_b128 v[232:235], v149 offset:37888
	ds_read_b128 v[236:239], v149 offset:38912
	ds_read_b128 v[240:243], v149 offset:39936
	s_add_u32 s30, s56, 0x80100
	s_addc_u32 s31, s57, 0
	s_mov_b32 m0, s70
	s_nop 0
	global_load_lds_dwordx4 v1, s[30:31] offset:0
	s_nop 0
	s_mov_b32 m0, s71
	s_nop 0
	global_load_lds_dwordx4 v143, s[30:31] offset:0
	s_waitcnt vmcnt(8)
	s_waitcnt lgkmcnt(0)
	s_barrier
	s_setprio 1
	v_mfma_f32_16x16x32_bf16 v[68:71], v[12:15], v[30:33], v[68:71]
	v_mfma_f32_16x16x32_bf16 v[130:133], v[16:19], v[64:67], v[68:71]
	v_mfma_f32_16x16x32_bf16 v[68:71], v[22:25], v[30:33], v[72:75]
	v_mfma_f32_16x16x32_bf16 v[126:129], v[26:29], v[64:67], v[68:71]
	v_mfma_f32_16x16x32_bf16 v[68:71], v[12:15], v[220:223], v[76:79]
	v_mfma_f32_16x16x32_bf16 v[114:117], v[16:19], v[224:227], v[68:71]
	v_mfma_f32_16x16x32_bf16 v[68:71], v[22:25], v[220:223], v[80:83]
	v_mfma_f32_16x16x32_bf16 v[110:113], v[26:29], v[224:227], v[68:71]
	v_mfma_f32_16x16x32_bf16 v[68:71], v[12:15], v[228:231], v[84:87]
	v_mfma_f32_16x16x32_bf16 v[98:101], v[16:19], v[232:235], v[68:71]
	v_mfma_f32_16x16x32_bf16 v[68:71], v[22:25], v[228:231], v[88:91]
	v_mfma_f32_16x16x32_bf16 v[94:97], v[26:29], v[232:235], v[68:71]
	v_mfma_f32_16x16x32_bf16 v[68:71], v[12:15], v[236:239], v[102:105]
	v_mfma_f32_16x16x32_bf16 v[82:85], v[16:19], v[240:243], v[68:71]
	v_mfma_f32_16x16x32_bf16 v[68:71], v[22:25], v[236:239], v[106:109]
	v_mfma_f32_16x16x32_bf16 v[78:81], v[26:29], v[240:243], v[68:71]
	s_setprio 0
	s_setprio 1
	v_mfma_f32_16x16x32_bf16 v[68:71], v[204:207], v[30:33], v[118:121]
	v_mfma_f32_16x16x32_bf16 v[30:33], v[212:215], v[30:33], v[36:39]
	v_mfma_f32_16x16x32_bf16 v[118:121], v[216:219], v[64:67], v[30:33]
	v_mfma_f32_16x16x32_bf16 v[30:33], v[204:207], v[220:223], v[40:43]
	v_mfma_f32_16x16x32_bf16 v[106:109], v[208:211], v[224:227], v[30:33]
	v_mfma_f32_16x16x32_bf16 v[30:33], v[212:215], v[220:223], v[44:47]
	v_mfma_f32_16x16x32_bf16 v[102:105], v[216:219], v[224:227], v[30:33]
	v_mfma_f32_16x16x32_bf16 v[30:33], v[204:207], v[228:231], v[48:51]
	v_mfma_f32_16x16x32_bf16 v[90:93], v[208:211], v[232:235], v[30:33]
	v_mfma_f32_16x16x32_bf16 v[30:33], v[212:215], v[228:231], v[52:55]
	v_mfma_f32_16x16x32_bf16 v[86:89], v[216:219], v[232:235], v[30:33]
	v_mfma_f32_16x16x32_bf16 v[30:33], v[204:207], v[236:239], v[56:59]
	v_mfma_f32_16x16x32_bf16 v[74:77], v[208:211], v[240:243], v[30:33]
	v_mfma_f32_16x16x32_bf16 v[30:33], v[212:215], v[236:239], v[60:63]
	v_mfma_f32_16x16x32_bf16 v[122:125], v[208:211], v[64:67], v[68:71]
	v_mfma_f32_16x16x32_bf16 v[70:73], v[216:219], v[240:243], v[30:33]
	s_barrier
	s_setprio 0
	ds_read_b128 v[38:41], v149 offset:49152
	ds_read_b128 v[42:45], v149 offset:50176
	ds_read_b128 v[220:223], v149 offset:51200
	ds_read_b128 v[224:227], v149 offset:52224
	ds_read_b128 v[228:231], v149 offset:53248
	ds_read_b128 v[232:235], v149 offset:54272
	ds_read_b128 v[236:239], v149 offset:55296
	ds_read_b128 v[240:243], v149 offset:56320
	s_add_u32 s30, s58, 0x180
	s_addc_u32 s31, s59, 0
	s_mov_b32 m0, s75
	s_nop 0
	global_load_lds_dwordx4 v142, s[30:31] offset:0
	s_nop 0
	s_mov_b32 m0, s76
	s_nop 0
	global_load_lds_dwordx4 v144, s[30:31] offset:0
	s_add_u32 s30, s58, 0x80180
	s_addc_u32 s31, s59, 0
	s_mov_b32 m0, s79
	s_nop 0
	global_load_lds_dwordx4 v142, s[30:31] offset:0
	s_nop 0
	s_mov_b32 m0, s80
	s_nop 0
	global_load_lds_dwordx4 v144, s[30:31] offset:0
	s_nop 0
	s_mov_b32 m0, s77
	s_nop 0
	global_load_lds_dwordx4 v1, s[40:41] offset:0
	s_nop 0
	s_mov_b32 m0, s78
	s_nop 0
	global_load_lds_dwordx4 v143, s[40:41] offset:0
	s_waitcnt vmcnt(8)
	s_waitcnt lgkmcnt(0)
	s_barrier
	s_setprio 1
	v_mfma_f32_16x16x32_bf16 v[30:33], v[12:15], v[38:41], v[138:141]
	v_mfma_f32_16x16x32_bf16 v[66:69], v[16:19], v[42:45], v[30:33]
	v_mfma_f32_16x16x32_bf16 v[30:33], v[22:25], v[38:41], v[152:155]
	v_mfma_f32_16x16x32_bf16 v[62:65], v[26:29], v[42:45], v[30:33]
	v_mfma_f32_16x16x32_bf16 v[30:33], v[12:15], v[220:223], v[156:159]
	v_mfma_f32_16x16x32_bf16 v[50:53], v[16:19], v[224:227], v[30:33]
	v_mfma_f32_16x16x32_bf16 v[30:33], v[22:25], v[220:223], v[160:163]
	v_mfma_f32_16x16x32_bf16 v[46:49], v[26:29], v[224:227], v[30:33]
	v_mfma_f32_16x16x32_bf16 v[30:33], v[12:15], v[228:231], v[164:167]
	v_mfma_f32_16x16x32_bf16 v[4:7], v[12:15], v[236:239], v[4:7]
	v_mfma_f32_16x16x32_bf16 v[34:37], v[16:19], v[232:235], v[30:33]
	v_mfma_f32_16x16x32_bf16 v[30:33], v[22:25], v[228:231], v[168:171]
	v_mfma_f32_16x16x32_bf16 v[18:21], v[16:19], v[240:243], v[4:7]
	v_mfma_f32_16x16x32_bf16 v[4:7], v[22:25], v[236:239], v[8:11]
	v_mfma_f32_16x16x32_bf16 v[30:33], v[26:29], v[232:235], v[30:33]
	v_mfma_f32_16x16x32_bf16 v[14:17], v[26:29], v[240:243], v[4:7]
	s_setprio 0
	s_setprio 1
	v_mfma_f32_16x16x32_bf16 v[4:7], v[204:207], v[38:41], v[172:175]
	v_mfma_f32_16x16x32_bf16 v[58:61], v[208:211], v[42:45], v[4:7]
	v_mfma_f32_16x16x32_bf16 v[4:7], v[212:215], v[38:41], v[176:179]
	v_mfma_f32_16x16x32_bf16 v[54:57], v[216:219], v[42:45], v[4:7]
	v_mfma_f32_16x16x32_bf16 v[4:7], v[204:207], v[220:223], v[180:183]
	v_mfma_f32_16x16x32_bf16 v[42:45], v[208:211], v[224:227], v[4:7]
	v_mfma_f32_16x16x32_bf16 v[4:7], v[212:215], v[220:223], v[184:187]
	v_mfma_f32_16x16x32_bf16 v[38:41], v[216:219], v[224:227], v[4:7]
	v_mfma_f32_16x16x32_bf16 v[4:7], v[204:207], v[228:231], v[188:191]
	v_mfma_f32_16x16x32_bf16 v[26:29], v[208:211], v[232:235], v[4:7]
	v_mfma_f32_16x16x32_bf16 v[4:7], v[212:215], v[228:231], v[192:195]
	v_mfma_f32_16x16x32_bf16 v[22:25], v[216:219], v[232:235], v[4:7]
	v_mfma_f32_16x16x32_bf16 v[4:7], v[204:207], v[236:239], v[196:199]
	v_mfma_f32_16x16x32_bf16 v[10:13], v[208:211], v[240:243], v[4:7]
	v_mfma_f32_16x16x32_bf16 v[4:7], v[212:215], v[236:239], v[200:203]
	v_mfma_f32_16x16x32_bf16 v[6:9], v[216:219], v[240:243], v[4:7]
	s_barrier
	s_setprio 0
	s_mov_b32 s64, 2
	s_branch .LBB0_627

.LBB0_628:
	ds_read_b128 v[138:141], v147
	ds_read_b128 v[152:155], v147 offset:1024
	ds_read_b128 v[156:159], v147 offset:2048
	ds_read_b128 v[160:163], v147 offset:3072
	ds_read_b128 v[164:167], v148
	ds_read_b128 v[168:171], v148 offset:1024
	ds_read_b128 v[172:175], v148 offset:2048
	ds_read_b128 v[176:179], v148 offset:3072
	s_cmp_eq_u32 s88, 28
	s_cselect_b32 s66, s47, s91
	s_cselect_b32 s67, s39, s92
	s_cselect_b32 s64, s87, s89
	s_cselect_b32 s65, s37, s90
	s_add_u32 s58, s66, 0x80
	s_addc_u32 s59, s67, 0
	ds_read_b128 v[180:183], v149
	ds_read_b128 v[184:187], v149 offset:1024
	ds_read_b128 v[188:191], v149 offset:2048
	ds_read_b128 v[192:195], v149 offset:3072
	ds_read_b128 v[196:199], v149 offset:4096
	ds_read_b128 v[200:203], v149 offset:5120
	ds_read_b128 v[204:207], v149 offset:6144
	ds_read_b128 v[208:211], v149 offset:7168
	s_mov_b32 m0, s81
	s_nop 0
	global_load_lds_dwordx4 v1, s[56:57] offset:0
	s_nop 0
	s_mov_b32 m0, s82
	s_nop 0
	global_load_lds_dwordx4 v143, s[56:57] offset:0
	s_waitcnt vmcnt(8)
	s_waitcnt lgkmcnt(0)
	s_barrier
	s_setprio 1
	v_mfma_f32_16x16x32_bf16 v[130:133], v[138:141], v[180:183], v[130:133]
	v_mfma_f32_16x16x32_bf16 v[130:133], v[152:155], v[184:187], v[130:133]
	v_mfma_f32_16x16x32_bf16 v[126:129], v[156:159], v[180:183], v[126:129]
	v_mfma_f32_16x16x32_bf16 v[126:129], v[160:163], v[184:187], v[126:129]
	v_mfma_f32_16x16x32_bf16 v[114:117], v[138:141], v[188:191], v[114:117]
	v_mfma_f32_16x16x32_bf16 v[114:117], v[152:155], v[192:195], v[114:117]
	v_mfma_f32_16x16x32_bf16 v[110:113], v[156:159], v[188:191], v[110:113]
	v_mfma_f32_16x16x32_bf16 v[110:113], v[160:163], v[192:195], v[110:113]
	v_mfma_f32_16x16x32_bf16 v[98:101], v[138:141], v[196:199], v[98:101]
	v_mfma_f32_16x16x32_bf16 v[98:101], v[152:155], v[200:203], v[98:101]
	v_mfma_f32_16x16x32_bf16 v[94:97], v[156:159], v[196:199], v[94:97]
	v_mfma_f32_16x16x32_bf16 v[94:97], v[160:163], v[200:203], v[94:97]
	v_mfma_f32_16x16x32_bf16 v[82:85], v[138:141], v[204:207], v[82:85]
	v_mfma_f32_16x16x32_bf16 v[82:85], v[152:155], v[208:211], v[82:85]
	v_mfma_f32_16x16x32_bf16 v[78:81], v[156:159], v[204:207], v[78:81]
	v_mfma_f32_16x16x32_bf16 v[78:81], v[160:163], v[208:211], v[78:81]
	s_setprio 0
	s_setprio 1
	v_mfma_f32_16x16x32_bf16 v[122:125], v[164:167], v[180:183], v[122:125]
	v_mfma_f32_16x16x32_bf16 v[122:125], v[168:171], v[184:187], v[122:125]
	v_mfma_f32_16x16x32_bf16 v[118:121], v[172:175], v[180:183], v[118:121]
	v_mfma_f32_16x16x32_bf16 v[118:121], v[176:179], v[184:187], v[118:121]
	v_mfma_f32_16x16x32_bf16 v[106:109], v[164:167], v[188:191], v[106:109]
	v_mfma_f32_16x16x32_bf16 v[106:109], v[168:171], v[192:195], v[106:109]
	v_mfma_f32_16x16x32_bf16 v[102:105], v[172:175], v[188:191], v[102:105]
	v_mfma_f32_16x16x32_bf16 v[102:105], v[176:179], v[192:195], v[102:105]
	v_mfma_f32_16x16x32_bf16 v[90:93], v[164:167], v[196:199], v[90:93]
	v_mfma_f32_16x16x32_bf16 v[90:93], v[168:171], v[200:203], v[90:93]
	v_mfma_f32_16x16x32_bf16 v[86:89], v[172:175], v[196:199], v[86:89]
	v_mfma_f32_16x16x32_bf16 v[86:89], v[176:179], v[200:203], v[86:89]
	v_mfma_f32_16x16x32_bf16 v[74:77], v[164:167], v[204:207], v[74:77]
	v_mfma_f32_16x16x32_bf16 v[74:77], v[168:171], v[208:211], v[74:77]
	v_mfma_f32_16x16x32_bf16 v[70:73], v[172:175], v[204:207], v[70:73]
	v_mfma_f32_16x16x32_bf16 v[70:73], v[176:179], v[208:211], v[70:73]
	s_barrier
	s_setprio 0
	ds_read_b128 v[180:183], v149 offset:16384
	ds_read_b128 v[184:187], v149 offset:17408
	ds_read_b128 v[188:191], v149 offset:18432
	ds_read_b128 v[192:195], v149 offset:19456
	ds_read_b128 v[196:199], v149 offset:20480
	ds_read_b128 v[200:203], v149 offset:21504
	ds_read_b128 v[204:207], v149 offset:22528
	ds_read_b128 v[208:211], v149 offset:23552
	s_mov_b32 m0, s52
	s_nop 0
	global_load_lds_dwordx4 v142, s[64:65] offset:0
	s_add_u32 s30, s64, 0x80000
	s_mov_b32 m0, s53
	s_nop 0
	global_load_lds_dwordx4 v144, s[64:65] offset:0
	s_addc_u32 s31, s65, 0
	s_mov_b32 m0, s55
	s_nop 0
	global_load_lds_dwordx4 v142, s[30:31] offset:0
	s_nop 0
	s_mov_b32 m0, s68
	s_nop 0
	global_load_lds_dwordx4 v144, s[30:31] offset:0
	s_nop 0
	s_mov_b32 m0, s33
	s_nop 0
	global_load_lds_dwordx4 v1, s[66:67] offset:0
	s_nop 0
	s_mov_b32 m0, s69
	s_nop 0
	global_load_lds_dwordx4 v143, s[66:67] offset:0
	s_waitcnt vmcnt(8)
	s_waitcnt lgkmcnt(0)
	s_barrier
	s_setprio 1
	v_mfma_f32_16x16x32_bf16 v[66:69], v[138:141], v[180:183], v[66:69]
	v_mfma_f32_16x16x32_bf16 v[66:69], v[152:155], v[184:187], v[66:69]
	v_mfma_f32_16x16x32_bf16 v[62:65], v[156:159], v[180:183], v[62:65]
	v_mfma_f32_16x16x32_bf16 v[62:65], v[160:163], v[184:187], v[62:65]
	v_mfma_f32_16x16x32_bf16 v[50:53], v[138:141], v[188:191], v[50:53]
	v_mfma_f32_16x16x32_bf16 v[50:53], v[152:155], v[192:195], v[50:53]
	v_mfma_f32_16x16x32_bf16 v[46:49], v[156:159], v[188:191], v[46:49]
	v_mfma_f32_16x16x32_bf16 v[46:49], v[160:163], v[192:195], v[46:49]
	v_mfma_f32_16x16x32_bf16 v[34:37], v[138:141], v[196:199], v[34:37]
	v_mfma_f32_16x16x32_bf16 v[34:37], v[152:155], v[200:203], v[34:37]
	v_mfma_f32_16x16x32_bf16 v[30:33], v[156:159], v[196:199], v[30:33]
	v_mfma_f32_16x16x32_bf16 v[30:33], v[160:163], v[200:203], v[30:33]
	v_mfma_f32_16x16x32_bf16 v[18:21], v[138:141], v[204:207], v[18:21]
	v_mfma_f32_16x16x32_bf16 v[18:21], v[152:155], v[208:211], v[18:21]
	v_mfma_f32_16x16x32_bf16 v[14:17], v[156:159], v[204:207], v[14:17]
	v_mfma_f32_16x16x32_bf16 v[14:17], v[160:163], v[208:211], v[14:17]
	s_setprio 0
	s_setprio 1
	v_mfma_f32_16x16x32_bf16 v[58:61], v[164:167], v[180:183], v[58:61]
	v_mfma_f32_16x16x32_bf16 v[54:57], v[172:175], v[180:183], v[54:57]
	v_mfma_f32_16x16x32_bf16 v[42:45], v[164:167], v[188:191], v[42:45]
	v_mfma_f32_16x16x32_bf16 v[38:41], v[172:175], v[188:191], v[38:41]
	v_mfma_f32_16x16x32_bf16 v[26:29], v[164:167], v[196:199], v[26:29]
	v_mfma_f32_16x16x32_bf16 v[22:25], v[172:175], v[196:199], v[22:25]
	v_mfma_f32_16x16x32_bf16 v[10:13], v[164:167], v[204:207], v[10:13]
	v_mfma_f32_16x16x32_bf16 v[4:7], v[172:175], v[204:207], v[6:9]
	v_mfma_f32_16x16x32_bf16 v[58:61], v[168:171], v[184:187], v[58:61]
	v_mfma_f32_16x16x32_bf16 v[54:57], v[176:179], v[184:187], v[54:57]
	v_mfma_f32_16x16x32_bf16 v[42:45], v[168:171], v[192:195], v[42:45]
	v_mfma_f32_16x16x32_bf16 v[38:41], v[176:179], v[192:195], v[38:41]
	v_mfma_f32_16x16x32_bf16 v[26:29], v[168:171], v[200:203], v[26:29]
	v_mfma_f32_16x16x32_bf16 v[22:25], v[176:179], v[200:203], v[22:25]
	v_mfma_f32_16x16x32_bf16 v[10:13], v[168:171], v[208:211], v[10:13]
	v_mfma_f32_16x16x32_bf16 v[4:7], v[176:179], v[208:211], v[4:7]
	s_barrier
	s_setprio 0
	ds_read_b128 v[138:141], v150
	ds_read_b128 v[152:155], v150 offset:1024
	ds_read_b128 v[156:159], v150 offset:2048
	ds_read_b128 v[160:163], v150 offset:3072
	ds_read_b128 v[164:167], v151
	ds_read_b128 v[168:171], v151 offset:1024
	ds_read_b128 v[172:175], v151 offset:2048
	ds_read_b128 v[176:179], v151 offset:3072
	ds_read_b128 v[180:183], v149 offset:32768
	ds_read_b128 v[184:187], v149 offset:33792
	ds_read_b128 v[188:191], v149 offset:34816
	ds_read_b128 v[192:195], v149 offset:35840
	ds_read_b128 v[196:199], v149 offset:36864
	ds_read_b128 v[200:203], v149 offset:37888
	ds_read_b128 v[204:207], v149 offset:38912
	ds_read_b128 v[208:211], v149 offset:39936
	s_add_u32 s30, s66, 0x80000
	s_addc_u32 s31, s67, 0
	s_mov_b32 m0, s70
	s_nop 0
	global_load_lds_dwordx4 v1, s[30:31] offset:0
	s_nop 0
	s_mov_b32 m0, s71
	s_nop 0
	global_load_lds_dwordx4 v143, s[30:31] offset:0
	s_waitcnt vmcnt(8)
	s_waitcnt lgkmcnt(0)
	s_barrier
	s_setprio 1
	v_mfma_f32_16x16x32_bf16 v[130:133], v[138:141], v[180:183], v[130:133]
	v_mfma_f32_16x16x32_bf16 v[130:133], v[152:155], v[184:187], v[130:133]
	v_mfma_f32_16x16x32_bf16 v[126:129], v[156:159], v[180:183], v[126:129]
	v_mfma_f32_16x16x32_bf16 v[126:129], v[160:163], v[184:187], v[126:129]
	v_mfma_f32_16x16x32_bf16 v[114:117], v[138:141], v[188:191], v[114:117]
	v_mfma_f32_16x16x32_bf16 v[114:117], v[152:155], v[192:195], v[114:117]
	v_mfma_f32_16x16x32_bf16 v[110:113], v[156:159], v[188:191], v[110:113]
	v_mfma_f32_16x16x32_bf16 v[110:113], v[160:163], v[192:195], v[110:113]
	v_mfma_f32_16x16x32_bf16 v[98:101], v[138:141], v[196:199], v[98:101]
	v_mfma_f32_16x16x32_bf16 v[98:101], v[152:155], v[200:203], v[98:101]
	v_mfma_f32_16x16x32_bf16 v[94:97], v[156:159], v[196:199], v[94:97]
	v_mfma_f32_16x16x32_bf16 v[94:97], v[160:163], v[200:203], v[94:97]
	v_mfma_f32_16x16x32_bf16 v[82:85], v[138:141], v[204:207], v[82:85]
	v_mfma_f32_16x16x32_bf16 v[82:85], v[152:155], v[208:211], v[82:85]
	v_mfma_f32_16x16x32_bf16 v[78:81], v[156:159], v[204:207], v[78:81]
	v_mfma_f32_16x16x32_bf16 v[78:81], v[160:163], v[208:211], v[78:81]
	s_setprio 0
	s_setprio 1
	v_mfma_f32_16x16x32_bf16 v[122:125], v[164:167], v[180:183], v[122:125]
	v_mfma_f32_16x16x32_bf16 v[122:125], v[168:171], v[184:187], v[122:125]
	v_mfma_f32_16x16x32_bf16 v[118:121], v[172:175], v[180:183], v[118:121]
	v_mfma_f32_16x16x32_bf16 v[118:121], v[176:179], v[184:187], v[118:121]
	v_mfma_f32_16x16x32_bf16 v[106:109], v[164:167], v[188:191], v[106:109]
	v_mfma_f32_16x16x32_bf16 v[106:109], v[168:171], v[192:195], v[106:109]
	v_mfma_f32_16x16x32_bf16 v[102:105], v[172:175], v[188:191], v[102:105]
	v_mfma_f32_16x16x32_bf16 v[102:105], v[176:179], v[192:195], v[102:105]
	v_mfma_f32_16x16x32_bf16 v[90:93], v[164:167], v[196:199], v[90:93]
	v_mfma_f32_16x16x32_bf16 v[90:93], v[168:171], v[200:203], v[90:93]
	v_mfma_f32_16x16x32_bf16 v[86:89], v[172:175], v[196:199], v[86:89]
	v_mfma_f32_16x16x32_bf16 v[86:89], v[176:179], v[200:203], v[86:89]
	v_mfma_f32_16x16x32_bf16 v[74:77], v[164:167], v[204:207], v[74:77]
	v_mfma_f32_16x16x32_bf16 v[74:77], v[168:171], v[208:211], v[74:77]
	v_mfma_f32_16x16x32_bf16 v[70:73], v[172:175], v[204:207], v[70:73]
	v_mfma_f32_16x16x32_bf16 v[70:73], v[176:179], v[208:211], v[70:73]
	s_barrier
	s_setprio 0
	ds_read_b128 v[180:183], v149 offset:49152
	ds_read_b128 v[184:187], v149 offset:50176
	ds_read_b128 v[188:191], v149 offset:51200
	ds_read_b128 v[192:195], v149 offset:52224
	ds_read_b128 v[196:199], v149 offset:53248
	ds_read_b128 v[200:203], v149 offset:54272
	ds_read_b128 v[204:207], v149 offset:55296
	ds_read_b128 v[208:211], v149 offset:56320
	s_add_u32 s30, s64, 0x80
	s_addc_u32 s31, s65, 0
	s_mov_b32 m0, s75
	s_nop 0
	global_load_lds_dwordx4 v142, s[30:31] offset:0
	s_nop 0
	s_mov_b32 m0, s76
	s_nop 0
	global_load_lds_dwordx4 v144, s[30:31] offset:0
	s_add_u32 s30, s64, 0x80080
	s_addc_u32 s31, s65, 0
	s_mov_b32 m0, s79
	s_nop 0
	global_load_lds_dwordx4 v142, s[30:31] offset:0
	s_nop 0
	s_mov_b32 m0, s80
	s_nop 0
	global_load_lds_dwordx4 v144, s[30:31] offset:0
	s_nop 0
	s_mov_b32 m0, s77
	s_nop 0
	global_load_lds_dwordx4 v1, s[58:59] offset:0
	s_nop 0
	s_mov_b32 m0, s78
	s_nop 0
	global_load_lds_dwordx4 v143, s[58:59] offset:0
	s_waitcnt vmcnt(8)
	s_waitcnt lgkmcnt(0)
	s_barrier
	s_setprio 1
	v_mfma_f32_16x16x32_bf16 v[66:69], v[138:141], v[180:183], v[66:69]
	v_mfma_f32_16x16x32_bf16 v[66:69], v[152:155], v[184:187], v[66:69]
	v_mfma_f32_16x16x32_bf16 v[62:65], v[156:159], v[180:183], v[62:65]
	v_mfma_f32_16x16x32_bf16 v[62:65], v[160:163], v[184:187], v[62:65]
	v_mfma_f32_16x16x32_bf16 v[50:53], v[138:141], v[188:191], v[50:53]
	v_mfma_f32_16x16x32_bf16 v[50:53], v[152:155], v[192:195], v[50:53]
	v_mfma_f32_16x16x32_bf16 v[46:49], v[156:159], v[188:191], v[46:49]
	v_mfma_f32_16x16x32_bf16 v[46:49], v[160:163], v[192:195], v[46:49]
	v_mfma_f32_16x16x32_bf16 v[34:37], v[138:141], v[196:199], v[34:37]
	v_mfma_f32_16x16x32_bf16 v[34:37], v[152:155], v[200:203], v[34:37]
	v_mfma_f32_16x16x32_bf16 v[30:33], v[156:159], v[196:199], v[30:33]
	v_mfma_f32_16x16x32_bf16 v[30:33], v[160:163], v[200:203], v[30:33]
	v_mfma_f32_16x16x32_bf16 v[18:21], v[138:141], v[204:207], v[18:21]
	v_mfma_f32_16x16x32_bf16 v[18:21], v[152:155], v[208:211], v[18:21]
	v_mfma_f32_16x16x32_bf16 v[14:17], v[156:159], v[204:207], v[14:17]
	v_mfma_f32_16x16x32_bf16 v[14:17], v[160:163], v[208:211], v[14:17]
	s_setprio 0
	s_setprio 1
	v_mfma_f32_16x16x32_bf16 v[58:61], v[164:167], v[180:183], v[58:61]
	v_mfma_f32_16x16x32_bf16 v[54:57], v[172:175], v[180:183], v[54:57]
	v_mfma_f32_16x16x32_bf16 v[42:45], v[164:167], v[188:191], v[42:45]
	v_mfma_f32_16x16x32_bf16 v[38:41], v[172:175], v[188:191], v[38:41]
	v_mfma_f32_16x16x32_bf16 v[26:29], v[164:167], v[196:199], v[26:29]
	v_mfma_f32_16x16x32_bf16 v[22:25], v[172:175], v[196:199], v[22:25]
	v_mfma_f32_16x16x32_bf16 v[8:11], v[164:167], v[204:207], v[10:13]
	v_mfma_f32_16x16x32_bf16 v[4:7], v[172:175], v[204:207], v[4:7]
	v_mfma_f32_16x16x32_bf16 v[58:61], v[168:171], v[184:187], v[58:61]
	v_mfma_f32_16x16x32_bf16 v[54:57], v[176:179], v[184:187], v[54:57]
	v_mfma_f32_16x16x32_bf16 v[42:45], v[168:171], v[192:195], v[42:45]
	v_mfma_f32_16x16x32_bf16 v[38:41], v[176:179], v[192:195], v[38:41]
	v_mfma_f32_16x16x32_bf16 v[26:29], v[168:171], v[200:203], v[26:29]
	v_mfma_f32_16x16x32_bf16 v[22:25], v[176:179], v[200:203], v[22:25]
	v_mfma_f32_16x16x32_bf16 v[10:13], v[168:171], v[208:211], v[8:11]
	v_mfma_f32_16x16x32_bf16 v[6:9], v[176:179], v[208:211], v[4:7]
	s_barrier
	s_setprio 0
	s_add_i32 s88, s88, 2
	s_add_u32 s89, s89, 0x100
	s_addc_u32 s90, s90, 0
	s_add_u32 s91, s91, 0x100
	s_addc_u32 s92, s92, 0
	s_add_u32 s56, s56, 0x100
	s_addc_u32 s57, s57, 0
	s_cmp_gt_u32 s88, 29
	s_cbranch_scc0 .LBB0_628
	s_and_b64 vcc, exec, s[20:21]
	s_cbranch_vccz .LBB0_631
	s_barrier

.LBB0_783:
	s_cmp_lg_u32 s77, 0
	s_mov_b32 s44, 0
	s_cbranch_scc0 .LBB0_785
	ds_read_b128 v[4:7], v152
	ds_read_b128 v[8:11], v152 offset:1024
	ds_read_b128 v[12:15], v152 offset:2048
	ds_read_b128 v[16:19], v152 offset:3072
	ds_read_b128 v[20:23], v153
	ds_read_b128 v[24:27], v153 offset:1024
	ds_read_b128 v[28:31], v153 offset:2048
	ds_read_b128 v[32:35], v153 offset:3072
	s_add_u32 s28, s38, 0x100
	s_addc_u32 s29, s39, 0
	s_add_u32 s30, s40, 0x100
	s_addc_u32 s31, s41, 0
	s_add_u32 s24, s38, 0x180
	s_addc_u32 s25, s39, 0
	ds_read_b128 v[36:39], v154
	ds_read_b128 v[40:43], v154 offset:1024
	ds_read_b128 v[44:47], v154 offset:2048
	ds_read_b128 v[48:51], v154 offset:3072
	ds_read_b128 v[52:55], v154 offset:4096
	ds_read_b128 v[56:59], v154 offset:5120
	ds_read_b128 v[60:63], v154 offset:6144
	ds_read_b128 v[64:67], v154 offset:7168
	s_add_u32 s42, s38, 0x80080
	s_addc_u32 s43, s39, 0
	s_mov_b32 m0, s68
	s_nop 0
	global_load_lds_dwordx4 v1, s[42:43] offset:0
	s_nop 0
	s_mov_b32 m0, s69
	s_nop 0
	global_load_lds_dwordx4 v147, s[42:43] offset:0
	s_waitcnt vmcnt(16)
	s_waitcnt lgkmcnt(0)
	s_barrier
	s_setprio 1
	v_mfma_f32_16x16x32_bf16 v[92:95], v[4:7], v[60:63], 0
	v_mfma_f32_16x16x32_bf16 v[68:71], v[4:7], v[36:39], 0
	v_mfma_f32_16x16x32_bf16 v[72:75], v[12:15], v[36:39], 0
	v_mfma_f32_16x16x32_bf16 v[76:79], v[4:7], v[44:47], 0
	v_mfma_f32_16x16x32_bf16 v[80:83], v[12:15], v[44:47], 0
	v_mfma_f32_16x16x32_bf16 v[84:87], v[4:7], v[52:55], 0
	v_mfma_f32_16x16x32_bf16 v[88:91], v[12:15], v[52:55], 0
	v_mfma_f32_16x16x32_bf16 v[102:105], v[8:11], v[64:67], v[92:95]
	v_mfma_f32_16x16x32_bf16 v[92:95], v[12:15], v[60:63], 0
	v_mfma_f32_16x16x32_bf16 v[68:71], v[8:11], v[40:43], v[68:71]
	v_mfma_f32_16x16x32_bf16 v[72:75], v[16:19], v[40:43], v[72:75]
	v_mfma_f32_16x16x32_bf16 v[76:79], v[8:11], v[48:51], v[76:79]
	v_mfma_f32_16x16x32_bf16 v[80:83], v[16:19], v[48:51], v[80:83]
	v_mfma_f32_16x16x32_bf16 v[84:87], v[8:11], v[56:59], v[84:87]
	v_mfma_f32_16x16x32_bf16 v[88:91], v[16:19], v[56:59], v[88:91]
	v_mfma_f32_16x16x32_bf16 v[106:109], v[16:19], v[64:67], v[92:95]
	s_setprio 0
	s_setprio 1
	v_mfma_f32_16x16x32_bf16 v[92:95], v[20:23], v[36:39], 0
	v_mfma_f32_16x16x32_bf16 v[36:39], v[28:31], v[36:39], 0
	v_mfma_f32_16x16x32_bf16 v[118:121], v[24:27], v[40:43], v[92:95]
	v_mfma_f32_16x16x32_bf16 v[36:39], v[32:35], v[40:43], v[36:39]
	v_mfma_f32_16x16x32_bf16 v[40:43], v[20:23], v[44:47], 0
	v_mfma_f32_16x16x32_bf16 v[44:47], v[28:31], v[44:47], 0
	v_mfma_f32_16x16x32_bf16 v[40:43], v[24:27], v[48:51], v[40:43]
	v_mfma_f32_16x16x32_bf16 v[44:47], v[32:35], v[48:51], v[44:47]
	v_mfma_f32_16x16x32_bf16 v[48:51], v[20:23], v[52:55], 0
	v_mfma_f32_16x16x32_bf16 v[52:55], v[28:31], v[52:55], 0
	v_mfma_f32_16x16x32_bf16 v[48:51], v[24:27], v[56:59], v[48:51]
	v_mfma_f32_16x16x32_bf16 v[52:55], v[32:35], v[56:59], v[52:55]
	v_mfma_f32_16x16x32_bf16 v[56:59], v[20:23], v[60:63], 0
	v_mfma_f32_16x16x32_bf16 v[60:63], v[28:31], v[60:63], 0
	v_mfma_f32_16x16x32_bf16 v[56:59], v[24:27], v[64:67], v[56:59]
	v_mfma_f32_16x16x32_bf16 v[60:63], v[32:35], v[64:67], v[60:63]
	s_barrier
	s_setprio 0
	ds_read_b128 v[64:67], v154 offset:16384
	ds_read_b128 v[92:95], v154 offset:17408
	ds_read_b128 v[96:99], v154 offset:18432
	ds_read_b128 v[110:113], v154 offset:19456
	ds_read_b128 v[114:117], v154 offset:20480
	ds_read_b128 v[122:125], v154 offset:21504
	ds_read_b128 v[126:129], v154 offset:22528
	ds_read_b128 v[130:133], v154 offset:23552
	s_mov_b32 m0, s37
	s_nop 0
	global_load_lds_dwordx4 v146, s[30:31] offset:0
	s_nop 0
	s_mov_b32 m0, s52
	s_nop 0
	global_load_lds_dwordx4 v148, s[30:31] offset:0
	s_add_u32 s30, s40, 0x80100
	s_addc_u32 s31, s41, 0
	s_mov_b32 m0, s53
	s_nop 0
	global_load_lds_dwordx4 v146, s[30:31] offset:0
	s_nop 0
	s_mov_b32 m0, s54
	s_nop 0
	global_load_lds_dwordx4 v148, s[30:31] offset:0
	s_nop 0
	s_mov_b32 m0, s23
	s_nop 0
	global_load_lds_dwordx4 v1, s[28:29] offset:0
	s_nop 0
	s_mov_b32 m0, s55
	s_nop 0
	global_load_lds_dwordx4 v147, s[28:29] offset:0
	s_waitcnt vmcnt(16)
	s_waitcnt lgkmcnt(0)
	s_barrier
	s_setprio 1
	v_mfma_f32_16x16x32_bf16 v[138:141], v[4:7], v[64:67], 0
	v_mfma_f32_16x16x32_bf16 v[158:161], v[4:7], v[96:99], 0
	v_mfma_f32_16x16x32_bf16 v[166:169], v[4:7], v[114:117], 0
	v_mfma_f32_16x16x32_bf16 v[4:7], v[4:7], v[126:129], 0
	v_mfma_f32_16x16x32_bf16 v[138:141], v[8:11], v[92:95], v[138:141]
	v_mfma_f32_16x16x32_bf16 v[158:161], v[8:11], v[110:113], v[158:161]
	v_mfma_f32_16x16x32_bf16 v[166:169], v[8:11], v[122:125], v[166:169]
	v_mfma_f32_16x16x32_bf16 v[4:7], v[8:11], v[130:133], v[4:7]
	v_mfma_f32_16x16x32_bf16 v[8:11], v[12:15], v[126:129], 0
	v_mfma_f32_16x16x32_bf16 v[142:145], v[12:15], v[64:67], 0
	v_mfma_f32_16x16x32_bf16 v[162:165], v[12:15], v[96:99], 0
	v_mfma_f32_16x16x32_bf16 v[170:173], v[12:15], v[114:117], 0
	v_mfma_f32_16x16x32_bf16 v[8:11], v[16:19], v[130:133], v[8:11]
	v_mfma_f32_16x16x32_bf16 v[142:145], v[16:19], v[92:95], v[142:145]
	v_mfma_f32_16x16x32_bf16 v[162:165], v[16:19], v[110:113], v[162:165]
	v_mfma_f32_16x16x32_bf16 v[170:173], v[16:19], v[122:125], v[170:173]
	s_setprio 0
	s_setprio 1
	v_mfma_f32_16x16x32_bf16 v[12:15], v[20:23], v[64:67], 0
	v_mfma_f32_16x16x32_bf16 v[174:177], v[24:27], v[92:95], v[12:15]
	v_mfma_f32_16x16x32_bf16 v[12:15], v[28:31], v[64:67], 0
	v_mfma_f32_16x16x32_bf16 v[178:181], v[32:35], v[92:95], v[12:15]
	v_mfma_f32_16x16x32_bf16 v[12:15], v[20:23], v[96:99], 0
	v_mfma_f32_16x16x32_bf16 v[182:185], v[24:27], v[110:113], v[12:15]
	v_mfma_f32_16x16x32_bf16 v[12:15], v[28:31], v[96:99], 0
	v_mfma_f32_16x16x32_bf16 v[186:189], v[32:35], v[110:113], v[12:15]
	v_mfma_f32_16x16x32_bf16 v[12:15], v[20:23], v[114:117], 0
	v_mfma_f32_16x16x32_bf16 v[190:193], v[24:27], v[122:125], v[12:15]
	v_mfma_f32_16x16x32_bf16 v[12:15], v[28:31], v[114:117], 0
	v_mfma_f32_16x16x32_bf16 v[194:197], v[32:35], v[122:125], v[12:15]
	v_mfma_f32_16x16x32_bf16 v[12:15], v[20:23], v[126:129], 0
	v_mfma_f32_16x16x32_bf16 v[198:201], v[24:27], v[130:133], v[12:15]
	v_mfma_f32_16x16x32_bf16 v[12:15], v[28:31], v[126:129], 0
	v_mfma_f32_16x16x32_bf16 v[202:205], v[32:35], v[130:133], v[12:15]
	s_barrier
	s_setprio 0
	s_nop 4
	ds_read_b128 v[12:15], v155
	ds_read_b128 v[16:19], v155 offset:1024
	ds_read_b128 v[22:25], v155 offset:2048
	ds_read_b128 v[26:29], v155 offset:3072
	ds_read_b128 v[206:209], v156
	ds_read_b128 v[210:213], v156 offset:1024
	ds_read_b128 v[214:217], v156 offset:2048
	ds_read_b128 v[218:221], v156 offset:3072
	ds_read_b128 v[30:33], v154 offset:32768
	ds_read_b128 v[64:67], v154 offset:33792
	ds_read_b128 v[222:225], v154 offset:34816
	ds_read_b128 v[226:229], v154 offset:35840
	ds_read_b128 v[230:233], v154 offset:36864
	ds_read_b128 v[234:237], v154 offset:37888
	ds_read_b128 v[238:241], v154 offset:38912
	ds_read_b128 v[242:245], v154 offset:39936
	s_add_u32 s28, s38, 0x80100
	s_addc_u32 s29, s39, 0
	s_mov_b32 m0, s56
	s_nop 0
	global_load_lds_dwordx4 v1, s[28:29] offset:0
	s_nop 0
	s_mov_b32 m0, s57
	s_nop 0
	global_load_lds_dwordx4 v147, s[28:29] offset:0
	s_waitcnt vmcnt(8)
	s_waitcnt lgkmcnt(0)
	s_barrier
	s_setprio 1
	v_mfma_f32_16x16x32_bf16 v[68:71], v[12:15], v[30:33], v[68:71]
	v_mfma_f32_16x16x32_bf16 v[130:133], v[16:19], v[64:67], v[68:71]
	v_mfma_f32_16x16x32_bf16 v[68:71], v[22:25], v[30:33], v[72:75]
	v_mfma_f32_16x16x32_bf16 v[126:129], v[26:29], v[64:67], v[68:71]
	v_mfma_f32_16x16x32_bf16 v[68:71], v[12:15], v[222:225], v[76:79]
	v_mfma_f32_16x16x32_bf16 v[114:117], v[16:19], v[226:229], v[68:71]
	v_mfma_f32_16x16x32_bf16 v[68:71], v[22:25], v[222:225], v[80:83]
	v_mfma_f32_16x16x32_bf16 v[110:113], v[26:29], v[226:229], v[68:71]
	v_mfma_f32_16x16x32_bf16 v[68:71], v[12:15], v[230:233], v[84:87]
	v_mfma_f32_16x16x32_bf16 v[98:101], v[16:19], v[234:237], v[68:71]
	v_mfma_f32_16x16x32_bf16 v[68:71], v[22:25], v[230:233], v[88:91]
	v_mfma_f32_16x16x32_bf16 v[94:97], v[26:29], v[234:237], v[68:71]
	v_mfma_f32_16x16x32_bf16 v[68:71], v[12:15], v[238:241], v[102:105]
	v_mfma_f32_16x16x32_bf16 v[82:85], v[16:19], v[242:245], v[68:71]
	v_mfma_f32_16x16x32_bf16 v[68:71], v[22:25], v[238:241], v[106:109]
	v_mfma_f32_16x16x32_bf16 v[78:81], v[26:29], v[242:245], v[68:71]
	s_setprio 0
	s_setprio 1
	v_mfma_f32_16x16x32_bf16 v[68:71], v[206:209], v[30:33], v[118:121]
	v_mfma_f32_16x16x32_bf16 v[30:33], v[214:217], v[30:33], v[36:39]
	v_mfma_f32_16x16x32_bf16 v[118:121], v[218:221], v[64:67], v[30:33]
	v_mfma_f32_16x16x32_bf16 v[30:33], v[206:209], v[222:225], v[40:43]
	v_mfma_f32_16x16x32_bf16 v[106:109], v[210:213], v[226:229], v[30:33]
	v_mfma_f32_16x16x32_bf16 v[30:33], v[214:217], v[222:225], v[44:47]
	v_mfma_f32_16x16x32_bf16 v[102:105], v[218:221], v[226:229], v[30:33]
	v_mfma_f32_16x16x32_bf16 v[30:33], v[206:209], v[230:233], v[48:51]
	v_mfma_f32_16x16x32_bf16 v[90:93], v[210:213], v[234:237], v[30:33]
	v_mfma_f32_16x16x32_bf16 v[30:33], v[214:217], v[230:233], v[52:55]
	v_mfma_f32_16x16x32_bf16 v[86:89], v[218:221], v[234:237], v[30:33]
	v_mfma_f32_16x16x32_bf16 v[30:33], v[206:209], v[238:241], v[56:59]
	v_mfma_f32_16x16x32_bf16 v[74:77], v[210:213], v[242:245], v[30:33]
	v_mfma_f32_16x16x32_bf16 v[30:33], v[214:217], v[238:241], v[60:63]
	v_mfma_f32_16x16x32_bf16 v[122:125], v[210:213], v[64:67], v[68:71]
	v_mfma_f32_16x16x32_bf16 v[66:69], v[218:221], v[242:245], v[30:33]
	s_barrier
	s_setprio 0
	ds_read_b128 v[38:41], v154 offset:49152
	ds_read_b128 v[42:45], v154 offset:50176
	ds_read_b128 v[222:225], v154 offset:51200
	ds_read_b128 v[226:229], v154 offset:52224
	ds_read_b128 v[230:233], v154 offset:53248
	ds_read_b128 v[234:237], v154 offset:54272
	ds_read_b128 v[238:241], v154 offset:55296
	ds_read_b128 v[242:245], v154 offset:56320
	s_add_u32 s28, s40, 0x180
	s_addc_u32 s29, s41, 0
	s_mov_b32 m0, s58
	s_nop 0
	global_load_lds_dwordx4 v146, s[28:29] offset:0
	s_nop 0
	s_mov_b32 m0, s59
	s_nop 0
	global_load_lds_dwordx4 v148, s[28:29] offset:0
	s_add_u32 s28, s40, 0x80180
	s_addc_u32 s29, s41, 0
	s_mov_b32 m0, s66
	s_nop 0
	global_load_lds_dwordx4 v146, s[28:29] offset:0
	s_nop 0
	s_mov_b32 m0, s67
	s_nop 0
	global_load_lds_dwordx4 v148, s[28:29] offset:0
	s_nop 0
	s_mov_b32 m0, s64
	s_nop 0
	global_load_lds_dwordx4 v1, s[24:25] offset:0
	s_nop 0
	s_mov_b32 m0, s65
	s_nop 0
	global_load_lds_dwordx4 v147, s[24:25] offset:0
	s_waitcnt vmcnt(8)
	s_waitcnt lgkmcnt(0)
	s_barrier
	s_setprio 1
	v_mfma_f32_16x16x32_bf16 v[30:33], v[12:15], v[38:41], v[138:141]
	v_mfma_f32_16x16x32_bf16 v[70:73], v[16:19], v[42:45], v[30:33]
	v_mfma_f32_16x16x32_bf16 v[30:33], v[22:25], v[38:41], v[142:145]
	v_mfma_f32_16x16x32_bf16 v[62:65], v[26:29], v[42:45], v[30:33]
	v_mfma_f32_16x16x32_bf16 v[30:33], v[12:15], v[222:225], v[158:161]
	v_mfma_f32_16x16x32_bf16 v[50:53], v[16:19], v[226:229], v[30:33]
	v_mfma_f32_16x16x32_bf16 v[30:33], v[22:25], v[222:225], v[162:165]
	v_mfma_f32_16x16x32_bf16 v[46:49], v[26:29], v[226:229], v[30:33]
	v_mfma_f32_16x16x32_bf16 v[30:33], v[12:15], v[230:233], v[166:169]
	v_mfma_f32_16x16x32_bf16 v[4:7], v[12:15], v[238:241], v[4:7]
	v_mfma_f32_16x16x32_bf16 v[34:37], v[16:19], v[234:237], v[30:33]
	v_mfma_f32_16x16x32_bf16 v[30:33], v[22:25], v[230:233], v[170:173]
	v_mfma_f32_16x16x32_bf16 v[18:21], v[16:19], v[242:245], v[4:7]
	v_mfma_f32_16x16x32_bf16 v[4:7], v[22:25], v[238:241], v[8:11]
	v_mfma_f32_16x16x32_bf16 v[30:33], v[26:29], v[234:237], v[30:33]
	v_mfma_f32_16x16x32_bf16 v[14:17], v[26:29], v[242:245], v[4:7]
	s_setprio 0
	s_setprio 1
	v_mfma_f32_16x16x32_bf16 v[4:7], v[206:209], v[38:41], v[174:177]
	v_mfma_f32_16x16x32_bf16 v[58:61], v[210:213], v[42:45], v[4:7]
	v_mfma_f32_16x16x32_bf16 v[4:7], v[214:217], v[38:41], v[178:181]
	v_mfma_f32_16x16x32_bf16 v[54:57], v[218:221], v[42:45], v[4:7]
	v_mfma_f32_16x16x32_bf16 v[4:7], v[206:209], v[222:225], v[182:185]
	v_mfma_f32_16x16x32_bf16 v[42:45], v[210:213], v[226:229], v[4:7]
	v_mfma_f32_16x16x32_bf16 v[4:7], v[214:217], v[222:225], v[186:189]
	v_mfma_f32_16x16x32_bf16 v[38:41], v[218:221], v[226:229], v[4:7]
	v_mfma_f32_16x16x32_bf16 v[4:7], v[206:209], v[230:233], v[190:193]
	v_mfma_f32_16x16x32_bf16 v[26:29], v[210:213], v[234:237], v[4:7]
	v_mfma_f32_16x16x32_bf16 v[4:7], v[214:217], v[230:233], v[194:197]
	v_mfma_f32_16x16x32_bf16 v[22:25], v[218:221], v[234:237], v[4:7]
	v_mfma_f32_16x16x32_bf16 v[4:7], v[206:209], v[238:241], v[198:201]
	v_mfma_f32_16x16x32_bf16 v[10:13], v[210:213], v[242:245], v[4:7]
	v_mfma_f32_16x16x32_bf16 v[4:7], v[214:217], v[238:241], v[202:205]
	v_mfma_f32_16x16x32_bf16 v[6:9], v[218:221], v[242:245], v[4:7]
	s_barrier
	s_setprio 0
	s_mov_b32 s44, 2
	s_branch .LBB0_786

.LBB0_787:
	ds_read_b128 v[138:141], v152
	ds_read_b128 v[142:145], v152 offset:1024
	ds_read_b128 v[158:161], v152 offset:2048
	ds_read_b128 v[162:165], v152 offset:3072
	ds_read_b128 v[166:169], v153
	ds_read_b128 v[170:173], v153 offset:1024
	ds_read_b128 v[174:177], v153 offset:2048
	ds_read_b128 v[178:181], v153 offset:3072
	s_cmp_eq_u32 s80, 28
	s_cselect_b32 s44, s78, s83
	s_cselect_b32 s45, s21, s84
	s_cselect_b32 s40, s79, s81
	s_cselect_b32 s41, s19, s82
	s_add_u32 s38, s44, 0x80
	s_addc_u32 s39, s45, 0
	ds_read_b128 v[182:185], v154
	ds_read_b128 v[186:189], v154 offset:1024
	ds_read_b128 v[190:193], v154 offset:2048
	ds_read_b128 v[194:197], v154 offset:3072
	ds_read_b128 v[198:201], v154 offset:4096
	ds_read_b128 v[202:205], v154 offset:5120
	ds_read_b128 v[206:209], v154 offset:6144
	ds_read_b128 v[210:213], v154 offset:7168
	s_add_u32 s30, s83, 0x7ff80
	s_addc_u32 s31, s84, 0
	s_mov_b32 m0, s68
	s_nop 0
	global_load_lds_dwordx4 v1, s[30:31] offset:0
	s_nop 0
	s_mov_b32 m0, s69
	s_nop 0
	global_load_lds_dwordx4 v147, s[30:31] offset:0
	s_waitcnt vmcnt(8)
	s_waitcnt lgkmcnt(0)
	s_barrier
	s_setprio 1
	v_mfma_f32_16x16x32_bf16 v[130:133], v[138:141], v[182:185], v[130:133]
	v_mfma_f32_16x16x32_bf16 v[130:133], v[142:145], v[186:189], v[130:133]
	v_mfma_f32_16x16x32_bf16 v[126:129], v[158:161], v[182:185], v[126:129]
	v_mfma_f32_16x16x32_bf16 v[126:129], v[162:165], v[186:189], v[126:129]
	v_mfma_f32_16x16x32_bf16 v[114:117], v[138:141], v[190:193], v[114:117]
	v_mfma_f32_16x16x32_bf16 v[114:117], v[142:145], v[194:197], v[114:117]
	v_mfma_f32_16x16x32_bf16 v[110:113], v[158:161], v[190:193], v[110:113]
	v_mfma_f32_16x16x32_bf16 v[110:113], v[162:165], v[194:197], v[110:113]
	v_mfma_f32_16x16x32_bf16 v[98:101], v[138:141], v[198:201], v[98:101]
	v_mfma_f32_16x16x32_bf16 v[98:101], v[142:145], v[202:205], v[98:101]
	v_mfma_f32_16x16x32_bf16 v[94:97], v[158:161], v[198:201], v[94:97]
	v_mfma_f32_16x16x32_bf16 v[94:97], v[162:165], v[202:205], v[94:97]
	v_mfma_f32_16x16x32_bf16 v[82:85], v[138:141], v[206:209], v[82:85]
	v_mfma_f32_16x16x32_bf16 v[82:85], v[142:145], v[210:213], v[82:85]
	v_mfma_f32_16x16x32_bf16 v[78:81], v[158:161], v[206:209], v[78:81]
	v_mfma_f32_16x16x32_bf16 v[78:81], v[162:165], v[210:213], v[78:81]
	s_setprio 0
	s_setprio 1
	v_mfma_f32_16x16x32_bf16 v[122:125], v[166:169], v[182:185], v[122:125]
	v_mfma_f32_16x16x32_bf16 v[122:125], v[170:173], v[186:189], v[122:125]
	v_mfma_f32_16x16x32_bf16 v[118:121], v[174:177], v[182:185], v[118:121]
	v_mfma_f32_16x16x32_bf16 v[118:121], v[178:181], v[186:189], v[118:121]
	v_mfma_f32_16x16x32_bf16 v[106:109], v[166:169], v[190:193], v[106:109]
	v_mfma_f32_16x16x32_bf16 v[106:109], v[170:173], v[194:197], v[106:109]
	v_mfma_f32_16x16x32_bf16 v[102:105], v[174:177], v[190:193], v[102:105]
	v_mfma_f32_16x16x32_bf16 v[102:105], v[178:181], v[194:197], v[102:105]
	v_mfma_f32_16x16x32_bf16 v[90:93], v[166:169], v[198:201], v[90:93]
	v_mfma_f32_16x16x32_bf16 v[90:93], v[170:173], v[202:205], v[90:93]
	v_mfma_f32_16x16x32_bf16 v[86:89], v[174:177], v[198:201], v[86:89]
	v_mfma_f32_16x16x32_bf16 v[86:89], v[178:181], v[202:205], v[86:89]
	v_mfma_f32_16x16x32_bf16 v[74:77], v[166:169], v[206:209], v[74:77]
	v_mfma_f32_16x16x32_bf16 v[74:77], v[170:173], v[210:213], v[74:77]
	v_mfma_f32_16x16x32_bf16 v[66:69], v[174:177], v[206:209], v[66:69]
	v_mfma_f32_16x16x32_bf16 v[66:69], v[178:181], v[210:213], v[66:69]
	s_barrier
	s_setprio 0
	ds_read_b128 v[182:185], v154 offset:16384
	ds_read_b128 v[186:189], v154 offset:17408
	ds_read_b128 v[190:193], v154 offset:18432
	ds_read_b128 v[194:197], v154 offset:19456
	ds_read_b128 v[198:201], v154 offset:20480
	ds_read_b128 v[202:205], v154 offset:21504
	ds_read_b128 v[206:209], v154 offset:22528
	ds_read_b128 v[210:213], v154 offset:23552
	s_mov_b32 m0, s37
	s_nop 0
	global_load_lds_dwordx4 v146, s[40:41] offset:0
	s_add_u32 s30, s40, 0x80000
	s_mov_b32 m0, s52
	s_nop 0
	global_load_lds_dwordx4 v148, s[40:41] offset:0
	s_addc_u32 s31, s41, 0
	s_mov_b32 m0, s53
	s_nop 0
	global_load_lds_dwordx4 v146, s[30:31] offset:0
	s_nop 0
	s_mov_b32 m0, s54
	s_nop 0
	global_load_lds_dwordx4 v148, s[30:31] offset:0
	s_nop 0
	s_mov_b32 m0, s23
	s_nop 0
	global_load_lds_dwordx4 v1, s[44:45] offset:0
	s_nop 0
	s_mov_b32 m0, s55
	s_nop 0
	global_load_lds_dwordx4 v147, s[44:45] offset:0
	s_waitcnt vmcnt(8)
	s_waitcnt lgkmcnt(0)
	s_barrier
	s_setprio 1
	v_mfma_f32_16x16x32_bf16 v[70:73], v[138:141], v[182:185], v[70:73]
	v_mfma_f32_16x16x32_bf16 v[70:73], v[142:145], v[186:189], v[70:73]
	v_mfma_f32_16x16x32_bf16 v[62:65], v[158:161], v[182:185], v[62:65]
	v_mfma_f32_16x16x32_bf16 v[62:65], v[162:165], v[186:189], v[62:65]
	v_mfma_f32_16x16x32_bf16 v[50:53], v[138:141], v[190:193], v[50:53]
	v_mfma_f32_16x16x32_bf16 v[50:53], v[142:145], v[194:197], v[50:53]
	v_mfma_f32_16x16x32_bf16 v[46:49], v[158:161], v[190:193], v[46:49]
	v_mfma_f32_16x16x32_bf16 v[46:49], v[162:165], v[194:197], v[46:49]
	v_mfma_f32_16x16x32_bf16 v[34:37], v[138:141], v[198:201], v[34:37]
	v_mfma_f32_16x16x32_bf16 v[34:37], v[142:145], v[202:205], v[34:37]
	v_mfma_f32_16x16x32_bf16 v[30:33], v[158:161], v[198:201], v[30:33]
	v_mfma_f32_16x16x32_bf16 v[30:33], v[162:165], v[202:205], v[30:33]
	v_mfma_f32_16x16x32_bf16 v[18:21], v[138:141], v[206:209], v[18:21]
	v_mfma_f32_16x16x32_bf16 v[18:21], v[142:145], v[210:213], v[18:21]
	v_mfma_f32_16x16x32_bf16 v[14:17], v[158:161], v[206:209], v[14:17]
	v_mfma_f32_16x16x32_bf16 v[14:17], v[162:165], v[210:213], v[14:17]
	s_setprio 0
	s_setprio 1
	v_mfma_f32_16x16x32_bf16 v[58:61], v[166:169], v[182:185], v[58:61]
	v_mfma_f32_16x16x32_bf16 v[54:57], v[174:177], v[182:185], v[54:57]
	v_mfma_f32_16x16x32_bf16 v[42:45], v[166:169], v[190:193], v[42:45]
	v_mfma_f32_16x16x32_bf16 v[38:41], v[174:177], v[190:193], v[38:41]
	v_mfma_f32_16x16x32_bf16 v[26:29], v[166:169], v[198:201], v[26:29]
	v_mfma_f32_16x16x32_bf16 v[22:25], v[174:177], v[198:201], v[22:25]
	v_mfma_f32_16x16x32_bf16 v[10:13], v[166:169], v[206:209], v[10:13]
	v_mfma_f32_16x16x32_bf16 v[4:7], v[174:177], v[206:209], v[6:9]
	v_mfma_f32_16x16x32_bf16 v[58:61], v[170:173], v[186:189], v[58:61]
	v_mfma_f32_16x16x32_bf16 v[54:57], v[178:181], v[186:189], v[54:57]
	v_mfma_f32_16x16x32_bf16 v[42:45], v[170:173], v[194:197], v[42:45]
	v_mfma_f32_16x16x32_bf16 v[38:41], v[178:181], v[194:197], v[38:41]
	v_mfma_f32_16x16x32_bf16 v[26:29], v[170:173], v[202:205], v[26:29]
	v_mfma_f32_16x16x32_bf16 v[22:25], v[178:181], v[202:205], v[22:25]
	v_mfma_f32_16x16x32_bf16 v[10:13], v[170:173], v[210:213], v[10:13]
	v_mfma_f32_16x16x32_bf16 v[4:7], v[178:181], v[210:213], v[4:7]
	s_barrier
	s_setprio 0
	ds_read_b128 v[138:141], v155
	ds_read_b128 v[142:145], v155 offset:1024
	ds_read_b128 v[158:161], v155 offset:2048
	ds_read_b128 v[162:165], v155 offset:3072
	ds_read_b128 v[166:169], v156
	ds_read_b128 v[170:173], v156 offset:1024
	ds_read_b128 v[174:177], v156 offset:2048
	ds_read_b128 v[178:181], v156 offset:3072
	ds_read_b128 v[182:185], v154 offset:32768
	ds_read_b128 v[186:189], v154 offset:33792
	ds_read_b128 v[190:193], v154 offset:34816
	ds_read_b128 v[194:197], v154 offset:35840
	ds_read_b128 v[198:201], v154 offset:36864
	ds_read_b128 v[202:205], v154 offset:37888
	ds_read_b128 v[206:209], v154 offset:38912
	ds_read_b128 v[210:213], v154 offset:39936
	s_add_u32 s30, s44, 0x80000
	s_addc_u32 s31, s45, 0
	s_mov_b32 m0, s56
	s_nop 0
	global_load_lds_dwordx4 v1, s[30:31] offset:0
	s_nop 0
	s_mov_b32 m0, s57
	s_nop 0
	global_load_lds_dwordx4 v147, s[30:31] offset:0
	s_waitcnt vmcnt(8)
	s_waitcnt lgkmcnt(0)
	s_barrier
	s_setprio 1
	v_mfma_f32_16x16x32_bf16 v[130:133], v[138:141], v[182:185], v[130:133]
	v_mfma_f32_16x16x32_bf16 v[130:133], v[142:145], v[186:189], v[130:133]
	v_mfma_f32_16x16x32_bf16 v[126:129], v[158:161], v[182:185], v[126:129]
	v_mfma_f32_16x16x32_bf16 v[126:129], v[162:165], v[186:189], v[126:129]
	v_mfma_f32_16x16x32_bf16 v[114:117], v[138:141], v[190:193], v[114:117]
	v_mfma_f32_16x16x32_bf16 v[114:117], v[142:145], v[194:197], v[114:117]
	v_mfma_f32_16x16x32_bf16 v[110:113], v[158:161], v[190:193], v[110:113]
	v_mfma_f32_16x16x32_bf16 v[110:113], v[162:165], v[194:197], v[110:113]
	v_mfma_f32_16x16x32_bf16 v[98:101], v[138:141], v[198:201], v[98:101]
	v_mfma_f32_16x16x32_bf16 v[98:101], v[142:145], v[202:205], v[98:101]
	v_mfma_f32_16x16x32_bf16 v[94:97], v[158:161], v[198:201], v[94:97]
	v_mfma_f32_16x16x32_bf16 v[94:97], v[162:165], v[202:205], v[94:97]
	v_mfma_f32_16x16x32_bf16 v[82:85], v[138:141], v[206:209], v[82:85]
	v_mfma_f32_16x16x32_bf16 v[82:85], v[142:145], v[210:213], v[82:85]
	v_mfma_f32_16x16x32_bf16 v[78:81], v[158:161], v[206:209], v[78:81]
	v_mfma_f32_16x16x32_bf16 v[78:81], v[162:165], v[210:213], v[78:81]
	s_setprio 0
	s_setprio 1
	v_mfma_f32_16x16x32_bf16 v[122:125], v[166:169], v[182:185], v[122:125]
	v_mfma_f32_16x16x32_bf16 v[122:125], v[170:173], v[186:189], v[122:125]
	v_mfma_f32_16x16x32_bf16 v[118:121], v[174:177], v[182:185], v[118:121]
	v_mfma_f32_16x16x32_bf16 v[118:121], v[178:181], v[186:189], v[118:121]
	v_mfma_f32_16x16x32_bf16 v[106:109], v[166:169], v[190:193], v[106:109]
	v_mfma_f32_16x16x32_bf16 v[106:109], v[170:173], v[194:197], v[106:109]
	v_mfma_f32_16x16x32_bf16 v[102:105], v[174:177], v[190:193], v[102:105]
	v_mfma_f32_16x16x32_bf16 v[102:105], v[178:181], v[194:197], v[102:105]
	v_mfma_f32_16x16x32_bf16 v[90:93], v[166:169], v[198:201], v[90:93]
	v_mfma_f32_16x16x32_bf16 v[90:93], v[170:173], v[202:205], v[90:93]
	v_mfma_f32_16x16x32_bf16 v[86:89], v[174:177], v[198:201], v[86:89]
	v_mfma_f32_16x16x32_bf16 v[86:89], v[178:181], v[202:205], v[86:89]
	v_mfma_f32_16x16x32_bf16 v[74:77], v[166:169], v[206:209], v[74:77]
	v_mfma_f32_16x16x32_bf16 v[74:77], v[170:173], v[210:213], v[74:77]
	v_mfma_f32_16x16x32_bf16 v[66:69], v[174:177], v[206:209], v[66:69]
	v_mfma_f32_16x16x32_bf16 v[66:69], v[178:181], v[210:213], v[66:69]
	s_barrier
	s_setprio 0
	ds_read_b128 v[182:185], v154 offset:49152
	ds_read_b128 v[186:189], v154 offset:50176
	ds_read_b128 v[190:193], v154 offset:51200
	ds_read_b128 v[194:197], v154 offset:52224
	ds_read_b128 v[198:201], v154 offset:53248
	ds_read_b128 v[202:205], v154 offset:54272
	ds_read_b128 v[206:209], v154 offset:55296
	ds_read_b128 v[210:213], v154 offset:56320
	s_add_u32 s30, s40, 0x80
	s_addc_u32 s31, s41, 0
	s_mov_b32 m0, s58
	s_nop 0
	global_load_lds_dwordx4 v146, s[30:31] offset:0
	s_nop 0
	s_mov_b32 m0, s59
	s_nop 0
	global_load_lds_dwordx4 v148, s[30:31] offset:0
	s_add_u32 s30, s40, 0x80080
	s_addc_u32 s31, s41, 0
	s_mov_b32 m0, s66
	s_nop 0
	global_load_lds_dwordx4 v146, s[30:31] offset:0
	s_nop 0
	s_mov_b32 m0, s67
	s_nop 0
	global_load_lds_dwordx4 v148, s[30:31] offset:0
	s_nop 0
	s_mov_b32 m0, s64
	s_nop 0
	global_load_lds_dwordx4 v1, s[38:39] offset:0
	s_nop 0
	s_mov_b32 m0, s65
	s_nop 0
	global_load_lds_dwordx4 v147, s[38:39] offset:0
	s_waitcnt vmcnt(8)
	s_waitcnt lgkmcnt(0)
	s_barrier
	s_setprio 1
	v_mfma_f32_16x16x32_bf16 v[70:73], v[138:141], v[182:185], v[70:73]
	v_mfma_f32_16x16x32_bf16 v[70:73], v[142:145], v[186:189], v[70:73]
	v_mfma_f32_16x16x32_bf16 v[62:65], v[158:161], v[182:185], v[62:65]
	v_mfma_f32_16x16x32_bf16 v[62:65], v[162:165], v[186:189], v[62:65]
	v_mfma_f32_16x16x32_bf16 v[50:53], v[138:141], v[190:193], v[50:53]
	v_mfma_f32_16x16x32_bf16 v[50:53], v[142:145], v[194:197], v[50:53]
	v_mfma_f32_16x16x32_bf16 v[46:49], v[158:161], v[190:193], v[46:49]
	v_mfma_f32_16x16x32_bf16 v[46:49], v[162:165], v[194:197], v[46:49]
	v_mfma_f32_16x16x32_bf16 v[34:37], v[138:141], v[198:201], v[34:37]
	v_mfma_f32_16x16x32_bf16 v[34:37], v[142:145], v[202:205], v[34:37]
	v_mfma_f32_16x16x32_bf16 v[30:33], v[158:161], v[198:201], v[30:33]
	v_mfma_f32_16x16x32_bf16 v[30:33], v[162:165], v[202:205], v[30:33]
	v_mfma_f32_16x16x32_bf16 v[18:21], v[138:141], v[206:209], v[18:21]
	v_mfma_f32_16x16x32_bf16 v[18:21], v[142:145], v[210:213], v[18:21]
	v_mfma_f32_16x16x32_bf16 v[14:17], v[158:161], v[206:209], v[14:17]
	v_mfma_f32_16x16x32_bf16 v[14:17], v[162:165], v[210:213], v[14:17]
	s_setprio 0
	s_setprio 1
	v_mfma_f32_16x16x32_bf16 v[58:61], v[166:169], v[182:185], v[58:61]
	v_mfma_f32_16x16x32_bf16 v[54:57], v[174:177], v[182:185], v[54:57]
	v_mfma_f32_16x16x32_bf16 v[42:45], v[166:169], v[190:193], v[42:45]
	v_mfma_f32_16x16x32_bf16 v[38:41], v[174:177], v[190:193], v[38:41]
	v_mfma_f32_16x16x32_bf16 v[26:29], v[166:169], v[198:201], v[26:29]
	v_mfma_f32_16x16x32_bf16 v[22:25], v[174:177], v[198:201], v[22:25]
	v_mfma_f32_16x16x32_bf16 v[8:11], v[166:169], v[206:209], v[10:13]
	v_mfma_f32_16x16x32_bf16 v[4:7], v[174:177], v[206:209], v[4:7]
	v_mfma_f32_16x16x32_bf16 v[58:61], v[170:173], v[186:189], v[58:61]
	v_mfma_f32_16x16x32_bf16 v[54:57], v[178:181], v[186:189], v[54:57]
	v_mfma_f32_16x16x32_bf16 v[42:45], v[170:173], v[194:197], v[42:45]
	v_mfma_f32_16x16x32_bf16 v[38:41], v[178:181], v[194:197], v[38:41]
	v_mfma_f32_16x16x32_bf16 v[26:29], v[170:173], v[202:205], v[26:29]
	v_mfma_f32_16x16x32_bf16 v[22:25], v[178:181], v[202:205], v[22:25]
	v_mfma_f32_16x16x32_bf16 v[10:13], v[170:173], v[210:213], v[8:11]
	v_mfma_f32_16x16x32_bf16 v[6:9], v[178:181], v[210:213], v[4:7]
	s_barrier
	s_setprio 0
	s_add_i32 s80, s80, 2
	s_add_u32 s81, s81, 0x100
	s_addc_u32 s82, s82, 0
	s_add_u32 s83, s83, 0x100
	s_addc_u32 s84, s84, 0
	s_cmp_gt_u32 s80, 29
	s_cbranch_scc0 .LBB0_787
	s_and_b64 vcc, exec, s[16:17]
	s_cbranch_vccz .LBB0_790
	s_barrier

.LBB0_867:
	ds_read_b128 v[4:7], v143
	ds_read_b128 v[8:11], v143 offset:1024
	ds_read_b128 v[12:15], v143 offset:2048
	ds_read_b128 v[16:19], v143 offset:3072
	ds_read_b128 v[20:23], v144
	ds_read_b128 v[24:27], v144 offset:1024
	ds_read_b128 v[28:31], v144 offset:2048
	ds_read_b128 v[32:35], v144 offset:3072
	s_add_u32 s44, s36, 0x100
	s_addc_u32 s45, s37, 0
	s_add_u32 s30, s38, 0x100
	s_addc_u32 s31, s39, 0
	s_add_u32 s40, s36, 0x180
	s_addc_u32 s41, s37, 0
	ds_read_b128 v[36:39], v145
	ds_read_b128 v[40:43], v145 offset:1024
	ds_read_b128 v[44:47], v145 offset:2048
	ds_read_b128 v[48:51], v145 offset:3072
	ds_read_b128 v[52:55], v145 offset:4096
	ds_read_b128 v[56:59], v145 offset:5120
	ds_read_b128 v[60:63], v145 offset:6144
	ds_read_b128 v[64:67], v145 offset:7168
	s_add_u32 s42, s36, 0x160080
	s_addc_u32 s43, s37, 0
	s_mov_b32 m0, s71
	s_nop 0
	global_load_lds_dwordx4 v1, s[42:43] offset:0
	s_nop 0
	s_mov_b32 m0, s72
	s_nop 0
	global_load_lds_dwordx4 v139, s[42:43] offset:0
	s_waitcnt vmcnt(24)
	s_waitcnt lgkmcnt(0)
	s_barrier
	s_setprio 1
	v_mfma_f32_16x16x32_bf16 v[92:95], v[4:7], v[60:63], 0
	v_mfma_f32_16x16x32_bf16 v[68:71], v[4:7], v[36:39], 0
	v_mfma_f32_16x16x32_bf16 v[72:75], v[12:15], v[36:39], 0
	v_mfma_f32_16x16x32_bf16 v[76:79], v[4:7], v[44:47], 0
	v_mfma_f32_16x16x32_bf16 v[80:83], v[12:15], v[44:47], 0
	v_mfma_f32_16x16x32_bf16 v[84:87], v[4:7], v[52:55], 0
	v_mfma_f32_16x16x32_bf16 v[88:91], v[12:15], v[52:55], 0
	v_mfma_f32_16x16x32_bf16 v[102:105], v[8:11], v[64:67], v[92:95]
	v_mfma_f32_16x16x32_bf16 v[92:95], v[12:15], v[60:63], 0
	v_mfma_f32_16x16x32_bf16 v[68:71], v[8:11], v[40:43], v[68:71]
	v_mfma_f32_16x16x32_bf16 v[72:75], v[16:19], v[40:43], v[72:75]
	v_mfma_f32_16x16x32_bf16 v[76:79], v[8:11], v[48:51], v[76:79]
	v_mfma_f32_16x16x32_bf16 v[80:83], v[16:19], v[48:51], v[80:83]
	v_mfma_f32_16x16x32_bf16 v[84:87], v[8:11], v[56:59], v[84:87]
	v_mfma_f32_16x16x32_bf16 v[88:91], v[16:19], v[56:59], v[88:91]
	v_mfma_f32_16x16x32_bf16 v[106:109], v[16:19], v[64:67], v[92:95]
	s_setprio 0
	s_setprio 1
	v_mfma_f32_16x16x32_bf16 v[92:95], v[20:23], v[36:39], 0
	v_mfma_f32_16x16x32_bf16 v[36:39], v[28:31], v[36:39], 0
	v_mfma_f32_16x16x32_bf16 v[118:121], v[24:27], v[40:43], v[92:95]
	v_mfma_f32_16x16x32_bf16 v[36:39], v[32:35], v[40:43], v[36:39]
	v_mfma_f32_16x16x32_bf16 v[40:43], v[20:23], v[44:47], 0
	v_mfma_f32_16x16x32_bf16 v[44:47], v[28:31], v[44:47], 0
	v_mfma_f32_16x16x32_bf16 v[40:43], v[24:27], v[48:51], v[40:43]
	v_mfma_f32_16x16x32_bf16 v[44:47], v[32:35], v[48:51], v[44:47]
	v_mfma_f32_16x16x32_bf16 v[48:51], v[20:23], v[52:55], 0
	v_mfma_f32_16x16x32_bf16 v[52:55], v[28:31], v[52:55], 0
	v_mfma_f32_16x16x32_bf16 v[48:51], v[24:27], v[56:59], v[48:51]
	v_mfma_f32_16x16x32_bf16 v[52:55], v[32:35], v[56:59], v[52:55]
	v_mfma_f32_16x16x32_bf16 v[56:59], v[20:23], v[60:63], 0
	v_mfma_f32_16x16x32_bf16 v[60:63], v[28:31], v[60:63], 0
	v_mfma_f32_16x16x32_bf16 v[56:59], v[24:27], v[64:67], v[56:59]
	v_mfma_f32_16x16x32_bf16 v[60:63], v[32:35], v[64:67], v[60:63]
	s_barrier
	s_setprio 0
	ds_read_b128 v[64:67], v145 offset:16384
	ds_read_b128 v[92:95], v145 offset:17408
	ds_read_b128 v[96:99], v145 offset:18432
	ds_read_b128 v[110:113], v145 offset:19456
	ds_read_b128 v[114:117], v145 offset:20480
	ds_read_b128 v[122:125], v145 offset:21504
	ds_read_b128 v[126:129], v145 offset:22528
	ds_read_b128 v[130:133], v145 offset:23552
	s_mov_b32 m0, s54
	s_nop 0
	global_load_lds_dwordx4 v138, s[30:31] offset:0
	s_nop 0
	s_mov_b32 m0, s55
	s_nop 0
	global_load_lds_dwordx4 v140, s[30:31] offset:0
	s_add_u32 s30, s38, 0x160100
	s_addc_u32 s31, s39, 0
	s_mov_b32 m0, s56
	s_nop 0
	global_load_lds_dwordx4 v138, s[30:31] offset:0
	s_nop 0
	s_mov_b32 m0, s57
	s_nop 0
	global_load_lds_dwordx4 v140, s[30:31] offset:0
	s_nop 0
	s_mov_b32 m0, s47
	s_nop 0
	global_load_lds_dwordx4 v1, s[44:45] offset:0
	s_nop 0
	s_mov_b32 m0, s58
	s_nop 0
	global_load_lds_dwordx4 v139, s[44:45] offset:0
	s_waitcnt vmcnt(24)
	s_waitcnt lgkmcnt(0)
	s_barrier
	s_setprio 1
	v_mfma_f32_16x16x32_bf16 v[148:151], v[4:7], v[64:67], 0
	v_mfma_f32_16x16x32_bf16 v[156:159], v[4:7], v[96:99], 0
	v_mfma_f32_16x16x32_bf16 v[164:167], v[4:7], v[114:117], 0
	v_mfma_f32_16x16x32_bf16 v[4:7], v[4:7], v[126:129], 0
	v_mfma_f32_16x16x32_bf16 v[148:151], v[8:11], v[92:95], v[148:151]
	v_mfma_f32_16x16x32_bf16 v[156:159], v[8:11], v[110:113], v[156:159]
	v_mfma_f32_16x16x32_bf16 v[164:167], v[8:11], v[122:125], v[164:167]
	v_mfma_f32_16x16x32_bf16 v[4:7], v[8:11], v[130:133], v[4:7]
	v_mfma_f32_16x16x32_bf16 v[8:11], v[12:15], v[126:129], 0
	v_mfma_f32_16x16x32_bf16 v[152:155], v[12:15], v[64:67], 0
	v_mfma_f32_16x16x32_bf16 v[160:163], v[12:15], v[96:99], 0
	v_mfma_f32_16x16x32_bf16 v[168:171], v[12:15], v[114:117], 0
	v_mfma_f32_16x16x32_bf16 v[8:11], v[16:19], v[130:133], v[8:11]
	v_mfma_f32_16x16x32_bf16 v[152:155], v[16:19], v[92:95], v[152:155]
	v_mfma_f32_16x16x32_bf16 v[160:163], v[16:19], v[110:113], v[160:163]
	v_mfma_f32_16x16x32_bf16 v[168:171], v[16:19], v[122:125], v[168:171]
	s_setprio 0
	s_setprio 1
	v_mfma_f32_16x16x32_bf16 v[12:15], v[20:23], v[64:67], 0
	v_mfma_f32_16x16x32_bf16 v[172:175], v[24:27], v[92:95], v[12:15]
	v_mfma_f32_16x16x32_bf16 v[12:15], v[28:31], v[64:67], 0
	v_mfma_f32_16x16x32_bf16 v[176:179], v[32:35], v[92:95], v[12:15]
	v_mfma_f32_16x16x32_bf16 v[12:15], v[20:23], v[96:99], 0
	v_mfma_f32_16x16x32_bf16 v[180:183], v[24:27], v[110:113], v[12:15]
	v_mfma_f32_16x16x32_bf16 v[12:15], v[28:31], v[96:99], 0
	v_mfma_f32_16x16x32_bf16 v[184:187], v[32:35], v[110:113], v[12:15]
	v_mfma_f32_16x16x32_bf16 v[12:15], v[20:23], v[114:117], 0
	v_mfma_f32_16x16x32_bf16 v[188:191], v[24:27], v[122:125], v[12:15]
	v_mfma_f32_16x16x32_bf16 v[12:15], v[28:31], v[114:117], 0
	v_mfma_f32_16x16x32_bf16 v[192:195], v[32:35], v[122:125], v[12:15]
	v_mfma_f32_16x16x32_bf16 v[12:15], v[20:23], v[126:129], 0
	v_mfma_f32_16x16x32_bf16 v[196:199], v[24:27], v[130:133], v[12:15]
	v_mfma_f32_16x16x32_bf16 v[12:15], v[28:31], v[126:129], 0
	v_mfma_f32_16x16x32_bf16 v[200:203], v[32:35], v[130:133], v[12:15]
	s_barrier
	s_setprio 0
	s_nop 4
	ds_read_b128 v[12:15], v146
	ds_read_b128 v[16:19], v146 offset:1024
	ds_read_b128 v[22:25], v146 offset:2048
	ds_read_b128 v[26:29], v146 offset:3072
	ds_read_b128 v[204:207], v147
	ds_read_b128 v[208:211], v147 offset:1024
	ds_read_b128 v[212:215], v147 offset:2048
	ds_read_b128 v[216:219], v147 offset:3072
	ds_read_b128 v[30:33], v145 offset:32768
	ds_read_b128 v[64:67], v145 offset:33792
	ds_read_b128 v[220:223], v145 offset:34816
	ds_read_b128 v[224:227], v145 offset:35840
	ds_read_b128 v[228:231], v145 offset:36864
	ds_read_b128 v[232:235], v145 offset:37888
	ds_read_b128 v[236:239], v145 offset:38912
	ds_read_b128 v[240:243], v145 offset:39936
	s_add_u32 s30, s36, 0x160100
	s_addc_u32 s31, s37, 0
	s_mov_b32 m0, s59
	s_nop 0
	global_load_lds_dwordx4 v1, s[30:31] offset:0
	s_nop 0
	s_mov_b32 m0, s64
	s_nop 0
	global_load_lds_dwordx4 v139, s[30:31] offset:0
	s_waitcnt vmcnt(8)
	s_waitcnt lgkmcnt(0)
	s_barrier
	s_setprio 1
	v_mfma_f32_16x16x32_bf16 v[68:71], v[12:15], v[30:33], v[68:71]
	v_mfma_f32_16x16x32_bf16 v[130:133], v[16:19], v[64:67], v[68:71]
	v_mfma_f32_16x16x32_bf16 v[68:71], v[22:25], v[30:33], v[72:75]
	v_mfma_f32_16x16x32_bf16 v[126:129], v[26:29], v[64:67], v[68:71]
	v_mfma_f32_16x16x32_bf16 v[68:71], v[12:15], v[220:223], v[76:79]
	v_mfma_f32_16x16x32_bf16 v[114:117], v[16:19], v[224:227], v[68:71]
	v_mfma_f32_16x16x32_bf16 v[68:71], v[22:25], v[220:223], v[80:83]
	v_mfma_f32_16x16x32_bf16 v[110:113], v[26:29], v[224:227], v[68:71]
	v_mfma_f32_16x16x32_bf16 v[68:71], v[12:15], v[228:231], v[84:87]
	v_mfma_f32_16x16x32_bf16 v[98:101], v[16:19], v[232:235], v[68:71]
	v_mfma_f32_16x16x32_bf16 v[68:71], v[22:25], v[228:231], v[88:91]
	v_mfma_f32_16x16x32_bf16 v[94:97], v[26:29], v[232:235], v[68:71]
	v_mfma_f32_16x16x32_bf16 v[68:71], v[12:15], v[236:239], v[102:105]
	v_mfma_f32_16x16x32_bf16 v[82:85], v[16:19], v[240:243], v[68:71]
	v_mfma_f32_16x16x32_bf16 v[68:71], v[22:25], v[236:239], v[106:109]
	v_mfma_f32_16x16x32_bf16 v[78:81], v[26:29], v[240:243], v[68:71]
	s_setprio 0
	s_setprio 1
	v_mfma_f32_16x16x32_bf16 v[68:71], v[204:207], v[30:33], v[118:121]
	v_mfma_f32_16x16x32_bf16 v[30:33], v[212:215], v[30:33], v[36:39]
	v_mfma_f32_16x16x32_bf16 v[118:121], v[216:219], v[64:67], v[30:33]
	v_mfma_f32_16x16x32_bf16 v[30:33], v[204:207], v[220:223], v[40:43]
	v_mfma_f32_16x16x32_bf16 v[106:109], v[208:211], v[224:227], v[30:33]
	v_mfma_f32_16x16x32_bf16 v[30:33], v[212:215], v[220:223], v[44:47]
	v_mfma_f32_16x16x32_bf16 v[102:105], v[216:219], v[224:227], v[30:33]
	v_mfma_f32_16x16x32_bf16 v[30:33], v[204:207], v[228:231], v[48:51]
	v_mfma_f32_16x16x32_bf16 v[90:93], v[208:211], v[232:235], v[30:33]
	v_mfma_f32_16x16x32_bf16 v[30:33], v[212:215], v[228:231], v[52:55]
	v_mfma_f32_16x16x32_bf16 v[86:89], v[216:219], v[232:235], v[30:33]
	v_mfma_f32_16x16x32_bf16 v[30:33], v[204:207], v[236:239], v[56:59]
	v_mfma_f32_16x16x32_bf16 v[122:125], v[208:211], v[64:67], v[68:71]
	v_mfma_f32_16x16x32_bf16 v[70:73], v[208:211], v[240:243], v[30:33]
	v_mfma_f32_16x16x32_bf16 v[30:33], v[212:215], v[236:239], v[60:63]
	v_mfma_f32_16x16x32_bf16 v[62:65], v[216:219], v[240:243], v[30:33]
	s_barrier
	s_setprio 0
	ds_read_b128 v[38:41], v145 offset:49152
	ds_read_b128 v[42:45], v145 offset:50176
	ds_read_b128 v[220:223], v145 offset:51200
	ds_read_b128 v[224:227], v145 offset:52224
	ds_read_b128 v[228:231], v145 offset:53248
	ds_read_b128 v[232:235], v145 offset:54272
	ds_read_b128 v[236:239], v145 offset:55296
	ds_read_b128 v[240:243], v145 offset:56320
	s_add_u32 s30, s38, 0x180
	s_addc_u32 s31, s39, 0
	s_mov_b32 m0, s65
	s_nop 0
	global_load_lds_dwordx4 v138, s[30:31] offset:0
	s_nop 0
	s_mov_b32 m0, s66
	s_nop 0
	global_load_lds_dwordx4 v140, s[30:31] offset:0
	s_add_u32 s30, s38, 0x160180
	s_addc_u32 s31, s39, 0
	s_mov_b32 m0, s69
	s_nop 0
	global_load_lds_dwordx4 v138, s[30:31] offset:0
	s_nop 0
	s_mov_b32 m0, s70
	s_nop 0
	global_load_lds_dwordx4 v140, s[30:31] offset:0
	s_nop 0
	s_mov_b32 m0, s67
	s_nop 0
	global_load_lds_dwordx4 v1, s[40:41] offset:0
	s_nop 0
	s_mov_b32 m0, s68
	s_nop 0
	global_load_lds_dwordx4 v139, s[40:41] offset:0
	s_waitcnt vmcnt(8)
	s_waitcnt lgkmcnt(0)
	s_barrier
	s_setprio 1
	v_mfma_f32_16x16x32_bf16 v[30:33], v[12:15], v[38:41], v[148:151]
	v_mfma_f32_16x16x32_bf16 v[74:77], v[16:19], v[42:45], v[30:33]
	v_mfma_f32_16x16x32_bf16 v[30:33], v[22:25], v[38:41], v[152:155]
	v_mfma_f32_16x16x32_bf16 v[66:69], v[26:29], v[42:45], v[30:33]
	v_mfma_f32_16x16x32_bf16 v[30:33], v[12:15], v[220:223], v[156:159]
	v_mfma_f32_16x16x32_bf16 v[50:53], v[16:19], v[224:227], v[30:33]
	v_mfma_f32_16x16x32_bf16 v[30:33], v[22:25], v[220:223], v[160:163]
	v_mfma_f32_16x16x32_bf16 v[46:49], v[26:29], v[224:227], v[30:33]
	v_mfma_f32_16x16x32_bf16 v[30:33], v[12:15], v[228:231], v[164:167]
	v_mfma_f32_16x16x32_bf16 v[4:7], v[12:15], v[236:239], v[4:7]
	v_mfma_f32_16x16x32_bf16 v[34:37], v[16:19], v[232:235], v[30:33]
	v_mfma_f32_16x16x32_bf16 v[30:33], v[22:25], v[228:231], v[168:171]
	v_mfma_f32_16x16x32_bf16 v[18:21], v[16:19], v[240:243], v[4:7]
	v_mfma_f32_16x16x32_bf16 v[4:7], v[22:25], v[236:239], v[8:11]
	v_mfma_f32_16x16x32_bf16 v[30:33], v[26:29], v[232:235], v[30:33]
	v_mfma_f32_16x16x32_bf16 v[14:17], v[26:29], v[240:243], v[4:7]
	s_setprio 0
	s_setprio 1
	v_mfma_f32_16x16x32_bf16 v[4:7], v[204:207], v[38:41], v[172:175]
	v_mfma_f32_16x16x32_bf16 v[58:61], v[208:211], v[42:45], v[4:7]
	v_mfma_f32_16x16x32_bf16 v[4:7], v[212:215], v[38:41], v[176:179]
	v_mfma_f32_16x16x32_bf16 v[54:57], v[216:219], v[42:45], v[4:7]
	v_mfma_f32_16x16x32_bf16 v[4:7], v[204:207], v[220:223], v[180:183]
	v_mfma_f32_16x16x32_bf16 v[42:45], v[208:211], v[224:227], v[4:7]
	v_mfma_f32_16x16x32_bf16 v[4:7], v[212:215], v[220:223], v[184:187]
	v_mfma_f32_16x16x32_bf16 v[38:41], v[216:219], v[224:227], v[4:7]
	v_mfma_f32_16x16x32_bf16 v[4:7], v[204:207], v[228:231], v[188:191]
	v_mfma_f32_16x16x32_bf16 v[26:29], v[208:211], v[232:235], v[4:7]
	v_mfma_f32_16x16x32_bf16 v[4:7], v[212:215], v[228:231], v[192:195]
	v_mfma_f32_16x16x32_bf16 v[22:25], v[216:219], v[232:235], v[4:7]
	v_mfma_f32_16x16x32_bf16 v[4:7], v[204:207], v[236:239], v[196:199]
	v_mfma_f32_16x16x32_bf16 v[10:13], v[208:211], v[240:243], v[4:7]
	v_mfma_f32_16x16x32_bf16 v[4:7], v[212:215], v[236:239], v[200:203]
	v_mfma_f32_16x16x32_bf16 v[6:9], v[216:219], v[240:243], v[4:7]
	s_barrier
	s_setprio 0
	s_mov_b32 s40, 2
	s_branch .LBB0_871

.LBB0_872:
	ds_read_b128 v[148:151], v143
	ds_read_b128 v[152:155], v143 offset:1024
	ds_read_b128 v[156:159], v143 offset:2048
	ds_read_b128 v[160:163], v143 offset:3072
	ds_read_b128 v[164:167], v144
	ds_read_b128 v[168:171], v144 offset:1024
	ds_read_b128 v[172:175], v144 offset:2048
	ds_read_b128 v[176:179], v144 offset:3072
	s_cmpk_eq_i32 s79, 0x54
	s_cselect_b32 s44, s6, s82
	s_cselect_b32 s45, s7, s83
	s_cselect_b32 s40, s28, s80
	s_cselect_b32 s41, s29, s81
	s_add_u32 s38, s44, 0x80
	s_addc_u32 s39, s45, 0
	ds_read_b128 v[180:183], v145
	ds_read_b128 v[184:187], v145 offset:1024
	ds_read_b128 v[188:191], v145 offset:2048
	ds_read_b128 v[192:195], v145 offset:3072
	ds_read_b128 v[196:199], v145 offset:4096
	ds_read_b128 v[200:203], v145 offset:5120
	ds_read_b128 v[204:207], v145 offset:6144
	ds_read_b128 v[208:211], v145 offset:7168
	s_mov_b32 m0, s71
	s_nop 0
	global_load_lds_dwordx4 v1, s[36:37] offset:0
	s_nop 0
	s_mov_b32 m0, s72
	s_nop 0
	global_load_lds_dwordx4 v139, s[36:37] offset:0
	s_waitcnt vmcnt(8)
	s_waitcnt lgkmcnt(0)
	s_barrier
	s_setprio 1
	v_mfma_f32_16x16x32_bf16 v[130:133], v[148:151], v[180:183], v[130:133]
	v_mfma_f32_16x16x32_bf16 v[130:133], v[152:155], v[184:187], v[130:133]
	v_mfma_f32_16x16x32_bf16 v[126:129], v[156:159], v[180:183], v[126:129]
	v_mfma_f32_16x16x32_bf16 v[126:129], v[160:163], v[184:187], v[126:129]
	v_mfma_f32_16x16x32_bf16 v[114:117], v[148:151], v[188:191], v[114:117]
	v_mfma_f32_16x16x32_bf16 v[114:117], v[152:155], v[192:195], v[114:117]
	v_mfma_f32_16x16x32_bf16 v[110:113], v[156:159], v[188:191], v[110:113]
	v_mfma_f32_16x16x32_bf16 v[110:113], v[160:163], v[192:195], v[110:113]
	v_mfma_f32_16x16x32_bf16 v[98:101], v[148:151], v[196:199], v[98:101]
	v_mfma_f32_16x16x32_bf16 v[98:101], v[152:155], v[200:203], v[98:101]
	v_mfma_f32_16x16x32_bf16 v[94:97], v[156:159], v[196:199], v[94:97]
	v_mfma_f32_16x16x32_bf16 v[94:97], v[160:163], v[200:203], v[94:97]
	v_mfma_f32_16x16x32_bf16 v[82:85], v[148:151], v[204:207], v[82:85]
	v_mfma_f32_16x16x32_bf16 v[82:85], v[152:155], v[208:211], v[82:85]
	v_mfma_f32_16x16x32_bf16 v[78:81], v[156:159], v[204:207], v[78:81]
	v_mfma_f32_16x16x32_bf16 v[78:81], v[160:163], v[208:211], v[78:81]
	s_setprio 0
	s_setprio 1
	v_mfma_f32_16x16x32_bf16 v[122:125], v[164:167], v[180:183], v[122:125]
	v_mfma_f32_16x16x32_bf16 v[122:125], v[168:171], v[184:187], v[122:125]
	v_mfma_f32_16x16x32_bf16 v[118:121], v[172:175], v[180:183], v[118:121]
	v_mfma_f32_16x16x32_bf16 v[118:121], v[176:179], v[184:187], v[118:121]
	v_mfma_f32_16x16x32_bf16 v[106:109], v[164:167], v[188:191], v[106:109]
	v_mfma_f32_16x16x32_bf16 v[106:109], v[168:171], v[192:195], v[106:109]
	v_mfma_f32_16x16x32_bf16 v[102:105], v[172:175], v[188:191], v[102:105]
	v_mfma_f32_16x16x32_bf16 v[102:105], v[176:179], v[192:195], v[102:105]
	v_mfma_f32_16x16x32_bf16 v[90:93], v[164:167], v[196:199], v[90:93]
	v_mfma_f32_16x16x32_bf16 v[90:93], v[168:171], v[200:203], v[90:93]
	v_mfma_f32_16x16x32_bf16 v[86:89], v[172:175], v[196:199], v[86:89]
	v_mfma_f32_16x16x32_bf16 v[86:89], v[176:179], v[200:203], v[86:89]
	v_mfma_f32_16x16x32_bf16 v[70:73], v[164:167], v[204:207], v[70:73]
	v_mfma_f32_16x16x32_bf16 v[70:73], v[168:171], v[208:211], v[70:73]
	v_mfma_f32_16x16x32_bf16 v[62:65], v[172:175], v[204:207], v[62:65]
	v_mfma_f32_16x16x32_bf16 v[62:65], v[176:179], v[208:211], v[62:65]
	s_barrier
	s_setprio 0
	ds_read_b128 v[180:183], v145 offset:16384
	ds_read_b128 v[184:187], v145 offset:17408
	ds_read_b128 v[188:191], v145 offset:18432
	ds_read_b128 v[192:195], v145 offset:19456
	ds_read_b128 v[196:199], v145 offset:20480
	ds_read_b128 v[200:203], v145 offset:21504
	ds_read_b128 v[204:207], v145 offset:22528
	ds_read_b128 v[208:211], v145 offset:23552
	s_mov_b32 m0, s54
	s_nop 0
	global_load_lds_dwordx4 v138, s[40:41] offset:0
	s_add_u32 s30, s40, 0x160000
	s_mov_b32 m0, s55
	s_nop 0
	global_load_lds_dwordx4 v140, s[40:41] offset:0
	s_addc_u32 s31, s41, 0
	s_mov_b32 m0, s56
	s_nop 0
	global_load_lds_dwordx4 v138, s[30:31] offset:0
	s_nop 0
	s_mov_b32 m0, s57
	s_nop 0
	global_load_lds_dwordx4 v140, s[30:31] offset:0
	s_nop 0
	s_mov_b32 m0, s47
	s_nop 0
	global_load_lds_dwordx4 v1, s[44:45] offset:0
	s_nop 0
	s_mov_b32 m0, s58
	s_nop 0
	global_load_lds_dwordx4 v139, s[44:45] offset:0
	s_waitcnt vmcnt(8)
	s_waitcnt lgkmcnt(0)
	s_barrier
	s_setprio 1
	v_mfma_f32_16x16x32_bf16 v[74:77], v[148:151], v[180:183], v[74:77]
	v_mfma_f32_16x16x32_bf16 v[74:77], v[152:155], v[184:187], v[74:77]
	v_mfma_f32_16x16x32_bf16 v[66:69], v[156:159], v[180:183], v[66:69]
	v_mfma_f32_16x16x32_bf16 v[66:69], v[160:163], v[184:187], v[66:69]
	v_mfma_f32_16x16x32_bf16 v[50:53], v[148:151], v[188:191], v[50:53]
	v_mfma_f32_16x16x32_bf16 v[50:53], v[152:155], v[192:195], v[50:53]
	v_mfma_f32_16x16x32_bf16 v[46:49], v[156:159], v[188:191], v[46:49]
	v_mfma_f32_16x16x32_bf16 v[46:49], v[160:163], v[192:195], v[46:49]
	v_mfma_f32_16x16x32_bf16 v[34:37], v[148:151], v[196:199], v[34:37]
	v_mfma_f32_16x16x32_bf16 v[34:37], v[152:155], v[200:203], v[34:37]
	v_mfma_f32_16x16x32_bf16 v[30:33], v[156:159], v[196:199], v[30:33]
	v_mfma_f32_16x16x32_bf16 v[30:33], v[160:163], v[200:203], v[30:33]
	v_mfma_f32_16x16x32_bf16 v[18:21], v[148:151], v[204:207], v[18:21]
	v_mfma_f32_16x16x32_bf16 v[18:21], v[152:155], v[208:211], v[18:21]
	v_mfma_f32_16x16x32_bf16 v[14:17], v[156:159], v[204:207], v[14:17]
	v_mfma_f32_16x16x32_bf16 v[14:17], v[160:163], v[208:211], v[14:17]
	s_setprio 0
	s_setprio 1
	v_mfma_f32_16x16x32_bf16 v[58:61], v[164:167], v[180:183], v[58:61]
	v_mfma_f32_16x16x32_bf16 v[54:57], v[172:175], v[180:183], v[54:57]
	v_mfma_f32_16x16x32_bf16 v[42:45], v[164:167], v[188:191], v[42:45]
	v_mfma_f32_16x16x32_bf16 v[38:41], v[172:175], v[188:191], v[38:41]
	v_mfma_f32_16x16x32_bf16 v[26:29], v[164:167], v[196:199], v[26:29]
	v_mfma_f32_16x16x32_bf16 v[22:25], v[172:175], v[196:199], v[22:25]
	v_mfma_f32_16x16x32_bf16 v[10:13], v[164:167], v[204:207], v[10:13]
	v_mfma_f32_16x16x32_bf16 v[4:7], v[172:175], v[204:207], v[6:9]
	v_mfma_f32_16x16x32_bf16 v[58:61], v[168:171], v[184:187], v[58:61]
	v_mfma_f32_16x16x32_bf16 v[54:57], v[176:179], v[184:187], v[54:57]
	v_mfma_f32_16x16x32_bf16 v[42:45], v[168:171], v[192:195], v[42:45]
	v_mfma_f32_16x16x32_bf16 v[38:41], v[176:179], v[192:195], v[38:41]
	v_mfma_f32_16x16x32_bf16 v[26:29], v[168:171], v[200:203], v[26:29]
	v_mfma_f32_16x16x32_bf16 v[22:25], v[176:179], v[200:203], v[22:25]
	v_mfma_f32_16x16x32_bf16 v[10:13], v[168:171], v[208:211], v[10:13]
	v_mfma_f32_16x16x32_bf16 v[4:7], v[176:179], v[208:211], v[4:7]
	s_barrier
	s_setprio 0
	ds_read_b128 v[148:151], v146
	ds_read_b128 v[152:155], v146 offset:1024
	ds_read_b128 v[156:159], v146 offset:2048
	ds_read_b128 v[160:163], v146 offset:3072
	ds_read_b128 v[164:167], v147
	ds_read_b128 v[168:171], v147 offset:1024
	ds_read_b128 v[172:175], v147 offset:2048
	ds_read_b128 v[176:179], v147 offset:3072
	ds_read_b128 v[180:183], v145 offset:32768
	ds_read_b128 v[184:187], v145 offset:33792
	ds_read_b128 v[188:191], v145 offset:34816
	ds_read_b128 v[192:195], v145 offset:35840
	ds_read_b128 v[196:199], v145 offset:36864
	ds_read_b128 v[200:203], v145 offset:37888
	ds_read_b128 v[204:207], v145 offset:38912
	ds_read_b128 v[208:211], v145 offset:39936
	s_add_u32 s30, s44, 0x160000
	s_addc_u32 s31, s45, 0
	s_mov_b32 m0, s59
	s_nop 0
	global_load_lds_dwordx4 v1, s[30:31] offset:0
	s_nop 0
	s_mov_b32 m0, s64
	s_nop 0
	global_load_lds_dwordx4 v139, s[30:31] offset:0
	s_waitcnt vmcnt(8)
	s_waitcnt lgkmcnt(0)
	s_barrier
	s_setprio 1
	v_mfma_f32_16x16x32_bf16 v[130:133], v[148:151], v[180:183], v[130:133]
	v_mfma_f32_16x16x32_bf16 v[130:133], v[152:155], v[184:187], v[130:133]
	v_mfma_f32_16x16x32_bf16 v[126:129], v[156:159], v[180:183], v[126:129]
	v_mfma_f32_16x16x32_bf16 v[126:129], v[160:163], v[184:187], v[126:129]
	v_mfma_f32_16x16x32_bf16 v[114:117], v[148:151], v[188:191], v[114:117]
	v_mfma_f32_16x16x32_bf16 v[114:117], v[152:155], v[192:195], v[114:117]
	v_mfma_f32_16x16x32_bf16 v[110:113], v[156:159], v[188:191], v[110:113]
	v_mfma_f32_16x16x32_bf16 v[110:113], v[160:163], v[192:195], v[110:113]
	v_mfma_f32_16x16x32_bf16 v[98:101], v[148:151], v[196:199], v[98:101]
	v_mfma_f32_16x16x32_bf16 v[98:101], v[152:155], v[200:203], v[98:101]
	v_mfma_f32_16x16x32_bf16 v[94:97], v[156:159], v[196:199], v[94:97]
	v_mfma_f32_16x16x32_bf16 v[94:97], v[160:163], v[200:203], v[94:97]
	v_mfma_f32_16x16x32_bf16 v[82:85], v[148:151], v[204:207], v[82:85]
	v_mfma_f32_16x16x32_bf16 v[82:85], v[152:155], v[208:211], v[82:85]
	v_mfma_f32_16x16x32_bf16 v[78:81], v[156:159], v[204:207], v[78:81]
	v_mfma_f32_16x16x32_bf16 v[78:81], v[160:163], v[208:211], v[78:81]
	s_setprio 0
	s_setprio 1
	v_mfma_f32_16x16x32_bf16 v[122:125], v[164:167], v[180:183], v[122:125]
	v_mfma_f32_16x16x32_bf16 v[122:125], v[168:171], v[184:187], v[122:125]
	v_mfma_f32_16x16x32_bf16 v[118:121], v[172:175], v[180:183], v[118:121]
	v_mfma_f32_16x16x32_bf16 v[118:121], v[176:179], v[184:187], v[118:121]
	v_mfma_f32_16x16x32_bf16 v[106:109], v[164:167], v[188:191], v[106:109]
	v_mfma_f32_16x16x32_bf16 v[106:109], v[168:171], v[192:195], v[106:109]
	v_mfma_f32_16x16x32_bf16 v[102:105], v[172:175], v[188:191], v[102:105]
	v_mfma_f32_16x16x32_bf16 v[102:105], v[176:179], v[192:195], v[102:105]
	v_mfma_f32_16x16x32_bf16 v[90:93], v[164:167], v[196:199], v[90:93]
	v_mfma_f32_16x16x32_bf16 v[90:93], v[168:171], v[200:203], v[90:93]
	v_mfma_f32_16x16x32_bf16 v[86:89], v[172:175], v[196:199], v[86:89]
	v_mfma_f32_16x16x32_bf16 v[86:89], v[176:179], v[200:203], v[86:89]
	v_mfma_f32_16x16x32_bf16 v[70:73], v[164:167], v[204:207], v[70:73]
	v_mfma_f32_16x16x32_bf16 v[70:73], v[168:171], v[208:211], v[70:73]
	v_mfma_f32_16x16x32_bf16 v[62:65], v[172:175], v[204:207], v[62:65]
	v_mfma_f32_16x16x32_bf16 v[62:65], v[176:179], v[208:211], v[62:65]
	s_barrier
	s_setprio 0
	ds_read_b128 v[180:183], v145 offset:49152
	ds_read_b128 v[184:187], v145 offset:50176
	ds_read_b128 v[188:191], v145 offset:51200
	ds_read_b128 v[192:195], v145 offset:52224
	ds_read_b128 v[196:199], v145 offset:53248
	ds_read_b128 v[200:203], v145 offset:54272
	ds_read_b128 v[204:207], v145 offset:55296
	ds_read_b128 v[208:211], v145 offset:56320
	s_add_u32 s30, s40, 0x80
	s_addc_u32 s31, s41, 0
	s_mov_b32 m0, s65
	s_nop 0
	global_load_lds_dwordx4 v138, s[30:31] offset:0
	s_nop 0
	s_mov_b32 m0, s66
	s_nop 0
	global_load_lds_dwordx4 v140, s[30:31] offset:0
	s_add_u32 s30, s40, 0x160080
	s_addc_u32 s31, s41, 0
	s_mov_b32 m0, s69
	s_nop 0
	global_load_lds_dwordx4 v138, s[30:31] offset:0
	s_nop 0
	s_mov_b32 m0, s70
	s_nop 0
	global_load_lds_dwordx4 v140, s[30:31] offset:0
	s_nop 0
	s_mov_b32 m0, s67
	s_nop 0
	global_load_lds_dwordx4 v1, s[38:39] offset:0
	s_nop 0
	s_mov_b32 m0, s68
	s_nop 0
	global_load_lds_dwordx4 v139, s[38:39] offset:0
	s_waitcnt vmcnt(8)
	s_waitcnt lgkmcnt(0)
	s_barrier
	s_setprio 1
	v_mfma_f32_16x16x32_bf16 v[74:77], v[148:151], v[180:183], v[74:77]
	v_mfma_f32_16x16x32_bf16 v[74:77], v[152:155], v[184:187], v[74:77]
	v_mfma_f32_16x16x32_bf16 v[66:69], v[156:159], v[180:183], v[66:69]
	v_mfma_f32_16x16x32_bf16 v[66:69], v[160:163], v[184:187], v[66:69]
	v_mfma_f32_16x16x32_bf16 v[50:53], v[148:151], v[188:191], v[50:53]
	v_mfma_f32_16x16x32_bf16 v[50:53], v[152:155], v[192:195], v[50:53]
	v_mfma_f32_16x16x32_bf16 v[46:49], v[156:159], v[188:191], v[46:49]
	v_mfma_f32_16x16x32_bf16 v[46:49], v[160:163], v[192:195], v[46:49]
	v_mfma_f32_16x16x32_bf16 v[34:37], v[148:151], v[196:199], v[34:37]
	v_mfma_f32_16x16x32_bf16 v[34:37], v[152:155], v[200:203], v[34:37]
	v_mfma_f32_16x16x32_bf16 v[30:33], v[156:159], v[196:199], v[30:33]
	v_mfma_f32_16x16x32_bf16 v[30:33], v[160:163], v[200:203], v[30:33]
	v_mfma_f32_16x16x32_bf16 v[18:21], v[148:151], v[204:207], v[18:21]
	v_mfma_f32_16x16x32_bf16 v[18:21], v[152:155], v[208:211], v[18:21]
	v_mfma_f32_16x16x32_bf16 v[14:17], v[156:159], v[204:207], v[14:17]
	v_mfma_f32_16x16x32_bf16 v[14:17], v[160:163], v[208:211], v[14:17]
	s_setprio 0
	s_setprio 1
	v_mfma_f32_16x16x32_bf16 v[58:61], v[164:167], v[180:183], v[58:61]
	v_mfma_f32_16x16x32_bf16 v[54:57], v[172:175], v[180:183], v[54:57]
	v_mfma_f32_16x16x32_bf16 v[42:45], v[164:167], v[188:191], v[42:45]
	v_mfma_f32_16x16x32_bf16 v[38:41], v[172:175], v[188:191], v[38:41]
	v_mfma_f32_16x16x32_bf16 v[26:29], v[164:167], v[196:199], v[26:29]
	v_mfma_f32_16x16x32_bf16 v[22:25], v[172:175], v[196:199], v[22:25]
	v_mfma_f32_16x16x32_bf16 v[8:11], v[164:167], v[204:207], v[10:13]
	v_mfma_f32_16x16x32_bf16 v[4:7], v[172:175], v[204:207], v[4:7]
	v_mfma_f32_16x16x32_bf16 v[58:61], v[168:171], v[184:187], v[58:61]
	v_mfma_f32_16x16x32_bf16 v[54:57], v[176:179], v[184:187], v[54:57]
	v_mfma_f32_16x16x32_bf16 v[42:45], v[168:171], v[192:195], v[42:45]
	v_mfma_f32_16x16x32_bf16 v[38:41], v[176:179], v[192:195], v[38:41]
	v_mfma_f32_16x16x32_bf16 v[26:29], v[168:171], v[200:203], v[26:29]
	v_mfma_f32_16x16x32_bf16 v[22:25], v[176:179], v[200:203], v[22:25]
	v_mfma_f32_16x16x32_bf16 v[10:13], v[168:171], v[208:211], v[8:11]
	v_mfma_f32_16x16x32_bf16 v[6:9], v[176:179], v[208:211], v[4:7]
	s_barrier
	s_setprio 0
	s_add_i32 s79, s79, 2
	s_add_u32 s80, s80, 0x100
	s_addc_u32 s81, s81, 0
	s_add_u32 s82, s82, 0x100
	s_addc_u32 s83, s83, 0
	s_add_u32 s36, s36, 0x100
	s_addc_u32 s37, s37, 0
	s_cmpk_gt_u32 s79, 0x55
	s_cbranch_scc0 .LBB0_872
	s_and_b64 vcc, exec, s[16:17]
	s_cbranch_vccz .LBB0_875
	s_barrier

.LBB0_1013:
	s_add_u32 s30, s40, s58
	s_addc_u32 s31, s41, 0
	s_add_u32 s42, s30, 0x100
	s_addc_u32 s43, s31, 0
	s_and_b64 s[30:31], s[54:55], exec
	s_cselect_b32 s67, s25, s43
	s_cselect_b32 s66, s94, s42
	s_add_u32 s30, s44, s58
	s_addc_u32 s31, s45, 0
	s_add_u32 s42, s30, 0x100
	s_addc_u32 s43, s31, 0
	s_add_u32 s56, s66, 0x80
	s_addc_u32 s57, s67, 0
	s_and_b64 s[30:31], s[54:55], exec
	s_cselect_b32 s69, s23, s43
	s_cselect_b32 s68, s95, s42
	s_add_u32 s30, s96, s58
	s_addc_u32 s31, s97, 0
	ds_read_b128 v[146:149], v141
	ds_read_b128 v[150:153], v141 offset:1024
	ds_read_b128 v[154:157], v141 offset:2048
	ds_read_b128 v[158:161], v141 offset:3072
	ds_read_b128 v[162:165], v142
	ds_read_b128 v[166:169], v142 offset:1024
	ds_read_b128 v[170:173], v142 offset:2048
	ds_read_b128 v[174:177], v142 offset:3072
	s_add_u32 s72, s30, 0x80
	s_addc_u32 s73, s31, 0
	s_add_u32 s70, s68, 0x10000
	s_addc_u32 s71, s69, 0
	s_add_u32 s64, s66, 0x10000
	s_addc_u32 s65, s67, 0
	s_add_u32 s58, s68, 0x80
	s_addc_u32 s59, s69, 0
	s_add_u32 s54, s68, 0x10080
	s_addc_u32 s55, s69, 0
	ds_read_b128 v[178:181], v143
	ds_read_b128 v[182:185], v143 offset:1024
	ds_read_b128 v[186:189], v143 offset:2048
	ds_read_b128 v[190:193], v143 offset:3072
	ds_read_b128 v[194:197], v143 offset:4096
	ds_read_b128 v[198:201], v143 offset:5120
	ds_read_b128 v[202:205], v143 offset:6144
	ds_read_b128 v[206:209], v143 offset:7168
	s_mov_b32 m0, s86
	s_nop 0
	global_load_lds_dwordx4 v1, s[72:73] offset:0
	s_nop 0
	s_mov_b32 m0, s87
	s_nop 0
	global_load_lds_dwordx4 v137, s[72:73] offset:0
	s_waitcnt vmcnt(8)
	s_waitcnt lgkmcnt(0)
	s_barrier
	s_setprio 1
	v_mfma_f32_16x16x32_bf16 v[126:129], v[146:149], v[178:181], v[126:129]
	v_mfma_f32_16x16x32_bf16 v[126:129], v[150:153], v[182:185], v[126:129]
	v_mfma_f32_16x16x32_bf16 v[122:125], v[154:157], v[178:181], v[122:125]
	v_mfma_f32_16x16x32_bf16 v[122:125], v[158:161], v[182:185], v[122:125]
	v_mfma_f32_16x16x32_bf16 v[118:121], v[146:149], v[186:189], v[118:121]
	v_mfma_f32_16x16x32_bf16 v[118:121], v[150:153], v[190:193], v[118:121]
	v_mfma_f32_16x16x32_bf16 v[110:113], v[154:157], v[186:189], v[110:113]
	v_mfma_f32_16x16x32_bf16 v[110:113], v[158:161], v[190:193], v[110:113]
	v_mfma_f32_16x16x32_bf16 v[102:105], v[146:149], v[194:197], v[102:105]
	v_mfma_f32_16x16x32_bf16 v[102:105], v[150:153], v[198:201], v[102:105]
	v_mfma_f32_16x16x32_bf16 v[94:97], v[154:157], v[194:197], v[94:97]
	v_mfma_f32_16x16x32_bf16 v[94:97], v[158:161], v[198:201], v[94:97]
	v_mfma_f32_16x16x32_bf16 v[86:89], v[146:149], v[202:205], v[86:89]
	v_mfma_f32_16x16x32_bf16 v[86:89], v[150:153], v[206:209], v[86:89]
	v_mfma_f32_16x16x32_bf16 v[78:81], v[154:157], v[202:205], v[78:81]
	v_mfma_f32_16x16x32_bf16 v[78:81], v[158:161], v[206:209], v[78:81]
	s_setprio 0
	s_setprio 1
	v_mfma_f32_16x16x32_bf16 v[114:117], v[162:165], v[178:181], v[114:117]
	v_mfma_f32_16x16x32_bf16 v[114:117], v[166:169], v[182:185], v[114:117]
	v_mfma_f32_16x16x32_bf16 v[106:109], v[170:173], v[178:181], v[106:109]
	v_mfma_f32_16x16x32_bf16 v[106:109], v[174:177], v[182:185], v[106:109]
	v_mfma_f32_16x16x32_bf16 v[98:101], v[162:165], v[186:189], v[98:101]
	v_mfma_f32_16x16x32_bf16 v[98:101], v[166:169], v[190:193], v[98:101]
	v_mfma_f32_16x16x32_bf16 v[90:93], v[170:173], v[186:189], v[90:93]
	v_mfma_f32_16x16x32_bf16 v[90:93], v[174:177], v[190:193], v[90:93]
	v_mfma_f32_16x16x32_bf16 v[82:85], v[162:165], v[194:197], v[82:85]
	v_mfma_f32_16x16x32_bf16 v[82:85], v[166:169], v[198:201], v[82:85]
	v_mfma_f32_16x16x32_bf16 v[74:77], v[170:173], v[194:197], v[74:77]
	v_mfma_f32_16x16x32_bf16 v[74:77], v[174:177], v[198:201], v[74:77]
	v_mfma_f32_16x16x32_bf16 v[70:73], v[162:165], v[202:205], v[70:73]
	v_mfma_f32_16x16x32_bf16 v[70:73], v[166:169], v[206:209], v[70:73]
	v_mfma_f32_16x16x32_bf16 v[66:69], v[170:173], v[202:205], v[66:69]
	v_mfma_f32_16x16x32_bf16 v[66:69], v[174:177], v[206:209], v[66:69]
	s_barrier
	s_setprio 0
	ds_read_b128 v[178:181], v143 offset:16384
	ds_read_b128 v[182:185], v143 offset:17408
	ds_read_b128 v[186:189], v143 offset:18432
	ds_read_b128 v[190:193], v143 offset:19456
	ds_read_b128 v[194:197], v143 offset:20480
	ds_read_b128 v[198:201], v143 offset:21504
	ds_read_b128 v[202:205], v143 offset:22528
	ds_read_b128 v[206:209], v143 offset:23552
	s_mov_b32 m0, s39
	s_nop 0
	global_load_lds_dwordx4 v136, s[68:69] offset:0
	s_nop 0
	s_mov_b32 m0, s74
	s_nop 0
	global_load_lds_dwordx4 v138, s[68:69] offset:0
	s_nop 0
	s_mov_b32 m0, s75
	s_nop 0
	global_load_lds_dwordx4 v136, s[70:71] offset:0
	s_nop 0
	s_mov_b32 m0, s76
	s_nop 0
	global_load_lds_dwordx4 v138, s[70:71] offset:0
	s_nop 0
	s_mov_b32 m0, s53
	s_nop 0
	global_load_lds_dwordx4 v1, s[66:67] offset:0
	s_nop 0
	s_mov_b32 m0, s77
	s_nop 0
	global_load_lds_dwordx4 v137, s[66:67] offset:0
	s_waitcnt vmcnt(8)
	s_waitcnt lgkmcnt(0)
	s_barrier
	s_setprio 1
	v_mfma_f32_16x16x32_bf16 v[62:65], v[146:149], v[178:181], v[62:65]
	v_mfma_f32_16x16x32_bf16 v[62:65], v[150:153], v[182:185], v[62:65]
	v_mfma_f32_16x16x32_bf16 v[58:61], v[154:157], v[178:181], v[58:61]
	v_mfma_f32_16x16x32_bf16 v[58:61], v[158:161], v[182:185], v[58:61]
	v_mfma_f32_16x16x32_bf16 v[54:57], v[146:149], v[186:189], v[54:57]
	v_mfma_f32_16x16x32_bf16 v[54:57], v[150:153], v[190:193], v[54:57]
	v_mfma_f32_16x16x32_bf16 v[46:49], v[154:157], v[186:189], v[46:49]
	v_mfma_f32_16x16x32_bf16 v[46:49], v[158:161], v[190:193], v[46:49]
	v_mfma_f32_16x16x32_bf16 v[38:41], v[146:149], v[194:197], v[38:41]
	v_mfma_f32_16x16x32_bf16 v[38:41], v[150:153], v[198:201], v[38:41]
	v_mfma_f32_16x16x32_bf16 v[30:33], v[154:157], v[194:197], v[30:33]
	v_mfma_f32_16x16x32_bf16 v[30:33], v[158:161], v[198:201], v[30:33]
	v_mfma_f32_16x16x32_bf16 v[22:25], v[146:149], v[202:205], v[22:25]
	v_mfma_f32_16x16x32_bf16 v[22:25], v[150:153], v[206:209], v[22:25]
	v_mfma_f32_16x16x32_bf16 v[14:17], v[154:157], v[202:205], v[14:17]
	v_mfma_f32_16x16x32_bf16 v[14:17], v[158:161], v[206:209], v[14:17]
	s_setprio 0
	s_setprio 1
	v_mfma_f32_16x16x32_bf16 v[50:53], v[162:165], v[178:181], v[50:53]
	v_mfma_f32_16x16x32_bf16 v[50:53], v[166:169], v[182:185], v[50:53]
	v_mfma_f32_16x16x32_bf16 v[42:45], v[170:173], v[178:181], v[42:45]
	v_mfma_f32_16x16x32_bf16 v[42:45], v[174:177], v[182:185], v[42:45]
	v_mfma_f32_16x16x32_bf16 v[34:37], v[162:165], v[186:189], v[34:37]
	v_mfma_f32_16x16x32_bf16 v[34:37], v[166:169], v[190:193], v[34:37]
	v_mfma_f32_16x16x32_bf16 v[26:29], v[170:173], v[186:189], v[26:29]
	v_mfma_f32_16x16x32_bf16 v[26:29], v[174:177], v[190:193], v[26:29]
	v_mfma_f32_16x16x32_bf16 v[18:21], v[162:165], v[194:197], v[18:21]
	v_mfma_f32_16x16x32_bf16 v[18:21], v[166:169], v[198:201], v[18:21]
	v_mfma_f32_16x16x32_bf16 v[10:13], v[170:173], v[194:197], v[10:13]
	v_mfma_f32_16x16x32_bf16 v[10:13], v[174:177], v[198:201], v[10:13]
	v_mfma_f32_16x16x32_bf16 v[6:9], v[162:165], v[202:205], v[6:9]
	v_mfma_f32_16x16x32_bf16 v[6:9], v[166:169], v[206:209], v[6:9]
	v_mfma_f32_16x16x32_bf16 v[2:5], v[170:173], v[202:205], v[2:5]
	v_mfma_f32_16x16x32_bf16 v[2:5], v[174:177], v[206:209], v[2:5]
	s_barrier
	s_setprio 0
	ds_read_b128 v[146:149], v144
	ds_read_b128 v[150:153], v144 offset:1024
	ds_read_b128 v[154:157], v144 offset:2048
	ds_read_b128 v[158:161], v144 offset:3072
	ds_read_b128 v[162:165], v145
	ds_read_b128 v[166:169], v145 offset:1024
	ds_read_b128 v[170:173], v145 offset:2048
	ds_read_b128 v[174:177], v145 offset:3072
	ds_read_b128 v[178:181], v143 offset:32768
	ds_read_b128 v[182:185], v143 offset:33792
	ds_read_b128 v[186:189], v143 offset:34816
	ds_read_b128 v[190:193], v143 offset:35840
	ds_read_b128 v[194:197], v143 offset:36864
	ds_read_b128 v[198:201], v143 offset:37888
	ds_read_b128 v[202:205], v143 offset:38912
	ds_read_b128 v[206:209], v143 offset:39936
	s_mov_b32 m0, s78
	s_nop 0
	global_load_lds_dwordx4 v1, s[64:65] offset:0
	s_nop 0
	s_mov_b32 m0, s79
	s_nop 0
	global_load_lds_dwordx4 v137, s[64:65] offset:0
	s_waitcnt vmcnt(8)
	s_waitcnt lgkmcnt(0)
	s_barrier
	s_setprio 1
	v_mfma_f32_16x16x32_bf16 v[126:129], v[146:149], v[178:181], v[126:129]
	v_mfma_f32_16x16x32_bf16 v[126:129], v[150:153], v[182:185], v[126:129]
	v_mfma_f32_16x16x32_bf16 v[122:125], v[154:157], v[178:181], v[122:125]
	v_mfma_f32_16x16x32_bf16 v[122:125], v[158:161], v[182:185], v[122:125]
	v_mfma_f32_16x16x32_bf16 v[118:121], v[146:149], v[186:189], v[118:121]
	v_mfma_f32_16x16x32_bf16 v[118:121], v[150:153], v[190:193], v[118:121]
	v_mfma_f32_16x16x32_bf16 v[110:113], v[154:157], v[186:189], v[110:113]
	v_mfma_f32_16x16x32_bf16 v[110:113], v[158:161], v[190:193], v[110:113]
	v_mfma_f32_16x16x32_bf16 v[102:105], v[146:149], v[194:197], v[102:105]
	v_mfma_f32_16x16x32_bf16 v[102:105], v[150:153], v[198:201], v[102:105]
	v_mfma_f32_16x16x32_bf16 v[94:97], v[154:157], v[194:197], v[94:97]
	v_mfma_f32_16x16x32_bf16 v[94:97], v[158:161], v[198:201], v[94:97]
	v_mfma_f32_16x16x32_bf16 v[86:89], v[146:149], v[202:205], v[86:89]
	v_mfma_f32_16x16x32_bf16 v[86:89], v[150:153], v[206:209], v[86:89]
	v_mfma_f32_16x16x32_bf16 v[78:81], v[154:157], v[202:205], v[78:81]
	v_mfma_f32_16x16x32_bf16 v[78:81], v[158:161], v[206:209], v[78:81]
	s_setprio 0
	s_setprio 1
	v_mfma_f32_16x16x32_bf16 v[114:117], v[162:165], v[178:181], v[114:117]
	v_mfma_f32_16x16x32_bf16 v[114:117], v[166:169], v[182:185], v[114:117]
	v_mfma_f32_16x16x32_bf16 v[106:109], v[170:173], v[178:181], v[106:109]
	v_mfma_f32_16x16x32_bf16 v[106:109], v[174:177], v[182:185], v[106:109]
	v_mfma_f32_16x16x32_bf16 v[98:101], v[162:165], v[186:189], v[98:101]
	v_mfma_f32_16x16x32_bf16 v[98:101], v[166:169], v[190:193], v[98:101]
	v_mfma_f32_16x16x32_bf16 v[90:93], v[170:173], v[186:189], v[90:93]
	v_mfma_f32_16x16x32_bf16 v[90:93], v[174:177], v[190:193], v[90:93]
	v_mfma_f32_16x16x32_bf16 v[82:85], v[162:165], v[194:197], v[82:85]
	v_mfma_f32_16x16x32_bf16 v[82:85], v[166:169], v[198:201], v[82:85]
	v_mfma_f32_16x16x32_bf16 v[74:77], v[170:173], v[194:197], v[74:77]
	v_mfma_f32_16x16x32_bf16 v[74:77], v[174:177], v[198:201], v[74:77]
	v_mfma_f32_16x16x32_bf16 v[70:73], v[162:165], v[202:205], v[70:73]
	v_mfma_f32_16x16x32_bf16 v[70:73], v[166:169], v[206:209], v[70:73]
	v_mfma_f32_16x16x32_bf16 v[66:69], v[170:173], v[202:205], v[66:69]
	v_mfma_f32_16x16x32_bf16 v[66:69], v[174:177], v[206:209], v[66:69]
	s_barrier
	s_setprio 0
	ds_read_b128 v[178:181], v143 offset:49152
	ds_read_b128 v[182:185], v143 offset:50176
	ds_read_b128 v[186:189], v143 offset:51200
	ds_read_b128 v[190:193], v143 offset:52224
	ds_read_b128 v[194:197], v143 offset:53248
	ds_read_b128 v[198:201], v143 offset:54272
	ds_read_b128 v[202:205], v143 offset:55296
	ds_read_b128 v[206:209], v143 offset:56320
	s_mov_b32 m0, s80
	s_nop 0
	global_load_lds_dwordx4 v136, s[58:59] offset:0
	s_nop 0
	s_mov_b32 m0, s81
	s_nop 0
	global_load_lds_dwordx4 v138, s[58:59] offset:0
	s_nop 0
	s_mov_b32 m0, s84
	s_nop 0
	global_load_lds_dwordx4 v136, s[54:55] offset:0
	s_nop 0
	s_mov_b32 m0, s85
	s_nop 0
	global_load_lds_dwordx4 v138, s[54:55] offset:0
	s_nop 0
	s_mov_b32 m0, s82
	s_nop 0
	global_load_lds_dwordx4 v1, s[56:57] offset:0
	s_nop 0
	s_mov_b32 m0, s83
	s_nop 0
	global_load_lds_dwordx4 v137, s[56:57] offset:0
	s_waitcnt vmcnt(8)
	s_waitcnt lgkmcnt(0)
	s_barrier
	s_setprio 1
	v_mfma_f32_16x16x32_bf16 v[62:65], v[146:149], v[178:181], v[62:65]
	v_mfma_f32_16x16x32_bf16 v[62:65], v[150:153], v[182:185], v[62:65]
	v_mfma_f32_16x16x32_bf16 v[58:61], v[154:157], v[178:181], v[58:61]
	v_mfma_f32_16x16x32_bf16 v[58:61], v[158:161], v[182:185], v[58:61]
	v_mfma_f32_16x16x32_bf16 v[54:57], v[146:149], v[186:189], v[54:57]
	v_mfma_f32_16x16x32_bf16 v[54:57], v[150:153], v[190:193], v[54:57]
	v_mfma_f32_16x16x32_bf16 v[46:49], v[154:157], v[186:189], v[46:49]
	v_mfma_f32_16x16x32_bf16 v[46:49], v[158:161], v[190:193], v[46:49]
	v_mfma_f32_16x16x32_bf16 v[38:41], v[146:149], v[194:197], v[38:41]
	v_mfma_f32_16x16x32_bf16 v[38:41], v[150:153], v[198:201], v[38:41]
	v_mfma_f32_16x16x32_bf16 v[30:33], v[154:157], v[194:197], v[30:33]
	v_mfma_f32_16x16x32_bf16 v[30:33], v[158:161], v[198:201], v[30:33]
	v_mfma_f32_16x16x32_bf16 v[22:25], v[146:149], v[202:205], v[22:25]
	v_mfma_f32_16x16x32_bf16 v[22:25], v[150:153], v[206:209], v[22:25]
	v_mfma_f32_16x16x32_bf16 v[14:17], v[154:157], v[202:205], v[14:17]
	v_mfma_f32_16x16x32_bf16 v[14:17], v[158:161], v[206:209], v[14:17]
	s_setprio 0
	s_setprio 1
	v_mfma_f32_16x16x32_bf16 v[50:53], v[162:165], v[178:181], v[50:53]
	v_mfma_f32_16x16x32_bf16 v[50:53], v[166:169], v[182:185], v[50:53]
	v_mfma_f32_16x16x32_bf16 v[42:45], v[170:173], v[178:181], v[42:45]
	v_mfma_f32_16x16x32_bf16 v[42:45], v[174:177], v[182:185], v[42:45]
	v_mfma_f32_16x16x32_bf16 v[34:37], v[162:165], v[186:189], v[34:37]
	v_mfma_f32_16x16x32_bf16 v[34:37], v[166:169], v[190:193], v[34:37]
	v_mfma_f32_16x16x32_bf16 v[26:29], v[170:173], v[186:189], v[26:29]
	v_mfma_f32_16x16x32_bf16 v[26:29], v[174:177], v[190:193], v[26:29]
	v_mfma_f32_16x16x32_bf16 v[18:21], v[162:165], v[194:197], v[18:21]
	v_mfma_f32_16x16x32_bf16 v[18:21], v[166:169], v[198:201], v[18:21]
	v_mfma_f32_16x16x32_bf16 v[10:13], v[170:173], v[194:197], v[10:13]
	v_mfma_f32_16x16x32_bf16 v[10:13], v[174:177], v[198:201], v[10:13]
	v_mfma_f32_16x16x32_bf16 v[6:9], v[162:165], v[202:205], v[6:9]
	v_mfma_f32_16x16x32_bf16 v[6:9], v[166:169], v[206:209], v[6:9]
	v_mfma_f32_16x16x32_bf16 v[2:5], v[170:173], v[202:205], v[2:5]
	v_mfma_f32_16x16x32_bf16 v[2:5], v[174:177], v[206:209], v[2:5]
	s_barrier
	s_setprio 0
	s_movk_i32 s58, 0x100
	s_andn2_b64 vcc, exec, s[46:47]
	s_mov_b64 s[54:55], -1
	s_mov_b64 s[46:47], 0
	s_cbranch_vccz .LBB0_1013
	s_and_b64 vcc, exec, s[14:15]
	s_cbranch_vccz .LBB0_1016
	s_barrier

.LBB0_2128:
	s_cmp_eq_u32 s29, 0
	s_mov_b32 s58, 0
	s_cbranch_scc1 .LBB0_2130
	ds_read_b128 v[4:7], v147
	ds_read_b128 v[8:11], v147 offset:1024
	ds_read_b128 v[12:15], v147 offset:2048
	ds_read_b128 v[16:19], v147 offset:3072
	ds_read_b128 v[20:23], v148
	ds_read_b128 v[24:27], v148 offset:1024
	ds_read_b128 v[28:31], v148 offset:2048
	ds_read_b128 v[32:35], v148 offset:3072
	s_add_u32 s40, s54, 0x100
	s_addc_u32 s41, s55, 0
	s_add_u32 s30, s56, 0x100
	s_addc_u32 s31, s57, 0
	s_add_u32 s38, s54, 0x180
	s_addc_u32 s39, s55, 0
	ds_read_b128 v[36:39], v149
	ds_read_b128 v[40:43], v149 offset:1024
	ds_read_b128 v[44:47], v149 offset:2048
	ds_read_b128 v[48:51], v149 offset:3072
	ds_read_b128 v[52:55], v149 offset:4096
	ds_read_b128 v[56:59], v149 offset:5120
	ds_read_b128 v[60:63], v149 offset:6144
	ds_read_b128 v[64:67], v149 offset:7168
	s_add_u32 s42, s54, 0x80080
	s_addc_u32 s43, s55, 0
	s_mov_b32 m0, s79
	s_nop 0
	global_load_lds_dwordx4 v1, s[42:43] offset:0
	s_nop 0
	s_mov_b32 m0, s80
	s_nop 0
	global_load_lds_dwordx4 v143, s[42:43] offset:0
	s_waitcnt vmcnt(24)
	s_waitcnt lgkmcnt(0)
	s_barrier
	s_setprio 1
	v_mfma_f32_16x16x32_bf16 v[92:95], v[4:7], v[60:63], 0
	v_mfma_f32_16x16x32_bf16 v[68:71], v[4:7], v[36:39], 0
	v_mfma_f32_16x16x32_bf16 v[72:75], v[12:15], v[36:39], 0
	v_mfma_f32_16x16x32_bf16 v[76:79], v[4:7], v[44:47], 0
	v_mfma_f32_16x16x32_bf16 v[80:83], v[12:15], v[44:47], 0
	v_mfma_f32_16x16x32_bf16 v[84:87], v[4:7], v[52:55], 0
	v_mfma_f32_16x16x32_bf16 v[88:91], v[12:15], v[52:55], 0
	v_mfma_f32_16x16x32_bf16 v[102:105], v[8:11], v[64:67], v[92:95]
	v_mfma_f32_16x16x32_bf16 v[92:95], v[12:15], v[60:63], 0
	v_mfma_f32_16x16x32_bf16 v[68:71], v[8:11], v[40:43], v[68:71]
	v_mfma_f32_16x16x32_bf16 v[72:75], v[16:19], v[40:43], v[72:75]
	v_mfma_f32_16x16x32_bf16 v[76:79], v[8:11], v[48:51], v[76:79]
	v_mfma_f32_16x16x32_bf16 v[80:83], v[16:19], v[48:51], v[80:83]
	v_mfma_f32_16x16x32_bf16 v[84:87], v[8:11], v[56:59], v[84:87]
	v_mfma_f32_16x16x32_bf16 v[88:91], v[16:19], v[56:59], v[88:91]
	v_mfma_f32_16x16x32_bf16 v[106:109], v[16:19], v[64:67], v[92:95]
	s_setprio 0
	s_setprio 1
	v_mfma_f32_16x16x32_bf16 v[92:95], v[20:23], v[36:39], 0
	v_mfma_f32_16x16x32_bf16 v[36:39], v[28:31], v[36:39], 0
	v_mfma_f32_16x16x32_bf16 v[118:121], v[24:27], v[40:43], v[92:95]
	v_mfma_f32_16x16x32_bf16 v[36:39], v[32:35], v[40:43], v[36:39]
	v_mfma_f32_16x16x32_bf16 v[40:43], v[20:23], v[44:47], 0
	v_mfma_f32_16x16x32_bf16 v[44:47], v[28:31], v[44:47], 0
	v_mfma_f32_16x16x32_bf16 v[40:43], v[24:27], v[48:51], v[40:43]
	v_mfma_f32_16x16x32_bf16 v[44:47], v[32:35], v[48:51], v[44:47]
	v_mfma_f32_16x16x32_bf16 v[48:51], v[20:23], v[52:55], 0
	v_mfma_f32_16x16x32_bf16 v[52:55], v[28:31], v[52:55], 0
	v_mfma_f32_16x16x32_bf16 v[48:51], v[24:27], v[56:59], v[48:51]
	v_mfma_f32_16x16x32_bf16 v[52:55], v[32:35], v[56:59], v[52:55]
	v_mfma_f32_16x16x32_bf16 v[56:59], v[20:23], v[60:63], 0
	v_mfma_f32_16x16x32_bf16 v[60:63], v[28:31], v[60:63], 0
	v_mfma_f32_16x16x32_bf16 v[56:59], v[24:27], v[64:67], v[56:59]
	v_mfma_f32_16x16x32_bf16 v[60:63], v[32:35], v[64:67], v[60:63]
	s_barrier
	s_setprio 0
	ds_read_b128 v[64:67], v149 offset:16384
	ds_read_b128 v[92:95], v149 offset:17408
	ds_read_b128 v[96:99], v149 offset:18432
	ds_read_b128 v[110:113], v149 offset:19456
	ds_read_b128 v[114:117], v149 offset:20480
	ds_read_b128 v[122:125], v149 offset:21504
	ds_read_b128 v[126:129], v149 offset:22528
	ds_read_b128 v[130:133], v149 offset:23552
	s_mov_b32 m0, s47
	s_nop 0
	global_load_lds_dwordx4 v142, s[30:31] offset:0
	s_nop 0
	s_mov_b32 m0, s52
	s_nop 0
	global_load_lds_dwordx4 v144, s[30:31] offset:0
	s_add_u32 s30, s56, 0x80100
	s_addc_u32 s31, s57, 0
	s_mov_b32 m0, s53
	s_nop 0
	global_load_lds_dwordx4 v142, s[30:31] offset:0
	s_nop 0
	s_mov_b32 m0, s66
	s_nop 0
	global_load_lds_dwordx4 v144, s[30:31] offset:0
	s_nop 0
	s_mov_b32 m0, s33
	s_nop 0
	global_load_lds_dwordx4 v1, s[40:41] offset:0
	s_nop 0
	s_mov_b32 m0, s67
	s_nop 0
	global_load_lds_dwordx4 v143, s[40:41] offset:0
	s_waitcnt vmcnt(24)
	s_waitcnt lgkmcnt(0)
	s_barrier
	s_setprio 1
	v_mfma_f32_16x16x32_bf16 v[138:141], v[4:7], v[64:67], 0
	v_mfma_f32_16x16x32_bf16 v[156:159], v[4:7], v[96:99], 0
	v_mfma_f32_16x16x32_bf16 v[164:167], v[4:7], v[114:117], 0
	v_mfma_f32_16x16x32_bf16 v[4:7], v[4:7], v[126:129], 0
	v_mfma_f32_16x16x32_bf16 v[138:141], v[8:11], v[92:95], v[138:141]
	v_mfma_f32_16x16x32_bf16 v[156:159], v[8:11], v[110:113], v[156:159]
	v_mfma_f32_16x16x32_bf16 v[164:167], v[8:11], v[122:125], v[164:167]
	v_mfma_f32_16x16x32_bf16 v[4:7], v[8:11], v[130:133], v[4:7]
	v_mfma_f32_16x16x32_bf16 v[8:11], v[12:15], v[126:129], 0
	v_mfma_f32_16x16x32_bf16 v[152:155], v[12:15], v[64:67], 0
	v_mfma_f32_16x16x32_bf16 v[160:163], v[12:15], v[96:99], 0
	v_mfma_f32_16x16x32_bf16 v[168:171], v[12:15], v[114:117], 0
	v_mfma_f32_16x16x32_bf16 v[8:11], v[16:19], v[130:133], v[8:11]
	v_mfma_f32_16x16x32_bf16 v[152:155], v[16:19], v[92:95], v[152:155]
	v_mfma_f32_16x16x32_bf16 v[160:163], v[16:19], v[110:113], v[160:163]
	v_mfma_f32_16x16x32_bf16 v[168:171], v[16:19], v[122:125], v[168:171]
	s_setprio 0
	s_setprio 1
	v_mfma_f32_16x16x32_bf16 v[12:15], v[20:23], v[64:67], 0
	v_mfma_f32_16x16x32_bf16 v[172:175], v[24:27], v[92:95], v[12:15]
	v_mfma_f32_16x16x32_bf16 v[12:15], v[28:31], v[64:67], 0
	v_mfma_f32_16x16x32_bf16 v[176:179], v[32:35], v[92:95], v[12:15]
	v_mfma_f32_16x16x32_bf16 v[12:15], v[20:23], v[96:99], 0
	v_mfma_f32_16x16x32_bf16 v[180:183], v[24:27], v[110:113], v[12:15]
	v_mfma_f32_16x16x32_bf16 v[12:15], v[28:31], v[96:99], 0
	v_mfma_f32_16x16x32_bf16 v[184:187], v[32:35], v[110:113], v[12:15]
	v_mfma_f32_16x16x32_bf16 v[12:15], v[20:23], v[114:117], 0
	v_mfma_f32_16x16x32_bf16 v[188:191], v[24:27], v[122:125], v[12:15]
	v_mfma_f32_16x16x32_bf16 v[12:15], v[28:31], v[114:117], 0
	v_mfma_f32_16x16x32_bf16 v[192:195], v[32:35], v[122:125], v[12:15]
	v_mfma_f32_16x16x32_bf16 v[12:15], v[20:23], v[126:129], 0
	v_mfma_f32_16x16x32_bf16 v[196:199], v[24:27], v[130:133], v[12:15]
	v_mfma_f32_16x16x32_bf16 v[12:15], v[28:31], v[126:129], 0
	v_mfma_f32_16x16x32_bf16 v[200:203], v[32:35], v[130:133], v[12:15]
	s_barrier
	s_setprio 0
	s_nop 4
	ds_read_b128 v[12:15], v150
	ds_read_b128 v[16:19], v150 offset:1024
	ds_read_b128 v[22:25], v150 offset:2048
	ds_read_b128 v[26:29], v150 offset:3072
	ds_read_b128 v[204:207], v151
	ds_read_b128 v[208:211], v151 offset:1024
	ds_read_b128 v[212:215], v151 offset:2048
	ds_read_b128 v[216:219], v151 offset:3072
	ds_read_b128 v[30:33], v149 offset:32768
	ds_read_b128 v[64:67], v149 offset:33792
	ds_read_b128 v[220:223], v149 offset:34816
	ds_read_b128 v[224:227], v149 offset:35840
	ds_read_b128 v[228:231], v149 offset:36864
	ds_read_b128 v[232:235], v149 offset:37888
	ds_read_b128 v[236:239], v149 offset:38912
	ds_read_b128 v[240:243], v149 offset:39936
	s_add_u32 s30, s54, 0x80100
	s_addc_u32 s31, s55, 0
	s_mov_b32 m0, s68
	s_nop 0
	global_load_lds_dwordx4 v1, s[30:31] offset:0
	s_nop 0
	s_mov_b32 m0, s69
	s_nop 0
	global_load_lds_dwordx4 v143, s[30:31] offset:0
	s_waitcnt vmcnt(8)
	s_waitcnt lgkmcnt(0)
	s_barrier
	s_setprio 1
	v_mfma_f32_16x16x32_bf16 v[68:71], v[12:15], v[30:33], v[68:71]
	v_mfma_f32_16x16x32_bf16 v[130:133], v[16:19], v[64:67], v[68:71]
	v_mfma_f32_16x16x32_bf16 v[68:71], v[22:25], v[30:33], v[72:75]
	v_mfma_f32_16x16x32_bf16 v[126:129], v[26:29], v[64:67], v[68:71]
	v_mfma_f32_16x16x32_bf16 v[68:71], v[12:15], v[220:223], v[76:79]
	v_mfma_f32_16x16x32_bf16 v[114:117], v[16:19], v[224:227], v[68:71]
	v_mfma_f32_16x16x32_bf16 v[68:71], v[22:25], v[220:223], v[80:83]
	v_mfma_f32_16x16x32_bf16 v[110:113], v[26:29], v[224:227], v[68:71]
	v_mfma_f32_16x16x32_bf16 v[68:71], v[12:15], v[228:231], v[84:87]
	v_mfma_f32_16x16x32_bf16 v[98:101], v[16:19], v[232:235], v[68:71]
	v_mfma_f32_16x16x32_bf16 v[68:71], v[22:25], v[228:231], v[88:91]
	v_mfma_f32_16x16x32_bf16 v[94:97], v[26:29], v[232:235], v[68:71]
	v_mfma_f32_16x16x32_bf16 v[68:71], v[12:15], v[236:239], v[102:105]
	v_mfma_f32_16x16x32_bf16 v[82:85], v[16:19], v[240:243], v[68:71]
	v_mfma_f32_16x16x32_bf16 v[68:71], v[22:25], v[236:239], v[106:109]
	v_mfma_f32_16x16x32_bf16 v[78:81], v[26:29], v[240:243], v[68:71]
	s_setprio 0
	s_setprio 1
	v_mfma_f32_16x16x32_bf16 v[68:71], v[204:207], v[30:33], v[118:121]
	v_mfma_f32_16x16x32_bf16 v[30:33], v[212:215], v[30:33], v[36:39]
	v_mfma_f32_16x16x32_bf16 v[118:121], v[216:219], v[64:67], v[30:33]
	v_mfma_f32_16x16x32_bf16 v[30:33], v[204:207], v[220:223], v[40:43]
	v_mfma_f32_16x16x32_bf16 v[106:109], v[208:211], v[224:227], v[30:33]
	v_mfma_f32_16x16x32_bf16 v[30:33], v[212:215], v[220:223], v[44:47]
	v_mfma_f32_16x16x32_bf16 v[102:105], v[216:219], v[224:227], v[30:33]
	v_mfma_f32_16x16x32_bf16 v[30:33], v[204:207], v[228:231], v[48:51]
	v_mfma_f32_16x16x32_bf16 v[90:93], v[208:211], v[232:235], v[30:33]
	v_mfma_f32_16x16x32_bf16 v[30:33], v[212:215], v[228:231], v[52:55]
	v_mfma_f32_16x16x32_bf16 v[86:89], v[216:219], v[232:235], v[30:33]
	v_mfma_f32_16x16x32_bf16 v[30:33], v[204:207], v[236:239], v[56:59]
	v_mfma_f32_16x16x32_bf16 v[74:77], v[208:211], v[240:243], v[30:33]
	v_mfma_f32_16x16x32_bf16 v[30:33], v[212:215], v[236:239], v[60:63]
	v_mfma_f32_16x16x32_bf16 v[122:125], v[208:211], v[64:67], v[68:71]
	v_mfma_f32_16x16x32_bf16 v[70:73], v[216:219], v[240:243], v[30:33]
	s_barrier
	s_setprio 0
	ds_read_b128 v[38:41], v149 offset:49152
	ds_read_b128 v[42:45], v149 offset:50176
	ds_read_b128 v[220:223], v149 offset:51200
	ds_read_b128 v[224:227], v149 offset:52224
	ds_read_b128 v[228:231], v149 offset:53248
	ds_read_b128 v[232:235], v149 offset:54272
	ds_read_b128 v[236:239], v149 offset:55296
	ds_read_b128 v[240:243], v149 offset:56320
	s_add_u32 s30, s56, 0x180
	s_addc_u32 s31, s57, 0
	s_mov_b32 m0, s73
	s_nop 0
	global_load_lds_dwordx4 v142, s[30:31] offset:0
	s_nop 0
	s_mov_b32 m0, s74
	s_nop 0
	global_load_lds_dwordx4 v144, s[30:31] offset:0
	s_add_u32 s30, s56, 0x80180
	s_addc_u32 s31, s57, 0
	s_mov_b32 m0, s77
	s_nop 0
	global_load_lds_dwordx4 v142, s[30:31] offset:0
	s_nop 0
	s_mov_b32 m0, s78
	s_nop 0
	global_load_lds_dwordx4 v144, s[30:31] offset:0
	s_nop 0
	s_mov_b32 m0, s75
	s_nop 0
	global_load_lds_dwordx4 v1, s[38:39] offset:0
	s_nop 0
	s_mov_b32 m0, s76
	s_nop 0
	global_load_lds_dwordx4 v143, s[38:39] offset:0
	s_waitcnt vmcnt(8)
	s_waitcnt lgkmcnt(0)
	s_barrier
	s_setprio 1
	v_mfma_f32_16x16x32_bf16 v[30:33], v[12:15], v[38:41], v[138:141]
	v_mfma_f32_16x16x32_bf16 v[66:69], v[16:19], v[42:45], v[30:33]
	v_mfma_f32_16x16x32_bf16 v[30:33], v[22:25], v[38:41], v[152:155]
	v_mfma_f32_16x16x32_bf16 v[62:65], v[26:29], v[42:45], v[30:33]
	v_mfma_f32_16x16x32_bf16 v[30:33], v[12:15], v[220:223], v[156:159]
	v_mfma_f32_16x16x32_bf16 v[50:53], v[16:19], v[224:227], v[30:33]
	v_mfma_f32_16x16x32_bf16 v[30:33], v[22:25], v[220:223], v[160:163]
	v_mfma_f32_16x16x32_bf16 v[46:49], v[26:29], v[224:227], v[30:33]
	v_mfma_f32_16x16x32_bf16 v[30:33], v[12:15], v[228:231], v[164:167]
	v_mfma_f32_16x16x32_bf16 v[4:7], v[12:15], v[236:239], v[4:7]
	v_mfma_f32_16x16x32_bf16 v[34:37], v[16:19], v[232:235], v[30:33]
	v_mfma_f32_16x16x32_bf16 v[30:33], v[22:25], v[228:231], v[168:171]
	v_mfma_f32_16x16x32_bf16 v[18:21], v[16:19], v[240:243], v[4:7]
	v_mfma_f32_16x16x32_bf16 v[4:7], v[22:25], v[236:239], v[8:11]
	v_mfma_f32_16x16x32_bf16 v[30:33], v[26:29], v[232:235], v[30:33]
	v_mfma_f32_16x16x32_bf16 v[14:17], v[26:29], v[240:243], v[4:7]
	s_setprio 0
	s_setprio 1
	v_mfma_f32_16x16x32_bf16 v[4:7], v[204:207], v[38:41], v[172:175]
	v_mfma_f32_16x16x32_bf16 v[58:61], v[208:211], v[42:45], v[4:7]
	v_mfma_f32_16x16x32_bf16 v[4:7], v[212:215], v[38:41], v[176:179]
	v_mfma_f32_16x16x32_bf16 v[54:57], v[216:219], v[42:45], v[4:7]
	v_mfma_f32_16x16x32_bf16 v[4:7], v[204:207], v[220:223], v[180:183]
	v_mfma_f32_16x16x32_bf16 v[42:45], v[208:211], v[224:227], v[4:7]
	v_mfma_f32_16x16x32_bf16 v[4:7], v[212:215], v[220:223], v[184:187]
	v_mfma_f32_16x16x32_bf16 v[38:41], v[216:219], v[224:227], v[4:7]
	v_mfma_f32_16x16x32_bf16 v[4:7], v[204:207], v[228:231], v[188:191]
	v_mfma_f32_16x16x32_bf16 v[26:29], v[208:211], v[232:235], v[4:7]
	v_mfma_f32_16x16x32_bf16 v[4:7], v[212:215], v[228:231], v[192:195]
	v_mfma_f32_16x16x32_bf16 v[22:25], v[216:219], v[232:235], v[4:7]
	v_mfma_f32_16x16x32_bf16 v[4:7], v[204:207], v[236:239], v[196:199]
	v_mfma_f32_16x16x32_bf16 v[10:13], v[208:211], v[240:243], v[4:7]
	v_mfma_f32_16x16x32_bf16 v[4:7], v[212:215], v[236:239], v[200:203]
	v_mfma_f32_16x16x32_bf16 v[6:9], v[216:219], v[240:243], v[4:7]
	s_barrier
	s_setprio 0
	s_mov_b32 s58, 2
	s_branch .LBB0_2131

; #define PG8_KSETUP() const bool last = (t == nt - 2); const char* a1 = cA + (size_t)(t + 1) * kstep; \
;             const char* a2 = last ? nA : cA + (size_t)(t + 2) * kstep; const char* b2 = last ? nB : cB + (size_t)(t + 2) * kstep; const char* a3 = a2 + kstep; const char* b3 = b2 + kstep; \
;             if (last && has_next) S.a_ready(nxt)
; template <class Epi, class Sched, bool ALIGN_EPI = false, bool SP2 = false>
; __device__ __forceinline__ void gemm_phase(PG8_LAS unsigned char* lds, const Gemm g, const Sched& S, const Epi& E) {
;     ...
;         int t0 = 0;
;         if constexpr (SP2 && Epi::NVM == 16) { if (ui > 0) { const int t = 0; PG8_KSETUP(); PG8_KITER_SP2(24, 24); t0 = 2; } }
;         if constexpr (SP2 && Epi::NVM == 8) { if (ui > 0) { const int t = 0; PG8_KSETUP(); PG8_KITER_SP2(16, 16); t0 = 2; } }
;         for (int t = t0; t < nt; t += 2) {
;             PG8_KSETUP();
;             if constexpr (SP2) {
;             PG8_KITER_SP2(8, 8);
.LBB0_2132:
	ds_read_b128 v[138:141], v147
	ds_read_b128 v[152:155], v147 offset:1024
	ds_read_b128 v[156:159], v147 offset:2048
	ds_read_b128 v[160:163], v147 offset:3072
	ds_read_b128 v[164:167], v148
	ds_read_b128 v[168:171], v148 offset:1024
	ds_read_b128 v[172:175], v148 offset:2048
	ds_read_b128 v[176:179], v148 offset:3072
	s_cmp_eq_u32 s86, 28
	s_cselect_b32 s64, s45, s89
	s_cselect_b32 s65, s37, s90
	s_cselect_b32 s58, s85, s87
	s_cselect_b32 s59, s29, s88
	s_add_u32 s56, s64, 0x80
	s_addc_u32 s57, s65, 0
	ds_read_b128 v[180:183], v149
	ds_read_b128 v[184:187], v149 offset:1024
	ds_read_b128 v[188:191], v149 offset:2048
	ds_read_b128 v[192:195], v149 offset:3072
	ds_read_b128 v[196:199], v149 offset:4096
	ds_read_b128 v[200:203], v149 offset:5120
	ds_read_b128 v[204:207], v149 offset:6144
	ds_read_b128 v[208:211], v149 offset:7168
	s_mov_b32 m0, s79
	s_nop 0
	global_load_lds_dwordx4 v1, s[54:55] offset:0
	s_nop 0
	s_mov_b32 m0, s80
	s_nop 0
	global_load_lds_dwordx4 v143, s[54:55] offset:0
	s_waitcnt vmcnt(8)
	s_waitcnt lgkmcnt(0)
	s_barrier
	s_setprio 1
	v_mfma_f32_16x16x32_bf16 v[130:133], v[138:141], v[180:183], v[130:133]
	v_mfma_f32_16x16x32_bf16 v[130:133], v[152:155], v[184:187], v[130:133]
	v_mfma_f32_16x16x32_bf16 v[126:129], v[156:159], v[180:183], v[126:129]
	v_mfma_f32_16x16x32_bf16 v[126:129], v[160:163], v[184:187], v[126:129]
	v_mfma_f32_16x16x32_bf16 v[114:117], v[138:141], v[188:191], v[114:117]
	v_mfma_f32_16x16x32_bf16 v[114:117], v[152:155], v[192:195], v[114:117]
	v_mfma_f32_16x16x32_bf16 v[110:113], v[156:159], v[188:191], v[110:113]
	v_mfma_f32_16x16x32_bf16 v[110:113], v[160:163], v[192:195], v[110:113]
	v_mfma_f32_16x16x32_bf16 v[98:101], v[138:141], v[196:199], v[98:101]
	v_mfma_f32_16x16x32_bf16 v[98:101], v[152:155], v[200:203], v[98:101]
	v_mfma_f32_16x16x32_bf16 v[94:97], v[156:159], v[196:199], v[94:97]
	v_mfma_f32_16x16x32_bf16 v[94:97], v[160:163], v[200:203], v[94:97]
	v_mfma_f32_16x16x32_bf16 v[82:85], v[138:141], v[204:207], v[82:85]
	v_mfma_f32_16x16x32_bf16 v[82:85], v[152:155], v[208:211], v[82:85]
	v_mfma_f32_16x16x32_bf16 v[78:81], v[156:159], v[204:207], v[78:81]
	v_mfma_f32_16x16x32_bf16 v[78:81], v[160:163], v[208:211], v[78:81]
	s_setprio 0
	s_setprio 1
	v_mfma_f32_16x16x32_bf16 v[122:125], v[164:167], v[180:183], v[122:125]
	v_mfma_f32_16x16x32_bf16 v[122:125], v[168:171], v[184:187], v[122:125]
	v_mfma_f32_16x16x32_bf16 v[118:121], v[172:175], v[180:183], v[118:121]
	v_mfma_f32_16x16x32_bf16 v[118:121], v[176:179], v[184:187], v[118:121]
	v_mfma_f32_16x16x32_bf16 v[106:109], v[164:167], v[188:191], v[106:109]
	v_mfma_f32_16x16x32_bf16 v[106:109], v[168:171], v[192:195], v[106:109]
	v_mfma_f32_16x16x32_bf16 v[102:105], v[172:175], v[188:191], v[102:105]
	v_mfma_f32_16x16x32_bf16 v[102:105], v[176:179], v[192:195], v[102:105]
	v_mfma_f32_16x16x32_bf16 v[90:93], v[164:167], v[196:199], v[90:93]
	v_mfma_f32_16x16x32_bf16 v[90:93], v[168:171], v[200:203], v[90:93]
	v_mfma_f32_16x16x32_bf16 v[86:89], v[172:175], v[196:199], v[86:89]
	v_mfma_f32_16x16x32_bf16 v[86:89], v[176:179], v[200:203], v[86:89]
	v_mfma_f32_16x16x32_bf16 v[74:77], v[164:167], v[204:207], v[74:77]
	v_mfma_f32_16x16x32_bf16 v[74:77], v[168:171], v[208:211], v[74:77]
	v_mfma_f32_16x16x32_bf16 v[70:73], v[172:175], v[204:207], v[70:73]
	v_mfma_f32_16x16x32_bf16 v[70:73], v[176:179], v[208:211], v[70:73]
	s_barrier
	s_setprio 0
	ds_read_b128 v[180:183], v149 offset:16384
	ds_read_b128 v[184:187], v149 offset:17408
	ds_read_b128 v[188:191], v149 offset:18432
	ds_read_b128 v[192:195], v149 offset:19456
	ds_read_b128 v[196:199], v149 offset:20480
	ds_read_b128 v[200:203], v149 offset:21504
	ds_read_b128 v[204:207], v149 offset:22528
	ds_read_b128 v[208:211], v149 offset:23552
	s_mov_b32 m0, s47
	s_nop 0
	global_load_lds_dwordx4 v142, s[58:59] offset:0
	s_add_u32 s30, s58, 0x80000
	s_mov_b32 m0, s52
	s_nop 0
	global_load_lds_dwordx4 v144, s[58:59] offset:0
	s_addc_u32 s31, s59, 0
	s_mov_b32 m0, s53
	s_nop 0
	global_load_lds_dwordx4 v142, s[30:31] offset:0
	s_nop 0
	s_mov_b32 m0, s66
	s_nop 0
	global_load_lds_dwordx4 v144, s[30:31] offset:0
	s_nop 0
	s_mov_b32 m0, s33
	s_nop 0
	global_load_lds_dwordx4 v1, s[64:65] offset:0
	s_nop 0
	s_mov_b32 m0, s67
	s_nop 0
	global_load_lds_dwordx4 v143, s[64:65] offset:0
	s_waitcnt vmcnt(8)
	s_waitcnt lgkmcnt(0)
	s_barrier
	s_setprio 1
	v_mfma_f32_16x16x32_bf16 v[66:69], v[138:141], v[180:183], v[66:69]
	v_mfma_f32_16x16x32_bf16 v[66:69], v[152:155], v[184:187], v[66:69]
	v_mfma_f32_16x16x32_bf16 v[62:65], v[156:159], v[180:183], v[62:65]
	v_mfma_f32_16x16x32_bf16 v[62:65], v[160:163], v[184:187], v[62:65]
	v_mfma_f32_16x16x32_bf16 v[50:53], v[138:141], v[188:191], v[50:53]
	v_mfma_f32_16x16x32_bf16 v[50:53], v[152:155], v[192:195], v[50:53]
	v_mfma_f32_16x16x32_bf16 v[46:49], v[156:159], v[188:191], v[46:49]
	v_mfma_f32_16x16x32_bf16 v[46:49], v[160:163], v[192:195], v[46:49]
	v_mfma_f32_16x16x32_bf16 v[34:37], v[138:141], v[196:199], v[34:37]
	v_mfma_f32_16x16x32_bf16 v[34:37], v[152:155], v[200:203], v[34:37]
	v_mfma_f32_16x16x32_bf16 v[30:33], v[156:159], v[196:199], v[30:33]
	v_mfma_f32_16x16x32_bf16 v[30:33], v[160:163], v[200:203], v[30:33]
	v_mfma_f32_16x16x32_bf16 v[18:21], v[138:141], v[204:207], v[18:21]
	v_mfma_f32_16x16x32_bf16 v[18:21], v[152:155], v[208:211], v[18:21]
	v_mfma_f32_16x16x32_bf16 v[14:17], v[156:159], v[204:207], v[14:17]
	v_mfma_f32_16x16x32_bf16 v[14:17], v[160:163], v[208:211], v[14:17]
	s_setprio 0
	s_setprio 1
	v_mfma_f32_16x16x32_bf16 v[58:61], v[164:167], v[180:183], v[58:61]
	v_mfma_f32_16x16x32_bf16 v[54:57], v[172:175], v[180:183], v[54:57]
	v_mfma_f32_16x16x32_bf16 v[42:45], v[164:167], v[188:191], v[42:45]
	v_mfma_f32_16x16x32_bf16 v[38:41], v[172:175], v[188:191], v[38:41]
	v_mfma_f32_16x16x32_bf16 v[26:29], v[164:167], v[196:199], v[26:29]
	v_mfma_f32_16x16x32_bf16 v[22:25], v[172:175], v[196:199], v[22:25]
	v_mfma_f32_16x16x32_bf16 v[10:13], v[164:167], v[204:207], v[10:13]
	v_mfma_f32_16x16x32_bf16 v[4:7], v[172:175], v[204:207], v[6:9]
	v_mfma_f32_16x16x32_bf16 v[58:61], v[168:171], v[184:187], v[58:61]
	v_mfma_f32_16x16x32_bf16 v[54:57], v[176:179], v[184:187], v[54:57]
	v_mfma_f32_16x16x32_bf16 v[42:45], v[168:171], v[192:195], v[42:45]
	v_mfma_f32_16x16x32_bf16 v[38:41], v[176:179], v[192:195], v[38:41]
	v_mfma_f32_16x16x32_bf16 v[26:29], v[168:171], v[200:203], v[26:29]
	v_mfma_f32_16x16x32_bf16 v[22:25], v[176:179], v[200:203], v[22:25]
	v_mfma_f32_16x16x32_bf16 v[10:13], v[168:171], v[208:211], v[10:13]
	v_mfma_f32_16x16x32_bf16 v[4:7], v[176:179], v[208:211], v[4:7]
	s_barrier
; #define PG8_KSETUP() const bool last = (t == nt - 2); const char* a1 = cA + (size_t)(t + 1) * kstep; \
;             const char* a2 = last ? nA : cA + (size_t)(t + 2) * kstep; const char* b2 = last ? nB : cB + (size_t)(t + 2) * kstep; const char* a3 = a2 + kstep; const char* b3 = b2 + kstep; \
;             if (last && has_next) S.a_ready(nxt)
; template <class Epi, class Sched, bool ALIGN_EPI = false, bool SP2 = false>
; __device__ __forceinline__ void gemm_phase(PG8_LAS unsigned char* lds, const Gemm g, const Sched& S, const Epi& E) {
;     ...
;         int t0 = 0;
;         if constexpr (SP2 && Epi::NVM == 16) { if (ui > 0) { const int t = 0; PG8_KSETUP(); PG8_KITER_SP2(24, 24); t0 = 2; } }
;         if constexpr (SP2 && Epi::NVM == 8) { if (ui > 0) { const int t = 0; PG8_KSETUP(); PG8_KITER_SP2(16, 16); t0 = 2; } }
;         for (int t = t0; t < nt; t += 2) {
;             PG8_KSETUP();
;             if constexpr (SP2) {
;             PG8_KITER_SP2(8, 8);
	s_setprio 0
	ds_read_b128 v[138:141], v150
	ds_read_b128 v[152:155], v150 offset:1024
	ds_read_b128 v[156:159], v150 offset:2048
	ds_read_b128 v[160:163], v150 offset:3072
	ds_read_b128 v[164:167], v151
	ds_read_b128 v[168:171], v151 offset:1024
	ds_read_b128 v[172:175], v151 offset:2048
	ds_read_b128 v[176:179], v151 offset:3072
	ds_read_b128 v[180:183], v149 offset:32768
	ds_read_b128 v[184:187], v149 offset:33792
	ds_read_b128 v[188:191], v149 offset:34816
	ds_read_b128 v[192:195], v149 offset:35840
	ds_read_b128 v[196:199], v149 offset:36864
	ds_read_b128 v[200:203], v149 offset:37888
	ds_read_b128 v[204:207], v149 offset:38912
	ds_read_b128 v[208:211], v149 offset:39936
	s_add_u32 s30, s64, 0x80000
	s_addc_u32 s31, s65, 0
	s_mov_b32 m0, s68
	s_nop 0
	global_load_lds_dwordx4 v1, s[30:31] offset:0
	s_nop 0
	s_mov_b32 m0, s69
	s_nop 0
	global_load_lds_dwordx4 v143, s[30:31] offset:0
	s_waitcnt vmcnt(8)
	s_waitcnt lgkmcnt(0)
	s_barrier
	s_setprio 1
	v_mfma_f32_16x16x32_bf16 v[130:133], v[138:141], v[180:183], v[130:133]
	v_mfma_f32_16x16x32_bf16 v[130:133], v[152:155], v[184:187], v[130:133]
	v_mfma_f32_16x16x32_bf16 v[126:129], v[156:159], v[180:183], v[126:129]
	v_mfma_f32_16x16x32_bf16 v[126:129], v[160:163], v[184:187], v[126:129]
	v_mfma_f32_16x16x32_bf16 v[114:117], v[138:141], v[188:191], v[114:117]
	v_mfma_f32_16x16x32_bf16 v[114:117], v[152:155], v[192:195], v[114:117]
	v_mfma_f32_16x16x32_bf16 v[110:113], v[156:159], v[188:191], v[110:113]
	v_mfma_f32_16x16x32_bf16 v[110:113], v[160:163], v[192:195], v[110:113]
	v_mfma_f32_16x16x32_bf16 v[98:101], v[138:141], v[196:199], v[98:101]
	v_mfma_f32_16x16x32_bf16 v[98:101], v[152:155], v[200:203], v[98:101]
	v_mfma_f32_16x16x32_bf16 v[94:97], v[156:159], v[196:199], v[94:97]
	v_mfma_f32_16x16x32_bf16 v[94:97], v[160:163], v[200:203], v[94:97]
	v_mfma_f32_16x16x32_bf16 v[82:85], v[138:141], v[204:207], v[82:85]
	v_mfma_f32_16x16x32_bf16 v[82:85], v[152:155], v[208:211], v[82:85]
	v_mfma_f32_16x16x32_bf16 v[78:81], v[156:159], v[204:207], v[78:81]
	v_mfma_f32_16x16x32_bf16 v[78:81], v[160:163], v[208:211], v[78:81]
	s_setprio 0
	s_setprio 1
	v_mfma_f32_16x16x32_bf16 v[122:125], v[164:167], v[180:183], v[122:125]
	v_mfma_f32_16x16x32_bf16 v[122:125], v[168:171], v[184:187], v[122:125]
	v_mfma_f32_16x16x32_bf16 v[118:121], v[172:175], v[180:183], v[118:121]
	v_mfma_f32_16x16x32_bf16 v[118:121], v[176:179], v[184:187], v[118:121]
	v_mfma_f32_16x16x32_bf16 v[106:109], v[164:167], v[188:191], v[106:109]
	v_mfma_f32_16x16x32_bf16 v[106:109], v[168:171], v[192:195], v[106:109]
	v_mfma_f32_16x16x32_bf16 v[102:105], v[172:175], v[188:191], v[102:105]
	v_mfma_f32_16x16x32_bf16 v[102:105], v[176:179], v[192:195], v[102:105]
	v_mfma_f32_16x16x32_bf16 v[90:93], v[164:167], v[196:199], v[90:93]
	v_mfma_f32_16x16x32_bf16 v[90:93], v[168:171], v[200:203], v[90:93]
	v_mfma_f32_16x16x32_bf16 v[86:89], v[172:175], v[196:199], v[86:89]
	v_mfma_f32_16x16x32_bf16 v[86:89], v[176:179], v[200:203], v[86:89]
	v_mfma_f32_16x16x32_bf16 v[74:77], v[164:167], v[204:207], v[74:77]
	v_mfma_f32_16x16x32_bf16 v[74:77], v[168:171], v[208:211], v[74:77]
	v_mfma_f32_16x16x32_bf16 v[70:73], v[172:175], v[204:207], v[70:73]
	v_mfma_f32_16x16x32_bf16 v[70:73], v[176:179], v[208:211], v[70:73]
	s_barrier
	s_setprio 0
	ds_read_b128 v[180:183], v149 offset:49152
	ds_read_b128 v[184:187], v149 offset:50176
	ds_read_b128 v[188:191], v149 offset:51200
	ds_read_b128 v[192:195], v149 offset:52224
	ds_read_b128 v[196:199], v149 offset:53248
	ds_read_b128 v[200:203], v149 offset:54272
	ds_read_b128 v[204:207], v149 offset:55296
	ds_read_b128 v[208:211], v149 offset:56320
	s_add_u32 s30, s58, 0x80
	s_addc_u32 s31, s59, 0
	s_mov_b32 m0, s73
	s_nop 0
	global_load_lds_dwordx4 v142, s[30:31] offset:0
	s_nop 0
	s_mov_b32 m0, s74
	s_nop 0
	global_load_lds_dwordx4 v144, s[30:31] offset:0
	s_add_u32 s30, s58, 0x80080
	s_addc_u32 s31, s59, 0
	s_mov_b32 m0, s77
	s_nop 0
	global_load_lds_dwordx4 v142, s[30:31] offset:0
	s_nop 0
	s_mov_b32 m0, s78
	s_nop 0
	global_load_lds_dwordx4 v144, s[30:31] offset:0
	s_nop 0
	s_mov_b32 m0, s75
	s_nop 0
	global_load_lds_dwordx4 v1, s[56:57] offset:0
	s_nop 0
	s_mov_b32 m0, s76
	s_nop 0
	global_load_lds_dwordx4 v143, s[56:57] offset:0
	s_waitcnt vmcnt(8)
	s_waitcnt lgkmcnt(0)
	s_barrier
	s_setprio 1
	v_mfma_f32_16x16x32_bf16 v[66:69], v[138:141], v[180:183], v[66:69]
	v_mfma_f32_16x16x32_bf16 v[66:69], v[152:155], v[184:187], v[66:69]
	v_mfma_f32_16x16x32_bf16 v[62:65], v[156:159], v[180:183], v[62:65]
	v_mfma_f32_16x16x32_bf16 v[62:65], v[160:163], v[184:187], v[62:65]
	v_mfma_f32_16x16x32_bf16 v[50:53], v[138:141], v[188:191], v[50:53]
	v_mfma_f32_16x16x32_bf16 v[50:53], v[152:155], v[192:195], v[50:53]
	v_mfma_f32_16x16x32_bf16 v[46:49], v[156:159], v[188:191], v[46:49]
	v_mfma_f32_16x16x32_bf16 v[46:49], v[160:163], v[192:195], v[46:49]
	v_mfma_f32_16x16x32_bf16 v[34:37], v[138:141], v[196:199], v[34:37]
	v_mfma_f32_16x16x32_bf16 v[34:37], v[152:155], v[200:203], v[34:37]
	v_mfma_f32_16x16x32_bf16 v[30:33], v[156:159], v[196:199], v[30:33]
	v_mfma_f32_16x16x32_bf16 v[30:33], v[160:163], v[200:203], v[30:33]
	v_mfma_f32_16x16x32_bf16 v[18:21], v[138:141], v[204:207], v[18:21]
	v_mfma_f32_16x16x32_bf16 v[18:21], v[152:155], v[208:211], v[18:21]
	v_mfma_f32_16x16x32_bf16 v[14:17], v[156:159], v[204:207], v[14:17]
	v_mfma_f32_16x16x32_bf16 v[14:17], v[160:163], v[208:211], v[14:17]
	s_setprio 0
	s_setprio 1
	v_mfma_f32_16x16x32_bf16 v[58:61], v[164:167], v[180:183], v[58:61]
	v_mfma_f32_16x16x32_bf16 v[54:57], v[172:175], v[180:183], v[54:57]
	v_mfma_f32_16x16x32_bf16 v[42:45], v[164:167], v[188:191], v[42:45]
	v_mfma_f32_16x16x32_bf16 v[38:41], v[172:175], v[188:191], v[38:41]
	v_mfma_f32_16x16x32_bf16 v[26:29], v[164:167], v[196:199], v[26:29]
	v_mfma_f32_16x16x32_bf16 v[22:25], v[172:175], v[196:199], v[22:25]
	v_mfma_f32_16x16x32_bf16 v[8:11], v[164:167], v[204:207], v[10:13]
	v_mfma_f32_16x16x32_bf16 v[4:7], v[172:175], v[204:207], v[4:7]
	v_mfma_f32_16x16x32_bf16 v[58:61], v[168:171], v[184:187], v[58:61]
	v_mfma_f32_16x16x32_bf16 v[54:57], v[176:179], v[184:187], v[54:57]
	v_mfma_f32_16x16x32_bf16 v[42:45], v[168:171], v[192:195], v[42:45]
	v_mfma_f32_16x16x32_bf16 v[38:41], v[176:179], v[192:195], v[38:41]
	v_mfma_f32_16x16x32_bf16 v[26:29], v[168:171], v[200:203], v[26:29]
	v_mfma_f32_16x16x32_bf16 v[22:25], v[176:179], v[200:203], v[22:25]
	v_mfma_f32_16x16x32_bf16 v[10:13], v[168:171], v[208:211], v[8:11]
	v_mfma_f32_16x16x32_bf16 v[6:9], v[176:179], v[208:211], v[4:7]
	s_barrier
	s_setprio 0
	s_add_i32 s86, s86, 2
	s_add_u32 s87, s87, 0x100
	s_addc_u32 s88, s88, 0
	s_add_u32 s89, s89, 0x100
	s_addc_u32 s90, s90, 0
	s_add_u32 s54, s54, 0x100
	s_addc_u32 s55, s55, 0
	s_cmp_gt_u32 s86, 29
	s_cbranch_scc0 .LBB0_2132
	s_and_b64 vcc, exec, s[18:19]
	s_cbranch_vccz .LBB0_2135
	s_barrier

; #define PG8_KSETUP() const bool last = (t == nt - 2); const char* a1 = cA + (size_t)(t + 1) * kstep; \
;             const char* a2 = last ? nA : cA + (size_t)(t + 2) * kstep; const char* b2 = last ? nB : cB + (size_t)(t + 2) * kstep; const char* a3 = a2 + kstep; const char* b3 = b2 + kstep; \
;             if (last && has_next) S.a_ready(nxt)
; template <class Epi, class Sched, bool ALIGN_EPI = false, bool SP2 = false>
; __device__ __forceinline__ void gemm_phase(PG8_LAS unsigned char* lds, const Gemm g, const Sched& S, const Epi& E) {
;     ...
;         int t0 = 0;
;         if constexpr (SP2 && Epi::NVM == 16) { if (ui > 0) { const int t = 0; PG8_KSETUP(); PG8_KITER_SP2(24, 24); t0 = 2; } }
.LBB0_2287:
	s_cmp_lg_u32 s75, 0
	s_mov_b32 s40, 0
	s_cbranch_scc0 .LBB0_2289
	ds_read_b128 v[4:7], v152
	ds_read_b128 v[8:11], v152 offset:1024
	ds_read_b128 v[12:15], v152 offset:2048
	ds_read_b128 v[16:19], v152 offset:3072
	ds_read_b128 v[20:23], v153
	ds_read_b128 v[24:27], v153 offset:1024
	ds_read_b128 v[28:31], v153 offset:2048
	ds_read_b128 v[32:35], v153 offset:3072
	s_add_u32 s24, s36, 0x100
	s_addc_u32 s25, s37, 0
	s_add_u32 s30, s38, 0x100
	s_addc_u32 s31, s39, 0
	s_add_u32 s22, s36, 0x180
	s_addc_u32 s23, s37, 0
	ds_read_b128 v[36:39], v154
	ds_read_b128 v[40:43], v154 offset:1024
	ds_read_b128 v[44:47], v154 offset:2048
	ds_read_b128 v[48:51], v154 offset:3072
	ds_read_b128 v[52:55], v154 offset:4096
	ds_read_b128 v[56:59], v154 offset:5120
	ds_read_b128 v[60:63], v154 offset:6144
	ds_read_b128 v[64:67], v154 offset:7168
	s_add_u32 s40, s36, 0x80080
	s_addc_u32 s41, s37, 0
	s_mov_b32 m0, s66
	s_nop 0
	global_load_lds_dwordx4 v1, s[40:41] offset:0
	s_nop 0
	s_mov_b32 m0, s67
	s_nop 0
	global_load_lds_dwordx4 v147, s[40:41] offset:0
	s_waitcnt vmcnt(16)
	s_waitcnt lgkmcnt(0)
	s_barrier
	s_setprio 1
	v_mfma_f32_16x16x32_bf16 v[92:95], v[4:7], v[60:63], 0
	v_mfma_f32_16x16x32_bf16 v[68:71], v[4:7], v[36:39], 0
	v_mfma_f32_16x16x32_bf16 v[72:75], v[12:15], v[36:39], 0
	v_mfma_f32_16x16x32_bf16 v[76:79], v[4:7], v[44:47], 0
	v_mfma_f32_16x16x32_bf16 v[80:83], v[12:15], v[44:47], 0
	v_mfma_f32_16x16x32_bf16 v[84:87], v[4:7], v[52:55], 0
	v_mfma_f32_16x16x32_bf16 v[88:91], v[12:15], v[52:55], 0
	v_mfma_f32_16x16x32_bf16 v[102:105], v[8:11], v[64:67], v[92:95]
	v_mfma_f32_16x16x32_bf16 v[92:95], v[12:15], v[60:63], 0
	v_mfma_f32_16x16x32_bf16 v[68:71], v[8:11], v[40:43], v[68:71]
	v_mfma_f32_16x16x32_bf16 v[72:75], v[16:19], v[40:43], v[72:75]
	v_mfma_f32_16x16x32_bf16 v[76:79], v[8:11], v[48:51], v[76:79]
	v_mfma_f32_16x16x32_bf16 v[80:83], v[16:19], v[48:51], v[80:83]
	v_mfma_f32_16x16x32_bf16 v[84:87], v[8:11], v[56:59], v[84:87]
	v_mfma_f32_16x16x32_bf16 v[88:91], v[16:19], v[56:59], v[88:91]
	v_mfma_f32_16x16x32_bf16 v[106:109], v[16:19], v[64:67], v[92:95]
	s_setprio 0
	s_setprio 1
	v_mfma_f32_16x16x32_bf16 v[92:95], v[20:23], v[36:39], 0
	v_mfma_f32_16x16x32_bf16 v[36:39], v[28:31], v[36:39], 0
	v_mfma_f32_16x16x32_bf16 v[118:121], v[24:27], v[40:43], v[92:95]
	v_mfma_f32_16x16x32_bf16 v[36:39], v[32:35], v[40:43], v[36:39]
	v_mfma_f32_16x16x32_bf16 v[40:43], v[20:23], v[44:47], 0
	v_mfma_f32_16x16x32_bf16 v[44:47], v[28:31], v[44:47], 0
	v_mfma_f32_16x16x32_bf16 v[40:43], v[24:27], v[48:51], v[40:43]
	v_mfma_f32_16x16x32_bf16 v[44:47], v[32:35], v[48:51], v[44:47]
	v_mfma_f32_16x16x32_bf16 v[48:51], v[20:23], v[52:55], 0
	v_mfma_f32_16x16x32_bf16 v[52:55], v[28:31], v[52:55], 0
	v_mfma_f32_16x16x32_bf16 v[48:51], v[24:27], v[56:59], v[48:51]
	v_mfma_f32_16x16x32_bf16 v[52:55], v[32:35], v[56:59], v[52:55]
	v_mfma_f32_16x16x32_bf16 v[56:59], v[20:23], v[60:63], 0
	v_mfma_f32_16x16x32_bf16 v[60:63], v[28:31], v[60:63], 0
	v_mfma_f32_16x16x32_bf16 v[56:59], v[24:27], v[64:67], v[56:59]
	v_mfma_f32_16x16x32_bf16 v[60:63], v[32:35], v[64:67], v[60:63]
	s_barrier
	s_setprio 0
	ds_read_b128 v[64:67], v154 offset:16384
	ds_read_b128 v[92:95], v154 offset:17408
	ds_read_b128 v[96:99], v154 offset:18432
	ds_read_b128 v[110:113], v154 offset:19456
	ds_read_b128 v[114:117], v154 offset:20480
	ds_read_b128 v[122:125], v154 offset:21504
	ds_read_b128 v[126:129], v154 offset:22528
	ds_read_b128 v[130:133], v154 offset:23552
	s_mov_b32 m0, s29
	s_nop 0
	global_load_lds_dwordx4 v146, s[30:31] offset:0
	s_nop 0
	s_mov_b32 m0, s46
	s_nop 0
	global_load_lds_dwordx4 v148, s[30:31] offset:0
	s_add_u32 s30, s38, 0x80100
	s_addc_u32 s31, s39, 0
	s_mov_b32 m0, s47
	s_nop 0
	global_load_lds_dwordx4 v146, s[30:31] offset:0
	s_nop 0
	s_mov_b32 m0, s52
	s_nop 0
	global_load_lds_dwordx4 v148, s[30:31] offset:0
	s_nop 0
	s_mov_b32 m0, s21
	s_nop 0
	global_load_lds_dwordx4 v1, s[24:25] offset:0
	s_nop 0
	s_mov_b32 m0, s53
	s_nop 0
	global_load_lds_dwordx4 v147, s[24:25] offset:0
	s_waitcnt vmcnt(16)
	s_waitcnt lgkmcnt(0)
	s_barrier
	s_setprio 1
	v_mfma_f32_16x16x32_bf16 v[138:141], v[4:7], v[64:67], 0
	v_mfma_f32_16x16x32_bf16 v[158:161], v[4:7], v[96:99], 0
	v_mfma_f32_16x16x32_bf16 v[166:169], v[4:7], v[114:117], 0
	v_mfma_f32_16x16x32_bf16 v[4:7], v[4:7], v[126:129], 0
	v_mfma_f32_16x16x32_bf16 v[138:141], v[8:11], v[92:95], v[138:141]
	v_mfma_f32_16x16x32_bf16 v[158:161], v[8:11], v[110:113], v[158:161]
	v_mfma_f32_16x16x32_bf16 v[166:169], v[8:11], v[122:125], v[166:169]
	v_mfma_f32_16x16x32_bf16 v[4:7], v[8:11], v[130:133], v[4:7]
	v_mfma_f32_16x16x32_bf16 v[8:11], v[12:15], v[126:129], 0
	v_mfma_f32_16x16x32_bf16 v[142:145], v[12:15], v[64:67], 0
	v_mfma_f32_16x16x32_bf16 v[162:165], v[12:15], v[96:99], 0
	v_mfma_f32_16x16x32_bf16 v[170:173], v[12:15], v[114:117], 0
	v_mfma_f32_16x16x32_bf16 v[8:11], v[16:19], v[130:133], v[8:11]
	v_mfma_f32_16x16x32_bf16 v[142:145], v[16:19], v[92:95], v[142:145]
	v_mfma_f32_16x16x32_bf16 v[162:165], v[16:19], v[110:113], v[162:165]
	v_mfma_f32_16x16x32_bf16 v[170:173], v[16:19], v[122:125], v[170:173]
	s_setprio 0
	s_setprio 1
	v_mfma_f32_16x16x32_bf16 v[12:15], v[20:23], v[64:67], 0
	v_mfma_f32_16x16x32_bf16 v[174:177], v[24:27], v[92:95], v[12:15]
	v_mfma_f32_16x16x32_bf16 v[12:15], v[28:31], v[64:67], 0
	v_mfma_f32_16x16x32_bf16 v[178:181], v[32:35], v[92:95], v[12:15]
	v_mfma_f32_16x16x32_bf16 v[12:15], v[20:23], v[96:99], 0
	v_mfma_f32_16x16x32_bf16 v[182:185], v[24:27], v[110:113], v[12:15]
	v_mfma_f32_16x16x32_bf16 v[12:15], v[28:31], v[96:99], 0
	v_mfma_f32_16x16x32_bf16 v[186:189], v[32:35], v[110:113], v[12:15]
	v_mfma_f32_16x16x32_bf16 v[12:15], v[20:23], v[114:117], 0
	v_mfma_f32_16x16x32_bf16 v[190:193], v[24:27], v[122:125], v[12:15]
	v_mfma_f32_16x16x32_bf16 v[12:15], v[28:31], v[114:117], 0
	v_mfma_f32_16x16x32_bf16 v[194:197], v[32:35], v[122:125], v[12:15]
	v_mfma_f32_16x16x32_bf16 v[12:15], v[20:23], v[126:129], 0
	v_mfma_f32_16x16x32_bf16 v[198:201], v[24:27], v[130:133], v[12:15]
	v_mfma_f32_16x16x32_bf16 v[12:15], v[28:31], v[126:129], 0
	v_mfma_f32_16x16x32_bf16 v[202:205], v[32:35], v[130:133], v[12:15]
	s_barrier
; #define PG8_KSETUP() const bool last = (t == nt - 2); const char* a1 = cA + (size_t)(t + 1) * kstep; \
;             const char* a2 = last ? nA : cA + (size_t)(t + 2) * kstep; const char* b2 = last ? nB : cB + (size_t)(t + 2) * kstep; const char* a3 = a2 + kstep; const char* b3 = b2 + kstep; \
;             if (last && has_next) S.a_ready(nxt)
; template <class Epi, class Sched, bool ALIGN_EPI = false, bool SP2 = false>
; __device__ __forceinline__ void gemm_phase(PG8_LAS unsigned char* lds, const Gemm g, const Sched& S, const Epi& E) {
;     ...
;         int t0 = 0;
;         if constexpr (SP2 && Epi::NVM == 16) { if (ui > 0) { const int t = 0; PG8_KSETUP(); PG8_KITER_SP2(24, 24); t0 = 2; } }
	s_setprio 0
	s_nop 4
	ds_read_b128 v[12:15], v155
	ds_read_b128 v[16:19], v155 offset:1024
	ds_read_b128 v[22:25], v155 offset:2048
	ds_read_b128 v[26:29], v155 offset:3072
	ds_read_b128 v[206:209], v156
	ds_read_b128 v[210:213], v156 offset:1024
	ds_read_b128 v[214:217], v156 offset:2048
	ds_read_b128 v[218:221], v156 offset:3072
	ds_read_b128 v[30:33], v154 offset:32768
	ds_read_b128 v[64:67], v154 offset:33792
	ds_read_b128 v[222:225], v154 offset:34816
	ds_read_b128 v[226:229], v154 offset:35840
	ds_read_b128 v[230:233], v154 offset:36864
	ds_read_b128 v[234:237], v154 offset:37888
	ds_read_b128 v[238:241], v154 offset:38912
	ds_read_b128 v[242:245], v154 offset:39936
	s_add_u32 s24, s36, 0x80100
	s_addc_u32 s25, s37, 0
	s_mov_b32 m0, s54
	s_nop 0
	global_load_lds_dwordx4 v1, s[24:25] offset:0
	s_nop 0
	s_mov_b32 m0, s55
	s_nop 0
	global_load_lds_dwordx4 v147, s[24:25] offset:0
	s_waitcnt vmcnt(8)
	s_waitcnt lgkmcnt(0)
	s_barrier
	s_setprio 1
	v_mfma_f32_16x16x32_bf16 v[68:71], v[12:15], v[30:33], v[68:71]
	v_mfma_f32_16x16x32_bf16 v[130:133], v[16:19], v[64:67], v[68:71]
	v_mfma_f32_16x16x32_bf16 v[68:71], v[22:25], v[30:33], v[72:75]
	v_mfma_f32_16x16x32_bf16 v[126:129], v[26:29], v[64:67], v[68:71]
	v_mfma_f32_16x16x32_bf16 v[68:71], v[12:15], v[222:225], v[76:79]
	v_mfma_f32_16x16x32_bf16 v[114:117], v[16:19], v[226:229], v[68:71]
	v_mfma_f32_16x16x32_bf16 v[68:71], v[22:25], v[222:225], v[80:83]
	v_mfma_f32_16x16x32_bf16 v[110:113], v[26:29], v[226:229], v[68:71]
	v_mfma_f32_16x16x32_bf16 v[68:71], v[12:15], v[230:233], v[84:87]
	v_mfma_f32_16x16x32_bf16 v[98:101], v[16:19], v[234:237], v[68:71]
	v_mfma_f32_16x16x32_bf16 v[68:71], v[22:25], v[230:233], v[88:91]
	v_mfma_f32_16x16x32_bf16 v[94:97], v[26:29], v[234:237], v[68:71]
	v_mfma_f32_16x16x32_bf16 v[68:71], v[12:15], v[238:241], v[102:105]
	v_mfma_f32_16x16x32_bf16 v[82:85], v[16:19], v[242:245], v[68:71]
	v_mfma_f32_16x16x32_bf16 v[68:71], v[22:25], v[238:241], v[106:109]
	v_mfma_f32_16x16x32_bf16 v[78:81], v[26:29], v[242:245], v[68:71]
	s_setprio 0
	s_setprio 1
	v_mfma_f32_16x16x32_bf16 v[68:71], v[206:209], v[30:33], v[118:121]
	v_mfma_f32_16x16x32_bf16 v[30:33], v[214:217], v[30:33], v[36:39]
	v_mfma_f32_16x16x32_bf16 v[118:121], v[218:221], v[64:67], v[30:33]
	v_mfma_f32_16x16x32_bf16 v[30:33], v[206:209], v[222:225], v[40:43]
	v_mfma_f32_16x16x32_bf16 v[106:109], v[210:213], v[226:229], v[30:33]
	v_mfma_f32_16x16x32_bf16 v[30:33], v[214:217], v[222:225], v[44:47]
	v_mfma_f32_16x16x32_bf16 v[102:105], v[218:221], v[226:229], v[30:33]
	v_mfma_f32_16x16x32_bf16 v[30:33], v[206:209], v[230:233], v[48:51]
	v_mfma_f32_16x16x32_bf16 v[90:93], v[210:213], v[234:237], v[30:33]
	v_mfma_f32_16x16x32_bf16 v[30:33], v[214:217], v[230:233], v[52:55]
	v_mfma_f32_16x16x32_bf16 v[86:89], v[218:221], v[234:237], v[30:33]
	v_mfma_f32_16x16x32_bf16 v[30:33], v[206:209], v[238:241], v[56:59]
	v_mfma_f32_16x16x32_bf16 v[74:77], v[210:213], v[242:245], v[30:33]
	v_mfma_f32_16x16x32_bf16 v[30:33], v[214:217], v[238:241], v[60:63]
	v_mfma_f32_16x16x32_bf16 v[122:125], v[210:213], v[64:67], v[68:71]
	v_mfma_f32_16x16x32_bf16 v[66:69], v[218:221], v[242:245], v[30:33]
	s_barrier
	s_setprio 0
	ds_read_b128 v[38:41], v154 offset:49152
	ds_read_b128 v[42:45], v154 offset:50176
	ds_read_b128 v[222:225], v154 offset:51200
	ds_read_b128 v[226:229], v154 offset:52224
	ds_read_b128 v[230:233], v154 offset:53248
	ds_read_b128 v[234:237], v154 offset:54272
	ds_read_b128 v[238:241], v154 offset:55296
	ds_read_b128 v[242:245], v154 offset:56320
	s_add_u32 s24, s38, 0x180
	s_addc_u32 s25, s39, 0
	s_mov_b32 m0, s56
	s_nop 0
	global_load_lds_dwordx4 v146, s[24:25] offset:0
	s_nop 0
	s_mov_b32 m0, s57
	s_nop 0
	global_load_lds_dwordx4 v148, s[24:25] offset:0
	s_add_u32 s24, s38, 0x80180
	s_addc_u32 s25, s39, 0
	s_mov_b32 m0, s64
	s_nop 0
	global_load_lds_dwordx4 v146, s[24:25] offset:0
	s_nop 0
	s_mov_b32 m0, s65
	s_nop 0
	global_load_lds_dwordx4 v148, s[24:25] offset:0
	s_nop 0
	s_mov_b32 m0, s58
	s_nop 0
	global_load_lds_dwordx4 v1, s[22:23] offset:0
	s_nop 0
	s_mov_b32 m0, s59
	s_nop 0
	global_load_lds_dwordx4 v147, s[22:23] offset:0
	s_waitcnt vmcnt(8)
	s_waitcnt lgkmcnt(0)
	s_barrier
	s_setprio 1
	v_mfma_f32_16x16x32_bf16 v[30:33], v[12:15], v[38:41], v[138:141]
	v_mfma_f32_16x16x32_bf16 v[70:73], v[16:19], v[42:45], v[30:33]
	v_mfma_f32_16x16x32_bf16 v[30:33], v[22:25], v[38:41], v[142:145]
	v_mfma_f32_16x16x32_bf16 v[62:65], v[26:29], v[42:45], v[30:33]
	v_mfma_f32_16x16x32_bf16 v[30:33], v[12:15], v[222:225], v[158:161]
	v_mfma_f32_16x16x32_bf16 v[50:53], v[16:19], v[226:229], v[30:33]
	v_mfma_f32_16x16x32_bf16 v[30:33], v[22:25], v[222:225], v[162:165]
	v_mfma_f32_16x16x32_bf16 v[46:49], v[26:29], v[226:229], v[30:33]
	v_mfma_f32_16x16x32_bf16 v[30:33], v[12:15], v[230:233], v[166:169]
	v_mfma_f32_16x16x32_bf16 v[4:7], v[12:15], v[238:241], v[4:7]
	v_mfma_f32_16x16x32_bf16 v[34:37], v[16:19], v[234:237], v[30:33]
	v_mfma_f32_16x16x32_bf16 v[30:33], v[22:25], v[230:233], v[170:173]
	v_mfma_f32_16x16x32_bf16 v[18:21], v[16:19], v[242:245], v[4:7]
	v_mfma_f32_16x16x32_bf16 v[4:7], v[22:25], v[238:241], v[8:11]
	v_mfma_f32_16x16x32_bf16 v[30:33], v[26:29], v[234:237], v[30:33]
	v_mfma_f32_16x16x32_bf16 v[14:17], v[26:29], v[242:245], v[4:7]
	s_setprio 0
	s_setprio 1
	v_mfma_f32_16x16x32_bf16 v[4:7], v[206:209], v[38:41], v[174:177]
	v_mfma_f32_16x16x32_bf16 v[58:61], v[210:213], v[42:45], v[4:7]
	v_mfma_f32_16x16x32_bf16 v[4:7], v[214:217], v[38:41], v[178:181]
	v_mfma_f32_16x16x32_bf16 v[54:57], v[218:221], v[42:45], v[4:7]
	v_mfma_f32_16x16x32_bf16 v[4:7], v[206:209], v[222:225], v[182:185]
	v_mfma_f32_16x16x32_bf16 v[42:45], v[210:213], v[226:229], v[4:7]
	v_mfma_f32_16x16x32_bf16 v[4:7], v[214:217], v[222:225], v[186:189]
	v_mfma_f32_16x16x32_bf16 v[38:41], v[218:221], v[226:229], v[4:7]
	v_mfma_f32_16x16x32_bf16 v[4:7], v[206:209], v[230:233], v[190:193]
	v_mfma_f32_16x16x32_bf16 v[26:29], v[210:213], v[234:237], v[4:7]
	v_mfma_f32_16x16x32_bf16 v[4:7], v[214:217], v[230:233], v[194:197]
	v_mfma_f32_16x16x32_bf16 v[22:25], v[218:221], v[234:237], v[4:7]
	v_mfma_f32_16x16x32_bf16 v[4:7], v[206:209], v[238:241], v[198:201]
	v_mfma_f32_16x16x32_bf16 v[10:13], v[210:213], v[242:245], v[4:7]
	v_mfma_f32_16x16x32_bf16 v[4:7], v[214:217], v[238:241], v[202:205]
	v_mfma_f32_16x16x32_bf16 v[6:9], v[218:221], v[242:245], v[4:7]
	s_barrier
	s_setprio 0
	s_mov_b32 s40, 2
	s_branch .LBB0_2290

; #define PG8_KSETUP() const bool last = (t == nt - 2); const char* a1 = cA + (size_t)(t + 1) * kstep; \
;             const char* a2 = last ? nA : cA + (size_t)(t + 2) * kstep; const char* b2 = last ? nB : cB + (size_t)(t + 2) * kstep; const char* a3 = a2 + kstep; const char* b3 = b2 + kstep; \
;             if (last && has_next) S.a_ready(nxt)
; template <class Epi, class Sched, bool ALIGN_EPI = false, bool SP2 = false>
; __device__ __forceinline__ void gemm_phase(PG8_LAS unsigned char* lds, const Gemm g, const Sched& S, const Epi& E) {
;     ...
;         int t0 = 0;
;         if constexpr (SP2 && Epi::NVM == 16) { if (ui > 0) { const int t = 0; PG8_KSETUP(); PG8_KITER_SP2(24, 24); t0 = 2; } }
;         if constexpr (SP2 && Epi::NVM == 8) { if (ui > 0) { const int t = 0; PG8_KSETUP(); PG8_KITER_SP2(16, 16); t0 = 2; } }
;         for (int t = t0; t < nt; t += 2) {
;             PG8_KSETUP();
;             if constexpr (SP2) {
;             PG8_KITER_SP2(8, 8);
.LBB0_2291:
	ds_read_b128 v[138:141], v152
	ds_read_b128 v[142:145], v152 offset:1024
	ds_read_b128 v[158:161], v152 offset:2048
	ds_read_b128 v[162:165], v152 offset:3072
	ds_read_b128 v[166:169], v153
	ds_read_b128 v[170:173], v153 offset:1024
	ds_read_b128 v[174:177], v153 offset:2048
	ds_read_b128 v[178:181], v153 offset:3072
	s_cmp_eq_u32 s78, 28
	s_cselect_b32 s40, s76, s81
	s_cselect_b32 s41, s19, s82
	s_cselect_b32 s38, s77, s79
	s_cselect_b32 s39, s17, s80
	s_add_u32 s36, s40, 0x80
	s_addc_u32 s37, s41, 0
	ds_read_b128 v[182:185], v154
	ds_read_b128 v[186:189], v154 offset:1024
	ds_read_b128 v[190:193], v154 offset:2048
	ds_read_b128 v[194:197], v154 offset:3072
	ds_read_b128 v[198:201], v154 offset:4096
	ds_read_b128 v[202:205], v154 offset:5120
	ds_read_b128 v[206:209], v154 offset:6144
	ds_read_b128 v[210:213], v154 offset:7168
	s_add_u32 s30, s81, 0x7ff80
	s_addc_u32 s31, s82, 0
	s_mov_b32 m0, s66
	s_nop 0
	global_load_lds_dwordx4 v1, s[30:31] offset:0
	s_nop 0
	s_mov_b32 m0, s67
	s_nop 0
	global_load_lds_dwordx4 v147, s[30:31] offset:0
	s_waitcnt vmcnt(8)
	s_waitcnt lgkmcnt(0)
	s_barrier
	s_setprio 1
	v_mfma_f32_16x16x32_bf16 v[130:133], v[138:141], v[182:185], v[130:133]
	v_mfma_f32_16x16x32_bf16 v[130:133], v[142:145], v[186:189], v[130:133]
	v_mfma_f32_16x16x32_bf16 v[126:129], v[158:161], v[182:185], v[126:129]
	v_mfma_f32_16x16x32_bf16 v[126:129], v[162:165], v[186:189], v[126:129]
	v_mfma_f32_16x16x32_bf16 v[114:117], v[138:141], v[190:193], v[114:117]
	v_mfma_f32_16x16x32_bf16 v[114:117], v[142:145], v[194:197], v[114:117]
	v_mfma_f32_16x16x32_bf16 v[110:113], v[158:161], v[190:193], v[110:113]
	v_mfma_f32_16x16x32_bf16 v[110:113], v[162:165], v[194:197], v[110:113]
	v_mfma_f32_16x16x32_bf16 v[98:101], v[138:141], v[198:201], v[98:101]
	v_mfma_f32_16x16x32_bf16 v[98:101], v[142:145], v[202:205], v[98:101]
	v_mfma_f32_16x16x32_bf16 v[94:97], v[158:161], v[198:201], v[94:97]
	v_mfma_f32_16x16x32_bf16 v[94:97], v[162:165], v[202:205], v[94:97]
	v_mfma_f32_16x16x32_bf16 v[82:85], v[138:141], v[206:209], v[82:85]
	v_mfma_f32_16x16x32_bf16 v[82:85], v[142:145], v[210:213], v[82:85]
	v_mfma_f32_16x16x32_bf16 v[78:81], v[158:161], v[206:209], v[78:81]
	v_mfma_f32_16x16x32_bf16 v[78:81], v[162:165], v[210:213], v[78:81]
	s_setprio 0
	s_setprio 1
	v_mfma_f32_16x16x32_bf16 v[122:125], v[166:169], v[182:185], v[122:125]
	v_mfma_f32_16x16x32_bf16 v[122:125], v[170:173], v[186:189], v[122:125]
	v_mfma_f32_16x16x32_bf16 v[118:121], v[174:177], v[182:185], v[118:121]
	v_mfma_f32_16x16x32_bf16 v[118:121], v[178:181], v[186:189], v[118:121]
	v_mfma_f32_16x16x32_bf16 v[106:109], v[166:169], v[190:193], v[106:109]
	v_mfma_f32_16x16x32_bf16 v[106:109], v[170:173], v[194:197], v[106:109]
	v_mfma_f32_16x16x32_bf16 v[102:105], v[174:177], v[190:193], v[102:105]
	v_mfma_f32_16x16x32_bf16 v[102:105], v[178:181], v[194:197], v[102:105]
	v_mfma_f32_16x16x32_bf16 v[90:93], v[166:169], v[198:201], v[90:93]
	v_mfma_f32_16x16x32_bf16 v[90:93], v[170:173], v[202:205], v[90:93]
	v_mfma_f32_16x16x32_bf16 v[86:89], v[174:177], v[198:201], v[86:89]
	v_mfma_f32_16x16x32_bf16 v[86:89], v[178:181], v[202:205], v[86:89]
	v_mfma_f32_16x16x32_bf16 v[74:77], v[166:169], v[206:209], v[74:77]
	v_mfma_f32_16x16x32_bf16 v[74:77], v[170:173], v[210:213], v[74:77]
	v_mfma_f32_16x16x32_bf16 v[66:69], v[174:177], v[206:209], v[66:69]
	v_mfma_f32_16x16x32_bf16 v[66:69], v[178:181], v[210:213], v[66:69]
	s_barrier
	s_setprio 0
	ds_read_b128 v[182:185], v154 offset:16384
	ds_read_b128 v[186:189], v154 offset:17408
	ds_read_b128 v[190:193], v154 offset:18432
	ds_read_b128 v[194:197], v154 offset:19456
	ds_read_b128 v[198:201], v154 offset:20480
	ds_read_b128 v[202:205], v154 offset:21504
	ds_read_b128 v[206:209], v154 offset:22528
	ds_read_b128 v[210:213], v154 offset:23552
	s_mov_b32 m0, s29
	s_nop 0
	global_load_lds_dwordx4 v146, s[38:39] offset:0
	s_add_u32 s30, s38, 0x80000
	s_mov_b32 m0, s46
	s_nop 0
	global_load_lds_dwordx4 v148, s[38:39] offset:0
	s_addc_u32 s31, s39, 0
	s_mov_b32 m0, s47
	s_nop 0
	global_load_lds_dwordx4 v146, s[30:31] offset:0
	s_nop 0
	s_mov_b32 m0, s52
	s_nop 0
	global_load_lds_dwordx4 v148, s[30:31] offset:0
	s_nop 0
	s_mov_b32 m0, s21
	s_nop 0
	global_load_lds_dwordx4 v1, s[40:41] offset:0
	s_nop 0
	s_mov_b32 m0, s53
	s_nop 0
	global_load_lds_dwordx4 v147, s[40:41] offset:0
	s_waitcnt vmcnt(8)
	s_waitcnt lgkmcnt(0)
	s_barrier
	s_setprio 1
	v_mfma_f32_16x16x32_bf16 v[70:73], v[138:141], v[182:185], v[70:73]
	v_mfma_f32_16x16x32_bf16 v[70:73], v[142:145], v[186:189], v[70:73]
	v_mfma_f32_16x16x32_bf16 v[62:65], v[158:161], v[182:185], v[62:65]
	v_mfma_f32_16x16x32_bf16 v[62:65], v[162:165], v[186:189], v[62:65]
	v_mfma_f32_16x16x32_bf16 v[50:53], v[138:141], v[190:193], v[50:53]
	v_mfma_f32_16x16x32_bf16 v[50:53], v[142:145], v[194:197], v[50:53]
	v_mfma_f32_16x16x32_bf16 v[46:49], v[158:161], v[190:193], v[46:49]
	v_mfma_f32_16x16x32_bf16 v[46:49], v[162:165], v[194:197], v[46:49]
	v_mfma_f32_16x16x32_bf16 v[34:37], v[138:141], v[198:201], v[34:37]
	v_mfma_f32_16x16x32_bf16 v[34:37], v[142:145], v[202:205], v[34:37]
	v_mfma_f32_16x16x32_bf16 v[30:33], v[158:161], v[198:201], v[30:33]
	v_mfma_f32_16x16x32_bf16 v[30:33], v[162:165], v[202:205], v[30:33]
	v_mfma_f32_16x16x32_bf16 v[18:21], v[138:141], v[206:209], v[18:21]
	v_mfma_f32_16x16x32_bf16 v[18:21], v[142:145], v[210:213], v[18:21]
	v_mfma_f32_16x16x32_bf16 v[14:17], v[158:161], v[206:209], v[14:17]
	v_mfma_f32_16x16x32_bf16 v[14:17], v[162:165], v[210:213], v[14:17]
	s_setprio 0
	s_setprio 1
	v_mfma_f32_16x16x32_bf16 v[58:61], v[166:169], v[182:185], v[58:61]
	v_mfma_f32_16x16x32_bf16 v[54:57], v[174:177], v[182:185], v[54:57]
	v_mfma_f32_16x16x32_bf16 v[42:45], v[166:169], v[190:193], v[42:45]
	v_mfma_f32_16x16x32_bf16 v[38:41], v[174:177], v[190:193], v[38:41]
	v_mfma_f32_16x16x32_bf16 v[26:29], v[166:169], v[198:201], v[26:29]
	v_mfma_f32_16x16x32_bf16 v[22:25], v[174:177], v[198:201], v[22:25]
	v_mfma_f32_16x16x32_bf16 v[10:13], v[166:169], v[206:209], v[10:13]
	v_mfma_f32_16x16x32_bf16 v[4:7], v[174:177], v[206:209], v[6:9]
	v_mfma_f32_16x16x32_bf16 v[58:61], v[170:173], v[186:189], v[58:61]
	v_mfma_f32_16x16x32_bf16 v[54:57], v[178:181], v[186:189], v[54:57]
	v_mfma_f32_16x16x32_bf16 v[42:45], v[170:173], v[194:197], v[42:45]
	v_mfma_f32_16x16x32_bf16 v[38:41], v[178:181], v[194:197], v[38:41]
	v_mfma_f32_16x16x32_bf16 v[26:29], v[170:173], v[202:205], v[26:29]
	v_mfma_f32_16x16x32_bf16 v[22:25], v[178:181], v[202:205], v[22:25]
	v_mfma_f32_16x16x32_bf16 v[10:13], v[170:173], v[210:213], v[10:13]
	v_mfma_f32_16x16x32_bf16 v[4:7], v[178:181], v[210:213], v[4:7]
	s_barrier
; #define PG8_KSETUP() const bool last = (t == nt - 2); const char* a1 = cA + (size_t)(t + 1) * kstep; \
;             const char* a2 = last ? nA : cA + (size_t)(t + 2) * kstep; const char* b2 = last ? nB : cB + (size_t)(t + 2) * kstep; const char* a3 = a2 + kstep; const char* b3 = b2 + kstep; \
;             if (last && has_next) S.a_ready(nxt)
; template <class Epi, class Sched, bool ALIGN_EPI = false, bool SP2 = false>
; __device__ __forceinline__ void gemm_phase(PG8_LAS unsigned char* lds, const Gemm g, const Sched& S, const Epi& E) {
;     ...
;         int t0 = 0;
;         if constexpr (SP2 && Epi::NVM == 16) { if (ui > 0) { const int t = 0; PG8_KSETUP(); PG8_KITER_SP2(24, 24); t0 = 2; } }
;         if constexpr (SP2 && Epi::NVM == 8) { if (ui > 0) { const int t = 0; PG8_KSETUP(); PG8_KITER_SP2(16, 16); t0 = 2; } }
;         for (int t = t0; t < nt; t += 2) {
;             PG8_KSETUP();
;             if constexpr (SP2) {
;             PG8_KITER_SP2(8, 8);
	s_setprio 0
	ds_read_b128 v[138:141], v155
	ds_read_b128 v[142:145], v155 offset:1024
	ds_read_b128 v[158:161], v155 offset:2048
	ds_read_b128 v[162:165], v155 offset:3072
	ds_read_b128 v[166:169], v156
	ds_read_b128 v[170:173], v156 offset:1024
	ds_read_b128 v[174:177], v156 offset:2048
	ds_read_b128 v[178:181], v156 offset:3072
	ds_read_b128 v[182:185], v154 offset:32768
	ds_read_b128 v[186:189], v154 offset:33792
	ds_read_b128 v[190:193], v154 offset:34816
	ds_read_b128 v[194:197], v154 offset:35840
	ds_read_b128 v[198:201], v154 offset:36864
	ds_read_b128 v[202:205], v154 offset:37888
	ds_read_b128 v[206:209], v154 offset:38912
	ds_read_b128 v[210:213], v154 offset:39936
	s_add_u32 s30, s40, 0x80000
	s_addc_u32 s31, s41, 0
	s_mov_b32 m0, s54
	s_nop 0
	global_load_lds_dwordx4 v1, s[30:31] offset:0
	s_nop 0
	s_mov_b32 m0, s55
	s_nop 0
	global_load_lds_dwordx4 v147, s[30:31] offset:0
	s_waitcnt vmcnt(8)
	s_waitcnt lgkmcnt(0)
	s_barrier
	s_setprio 1
	v_mfma_f32_16x16x32_bf16 v[130:133], v[138:141], v[182:185], v[130:133]
	v_mfma_f32_16x16x32_bf16 v[130:133], v[142:145], v[186:189], v[130:133]
	v_mfma_f32_16x16x32_bf16 v[126:129], v[158:161], v[182:185], v[126:129]
	v_mfma_f32_16x16x32_bf16 v[126:129], v[162:165], v[186:189], v[126:129]
	v_mfma_f32_16x16x32_bf16 v[114:117], v[138:141], v[190:193], v[114:117]
	v_mfma_f32_16x16x32_bf16 v[114:117], v[142:145], v[194:197], v[114:117]
	v_mfma_f32_16x16x32_bf16 v[110:113], v[158:161], v[190:193], v[110:113]
	v_mfma_f32_16x16x32_bf16 v[110:113], v[162:165], v[194:197], v[110:113]
	v_mfma_f32_16x16x32_bf16 v[98:101], v[138:141], v[198:201], v[98:101]
	v_mfma_f32_16x16x32_bf16 v[98:101], v[142:145], v[202:205], v[98:101]
	v_mfma_f32_16x16x32_bf16 v[94:97], v[158:161], v[198:201], v[94:97]
	v_mfma_f32_16x16x32_bf16 v[94:97], v[162:165], v[202:205], v[94:97]
	v_mfma_f32_16x16x32_bf16 v[82:85], v[138:141], v[206:209], v[82:85]
	v_mfma_f32_16x16x32_bf16 v[82:85], v[142:145], v[210:213], v[82:85]
	v_mfma_f32_16x16x32_bf16 v[78:81], v[158:161], v[206:209], v[78:81]
	v_mfma_f32_16x16x32_bf16 v[78:81], v[162:165], v[210:213], v[78:81]
	s_setprio 0
	s_setprio 1
	v_mfma_f32_16x16x32_bf16 v[122:125], v[166:169], v[182:185], v[122:125]
	v_mfma_f32_16x16x32_bf16 v[122:125], v[170:173], v[186:189], v[122:125]
	v_mfma_f32_16x16x32_bf16 v[118:121], v[174:177], v[182:185], v[118:121]
	v_mfma_f32_16x16x32_bf16 v[118:121], v[178:181], v[186:189], v[118:121]
	v_mfma_f32_16x16x32_bf16 v[106:109], v[166:169], v[190:193], v[106:109]
	v_mfma_f32_16x16x32_bf16 v[106:109], v[170:173], v[194:197], v[106:109]
	v_mfma_f32_16x16x32_bf16 v[102:105], v[174:177], v[190:193], v[102:105]
	v_mfma_f32_16x16x32_bf16 v[102:105], v[178:181], v[194:197], v[102:105]
	v_mfma_f32_16x16x32_bf16 v[90:93], v[166:169], v[198:201], v[90:93]
	v_mfma_f32_16x16x32_bf16 v[90:93], v[170:173], v[202:205], v[90:93]
	v_mfma_f32_16x16x32_bf16 v[86:89], v[174:177], v[198:201], v[86:89]
	v_mfma_f32_16x16x32_bf16 v[86:89], v[178:181], v[202:205], v[86:89]
	v_mfma_f32_16x16x32_bf16 v[74:77], v[166:169], v[206:209], v[74:77]
	v_mfma_f32_16x16x32_bf16 v[74:77], v[170:173], v[210:213], v[74:77]
	v_mfma_f32_16x16x32_bf16 v[66:69], v[174:177], v[206:209], v[66:69]
	v_mfma_f32_16x16x32_bf16 v[66:69], v[178:181], v[210:213], v[66:69]
	s_barrier
	s_setprio 0
	ds_read_b128 v[182:185], v154 offset:49152
	ds_read_b128 v[186:189], v154 offset:50176
	ds_read_b128 v[190:193], v154 offset:51200
	ds_read_b128 v[194:197], v154 offset:52224
	ds_read_b128 v[198:201], v154 offset:53248
	ds_read_b128 v[202:205], v154 offset:54272
	ds_read_b128 v[206:209], v154 offset:55296
	ds_read_b128 v[210:213], v154 offset:56320
	s_add_u32 s30, s38, 0x80
	s_addc_u32 s31, s39, 0
	s_mov_b32 m0, s56
	s_nop 0
	global_load_lds_dwordx4 v146, s[30:31] offset:0
	s_nop 0
	s_mov_b32 m0, s57
	s_nop 0
	global_load_lds_dwordx4 v148, s[30:31] offset:0
	s_add_u32 s30, s38, 0x80080
	s_addc_u32 s31, s39, 0
	s_mov_b32 m0, s64
	s_nop 0
	global_load_lds_dwordx4 v146, s[30:31] offset:0
	s_nop 0
	s_mov_b32 m0, s65
	s_nop 0
	global_load_lds_dwordx4 v148, s[30:31] offset:0
	s_nop 0
	s_mov_b32 m0, s58
	s_nop 0
	global_load_lds_dwordx4 v1, s[36:37] offset:0
	s_nop 0
	s_mov_b32 m0, s59
	s_nop 0
	global_load_lds_dwordx4 v147, s[36:37] offset:0
	s_waitcnt vmcnt(8)
	s_waitcnt lgkmcnt(0)
	s_barrier
	s_setprio 1
	v_mfma_f32_16x16x32_bf16 v[70:73], v[138:141], v[182:185], v[70:73]
	v_mfma_f32_16x16x32_bf16 v[70:73], v[142:145], v[186:189], v[70:73]
	v_mfma_f32_16x16x32_bf16 v[62:65], v[158:161], v[182:185], v[62:65]
	v_mfma_f32_16x16x32_bf16 v[62:65], v[162:165], v[186:189], v[62:65]
	v_mfma_f32_16x16x32_bf16 v[50:53], v[138:141], v[190:193], v[50:53]
	v_mfma_f32_16x16x32_bf16 v[50:53], v[142:145], v[194:197], v[50:53]
	v_mfma_f32_16x16x32_bf16 v[46:49], v[158:161], v[190:193], v[46:49]
	v_mfma_f32_16x16x32_bf16 v[46:49], v[162:165], v[194:197], v[46:49]
	v_mfma_f32_16x16x32_bf16 v[34:37], v[138:141], v[198:201], v[34:37]
	v_mfma_f32_16x16x32_bf16 v[34:37], v[142:145], v[202:205], v[34:37]
	v_mfma_f32_16x16x32_bf16 v[30:33], v[158:161], v[198:201], v[30:33]
	v_mfma_f32_16x16x32_bf16 v[30:33], v[162:165], v[202:205], v[30:33]
	v_mfma_f32_16x16x32_bf16 v[18:21], v[138:141], v[206:209], v[18:21]
	v_mfma_f32_16x16x32_bf16 v[18:21], v[142:145], v[210:213], v[18:21]
	v_mfma_f32_16x16x32_bf16 v[14:17], v[158:161], v[206:209], v[14:17]
	v_mfma_f32_16x16x32_bf16 v[14:17], v[162:165], v[210:213], v[14:17]
	s_setprio 0
	s_setprio 1
	v_mfma_f32_16x16x32_bf16 v[58:61], v[166:169], v[182:185], v[58:61]
	v_mfma_f32_16x16x32_bf16 v[54:57], v[174:177], v[182:185], v[54:57]
	v_mfma_f32_16x16x32_bf16 v[42:45], v[166:169], v[190:193], v[42:45]
	v_mfma_f32_16x16x32_bf16 v[38:41], v[174:177], v[190:193], v[38:41]
	v_mfma_f32_16x16x32_bf16 v[26:29], v[166:169], v[198:201], v[26:29]
	v_mfma_f32_16x16x32_bf16 v[22:25], v[174:177], v[198:201], v[22:25]
	v_mfma_f32_16x16x32_bf16 v[8:11], v[166:169], v[206:209], v[10:13]
	v_mfma_f32_16x16x32_bf16 v[4:7], v[174:177], v[206:209], v[4:7]
	v_mfma_f32_16x16x32_bf16 v[58:61], v[170:173], v[186:189], v[58:61]
	v_mfma_f32_16x16x32_bf16 v[54:57], v[178:181], v[186:189], v[54:57]
	v_mfma_f32_16x16x32_bf16 v[42:45], v[170:173], v[194:197], v[42:45]
	v_mfma_f32_16x16x32_bf16 v[38:41], v[178:181], v[194:197], v[38:41]
	v_mfma_f32_16x16x32_bf16 v[26:29], v[170:173], v[202:205], v[26:29]
	v_mfma_f32_16x16x32_bf16 v[22:25], v[178:181], v[202:205], v[22:25]
	v_mfma_f32_16x16x32_bf16 v[10:13], v[170:173], v[210:213], v[8:11]
	v_mfma_f32_16x16x32_bf16 v[6:9], v[178:181], v[210:213], v[4:7]
	s_barrier
	s_setprio 0
	s_add_i32 s78, s78, 2
	s_add_u32 s79, s79, 0x100
	s_addc_u32 s80, s80, 0
	s_add_u32 s81, s81, 0x100
	s_addc_u32 s82, s82, 0
	s_cmp_gt_u32 s78, 29
	s_cbranch_scc0 .LBB0_2291
	s_and_b64 vcc, exec, s[14:15]
	s_cbranch_vccz .LBB0_2294
	s_barrier

; #define PG8_KSETUP() const bool last = (t == nt - 2); const char* a1 = cA + (size_t)(t + 1) * kstep; \
;             const char* a2 = last ? nA : cA + (size_t)(t + 2) * kstep; const char* b2 = last ? nB : cB + (size_t)(t + 2) * kstep; const char* a3 = a2 + kstep; const char* b3 = b2 + kstep; \
;             if (last && has_next) S.a_ready(nxt)
; template <class Epi, class Sched, bool ALIGN_EPI = false, bool SP2 = false>
; __device__ __forceinline__ void gemm_phase(PG8_LAS unsigned char* lds, const Gemm g, const Sched& S, const Epi& E) {
;     ...
;         int t0 = 0;
;         if constexpr (SP2 && Epi::NVM == 16) { if (ui > 0) { const int t = 0; PG8_KSETUP(); PG8_KITER_SP2(24, 24); t0 = 2; } }
.LBB0_2373:
	ds_read_b128 v[4:7], v147
	ds_read_b128 v[8:11], v147 offset:1024
	ds_read_b128 v[12:15], v147 offset:2048
	ds_read_b128 v[16:19], v147 offset:3072
	ds_read_b128 v[20:23], v148
	ds_read_b128 v[24:27], v148 offset:1024
	ds_read_b128 v[28:31], v148 offset:2048
	ds_read_b128 v[32:35], v148 offset:3072
	s_add_u32 s44, s36, 0x100
	s_addc_u32 s45, s37, 0
	s_add_u32 s30, s38, 0x100
	s_addc_u32 s31, s39, 0
	s_add_u32 s40, s36, 0x180
	s_addc_u32 s41, s37, 0
	ds_read_b128 v[36:39], v149
	ds_read_b128 v[40:43], v149 offset:1024
	ds_read_b128 v[44:47], v149 offset:2048
	ds_read_b128 v[48:51], v149 offset:3072
	ds_read_b128 v[52:55], v149 offset:4096
	ds_read_b128 v[56:59], v149 offset:5120
	ds_read_b128 v[60:63], v149 offset:6144
	ds_read_b128 v[64:67], v149 offset:7168
	s_add_u32 s42, s36, 0x160080
	s_addc_u32 s43, s37, 0
	s_mov_b32 m0, s72
	s_nop 0
	global_load_lds_dwordx4 v1, s[42:43] offset:0
	s_nop 0
	s_mov_b32 m0, s73
	s_nop 0
	global_load_lds_dwordx4 v143, s[42:43] offset:0
	s_waitcnt vmcnt(24)
	s_waitcnt lgkmcnt(0)
	s_barrier
	s_setprio 1
	v_mfma_f32_16x16x32_bf16 v[92:95], v[4:7], v[60:63], 0
	v_mfma_f32_16x16x32_bf16 v[68:71], v[4:7], v[36:39], 0
	v_mfma_f32_16x16x32_bf16 v[72:75], v[12:15], v[36:39], 0
	v_mfma_f32_16x16x32_bf16 v[76:79], v[4:7], v[44:47], 0
	v_mfma_f32_16x16x32_bf16 v[80:83], v[12:15], v[44:47], 0
	v_mfma_f32_16x16x32_bf16 v[84:87], v[4:7], v[52:55], 0
	v_mfma_f32_16x16x32_bf16 v[88:91], v[12:15], v[52:55], 0
	v_mfma_f32_16x16x32_bf16 v[102:105], v[8:11], v[64:67], v[92:95]
	v_mfma_f32_16x16x32_bf16 v[92:95], v[12:15], v[60:63], 0
	v_mfma_f32_16x16x32_bf16 v[68:71], v[8:11], v[40:43], v[68:71]
	v_mfma_f32_16x16x32_bf16 v[72:75], v[16:19], v[40:43], v[72:75]
	v_mfma_f32_16x16x32_bf16 v[76:79], v[8:11], v[48:51], v[76:79]
	v_mfma_f32_16x16x32_bf16 v[80:83], v[16:19], v[48:51], v[80:83]
	v_mfma_f32_16x16x32_bf16 v[84:87], v[8:11], v[56:59], v[84:87]
	v_mfma_f32_16x16x32_bf16 v[88:91], v[16:19], v[56:59], v[88:91]
	v_mfma_f32_16x16x32_bf16 v[106:109], v[16:19], v[64:67], v[92:95]
	s_setprio 0
	s_setprio 1
	v_mfma_f32_16x16x32_bf16 v[92:95], v[20:23], v[36:39], 0
	v_mfma_f32_16x16x32_bf16 v[36:39], v[28:31], v[36:39], 0
	v_mfma_f32_16x16x32_bf16 v[118:121], v[24:27], v[40:43], v[92:95]
	v_mfma_f32_16x16x32_bf16 v[36:39], v[32:35], v[40:43], v[36:39]
	v_mfma_f32_16x16x32_bf16 v[40:43], v[20:23], v[44:47], 0
	v_mfma_f32_16x16x32_bf16 v[44:47], v[28:31], v[44:47], 0
	v_mfma_f32_16x16x32_bf16 v[40:43], v[24:27], v[48:51], v[40:43]
	v_mfma_f32_16x16x32_bf16 v[44:47], v[32:35], v[48:51], v[44:47]
	v_mfma_f32_16x16x32_bf16 v[48:51], v[20:23], v[52:55], 0
	v_mfma_f32_16x16x32_bf16 v[52:55], v[28:31], v[52:55], 0
	v_mfma_f32_16x16x32_bf16 v[48:51], v[24:27], v[56:59], v[48:51]
	v_mfma_f32_16x16x32_bf16 v[52:55], v[32:35], v[56:59], v[52:55]
	v_mfma_f32_16x16x32_bf16 v[56:59], v[20:23], v[60:63], 0
	v_mfma_f32_16x16x32_bf16 v[60:63], v[28:31], v[60:63], 0
	v_mfma_f32_16x16x32_bf16 v[56:59], v[24:27], v[64:67], v[56:59]
	v_mfma_f32_16x16x32_bf16 v[60:63], v[32:35], v[64:67], v[60:63]
	s_barrier
	s_setprio 0
	ds_read_b128 v[64:67], v149 offset:16384
	ds_read_b128 v[92:95], v149 offset:17408
	ds_read_b128 v[96:99], v149 offset:18432
	ds_read_b128 v[110:113], v149 offset:19456
	ds_read_b128 v[114:117], v149 offset:20480
	ds_read_b128 v[122:125], v149 offset:21504
	ds_read_b128 v[126:129], v149 offset:22528
	ds_read_b128 v[130:133], v149 offset:23552
	s_mov_b32 m0, s52
	s_nop 0
	global_load_lds_dwordx4 v142, s[30:31] offset:0
	s_nop 0
	s_mov_b32 m0, s53
	s_nop 0
	global_load_lds_dwordx4 v144, s[30:31] offset:0
	s_add_u32 s30, s38, 0x160100
	s_addc_u32 s31, s39, 0
	s_mov_b32 m0, s54
	s_nop 0
	global_load_lds_dwordx4 v142, s[30:31] offset:0
	s_nop 0
	s_mov_b32 m0, s55
	s_nop 0
	global_load_lds_dwordx4 v144, s[30:31] offset:0
	s_nop 0
	s_mov_b32 m0, s47
	s_nop 0
	global_load_lds_dwordx4 v1, s[44:45] offset:0
	s_nop 0
	s_mov_b32 m0, s56
	s_nop 0
	global_load_lds_dwordx4 v143, s[44:45] offset:0
	s_waitcnt vmcnt(24)
	s_waitcnt lgkmcnt(0)
	s_barrier
	s_setprio 1
	v_mfma_f32_16x16x32_bf16 v[138:141], v[4:7], v[64:67], 0
	v_mfma_f32_16x16x32_bf16 v[156:159], v[4:7], v[96:99], 0
	v_mfma_f32_16x16x32_bf16 v[164:167], v[4:7], v[114:117], 0
	v_mfma_f32_16x16x32_bf16 v[4:7], v[4:7], v[126:129], 0
	v_mfma_f32_16x16x32_bf16 v[138:141], v[8:11], v[92:95], v[138:141]
	v_mfma_f32_16x16x32_bf16 v[156:159], v[8:11], v[110:113], v[156:159]
	v_mfma_f32_16x16x32_bf16 v[164:167], v[8:11], v[122:125], v[164:167]
	v_mfma_f32_16x16x32_bf16 v[4:7], v[8:11], v[130:133], v[4:7]
	v_mfma_f32_16x16x32_bf16 v[8:11], v[12:15], v[126:129], 0
	v_mfma_f32_16x16x32_bf16 v[152:155], v[12:15], v[64:67], 0
	v_mfma_f32_16x16x32_bf16 v[160:163], v[12:15], v[96:99], 0
	v_mfma_f32_16x16x32_bf16 v[168:171], v[12:15], v[114:117], 0
	v_mfma_f32_16x16x32_bf16 v[8:11], v[16:19], v[130:133], v[8:11]
	v_mfma_f32_16x16x32_bf16 v[152:155], v[16:19], v[92:95], v[152:155]
	v_mfma_f32_16x16x32_bf16 v[160:163], v[16:19], v[110:113], v[160:163]
	v_mfma_f32_16x16x32_bf16 v[168:171], v[16:19], v[122:125], v[168:171]
	s_setprio 0
	s_setprio 1
	v_mfma_f32_16x16x32_bf16 v[12:15], v[20:23], v[64:67], 0
	v_mfma_f32_16x16x32_bf16 v[172:175], v[24:27], v[92:95], v[12:15]
	v_mfma_f32_16x16x32_bf16 v[12:15], v[28:31], v[64:67], 0
	v_mfma_f32_16x16x32_bf16 v[176:179], v[32:35], v[92:95], v[12:15]
	v_mfma_f32_16x16x32_bf16 v[12:15], v[20:23], v[96:99], 0
	v_mfma_f32_16x16x32_bf16 v[180:183], v[24:27], v[110:113], v[12:15]
	v_mfma_f32_16x16x32_bf16 v[12:15], v[28:31], v[96:99], 0
	v_mfma_f32_16x16x32_bf16 v[184:187], v[32:35], v[110:113], v[12:15]
	v_mfma_f32_16x16x32_bf16 v[12:15], v[20:23], v[114:117], 0
	v_mfma_f32_16x16x32_bf16 v[188:191], v[24:27], v[122:125], v[12:15]
	v_mfma_f32_16x16x32_bf16 v[12:15], v[28:31], v[114:117], 0
	v_mfma_f32_16x16x32_bf16 v[192:195], v[32:35], v[122:125], v[12:15]
	v_mfma_f32_16x16x32_bf16 v[12:15], v[20:23], v[126:129], 0
	v_mfma_f32_16x16x32_bf16 v[196:199], v[24:27], v[130:133], v[12:15]
	v_mfma_f32_16x16x32_bf16 v[12:15], v[28:31], v[126:129], 0
	v_mfma_f32_16x16x32_bf16 v[200:203], v[32:35], v[130:133], v[12:15]
	s_barrier
; #define PG8_KSETUP() const bool last = (t == nt - 2); const char* a1 = cA + (size_t)(t + 1) * kstep; \
;             const char* a2 = last ? nA : cA + (size_t)(t + 2) * kstep; const char* b2 = last ? nB : cB + (size_t)(t + 2) * kstep; const char* a3 = a2 + kstep; const char* b3 = b2 + kstep; \
;             if (last && has_next) S.a_ready(nxt)
; template <class Epi, class Sched, bool ALIGN_EPI = false, bool SP2 = false>
; __device__ __forceinline__ void gemm_phase(PG8_LAS unsigned char* lds, const Gemm g, const Sched& S, const Epi& E) {
;     ...
;         int t0 = 0;
;         if constexpr (SP2 && Epi::NVM == 16) { if (ui > 0) { const int t = 0; PG8_KSETUP(); PG8_KITER_SP2(24, 24); t0 = 2; } }
	s_setprio 0
	s_nop 4
	ds_read_b128 v[12:15], v150
	ds_read_b128 v[16:19], v150 offset:1024
	ds_read_b128 v[22:25], v150 offset:2048
	ds_read_b128 v[26:29], v150 offset:3072
	ds_read_b128 v[204:207], v151
	ds_read_b128 v[208:211], v151 offset:1024
	ds_read_b128 v[212:215], v151 offset:2048
	ds_read_b128 v[216:219], v151 offset:3072
	ds_read_b128 v[30:33], v149 offset:32768
	ds_read_b128 v[64:67], v149 offset:33792
	ds_read_b128 v[220:223], v149 offset:34816
	ds_read_b128 v[224:227], v149 offset:35840
	ds_read_b128 v[228:231], v149 offset:36864
	ds_read_b128 v[232:235], v149 offset:37888
	ds_read_b128 v[236:239], v149 offset:38912
	ds_read_b128 v[240:243], v149 offset:39936
	s_add_u32 s30, s36, 0x160100
	s_addc_u32 s31, s37, 0
	s_mov_b32 m0, s57
	s_nop 0
	global_load_lds_dwordx4 v1, s[30:31] offset:0
	s_nop 0
	s_mov_b32 m0, s58
	s_nop 0
	global_load_lds_dwordx4 v143, s[30:31] offset:0
	s_waitcnt vmcnt(8)
	s_waitcnt lgkmcnt(0)
	s_barrier
	s_setprio 1
	v_mfma_f32_16x16x32_bf16 v[68:71], v[12:15], v[30:33], v[68:71]
	v_mfma_f32_16x16x32_bf16 v[130:133], v[16:19], v[64:67], v[68:71]
	v_mfma_f32_16x16x32_bf16 v[68:71], v[22:25], v[30:33], v[72:75]
	v_mfma_f32_16x16x32_bf16 v[126:129], v[26:29], v[64:67], v[68:71]
	v_mfma_f32_16x16x32_bf16 v[68:71], v[12:15], v[220:223], v[76:79]
	v_mfma_f32_16x16x32_bf16 v[114:117], v[16:19], v[224:227], v[68:71]
	v_mfma_f32_16x16x32_bf16 v[68:71], v[22:25], v[220:223], v[80:83]
	v_mfma_f32_16x16x32_bf16 v[110:113], v[26:29], v[224:227], v[68:71]
	v_mfma_f32_16x16x32_bf16 v[68:71], v[12:15], v[228:231], v[84:87]
	v_mfma_f32_16x16x32_bf16 v[98:101], v[16:19], v[232:235], v[68:71]
	v_mfma_f32_16x16x32_bf16 v[68:71], v[22:25], v[228:231], v[88:91]
	v_mfma_f32_16x16x32_bf16 v[94:97], v[26:29], v[232:235], v[68:71]
	v_mfma_f32_16x16x32_bf16 v[68:71], v[12:15], v[236:239], v[102:105]
	v_mfma_f32_16x16x32_bf16 v[82:85], v[16:19], v[240:243], v[68:71]
	v_mfma_f32_16x16x32_bf16 v[68:71], v[22:25], v[236:239], v[106:109]
	v_mfma_f32_16x16x32_bf16 v[78:81], v[26:29], v[240:243], v[68:71]
	s_setprio 0
	s_setprio 1
	v_mfma_f32_16x16x32_bf16 v[68:71], v[204:207], v[30:33], v[118:121]
	v_mfma_f32_16x16x32_bf16 v[30:33], v[212:215], v[30:33], v[36:39]
	v_mfma_f32_16x16x32_bf16 v[118:121], v[216:219], v[64:67], v[30:33]
	v_mfma_f32_16x16x32_bf16 v[30:33], v[204:207], v[220:223], v[40:43]
	v_mfma_f32_16x16x32_bf16 v[106:109], v[208:211], v[224:227], v[30:33]
	v_mfma_f32_16x16x32_bf16 v[30:33], v[212:215], v[220:223], v[44:47]
	v_mfma_f32_16x16x32_bf16 v[102:105], v[216:219], v[224:227], v[30:33]
	v_mfma_f32_16x16x32_bf16 v[30:33], v[204:207], v[228:231], v[48:51]
	v_mfma_f32_16x16x32_bf16 v[90:93], v[208:211], v[232:235], v[30:33]
	v_mfma_f32_16x16x32_bf16 v[30:33], v[212:215], v[228:231], v[52:55]
	v_mfma_f32_16x16x32_bf16 v[86:89], v[216:219], v[232:235], v[30:33]
	v_mfma_f32_16x16x32_bf16 v[30:33], v[204:207], v[236:239], v[56:59]
	v_mfma_f32_16x16x32_bf16 v[74:77], v[208:211], v[240:243], v[30:33]
	v_mfma_f32_16x16x32_bf16 v[30:33], v[212:215], v[236:239], v[60:63]
	v_mfma_f32_16x16x32_bf16 v[122:125], v[208:211], v[64:67], v[68:71]
	v_mfma_f32_16x16x32_bf16 v[70:73], v[216:219], v[240:243], v[30:33]
	s_barrier
	s_setprio 0
	ds_read_b128 v[38:41], v149 offset:49152
	ds_read_b128 v[42:45], v149 offset:50176
	ds_read_b128 v[220:223], v149 offset:51200
	ds_read_b128 v[224:227], v149 offset:52224
	ds_read_b128 v[228:231], v149 offset:53248
	ds_read_b128 v[232:235], v149 offset:54272
	ds_read_b128 v[236:239], v149 offset:55296
	ds_read_b128 v[240:243], v149 offset:56320
	s_add_u32 s30, s38, 0x180
	s_addc_u32 s31, s39, 0
	s_mov_b32 m0, s66
	s_nop 0
	global_load_lds_dwordx4 v142, s[30:31] offset:0
	s_nop 0
	s_mov_b32 m0, s67
	s_nop 0
	global_load_lds_dwordx4 v144, s[30:31] offset:0
	s_add_u32 s30, s38, 0x160180
	s_addc_u32 s31, s39, 0
	s_mov_b32 m0, s70
	s_nop 0
	global_load_lds_dwordx4 v142, s[30:31] offset:0
	s_nop 0
	s_mov_b32 m0, s71
	s_nop 0
	global_load_lds_dwordx4 v144, s[30:31] offset:0
	s_nop 0
	s_mov_b32 m0, s68
	s_nop 0
	global_load_lds_dwordx4 v1, s[40:41] offset:0
	s_nop 0
	s_mov_b32 m0, s69
	s_nop 0
	global_load_lds_dwordx4 v143, s[40:41] offset:0
	s_waitcnt vmcnt(8)
	s_waitcnt lgkmcnt(0)
	s_barrier
	s_setprio 1
	v_mfma_f32_16x16x32_bf16 v[30:33], v[12:15], v[38:41], v[138:141]
	v_mfma_f32_16x16x32_bf16 v[66:69], v[16:19], v[42:45], v[30:33]
	v_mfma_f32_16x16x32_bf16 v[30:33], v[22:25], v[38:41], v[152:155]
	v_mfma_f32_16x16x32_bf16 v[62:65], v[26:29], v[42:45], v[30:33]
	v_mfma_f32_16x16x32_bf16 v[30:33], v[12:15], v[220:223], v[156:159]
	v_mfma_f32_16x16x32_bf16 v[50:53], v[16:19], v[224:227], v[30:33]
	v_mfma_f32_16x16x32_bf16 v[30:33], v[22:25], v[220:223], v[160:163]
	v_mfma_f32_16x16x32_bf16 v[46:49], v[26:29], v[224:227], v[30:33]
	v_mfma_f32_16x16x32_bf16 v[30:33], v[12:15], v[228:231], v[164:167]
	v_mfma_f32_16x16x32_bf16 v[4:7], v[12:15], v[236:239], v[4:7]
	v_mfma_f32_16x16x32_bf16 v[34:37], v[16:19], v[232:235], v[30:33]
	v_mfma_f32_16x16x32_bf16 v[30:33], v[22:25], v[228:231], v[168:171]
	v_mfma_f32_16x16x32_bf16 v[18:21], v[16:19], v[240:243], v[4:7]
	v_mfma_f32_16x16x32_bf16 v[4:7], v[22:25], v[236:239], v[8:11]
	v_mfma_f32_16x16x32_bf16 v[30:33], v[26:29], v[232:235], v[30:33]
	v_mfma_f32_16x16x32_bf16 v[14:17], v[26:29], v[240:243], v[4:7]
	s_setprio 0
	s_setprio 1
	v_mfma_f32_16x16x32_bf16 v[4:7], v[204:207], v[38:41], v[172:175]
	v_mfma_f32_16x16x32_bf16 v[58:61], v[208:211], v[42:45], v[4:7]
	v_mfma_f32_16x16x32_bf16 v[4:7], v[212:215], v[38:41], v[176:179]
	v_mfma_f32_16x16x32_bf16 v[54:57], v[216:219], v[42:45], v[4:7]
	v_mfma_f32_16x16x32_bf16 v[4:7], v[204:207], v[220:223], v[180:183]
	v_mfma_f32_16x16x32_bf16 v[42:45], v[208:211], v[224:227], v[4:7]
	v_mfma_f32_16x16x32_bf16 v[4:7], v[212:215], v[220:223], v[184:187]
	v_mfma_f32_16x16x32_bf16 v[38:41], v[216:219], v[224:227], v[4:7]
	v_mfma_f32_16x16x32_bf16 v[4:7], v[204:207], v[228:231], v[188:191]
	v_mfma_f32_16x16x32_bf16 v[26:29], v[208:211], v[232:235], v[4:7]
	v_mfma_f32_16x16x32_bf16 v[4:7], v[212:215], v[228:231], v[192:195]
	v_mfma_f32_16x16x32_bf16 v[22:25], v[216:219], v[232:235], v[4:7]
	v_mfma_f32_16x16x32_bf16 v[4:7], v[204:207], v[236:239], v[196:199]
	v_mfma_f32_16x16x32_bf16 v[10:13], v[208:211], v[240:243], v[4:7]
	v_mfma_f32_16x16x32_bf16 v[4:7], v[212:215], v[236:239], v[200:203]
	v_mfma_f32_16x16x32_bf16 v[6:9], v[216:219], v[240:243], v[4:7]
	s_barrier
	s_setprio 0
	s_mov_b32 s40, 2
	s_branch .LBB0_2377

; #define PG8_KSETUP() const bool last = (t == nt - 2); const char* a1 = cA + (size_t)(t + 1) * kstep; \
;             const char* a2 = last ? nA : cA + (size_t)(t + 2) * kstep; const char* b2 = last ? nB : cB + (size_t)(t + 2) * kstep; const char* a3 = a2 + kstep; const char* b3 = b2 + kstep; \
;             if (last && has_next) S.a_ready(nxt)
; template <class Epi, class Sched, bool ALIGN_EPI = false, bool SP2 = false>
; __device__ __forceinline__ void gemm_phase(PG8_LAS unsigned char* lds, const Gemm g, const Sched& S, const Epi& E) {
;     ...
;         int t0 = 0;
;         if constexpr (SP2 && Epi::NVM == 16) { if (ui > 0) { const int t = 0; PG8_KSETUP(); PG8_KITER_SP2(24, 24); t0 = 2; } }
;         if constexpr (SP2 && Epi::NVM == 8) { if (ui > 0) { const int t = 0; PG8_KSETUP(); PG8_KITER_SP2(16, 16); t0 = 2; } }
;         for (int t = t0; t < nt; t += 2) {
;             PG8_KSETUP();
;             if constexpr (SP2) {
;             PG8_KITER_SP2(8, 8);
.LBB0_2378:
	ds_read_b128 v[138:141], v147
	ds_read_b128 v[152:155], v147 offset:1024
	ds_read_b128 v[156:159], v147 offset:2048
	ds_read_b128 v[160:163], v147 offset:3072
	ds_read_b128 v[164:167], v148
	ds_read_b128 v[168:171], v148 offset:1024
	ds_read_b128 v[172:175], v148 offset:2048
	ds_read_b128 v[176:179], v148 offset:3072
	s_cmpk_eq_i32 s82, 0x54
	s_cselect_b32 s44, s8, s85
	s_cselect_b32 s45, s9, s86
	s_cselect_b32 s40, s28, s83
	s_cselect_b32 s41, s29, s84
	s_add_u32 s38, s44, 0x80
	s_addc_u32 s39, s45, 0
	ds_read_b128 v[180:183], v149
	ds_read_b128 v[184:187], v149 offset:1024
	ds_read_b128 v[188:191], v149 offset:2048
	ds_read_b128 v[192:195], v149 offset:3072
	ds_read_b128 v[196:199], v149 offset:4096
	ds_read_b128 v[200:203], v149 offset:5120
	ds_read_b128 v[204:207], v149 offset:6144
	ds_read_b128 v[208:211], v149 offset:7168
	s_mov_b32 m0, s72
	s_nop 0
	global_load_lds_dwordx4 v1, s[36:37] offset:0
	s_nop 0
	s_mov_b32 m0, s73
	s_nop 0
	global_load_lds_dwordx4 v143, s[36:37] offset:0
	s_waitcnt vmcnt(8)
	s_waitcnt lgkmcnt(0)
	s_barrier
	s_setprio 1
	v_mfma_f32_16x16x32_bf16 v[130:133], v[138:141], v[180:183], v[130:133]
	v_mfma_f32_16x16x32_bf16 v[130:133], v[152:155], v[184:187], v[130:133]
	v_mfma_f32_16x16x32_bf16 v[126:129], v[156:159], v[180:183], v[126:129]
	v_mfma_f32_16x16x32_bf16 v[126:129], v[160:163], v[184:187], v[126:129]
	v_mfma_f32_16x16x32_bf16 v[114:117], v[138:141], v[188:191], v[114:117]
	v_mfma_f32_16x16x32_bf16 v[114:117], v[152:155], v[192:195], v[114:117]
	v_mfma_f32_16x16x32_bf16 v[110:113], v[156:159], v[188:191], v[110:113]
	v_mfma_f32_16x16x32_bf16 v[110:113], v[160:163], v[192:195], v[110:113]
	v_mfma_f32_16x16x32_bf16 v[98:101], v[138:141], v[196:199], v[98:101]
	v_mfma_f32_16x16x32_bf16 v[98:101], v[152:155], v[200:203], v[98:101]
	v_mfma_f32_16x16x32_bf16 v[94:97], v[156:159], v[196:199], v[94:97]
	v_mfma_f32_16x16x32_bf16 v[94:97], v[160:163], v[200:203], v[94:97]
	v_mfma_f32_16x16x32_bf16 v[82:85], v[138:141], v[204:207], v[82:85]
	v_mfma_f32_16x16x32_bf16 v[82:85], v[152:155], v[208:211], v[82:85]
	v_mfma_f32_16x16x32_bf16 v[78:81], v[156:159], v[204:207], v[78:81]
	v_mfma_f32_16x16x32_bf16 v[78:81], v[160:163], v[208:211], v[78:81]
	s_setprio 0
	s_setprio 1
	v_mfma_f32_16x16x32_bf16 v[122:125], v[164:167], v[180:183], v[122:125]
	v_mfma_f32_16x16x32_bf16 v[122:125], v[168:171], v[184:187], v[122:125]
	v_mfma_f32_16x16x32_bf16 v[118:121], v[172:175], v[180:183], v[118:121]
	v_mfma_f32_16x16x32_bf16 v[118:121], v[176:179], v[184:187], v[118:121]
	v_mfma_f32_16x16x32_bf16 v[106:109], v[164:167], v[188:191], v[106:109]
	v_mfma_f32_16x16x32_bf16 v[106:109], v[168:171], v[192:195], v[106:109]
	v_mfma_f32_16x16x32_bf16 v[102:105], v[172:175], v[188:191], v[102:105]
	v_mfma_f32_16x16x32_bf16 v[102:105], v[176:179], v[192:195], v[102:105]
	v_mfma_f32_16x16x32_bf16 v[90:93], v[164:167], v[196:199], v[90:93]
	v_mfma_f32_16x16x32_bf16 v[90:93], v[168:171], v[200:203], v[90:93]
	v_mfma_f32_16x16x32_bf16 v[86:89], v[172:175], v[196:199], v[86:89]
	v_mfma_f32_16x16x32_bf16 v[86:89], v[176:179], v[200:203], v[86:89]
	v_mfma_f32_16x16x32_bf16 v[74:77], v[164:167], v[204:207], v[74:77]
	v_mfma_f32_16x16x32_bf16 v[74:77], v[168:171], v[208:211], v[74:77]
	v_mfma_f32_16x16x32_bf16 v[70:73], v[172:175], v[204:207], v[70:73]
	v_mfma_f32_16x16x32_bf16 v[70:73], v[176:179], v[208:211], v[70:73]
	s_barrier
	s_setprio 0
	ds_read_b128 v[180:183], v149 offset:16384
	ds_read_b128 v[184:187], v149 offset:17408
	ds_read_b128 v[188:191], v149 offset:18432
	ds_read_b128 v[192:195], v149 offset:19456
	ds_read_b128 v[196:199], v149 offset:20480
	ds_read_b128 v[200:203], v149 offset:21504
	ds_read_b128 v[204:207], v149 offset:22528
	ds_read_b128 v[208:211], v149 offset:23552
	s_mov_b32 m0, s52
	s_nop 0
	global_load_lds_dwordx4 v142, s[40:41] offset:0
	s_add_u32 s30, s40, 0x160000
	s_mov_b32 m0, s53
	s_nop 0
	global_load_lds_dwordx4 v144, s[40:41] offset:0
	s_addc_u32 s31, s41, 0
	s_mov_b32 m0, s54
	s_nop 0
	global_load_lds_dwordx4 v142, s[30:31] offset:0
	s_nop 0
	s_mov_b32 m0, s55
	s_nop 0
	global_load_lds_dwordx4 v144, s[30:31] offset:0
	s_nop 0
	s_mov_b32 m0, s47
	s_nop 0
	global_load_lds_dwordx4 v1, s[44:45] offset:0
	s_nop 0
	s_mov_b32 m0, s56
	s_nop 0
	global_load_lds_dwordx4 v143, s[44:45] offset:0
	s_waitcnt vmcnt(8)
	s_waitcnt lgkmcnt(0)
	s_barrier
	s_setprio 1
	v_mfma_f32_16x16x32_bf16 v[66:69], v[138:141], v[180:183], v[66:69]
	v_mfma_f32_16x16x32_bf16 v[66:69], v[152:155], v[184:187], v[66:69]
	v_mfma_f32_16x16x32_bf16 v[62:65], v[156:159], v[180:183], v[62:65]
	v_mfma_f32_16x16x32_bf16 v[62:65], v[160:163], v[184:187], v[62:65]
	v_mfma_f32_16x16x32_bf16 v[50:53], v[138:141], v[188:191], v[50:53]
	v_mfma_f32_16x16x32_bf16 v[50:53], v[152:155], v[192:195], v[50:53]
	v_mfma_f32_16x16x32_bf16 v[46:49], v[156:159], v[188:191], v[46:49]
	v_mfma_f32_16x16x32_bf16 v[46:49], v[160:163], v[192:195], v[46:49]
	v_mfma_f32_16x16x32_bf16 v[34:37], v[138:141], v[196:199], v[34:37]
	v_mfma_f32_16x16x32_bf16 v[34:37], v[152:155], v[200:203], v[34:37]
	v_mfma_f32_16x16x32_bf16 v[30:33], v[156:159], v[196:199], v[30:33]
	v_mfma_f32_16x16x32_bf16 v[30:33], v[160:163], v[200:203], v[30:33]
	v_mfma_f32_16x16x32_bf16 v[18:21], v[138:141], v[204:207], v[18:21]
	v_mfma_f32_16x16x32_bf16 v[18:21], v[152:155], v[208:211], v[18:21]
	v_mfma_f32_16x16x32_bf16 v[14:17], v[156:159], v[204:207], v[14:17]
	v_mfma_f32_16x16x32_bf16 v[14:17], v[160:163], v[208:211], v[14:17]
	s_setprio 0
	s_setprio 1
	v_mfma_f32_16x16x32_bf16 v[58:61], v[164:167], v[180:183], v[58:61]
	v_mfma_f32_16x16x32_bf16 v[54:57], v[172:175], v[180:183], v[54:57]
	v_mfma_f32_16x16x32_bf16 v[42:45], v[164:167], v[188:191], v[42:45]
	v_mfma_f32_16x16x32_bf16 v[38:41], v[172:175], v[188:191], v[38:41]
	v_mfma_f32_16x16x32_bf16 v[26:29], v[164:167], v[196:199], v[26:29]
	v_mfma_f32_16x16x32_bf16 v[22:25], v[172:175], v[196:199], v[22:25]
	v_mfma_f32_16x16x32_bf16 v[10:13], v[164:167], v[204:207], v[10:13]
	v_mfma_f32_16x16x32_bf16 v[4:7], v[172:175], v[204:207], v[6:9]
	v_mfma_f32_16x16x32_bf16 v[58:61], v[168:171], v[184:187], v[58:61]
	v_mfma_f32_16x16x32_bf16 v[54:57], v[176:179], v[184:187], v[54:57]
	v_mfma_f32_16x16x32_bf16 v[42:45], v[168:171], v[192:195], v[42:45]
	v_mfma_f32_16x16x32_bf16 v[38:41], v[176:179], v[192:195], v[38:41]
	v_mfma_f32_16x16x32_bf16 v[26:29], v[168:171], v[200:203], v[26:29]
	v_mfma_f32_16x16x32_bf16 v[22:25], v[176:179], v[200:203], v[22:25]
	v_mfma_f32_16x16x32_bf16 v[10:13], v[168:171], v[208:211], v[10:13]
	v_mfma_f32_16x16x32_bf16 v[4:7], v[176:179], v[208:211], v[4:7]
	s_barrier
; #define PG8_KSETUP() const bool last = (t == nt - 2); const char* a1 = cA + (size_t)(t + 1) * kstep; \
;             const char* a2 = last ? nA : cA + (size_t)(t + 2) * kstep; const char* b2 = last ? nB : cB + (size_t)(t + 2) * kstep; const char* a3 = a2 + kstep; const char* b3 = b2 + kstep; \
;             if (last && has_next) S.a_ready(nxt)
; template <class Epi, class Sched, bool ALIGN_EPI = false, bool SP2 = false>
; __device__ __forceinline__ void gemm_phase(PG8_LAS unsigned char* lds, const Gemm g, const Sched& S, const Epi& E) {
;     ...
;         int t0 = 0;
;         if constexpr (SP2 && Epi::NVM == 16) { if (ui > 0) { const int t = 0; PG8_KSETUP(); PG8_KITER_SP2(24, 24); t0 = 2; } }
;         if constexpr (SP2 && Epi::NVM == 8) { if (ui > 0) { const int t = 0; PG8_KSETUP(); PG8_KITER_SP2(16, 16); t0 = 2; } }
;         for (int t = t0; t < nt; t += 2) {
;             PG8_KSETUP();
;             if constexpr (SP2) {
;             PG8_KITER_SP2(8, 8);
	s_setprio 0
	ds_read_b128 v[138:141], v150
	ds_read_b128 v[152:155], v150 offset:1024
	ds_read_b128 v[156:159], v150 offset:2048
	ds_read_b128 v[160:163], v150 offset:3072
	ds_read_b128 v[164:167], v151
	ds_read_b128 v[168:171], v151 offset:1024
	ds_read_b128 v[172:175], v151 offset:2048
	ds_read_b128 v[176:179], v151 offset:3072
	ds_read_b128 v[180:183], v149 offset:32768
	ds_read_b128 v[184:187], v149 offset:33792
	ds_read_b128 v[188:191], v149 offset:34816
	ds_read_b128 v[192:195], v149 offset:35840
	ds_read_b128 v[196:199], v149 offset:36864
	ds_read_b128 v[200:203], v149 offset:37888
	ds_read_b128 v[204:207], v149 offset:38912
	ds_read_b128 v[208:211], v149 offset:39936
	s_add_u32 s30, s44, 0x160000
	s_addc_u32 s31, s45, 0
	s_mov_b32 m0, s57
	s_nop 0
	global_load_lds_dwordx4 v1, s[30:31] offset:0
	s_nop 0
	s_mov_b32 m0, s58
	s_nop 0
	global_load_lds_dwordx4 v143, s[30:31] offset:0
	s_waitcnt vmcnt(8)
	s_waitcnt lgkmcnt(0)
	s_barrier
	s_setprio 1
	v_mfma_f32_16x16x32_bf16 v[130:133], v[138:141], v[180:183], v[130:133]
	v_mfma_f32_16x16x32_bf16 v[130:133], v[152:155], v[184:187], v[130:133]
	v_mfma_f32_16x16x32_bf16 v[126:129], v[156:159], v[180:183], v[126:129]
	v_mfma_f32_16x16x32_bf16 v[126:129], v[160:163], v[184:187], v[126:129]
	v_mfma_f32_16x16x32_bf16 v[114:117], v[138:141], v[188:191], v[114:117]
	v_mfma_f32_16x16x32_bf16 v[114:117], v[152:155], v[192:195], v[114:117]
	v_mfma_f32_16x16x32_bf16 v[110:113], v[156:159], v[188:191], v[110:113]
	v_mfma_f32_16x16x32_bf16 v[110:113], v[160:163], v[192:195], v[110:113]
	v_mfma_f32_16x16x32_bf16 v[98:101], v[138:141], v[196:199], v[98:101]
	v_mfma_f32_16x16x32_bf16 v[98:101], v[152:155], v[200:203], v[98:101]
	v_mfma_f32_16x16x32_bf16 v[94:97], v[156:159], v[196:199], v[94:97]
	v_mfma_f32_16x16x32_bf16 v[94:97], v[160:163], v[200:203], v[94:97]
	v_mfma_f32_16x16x32_bf16 v[82:85], v[138:141], v[204:207], v[82:85]
	v_mfma_f32_16x16x32_bf16 v[82:85], v[152:155], v[208:211], v[82:85]
	v_mfma_f32_16x16x32_bf16 v[78:81], v[156:159], v[204:207], v[78:81]
	v_mfma_f32_16x16x32_bf16 v[78:81], v[160:163], v[208:211], v[78:81]
	s_setprio 0
	s_setprio 1
	v_mfma_f32_16x16x32_bf16 v[122:125], v[164:167], v[180:183], v[122:125]
	v_mfma_f32_16x16x32_bf16 v[122:125], v[168:171], v[184:187], v[122:125]
	v_mfma_f32_16x16x32_bf16 v[118:121], v[172:175], v[180:183], v[118:121]
	v_mfma_f32_16x16x32_bf16 v[118:121], v[176:179], v[184:187], v[118:121]
	v_mfma_f32_16x16x32_bf16 v[106:109], v[164:167], v[188:191], v[106:109]
	v_mfma_f32_16x16x32_bf16 v[106:109], v[168:171], v[192:195], v[106:109]
	v_mfma_f32_16x16x32_bf16 v[102:105], v[172:175], v[188:191], v[102:105]
	v_mfma_f32_16x16x32_bf16 v[102:105], v[176:179], v[192:195], v[102:105]
	v_mfma_f32_16x16x32_bf16 v[90:93], v[164:167], v[196:199], v[90:93]
	v_mfma_f32_16x16x32_bf16 v[90:93], v[168:171], v[200:203], v[90:93]
	v_mfma_f32_16x16x32_bf16 v[86:89], v[172:175], v[196:199], v[86:89]
	v_mfma_f32_16x16x32_bf16 v[86:89], v[176:179], v[200:203], v[86:89]
	v_mfma_f32_16x16x32_bf16 v[74:77], v[164:167], v[204:207], v[74:77]
	v_mfma_f32_16x16x32_bf16 v[74:77], v[168:171], v[208:211], v[74:77]
	v_mfma_f32_16x16x32_bf16 v[70:73], v[172:175], v[204:207], v[70:73]
	v_mfma_f32_16x16x32_bf16 v[70:73], v[176:179], v[208:211], v[70:73]
	s_barrier
	s_setprio 0
	ds_read_b128 v[180:183], v149 offset:49152
	ds_read_b128 v[184:187], v149 offset:50176
	ds_read_b128 v[188:191], v149 offset:51200
	ds_read_b128 v[192:195], v149 offset:52224
	ds_read_b128 v[196:199], v149 offset:53248
	ds_read_b128 v[200:203], v149 offset:54272
	ds_read_b128 v[204:207], v149 offset:55296
	ds_read_b128 v[208:211], v149 offset:56320
	s_add_u32 s30, s40, 0x80
	s_addc_u32 s31, s41, 0
	s_mov_b32 m0, s66
	s_nop 0
	global_load_lds_dwordx4 v142, s[30:31] offset:0
	s_nop 0
	s_mov_b32 m0, s67
	s_nop 0
	global_load_lds_dwordx4 v144, s[30:31] offset:0
	s_add_u32 s30, s40, 0x160080
	s_addc_u32 s31, s41, 0
	s_mov_b32 m0, s70
	s_nop 0
	global_load_lds_dwordx4 v142, s[30:31] offset:0
	s_nop 0
	s_mov_b32 m0, s71
	s_nop 0
	global_load_lds_dwordx4 v144, s[30:31] offset:0
	s_nop 0
	s_mov_b32 m0, s68
	s_nop 0
	global_load_lds_dwordx4 v1, s[38:39] offset:0
	s_nop 0
	s_mov_b32 m0, s69
	s_nop 0
	global_load_lds_dwordx4 v143, s[38:39] offset:0
	s_waitcnt vmcnt(8)
	s_waitcnt lgkmcnt(0)
	s_barrier
	s_setprio 1
	v_mfma_f32_16x16x32_bf16 v[66:69], v[138:141], v[180:183], v[66:69]
	v_mfma_f32_16x16x32_bf16 v[66:69], v[152:155], v[184:187], v[66:69]
	v_mfma_f32_16x16x32_bf16 v[62:65], v[156:159], v[180:183], v[62:65]
	v_mfma_f32_16x16x32_bf16 v[62:65], v[160:163], v[184:187], v[62:65]
	v_mfma_f32_16x16x32_bf16 v[50:53], v[138:141], v[188:191], v[50:53]
	v_mfma_f32_16x16x32_bf16 v[50:53], v[152:155], v[192:195], v[50:53]
	v_mfma_f32_16x16x32_bf16 v[46:49], v[156:159], v[188:191], v[46:49]
	v_mfma_f32_16x16x32_bf16 v[46:49], v[160:163], v[192:195], v[46:49]
	v_mfma_f32_16x16x32_bf16 v[34:37], v[138:141], v[196:199], v[34:37]
	v_mfma_f32_16x16x32_bf16 v[34:37], v[152:155], v[200:203], v[34:37]
	v_mfma_f32_16x16x32_bf16 v[30:33], v[156:159], v[196:199], v[30:33]
	v_mfma_f32_16x16x32_bf16 v[30:33], v[160:163], v[200:203], v[30:33]
	v_mfma_f32_16x16x32_bf16 v[18:21], v[138:141], v[204:207], v[18:21]
	v_mfma_f32_16x16x32_bf16 v[18:21], v[152:155], v[208:211], v[18:21]
	v_mfma_f32_16x16x32_bf16 v[14:17], v[156:159], v[204:207], v[14:17]
	v_mfma_f32_16x16x32_bf16 v[14:17], v[160:163], v[208:211], v[14:17]
	s_setprio 0
	s_setprio 1
	v_mfma_f32_16x16x32_bf16 v[58:61], v[164:167], v[180:183], v[58:61]
	v_mfma_f32_16x16x32_bf16 v[54:57], v[172:175], v[180:183], v[54:57]
	v_mfma_f32_16x16x32_bf16 v[42:45], v[164:167], v[188:191], v[42:45]
	v_mfma_f32_16x16x32_bf16 v[38:41], v[172:175], v[188:191], v[38:41]
	v_mfma_f32_16x16x32_bf16 v[26:29], v[164:167], v[196:199], v[26:29]
	v_mfma_f32_16x16x32_bf16 v[22:25], v[172:175], v[196:199], v[22:25]
	v_mfma_f32_16x16x32_bf16 v[8:11], v[164:167], v[204:207], v[10:13]
	v_mfma_f32_16x16x32_bf16 v[4:7], v[172:175], v[204:207], v[4:7]
	v_mfma_f32_16x16x32_bf16 v[58:61], v[168:171], v[184:187], v[58:61]
	v_mfma_f32_16x16x32_bf16 v[54:57], v[176:179], v[184:187], v[54:57]
	v_mfma_f32_16x16x32_bf16 v[42:45], v[168:171], v[192:195], v[42:45]
	v_mfma_f32_16x16x32_bf16 v[38:41], v[176:179], v[192:195], v[38:41]
	v_mfma_f32_16x16x32_bf16 v[26:29], v[168:171], v[200:203], v[26:29]
	v_mfma_f32_16x16x32_bf16 v[22:25], v[176:179], v[200:203], v[22:25]
	v_mfma_f32_16x16x32_bf16 v[10:13], v[168:171], v[208:211], v[8:11]
	v_mfma_f32_16x16x32_bf16 v[6:9], v[176:179], v[208:211], v[4:7]
	s_barrier
	s_setprio 0
	s_add_i32 s82, s82, 2
	s_add_u32 s83, s83, 0x100
	s_addc_u32 s84, s84, 0
	s_add_u32 s85, s85, 0x100
	s_addc_u32 s86, s86, 0
	s_add_u32 s36, s36, 0x100
	s_addc_u32 s37, s37, 0
	s_cmpk_gt_u32 s82, 0x55
	s_cbranch_scc0 .LBB0_2378
	s_and_b64 vcc, exec, s[16:17]
	s_cbranch_vccz .LBB0_2381
	s_barrier

; #define PG8_KSETUP() const bool last = (t == nt - 2); const char* a1 = cA + (size_t)(t + 1) * kstep; \
;             const char* a2 = last ? nA : cA + (size_t)(t + 2) * kstep; const char* b2 = last ? nB : cB + (size_t)(t + 2) * kstep; const char* a3 = a2 + kstep; const char* b3 = b2 + kstep; \
;             if (last && has_next) S.a_ready(nxt)
; template <class Epi, class Sched, bool ALIGN_EPI = false, bool SP2 = false>
; __device__ __forceinline__ void gemm_phase(PG8_LAS unsigned char* lds, const Gemm g, const Sched& S, const Epi& E) {
;     ...
;         int t0 = 0;
;         if constexpr (SP2 && Epi::NVM == 16) { if (ui > 0) { const int t = 0; PG8_KSETUP(); PG8_KITER_SP2(24, 24); t0 = 2; } }
;         if constexpr (SP2 && Epi::NVM == 8) { if (ui > 0) { const int t = 0; PG8_KSETUP(); PG8_KITER_SP2(16, 16); t0 = 2; } }
;         for (int t = t0; t < nt; t += 2) {
;             PG8_KSETUP();
;             if constexpr (SP2) {
;             PG8_KITER_SP2(8, 8);
.LBB0_2536:
	ds_read_b128 v[160:163], v155
	ds_read_b128 v[168:171], v155 offset:1024
	ds_read_b128 v[172:175], v155 offset:2048
	ds_read_b128 v[176:179], v155 offset:3072
	ds_read_b128 v[180:183], v159
	ds_read_b128 v[184:187], v159 offset:1024
	ds_read_b128 v[188:191], v159 offset:2048
	ds_read_b128 v[192:195], v159 offset:3072
	s_cmp_eq_u32 s91, 28
	s_cselect_b32 s56, s45, s89
	s_cselect_b32 s57, s37, s90
	s_cselect_b32 s54, s86, s87
	s_cselect_b32 s55, s29, s88
	s_add_u32 s46, s56, 0x80
	s_addc_u32 s47, s57, 0
	ds_read_b128 v[196:199], v164
	ds_read_b128 v[200:203], v164 offset:1024
	ds_read_b128 v[204:207], v164 offset:2048
	ds_read_b128 v[208:211], v164 offset:3072
	ds_read_b128 v[212:215], v164 offset:4096
	ds_read_b128 v[216:219], v164 offset:5120
	ds_read_b128 v[220:223], v164 offset:6144
	ds_read_b128 v[224:227], v164 offset:7168
	s_add_u32 s30, s89, 0x7ff80
	s_addc_u32 s31, s90, 0
	s_mov_b32 m0, s78
	s_nop 0
	global_load_lds_dwordx4 v1, s[30:31] offset:0
	s_nop 0
	s_mov_b32 m0, s79
	s_nop 0
	global_load_lds_dwordx4 v139, s[30:31] offset:0
	s_waitcnt vmcnt(8)
	s_waitcnt lgkmcnt(0)
	s_barrier
	s_setprio 1
	v_mfma_f32_16x16x32_bf16 v[126:129], v[160:163], v[196:199], v[126:129]
	v_mfma_f32_16x16x32_bf16 v[126:129], v[168:171], v[200:203], v[126:129]
	v_mfma_f32_16x16x32_bf16 v[122:125], v[172:175], v[196:199], v[122:125]
	v_mfma_f32_16x16x32_bf16 v[122:125], v[176:179], v[200:203], v[122:125]
	v_mfma_f32_16x16x32_bf16 v[114:117], v[160:163], v[204:207], v[114:117]
	v_mfma_f32_16x16x32_bf16 v[114:117], v[168:171], v[208:211], v[114:117]
	v_mfma_f32_16x16x32_bf16 v[106:109], v[172:175], v[204:207], v[106:109]
	v_mfma_f32_16x16x32_bf16 v[106:109], v[176:179], v[208:211], v[106:109]
	v_mfma_f32_16x16x32_bf16 v[98:101], v[160:163], v[212:215], v[98:101]
	v_mfma_f32_16x16x32_bf16 v[98:101], v[168:171], v[216:219], v[98:101]
	v_mfma_f32_16x16x32_bf16 v[90:93], v[172:175], v[212:215], v[90:93]
	v_mfma_f32_16x16x32_bf16 v[90:93], v[176:179], v[216:219], v[90:93]
	v_mfma_f32_16x16x32_bf16 v[82:85], v[160:163], v[220:223], v[82:85]
	v_mfma_f32_16x16x32_bf16 v[82:85], v[168:171], v[224:227], v[82:85]
	v_mfma_f32_16x16x32_bf16 v[74:77], v[172:175], v[220:223], v[74:77]
	v_mfma_f32_16x16x32_bf16 v[74:77], v[176:179], v[224:227], v[74:77]
	s_setprio 0
	s_setprio 1
	v_mfma_f32_16x16x32_bf16 v[118:121], v[180:183], v[196:199], v[118:121]
	v_mfma_f32_16x16x32_bf16 v[118:121], v[184:187], v[200:203], v[118:121]
	v_mfma_f32_16x16x32_bf16 v[110:113], v[188:191], v[196:199], v[110:113]
	v_mfma_f32_16x16x32_bf16 v[110:113], v[192:195], v[200:203], v[110:113]
	v_mfma_f32_16x16x32_bf16 v[102:105], v[180:183], v[204:207], v[102:105]
	v_mfma_f32_16x16x32_bf16 v[102:105], v[184:187], v[208:211], v[102:105]
	v_mfma_f32_16x16x32_bf16 v[94:97], v[188:191], v[204:207], v[94:97]
	v_mfma_f32_16x16x32_bf16 v[94:97], v[192:195], v[208:211], v[94:97]
	v_mfma_f32_16x16x32_bf16 v[86:89], v[180:183], v[212:215], v[86:89]
	v_mfma_f32_16x16x32_bf16 v[86:89], v[184:187], v[216:219], v[86:89]
	v_mfma_f32_16x16x32_bf16 v[78:81], v[188:191], v[212:215], v[78:81]
	v_mfma_f32_16x16x32_bf16 v[78:81], v[192:195], v[216:219], v[78:81]
	v_mfma_f32_16x16x32_bf16 v[70:73], v[180:183], v[220:223], v[70:73]
	v_mfma_f32_16x16x32_bf16 v[70:73], v[184:187], v[224:227], v[70:73]
	v_mfma_f32_16x16x32_bf16 v[66:69], v[188:191], v[220:223], v[66:69]
	v_mfma_f32_16x16x32_bf16 v[66:69], v[192:195], v[224:227], v[66:69]
	s_barrier
	s_setprio 0
	ds_read_b128 v[196:199], v164 offset:16384
	ds_read_b128 v[200:203], v164 offset:17408
	ds_read_b128 v[204:207], v164 offset:18432
	ds_read_b128 v[208:211], v164 offset:19456
	ds_read_b128 v[212:215], v164 offset:20480
	ds_read_b128 v[216:219], v164 offset:21504
	ds_read_b128 v[220:223], v164 offset:22528
	ds_read_b128 v[224:227], v164 offset:23552
	s_mov_b32 m0, s64
	s_nop 0
	global_load_lds_dwordx4 v137, s[54:55] offset:0
	s_add_u32 s30, s54, 0x80000
	s_mov_b32 m0, s65
	s_nop 0
	global_load_lds_dwordx4 v141, s[54:55] offset:0
	s_addc_u32 s31, s55, 0
	s_mov_b32 m0, s66
	s_nop 0
	global_load_lds_dwordx4 v137, s[30:31] offset:0
	s_nop 0
	s_mov_b32 m0, s67
	s_nop 0
	global_load_lds_dwordx4 v141, s[30:31] offset:0
	s_nop 0
	s_mov_b32 m0, s53
	s_nop 0
	global_load_lds_dwordx4 v1, s[56:57] offset:0
	s_nop 0
	s_mov_b32 m0, s68
	s_nop 0
	global_load_lds_dwordx4 v139, s[56:57] offset:0
	s_waitcnt vmcnt(8)
	s_waitcnt lgkmcnt(0)
	s_barrier
	s_setprio 1
	v_mfma_f32_16x16x32_bf16 v[62:65], v[160:163], v[196:199], v[62:65]
	v_mfma_f32_16x16x32_bf16 v[62:65], v[168:171], v[200:203], v[62:65]
	v_mfma_f32_16x16x32_bf16 v[58:61], v[172:175], v[196:199], v[58:61]
	v_mfma_f32_16x16x32_bf16 v[58:61], v[176:179], v[200:203], v[58:61]
	v_mfma_f32_16x16x32_bf16 v[50:53], v[160:163], v[204:207], v[50:53]
	v_mfma_f32_16x16x32_bf16 v[50:53], v[168:171], v[208:211], v[50:53]
	v_mfma_f32_16x16x32_bf16 v[42:45], v[172:175], v[204:207], v[42:45]
	v_mfma_f32_16x16x32_bf16 v[42:45], v[176:179], v[208:211], v[42:45]
	v_mfma_f32_16x16x32_bf16 v[34:37], v[160:163], v[212:215], v[34:37]
	v_mfma_f32_16x16x32_bf16 v[34:37], v[168:171], v[216:219], v[34:37]
	v_mfma_f32_16x16x32_bf16 v[26:29], v[172:175], v[212:215], v[26:29]
	v_mfma_f32_16x16x32_bf16 v[26:29], v[176:179], v[216:219], v[26:29]
	v_mfma_f32_16x16x32_bf16 v[18:21], v[160:163], v[220:223], v[18:21]
	v_mfma_f32_16x16x32_bf16 v[18:21], v[168:171], v[224:227], v[18:21]
	v_mfma_f32_16x16x32_bf16 v[10:13], v[172:175], v[220:223], v[10:13]
	v_mfma_f32_16x16x32_bf16 v[10:13], v[176:179], v[224:227], v[10:13]
	s_setprio 0
	s_setprio 1
	v_mfma_f32_16x16x32_bf16 v[54:57], v[180:183], v[196:199], v[54:57]
	v_mfma_f32_16x16x32_bf16 v[54:57], v[184:187], v[200:203], v[54:57]
	v_mfma_f32_16x16x32_bf16 v[46:49], v[188:191], v[196:199], v[46:49]
	v_mfma_f32_16x16x32_bf16 v[46:49], v[192:195], v[200:203], v[46:49]
	v_mfma_f32_16x16x32_bf16 v[38:41], v[180:183], v[204:207], v[38:41]
	v_mfma_f32_16x16x32_bf16 v[38:41], v[184:187], v[208:211], v[38:41]
	v_mfma_f32_16x16x32_bf16 v[30:33], v[188:191], v[204:207], v[30:33]
	v_mfma_f32_16x16x32_bf16 v[30:33], v[192:195], v[208:211], v[30:33]
	v_mfma_f32_16x16x32_bf16 v[22:25], v[180:183], v[212:215], v[22:25]
	v_mfma_f32_16x16x32_bf16 v[22:25], v[184:187], v[216:219], v[22:25]
	v_mfma_f32_16x16x32_bf16 v[14:17], v[188:191], v[212:215], v[14:17]
	v_mfma_f32_16x16x32_bf16 v[14:17], v[192:195], v[216:219], v[14:17]
	v_mfma_f32_16x16x32_bf16 v[6:9], v[180:183], v[220:223], v[6:9]
	v_mfma_f32_16x16x32_bf16 v[6:9], v[184:187], v[224:227], v[6:9]
	v_mfma_f32_16x16x32_bf16 v[2:5], v[188:191], v[220:223], v[2:5]
	v_mfma_f32_16x16x32_bf16 v[2:5], v[192:195], v[224:227], v[2:5]
	s_barrier
; #define PG8_KSETUP() const bool last = (t == nt - 2); const char* a1 = cA + (size_t)(t + 1) * kstep; \
;             const char* a2 = last ? nA : cA + (size_t)(t + 2) * kstep; const char* b2 = last ? nB : cB + (size_t)(t + 2) * kstep; const char* a3 = a2 + kstep; const char* b3 = b2 + kstep; \
;             if (last && has_next) S.a_ready(nxt)
; template <class Epi, class Sched, bool ALIGN_EPI = false, bool SP2 = false>
; __device__ __forceinline__ void gemm_phase(PG8_LAS unsigned char* lds, const Gemm g, const Sched& S, const Epi& E) {
;     ...
;         int t0 = 0;
;         if constexpr (SP2 && Epi::NVM == 16) { if (ui > 0) { const int t = 0; PG8_KSETUP(); PG8_KITER_SP2(24, 24); t0 = 2; } }
;         if constexpr (SP2 && Epi::NVM == 8) { if (ui > 0) { const int t = 0; PG8_KSETUP(); PG8_KITER_SP2(16, 16); t0 = 2; } }
;         for (int t = t0; t < nt; t += 2) {
;             PG8_KSETUP();
;             if constexpr (SP2) {
;             PG8_KITER_SP2(8, 8);
	s_setprio 0
	ds_read_b128 v[160:163], v165
	ds_read_b128 v[168:171], v165 offset:1024
	ds_read_b128 v[172:175], v165 offset:2048
	ds_read_b128 v[176:179], v165 offset:3072
	ds_read_b128 v[180:183], v166
	ds_read_b128 v[184:187], v166 offset:1024
	ds_read_b128 v[188:191], v166 offset:2048
	ds_read_b128 v[192:195], v166 offset:3072
	ds_read_b128 v[196:199], v164 offset:32768
	ds_read_b128 v[200:203], v164 offset:33792
	ds_read_b128 v[204:207], v164 offset:34816
	ds_read_b128 v[208:211], v164 offset:35840
	ds_read_b128 v[212:215], v164 offset:36864
	ds_read_b128 v[216:219], v164 offset:37888
	ds_read_b128 v[220:223], v164 offset:38912
	ds_read_b128 v[224:227], v164 offset:39936
	s_add_u32 s30, s56, 0x80000
	s_addc_u32 s31, s57, 0
	s_mov_b32 m0, s69
	s_nop 0
	global_load_lds_dwordx4 v1, s[30:31] offset:0
	s_nop 0
	s_mov_b32 m0, s70
	s_nop 0
	global_load_lds_dwordx4 v139, s[30:31] offset:0
	s_waitcnt vmcnt(8)
	s_waitcnt lgkmcnt(0)
	s_barrier
	s_setprio 1
	v_mfma_f32_16x16x32_bf16 v[126:129], v[160:163], v[196:199], v[126:129]
	v_mfma_f32_16x16x32_bf16 v[126:129], v[168:171], v[200:203], v[126:129]
	v_mfma_f32_16x16x32_bf16 v[122:125], v[172:175], v[196:199], v[122:125]
	v_mfma_f32_16x16x32_bf16 v[122:125], v[176:179], v[200:203], v[122:125]
	v_mfma_f32_16x16x32_bf16 v[114:117], v[160:163], v[204:207], v[114:117]
	v_mfma_f32_16x16x32_bf16 v[114:117], v[168:171], v[208:211], v[114:117]
	v_mfma_f32_16x16x32_bf16 v[106:109], v[172:175], v[204:207], v[106:109]
	v_mfma_f32_16x16x32_bf16 v[106:109], v[176:179], v[208:211], v[106:109]
	v_mfma_f32_16x16x32_bf16 v[98:101], v[160:163], v[212:215], v[98:101]
	v_mfma_f32_16x16x32_bf16 v[98:101], v[168:171], v[216:219], v[98:101]
	v_mfma_f32_16x16x32_bf16 v[90:93], v[172:175], v[212:215], v[90:93]
	v_mfma_f32_16x16x32_bf16 v[90:93], v[176:179], v[216:219], v[90:93]
	v_mfma_f32_16x16x32_bf16 v[82:85], v[160:163], v[220:223], v[82:85]
	v_mfma_f32_16x16x32_bf16 v[82:85], v[168:171], v[224:227], v[82:85]
	v_mfma_f32_16x16x32_bf16 v[74:77], v[172:175], v[220:223], v[74:77]
	v_mfma_f32_16x16x32_bf16 v[74:77], v[176:179], v[224:227], v[74:77]
	s_setprio 0
	s_setprio 1
	v_mfma_f32_16x16x32_bf16 v[118:121], v[180:183], v[196:199], v[118:121]
	v_mfma_f32_16x16x32_bf16 v[118:121], v[184:187], v[200:203], v[118:121]
	v_mfma_f32_16x16x32_bf16 v[110:113], v[188:191], v[196:199], v[110:113]
	v_mfma_f32_16x16x32_bf16 v[110:113], v[192:195], v[200:203], v[110:113]
	v_mfma_f32_16x16x32_bf16 v[102:105], v[180:183], v[204:207], v[102:105]
	v_mfma_f32_16x16x32_bf16 v[102:105], v[184:187], v[208:211], v[102:105]
	v_mfma_f32_16x16x32_bf16 v[94:97], v[188:191], v[204:207], v[94:97]
	v_mfma_f32_16x16x32_bf16 v[94:97], v[192:195], v[208:211], v[94:97]
	v_mfma_f32_16x16x32_bf16 v[86:89], v[180:183], v[212:215], v[86:89]
	v_mfma_f32_16x16x32_bf16 v[86:89], v[184:187], v[216:219], v[86:89]
	v_mfma_f32_16x16x32_bf16 v[78:81], v[188:191], v[212:215], v[78:81]
	v_mfma_f32_16x16x32_bf16 v[78:81], v[192:195], v[216:219], v[78:81]
	v_mfma_f32_16x16x32_bf16 v[70:73], v[180:183], v[220:223], v[70:73]
	v_mfma_f32_16x16x32_bf16 v[70:73], v[184:187], v[224:227], v[70:73]
	v_mfma_f32_16x16x32_bf16 v[66:69], v[188:191], v[220:223], v[66:69]
	v_mfma_f32_16x16x32_bf16 v[66:69], v[192:195], v[224:227], v[66:69]
	s_barrier
	s_setprio 0
	ds_read_b128 v[196:199], v164 offset:49152
	ds_read_b128 v[200:203], v164 offset:50176
	ds_read_b128 v[204:207], v164 offset:51200
	ds_read_b128 v[208:211], v164 offset:52224
	ds_read_b128 v[212:215], v164 offset:53248
	ds_read_b128 v[216:219], v164 offset:54272
	ds_read_b128 v[220:223], v164 offset:55296
	ds_read_b128 v[224:227], v164 offset:56320
	s_add_u32 s30, s54, 0x80
	s_addc_u32 s31, s55, 0
	s_mov_b32 m0, s72
	s_nop 0
	global_load_lds_dwordx4 v137, s[30:31] offset:0
	s_nop 0
	s_mov_b32 m0, s73
	s_nop 0
	global_load_lds_dwordx4 v141, s[30:31] offset:0
	s_add_u32 s30, s54, 0x80080
	s_addc_u32 s31, s55, 0
	s_mov_b32 m0, s76
	s_nop 0
	global_load_lds_dwordx4 v137, s[30:31] offset:0
	s_nop 0
	s_mov_b32 m0, s77
	s_nop 0
	global_load_lds_dwordx4 v141, s[30:31] offset:0
	s_nop 0
	s_mov_b32 m0, s74
	s_nop 0
	global_load_lds_dwordx4 v1, s[46:47] offset:0
	s_nop 0
	s_mov_b32 m0, s75
	s_nop 0
	global_load_lds_dwordx4 v139, s[46:47] offset:0
	s_waitcnt vmcnt(8)
	s_waitcnt lgkmcnt(0)
	s_barrier
	s_setprio 1
	v_mfma_f32_16x16x32_bf16 v[62:65], v[160:163], v[196:199], v[62:65]
	v_mfma_f32_16x16x32_bf16 v[62:65], v[168:171], v[200:203], v[62:65]
	v_mfma_f32_16x16x32_bf16 v[58:61], v[172:175], v[196:199], v[58:61]
	v_mfma_f32_16x16x32_bf16 v[58:61], v[176:179], v[200:203], v[58:61]
	v_mfma_f32_16x16x32_bf16 v[50:53], v[160:163], v[204:207], v[50:53]
	v_mfma_f32_16x16x32_bf16 v[50:53], v[168:171], v[208:211], v[50:53]
	v_mfma_f32_16x16x32_bf16 v[42:45], v[172:175], v[204:207], v[42:45]
	v_mfma_f32_16x16x32_bf16 v[42:45], v[176:179], v[208:211], v[42:45]
	v_mfma_f32_16x16x32_bf16 v[34:37], v[160:163], v[212:215], v[34:37]
	v_mfma_f32_16x16x32_bf16 v[34:37], v[168:171], v[216:219], v[34:37]
	v_mfma_f32_16x16x32_bf16 v[26:29], v[172:175], v[212:215], v[26:29]
	v_mfma_f32_16x16x32_bf16 v[26:29], v[176:179], v[216:219], v[26:29]
	v_mfma_f32_16x16x32_bf16 v[18:21], v[160:163], v[220:223], v[18:21]
	v_mfma_f32_16x16x32_bf16 v[18:21], v[168:171], v[224:227], v[18:21]
	v_mfma_f32_16x16x32_bf16 v[10:13], v[172:175], v[220:223], v[10:13]
	v_mfma_f32_16x16x32_bf16 v[10:13], v[176:179], v[224:227], v[10:13]
	s_setprio 0
	s_setprio 1
	v_mfma_f32_16x16x32_bf16 v[54:57], v[180:183], v[196:199], v[54:57]
	v_mfma_f32_16x16x32_bf16 v[54:57], v[184:187], v[200:203], v[54:57]
	v_mfma_f32_16x16x32_bf16 v[46:49], v[188:191], v[196:199], v[46:49]
	v_mfma_f32_16x16x32_bf16 v[46:49], v[192:195], v[200:203], v[46:49]
	v_mfma_f32_16x16x32_bf16 v[38:41], v[180:183], v[204:207], v[38:41]
	v_mfma_f32_16x16x32_bf16 v[38:41], v[184:187], v[208:211], v[38:41]
	v_mfma_f32_16x16x32_bf16 v[30:33], v[188:191], v[204:207], v[30:33]
	v_mfma_f32_16x16x32_bf16 v[30:33], v[192:195], v[208:211], v[30:33]
	v_mfma_f32_16x16x32_bf16 v[22:25], v[180:183], v[212:215], v[22:25]
	v_mfma_f32_16x16x32_bf16 v[22:25], v[184:187], v[216:219], v[22:25]
	v_mfma_f32_16x16x32_bf16 v[14:17], v[188:191], v[212:215], v[14:17]
	v_mfma_f32_16x16x32_bf16 v[14:17], v[192:195], v[216:219], v[14:17]
	v_mfma_f32_16x16x32_bf16 v[6:9], v[180:183], v[220:223], v[6:9]
	v_mfma_f32_16x16x32_bf16 v[6:9], v[184:187], v[224:227], v[6:9]
	v_mfma_f32_16x16x32_bf16 v[2:5], v[188:191], v[220:223], v[2:5]
	v_mfma_f32_16x16x32_bf16 v[2:5], v[192:195], v[224:227], v[2:5]
	s_barrier
	s_setprio 0
	s_add_i32 s91, s91, 2
	s_add_u32 s87, s87, 0x100
	s_addc_u32 s88, s88, 0
	s_add_u32 s89, s89, 0x100
	s_addc_u32 s90, s90, 0
	s_cmp_gt_u32 s91, 29
	s_cbranch_scc0 .LBB0_2536
	s_and_b64 vcc, exec, s[18:19]
	s_cbranch_vccz .LBB0_2539
	s_barrier

; #define PG8_KSETUP() const bool last = (t == nt - 2); const char* a1 = cA + (size_t)(t + 1) * kstep; \
;             const char* a2 = last ? nA : cA + (size_t)(t + 2) * kstep; const char* b2 = last ? nB : cB + (size_t)(t + 2) * kstep; const char* a3 = a2 + kstep; const char* b3 = b2 + kstep; \
;             if (last && has_next) S.a_ready(nxt)
; template <class Epi, class Sched, bool ALIGN_EPI = false, bool SP2 = false>
; __device__ __forceinline__ void gemm_phase(PG8_LAS unsigned char* lds, const Gemm g, const Sched& S, const Epi& E) {
;     ...
;         int t0 = 0;
;         if constexpr (SP2 && Epi::NVM == 16) { if (ui > 0) { const int t = 0; PG8_KSETUP(); PG8_KITER_SP2(24, 24); t0 = 2; } }
.LBB0_2710:
	s_cmp_eq_u32 s29, 0
	s_mov_b32 s56, 0
	s_cbranch_scc1 .LBB0_2712
	ds_read_b128 v[4:7], v147
	ds_read_b128 v[8:11], v147 offset:1024
	ds_read_b128 v[12:15], v147 offset:2048
	ds_read_b128 v[16:19], v147 offset:3072
	ds_read_b128 v[20:23], v148
	ds_read_b128 v[24:27], v148 offset:1024
	ds_read_b128 v[28:31], v148 offset:2048
	ds_read_b128 v[32:35], v148 offset:3072
	s_add_u32 s40, s46, 0x100
	s_addc_u32 s41, s47, 0
	s_add_u32 s30, s54, 0x100
	s_addc_u32 s31, s55, 0
	s_add_u32 s38, s46, 0x180
	s_addc_u32 s39, s47, 0
	ds_read_b128 v[36:39], v149
	ds_read_b128 v[40:43], v149 offset:1024
	ds_read_b128 v[44:47], v149 offset:2048
	ds_read_b128 v[48:51], v149 offset:3072
	ds_read_b128 v[52:55], v149 offset:4096
	ds_read_b128 v[56:59], v149 offset:5120
	ds_read_b128 v[60:63], v149 offset:6144
	ds_read_b128 v[64:67], v149 offset:7168
	s_add_u32 s48, s46, 0x80080
	s_addc_u32 s49, s47, 0
	s_mov_b32 m0, s77
	s_nop 0
	global_load_lds_dwordx4 v1, s[48:49] offset:0
	s_nop 0
	s_mov_b32 m0, s78
	s_nop 0
	global_load_lds_dwordx4 v143, s[48:49] offset:0
	s_waitcnt vmcnt(24)
	s_waitcnt lgkmcnt(0)
	s_barrier
	s_setprio 1
	v_mfma_f32_16x16x32_bf16 v[92:95], v[4:7], v[60:63], 0
	v_mfma_f32_16x16x32_bf16 v[68:71], v[4:7], v[36:39], 0
	v_mfma_f32_16x16x32_bf16 v[72:75], v[12:15], v[36:39], 0
	v_mfma_f32_16x16x32_bf16 v[76:79], v[4:7], v[44:47], 0
	v_mfma_f32_16x16x32_bf16 v[80:83], v[12:15], v[44:47], 0
	v_mfma_f32_16x16x32_bf16 v[84:87], v[4:7], v[52:55], 0
	v_mfma_f32_16x16x32_bf16 v[88:91], v[12:15], v[52:55], 0
	v_mfma_f32_16x16x32_bf16 v[102:105], v[8:11], v[64:67], v[92:95]
	v_mfma_f32_16x16x32_bf16 v[92:95], v[12:15], v[60:63], 0
	v_mfma_f32_16x16x32_bf16 v[68:71], v[8:11], v[40:43], v[68:71]
	v_mfma_f32_16x16x32_bf16 v[72:75], v[16:19], v[40:43], v[72:75]
	v_mfma_f32_16x16x32_bf16 v[76:79], v[8:11], v[48:51], v[76:79]
	v_mfma_f32_16x16x32_bf16 v[80:83], v[16:19], v[48:51], v[80:83]
	v_mfma_f32_16x16x32_bf16 v[84:87], v[8:11], v[56:59], v[84:87]
	v_mfma_f32_16x16x32_bf16 v[88:91], v[16:19], v[56:59], v[88:91]
	v_mfma_f32_16x16x32_bf16 v[106:109], v[16:19], v[64:67], v[92:95]
	s_setprio 0
	s_setprio 1
	v_mfma_f32_16x16x32_bf16 v[92:95], v[20:23], v[36:39], 0
	v_mfma_f32_16x16x32_bf16 v[36:39], v[28:31], v[36:39], 0
	v_mfma_f32_16x16x32_bf16 v[118:121], v[24:27], v[40:43], v[92:95]
	v_mfma_f32_16x16x32_bf16 v[36:39], v[32:35], v[40:43], v[36:39]
	v_mfma_f32_16x16x32_bf16 v[40:43], v[20:23], v[44:47], 0
	v_mfma_f32_16x16x32_bf16 v[44:47], v[28:31], v[44:47], 0
	v_mfma_f32_16x16x32_bf16 v[40:43], v[24:27], v[48:51], v[40:43]
	v_mfma_f32_16x16x32_bf16 v[44:47], v[32:35], v[48:51], v[44:47]
	v_mfma_f32_16x16x32_bf16 v[48:51], v[20:23], v[52:55], 0
	v_mfma_f32_16x16x32_bf16 v[52:55], v[28:31], v[52:55], 0
	v_mfma_f32_16x16x32_bf16 v[48:51], v[24:27], v[56:59], v[48:51]
	v_mfma_f32_16x16x32_bf16 v[52:55], v[32:35], v[56:59], v[52:55]
	v_mfma_f32_16x16x32_bf16 v[56:59], v[20:23], v[60:63], 0
	v_mfma_f32_16x16x32_bf16 v[60:63], v[28:31], v[60:63], 0
	v_mfma_f32_16x16x32_bf16 v[56:59], v[24:27], v[64:67], v[56:59]
	v_mfma_f32_16x16x32_bf16 v[60:63], v[32:35], v[64:67], v[60:63]
	s_barrier
	s_setprio 0
	ds_read_b128 v[64:67], v149 offset:16384
	ds_read_b128 v[92:95], v149 offset:17408
	ds_read_b128 v[96:99], v149 offset:18432
	ds_read_b128 v[110:113], v149 offset:19456
	ds_read_b128 v[114:117], v149 offset:20480
	ds_read_b128 v[122:125], v149 offset:21504
	ds_read_b128 v[126:129], v149 offset:22528
	ds_read_b128 v[130:133], v149 offset:23552
	s_mov_b32 m0, s45
	s_nop 0
	global_load_lds_dwordx4 v142, s[30:31] offset:0
	s_nop 0
	s_mov_b32 m0, s52
	s_nop 0
	global_load_lds_dwordx4 v144, s[30:31] offset:0
	s_add_u32 s30, s54, 0x80100
	s_addc_u32 s31, s55, 0
	s_mov_b32 m0, s53
	s_nop 0
	global_load_lds_dwordx4 v142, s[30:31] offset:0
	s_nop 0
	s_mov_b32 m0, s64
	s_nop 0
	global_load_lds_dwordx4 v144, s[30:31] offset:0
	s_nop 0
	s_mov_b32 m0, s33
	s_nop 0
	global_load_lds_dwordx4 v1, s[40:41] offset:0
	s_nop 0
	s_mov_b32 m0, s65
	s_nop 0
	global_load_lds_dwordx4 v143, s[40:41] offset:0
	s_waitcnt vmcnt(24)
	s_waitcnt lgkmcnt(0)
	s_barrier
	s_setprio 1
	v_mfma_f32_16x16x32_bf16 v[138:141], v[4:7], v[64:67], 0
	v_mfma_f32_16x16x32_bf16 v[156:159], v[4:7], v[96:99], 0
	v_mfma_f32_16x16x32_bf16 v[164:167], v[4:7], v[114:117], 0
	v_mfma_f32_16x16x32_bf16 v[4:7], v[4:7], v[126:129], 0
	v_mfma_f32_16x16x32_bf16 v[138:141], v[8:11], v[92:95], v[138:141]
	v_mfma_f32_16x16x32_bf16 v[156:159], v[8:11], v[110:113], v[156:159]
	v_mfma_f32_16x16x32_bf16 v[164:167], v[8:11], v[122:125], v[164:167]
	v_mfma_f32_16x16x32_bf16 v[4:7], v[8:11], v[130:133], v[4:7]
	v_mfma_f32_16x16x32_bf16 v[8:11], v[12:15], v[126:129], 0
	v_mfma_f32_16x16x32_bf16 v[152:155], v[12:15], v[64:67], 0
	v_mfma_f32_16x16x32_bf16 v[160:163], v[12:15], v[96:99], 0
	v_mfma_f32_16x16x32_bf16 v[168:171], v[12:15], v[114:117], 0
	v_mfma_f32_16x16x32_bf16 v[8:11], v[16:19], v[130:133], v[8:11]
	v_mfma_f32_16x16x32_bf16 v[152:155], v[16:19], v[92:95], v[152:155]
	v_mfma_f32_16x16x32_bf16 v[160:163], v[16:19], v[110:113], v[160:163]
	v_mfma_f32_16x16x32_bf16 v[168:171], v[16:19], v[122:125], v[168:171]
	s_setprio 0
	s_setprio 1
	v_mfma_f32_16x16x32_bf16 v[12:15], v[20:23], v[64:67], 0
	v_mfma_f32_16x16x32_bf16 v[172:175], v[24:27], v[92:95], v[12:15]
	v_mfma_f32_16x16x32_bf16 v[12:15], v[28:31], v[64:67], 0
	v_mfma_f32_16x16x32_bf16 v[176:179], v[32:35], v[92:95], v[12:15]
	v_mfma_f32_16x16x32_bf16 v[12:15], v[20:23], v[96:99], 0
	v_mfma_f32_16x16x32_bf16 v[180:183], v[24:27], v[110:113], v[12:15]
	v_mfma_f32_16x16x32_bf16 v[12:15], v[28:31], v[96:99], 0
	v_mfma_f32_16x16x32_bf16 v[184:187], v[32:35], v[110:113], v[12:15]
	v_mfma_f32_16x16x32_bf16 v[12:15], v[20:23], v[114:117], 0
	v_mfma_f32_16x16x32_bf16 v[188:191], v[24:27], v[122:125], v[12:15]
	v_mfma_f32_16x16x32_bf16 v[12:15], v[28:31], v[114:117], 0
	v_mfma_f32_16x16x32_bf16 v[192:195], v[32:35], v[122:125], v[12:15]
	v_mfma_f32_16x16x32_bf16 v[12:15], v[20:23], v[126:129], 0
	v_mfma_f32_16x16x32_bf16 v[196:199], v[24:27], v[130:133], v[12:15]
	v_mfma_f32_16x16x32_bf16 v[12:15], v[28:31], v[126:129], 0
	v_mfma_f32_16x16x32_bf16 v[200:203], v[32:35], v[130:133], v[12:15]
	s_barrier
; #define PG8_KSETUP() const bool last = (t == nt - 2); const char* a1 = cA + (size_t)(t + 1) * kstep; \
;             const char* a2 = last ? nA : cA + (size_t)(t + 2) * kstep; const char* b2 = last ? nB : cB + (size_t)(t + 2) * kstep; const char* a3 = a2 + kstep; const char* b3 = b2 + kstep; \
;             if (last && has_next) S.a_ready(nxt)
; template <class Epi, class Sched, bool ALIGN_EPI = false, bool SP2 = false>
; __device__ __forceinline__ void gemm_phase(PG8_LAS unsigned char* lds, const Gemm g, const Sched& S, const Epi& E) {
;     ...
;         int t0 = 0;
;         if constexpr (SP2 && Epi::NVM == 16) { if (ui > 0) { const int t = 0; PG8_KSETUP(); PG8_KITER_SP2(24, 24); t0 = 2; } }
	s_setprio 0
	s_nop 4
	ds_read_b128 v[12:15], v150
	ds_read_b128 v[16:19], v150 offset:1024
	ds_read_b128 v[22:25], v150 offset:2048
	ds_read_b128 v[26:29], v150 offset:3072
	ds_read_b128 v[204:207], v151
	ds_read_b128 v[208:211], v151 offset:1024
	ds_read_b128 v[212:215], v151 offset:2048
	ds_read_b128 v[216:219], v151 offset:3072
	ds_read_b128 v[30:33], v149 offset:32768
	ds_read_b128 v[64:67], v149 offset:33792
	ds_read_b128 v[220:223], v149 offset:34816
	ds_read_b128 v[224:227], v149 offset:35840
	ds_read_b128 v[228:231], v149 offset:36864
	ds_read_b128 v[232:235], v149 offset:37888
	ds_read_b128 v[236:239], v149 offset:38912
	ds_read_b128 v[240:243], v149 offset:39936
	s_add_u32 s30, s46, 0x80100
	s_addc_u32 s31, s47, 0
	s_mov_b32 m0, s66
	s_nop 0
	global_load_lds_dwordx4 v1, s[30:31] offset:0
	s_nop 0
	s_mov_b32 m0, s67
	s_nop 0
	global_load_lds_dwordx4 v143, s[30:31] offset:0
	s_waitcnt vmcnt(8)
	s_waitcnt lgkmcnt(0)
	s_barrier
	s_setprio 1
	v_mfma_f32_16x16x32_bf16 v[68:71], v[12:15], v[30:33], v[68:71]
	v_mfma_f32_16x16x32_bf16 v[130:133], v[16:19], v[64:67], v[68:71]
	v_mfma_f32_16x16x32_bf16 v[68:71], v[22:25], v[30:33], v[72:75]
	v_mfma_f32_16x16x32_bf16 v[126:129], v[26:29], v[64:67], v[68:71]
	v_mfma_f32_16x16x32_bf16 v[68:71], v[12:15], v[220:223], v[76:79]
	v_mfma_f32_16x16x32_bf16 v[114:117], v[16:19], v[224:227], v[68:71]
	v_mfma_f32_16x16x32_bf16 v[68:71], v[22:25], v[220:223], v[80:83]
	v_mfma_f32_16x16x32_bf16 v[110:113], v[26:29], v[224:227], v[68:71]
	v_mfma_f32_16x16x32_bf16 v[68:71], v[12:15], v[228:231], v[84:87]
	v_mfma_f32_16x16x32_bf16 v[98:101], v[16:19], v[232:235], v[68:71]
	v_mfma_f32_16x16x32_bf16 v[68:71], v[22:25], v[228:231], v[88:91]
	v_mfma_f32_16x16x32_bf16 v[94:97], v[26:29], v[232:235], v[68:71]
	v_mfma_f32_16x16x32_bf16 v[68:71], v[12:15], v[236:239], v[102:105]
	v_mfma_f32_16x16x32_bf16 v[82:85], v[16:19], v[240:243], v[68:71]
	v_mfma_f32_16x16x32_bf16 v[68:71], v[22:25], v[236:239], v[106:109]
	v_mfma_f32_16x16x32_bf16 v[78:81], v[26:29], v[240:243], v[68:71]
	s_setprio 0
	s_setprio 1
	v_mfma_f32_16x16x32_bf16 v[68:71], v[204:207], v[30:33], v[118:121]
	v_mfma_f32_16x16x32_bf16 v[30:33], v[212:215], v[30:33], v[36:39]
	v_mfma_f32_16x16x32_bf16 v[118:121], v[216:219], v[64:67], v[30:33]
	v_mfma_f32_16x16x32_bf16 v[30:33], v[204:207], v[220:223], v[40:43]
	v_mfma_f32_16x16x32_bf16 v[106:109], v[208:211], v[224:227], v[30:33]
	v_mfma_f32_16x16x32_bf16 v[30:33], v[212:215], v[220:223], v[44:47]
	v_mfma_f32_16x16x32_bf16 v[102:105], v[216:219], v[224:227], v[30:33]
	v_mfma_f32_16x16x32_bf16 v[30:33], v[204:207], v[228:231], v[48:51]
	v_mfma_f32_16x16x32_bf16 v[90:93], v[208:211], v[232:235], v[30:33]
	v_mfma_f32_16x16x32_bf16 v[30:33], v[212:215], v[228:231], v[52:55]
	v_mfma_f32_16x16x32_bf16 v[86:89], v[216:219], v[232:235], v[30:33]
	v_mfma_f32_16x16x32_bf16 v[30:33], v[204:207], v[236:239], v[56:59]
	v_mfma_f32_16x16x32_bf16 v[74:77], v[208:211], v[240:243], v[30:33]
	v_mfma_f32_16x16x32_bf16 v[30:33], v[212:215], v[236:239], v[60:63]
	v_mfma_f32_16x16x32_bf16 v[122:125], v[208:211], v[64:67], v[68:71]
	v_mfma_f32_16x16x32_bf16 v[70:73], v[216:219], v[240:243], v[30:33]
	s_barrier
	s_setprio 0
	ds_read_b128 v[38:41], v149 offset:49152
	ds_read_b128 v[42:45], v149 offset:50176
	ds_read_b128 v[220:223], v149 offset:51200
	ds_read_b128 v[224:227], v149 offset:52224
	ds_read_b128 v[228:231], v149 offset:53248
	ds_read_b128 v[232:235], v149 offset:54272
	ds_read_b128 v[236:239], v149 offset:55296
	ds_read_b128 v[240:243], v149 offset:56320
	s_add_u32 s30, s54, 0x180
	s_addc_u32 s31, s55, 0
	s_mov_b32 m0, s71
	s_nop 0
	global_load_lds_dwordx4 v142, s[30:31] offset:0
	s_nop 0
	s_mov_b32 m0, s72
	s_nop 0
	global_load_lds_dwordx4 v144, s[30:31] offset:0
	s_add_u32 s30, s54, 0x80180
	s_addc_u32 s31, s55, 0
	s_mov_b32 m0, s75
	s_nop 0
	global_load_lds_dwordx4 v142, s[30:31] offset:0
	s_nop 0
	s_mov_b32 m0, s76
	s_nop 0
	global_load_lds_dwordx4 v144, s[30:31] offset:0
	s_nop 0
	s_mov_b32 m0, s73
	s_nop 0
	global_load_lds_dwordx4 v1, s[38:39] offset:0
	s_nop 0
	s_mov_b32 m0, s74
	s_nop 0
	global_load_lds_dwordx4 v143, s[38:39] offset:0
	s_waitcnt vmcnt(8)
	s_waitcnt lgkmcnt(0)
	s_barrier
	s_setprio 1
	v_mfma_f32_16x16x32_bf16 v[30:33], v[12:15], v[38:41], v[138:141]
	v_mfma_f32_16x16x32_bf16 v[66:69], v[16:19], v[42:45], v[30:33]
	v_mfma_f32_16x16x32_bf16 v[30:33], v[22:25], v[38:41], v[152:155]
	v_mfma_f32_16x16x32_bf16 v[62:65], v[26:29], v[42:45], v[30:33]
	v_mfma_f32_16x16x32_bf16 v[30:33], v[12:15], v[220:223], v[156:159]
	v_mfma_f32_16x16x32_bf16 v[50:53], v[16:19], v[224:227], v[30:33]
	v_mfma_f32_16x16x32_bf16 v[30:33], v[22:25], v[220:223], v[160:163]
	v_mfma_f32_16x16x32_bf16 v[46:49], v[26:29], v[224:227], v[30:33]
	v_mfma_f32_16x16x32_bf16 v[30:33], v[12:15], v[228:231], v[164:167]
	v_mfma_f32_16x16x32_bf16 v[4:7], v[12:15], v[236:239], v[4:7]
	v_mfma_f32_16x16x32_bf16 v[34:37], v[16:19], v[232:235], v[30:33]
	v_mfma_f32_16x16x32_bf16 v[30:33], v[22:25], v[228:231], v[168:171]
	v_mfma_f32_16x16x32_bf16 v[18:21], v[16:19], v[240:243], v[4:7]
	v_mfma_f32_16x16x32_bf16 v[4:7], v[22:25], v[236:239], v[8:11]
	v_mfma_f32_16x16x32_bf16 v[30:33], v[26:29], v[232:235], v[30:33]
	v_mfma_f32_16x16x32_bf16 v[14:17], v[26:29], v[240:243], v[4:7]
	s_setprio 0
	s_setprio 1
	v_mfma_f32_16x16x32_bf16 v[4:7], v[204:207], v[38:41], v[172:175]
	v_mfma_f32_16x16x32_bf16 v[58:61], v[208:211], v[42:45], v[4:7]
	v_mfma_f32_16x16x32_bf16 v[4:7], v[212:215], v[38:41], v[176:179]
	v_mfma_f32_16x16x32_bf16 v[54:57], v[216:219], v[42:45], v[4:7]
	v_mfma_f32_16x16x32_bf16 v[4:7], v[204:207], v[220:223], v[180:183]
	v_mfma_f32_16x16x32_bf16 v[42:45], v[208:211], v[224:227], v[4:7]
	v_mfma_f32_16x16x32_bf16 v[4:7], v[212:215], v[220:223], v[184:187]
	v_mfma_f32_16x16x32_bf16 v[38:41], v[216:219], v[224:227], v[4:7]
	v_mfma_f32_16x16x32_bf16 v[4:7], v[204:207], v[228:231], v[188:191]
	v_mfma_f32_16x16x32_bf16 v[26:29], v[208:211], v[232:235], v[4:7]
	v_mfma_f32_16x16x32_bf16 v[4:7], v[212:215], v[228:231], v[192:195]
	v_mfma_f32_16x16x32_bf16 v[22:25], v[216:219], v[232:235], v[4:7]
	v_mfma_f32_16x16x32_bf16 v[4:7], v[204:207], v[236:239], v[196:199]
	v_mfma_f32_16x16x32_bf16 v[10:13], v[208:211], v[240:243], v[4:7]
	v_mfma_f32_16x16x32_bf16 v[4:7], v[212:215], v[236:239], v[200:203]
	v_mfma_f32_16x16x32_bf16 v[6:9], v[216:219], v[240:243], v[4:7]
	s_barrier
	s_setprio 0
	s_mov_b32 s56, 2
	s_branch .LBB0_2713

; #define PG8_KSETUP() const bool last = (t == nt - 2); const char* a1 = cA + (size_t)(t + 1) * kstep; \
;             const char* a2 = last ? nA : cA + (size_t)(t + 2) * kstep; const char* b2 = last ? nB : cB + (size_t)(t + 2) * kstep; const char* a3 = a2 + kstep; const char* b3 = b2 + kstep; \
;             if (last && has_next) S.a_ready(nxt)
; template <class Epi, class Sched, bool ALIGN_EPI = false, bool SP2 = false>
; __device__ __forceinline__ void gemm_phase(PG8_LAS unsigned char* lds, const Gemm g, const Sched& S, const Epi& E) {
;     ...
;         int t0 = 0;
;         if constexpr (SP2 && Epi::NVM == 16) { if (ui > 0) { const int t = 0; PG8_KSETUP(); PG8_KITER_SP2(24, 24); t0 = 2; } }
;         if constexpr (SP2 && Epi::NVM == 8) { if (ui > 0) { const int t = 0; PG8_KSETUP(); PG8_KITER_SP2(16, 16); t0 = 2; } }
;         for (int t = t0; t < nt; t += 2) {
;             PG8_KSETUP();
;             if constexpr (SP2) {
;             PG8_KITER_SP2(8, 8);
.LBB0_2714:
	ds_read_b128 v[138:141], v147
	ds_read_b128 v[152:155], v147 offset:1024
	ds_read_b128 v[156:159], v147 offset:2048
	ds_read_b128 v[160:163], v147 offset:3072
	ds_read_b128 v[164:167], v148
	ds_read_b128 v[168:171], v148 offset:1024
	ds_read_b128 v[172:175], v148 offset:2048
	ds_read_b128 v[176:179], v148 offset:3072
	s_cmp_eq_u32 s84, 28
	s_cselect_b32 s58, s43, s87
	s_cselect_b32 s59, s37, s88
	s_cselect_b32 s56, s83, s85
	s_cselect_b32 s57, s29, s86
	s_add_u32 s54, s58, 0x80
	s_addc_u32 s55, s59, 0
	ds_read_b128 v[180:183], v149
	ds_read_b128 v[184:187], v149 offset:1024
	ds_read_b128 v[188:191], v149 offset:2048
	ds_read_b128 v[192:195], v149 offset:3072
	ds_read_b128 v[196:199], v149 offset:4096
	ds_read_b128 v[200:203], v149 offset:5120
	ds_read_b128 v[204:207], v149 offset:6144
	ds_read_b128 v[208:211], v149 offset:7168
	s_mov_b32 m0, s77
	s_nop 0
	global_load_lds_dwordx4 v1, s[46:47] offset:0
	s_nop 0
	s_mov_b32 m0, s78
	s_nop 0
	global_load_lds_dwordx4 v143, s[46:47] offset:0
	s_waitcnt vmcnt(8)
	s_waitcnt lgkmcnt(0)
	s_barrier
	s_setprio 1
	v_mfma_f32_16x16x32_bf16 v[130:133], v[138:141], v[180:183], v[130:133]
	v_mfma_f32_16x16x32_bf16 v[130:133], v[152:155], v[184:187], v[130:133]
	v_mfma_f32_16x16x32_bf16 v[126:129], v[156:159], v[180:183], v[126:129]
	v_mfma_f32_16x16x32_bf16 v[126:129], v[160:163], v[184:187], v[126:129]
	v_mfma_f32_16x16x32_bf16 v[114:117], v[138:141], v[188:191], v[114:117]
	v_mfma_f32_16x16x32_bf16 v[114:117], v[152:155], v[192:195], v[114:117]
	v_mfma_f32_16x16x32_bf16 v[110:113], v[156:159], v[188:191], v[110:113]
	v_mfma_f32_16x16x32_bf16 v[110:113], v[160:163], v[192:195], v[110:113]
	v_mfma_f32_16x16x32_bf16 v[98:101], v[138:141], v[196:199], v[98:101]
	v_mfma_f32_16x16x32_bf16 v[98:101], v[152:155], v[200:203], v[98:101]
	v_mfma_f32_16x16x32_bf16 v[94:97], v[156:159], v[196:199], v[94:97]
	v_mfma_f32_16x16x32_bf16 v[94:97], v[160:163], v[200:203], v[94:97]
	v_mfma_f32_16x16x32_bf16 v[82:85], v[138:141], v[204:207], v[82:85]
	v_mfma_f32_16x16x32_bf16 v[82:85], v[152:155], v[208:211], v[82:85]
	v_mfma_f32_16x16x32_bf16 v[78:81], v[156:159], v[204:207], v[78:81]
	v_mfma_f32_16x16x32_bf16 v[78:81], v[160:163], v[208:211], v[78:81]
	s_setprio 0
	s_setprio 1
	v_mfma_f32_16x16x32_bf16 v[122:125], v[164:167], v[180:183], v[122:125]
	v_mfma_f32_16x16x32_bf16 v[122:125], v[168:171], v[184:187], v[122:125]
	v_mfma_f32_16x16x32_bf16 v[118:121], v[172:175], v[180:183], v[118:121]
	v_mfma_f32_16x16x32_bf16 v[118:121], v[176:179], v[184:187], v[118:121]
	v_mfma_f32_16x16x32_bf16 v[106:109], v[164:167], v[188:191], v[106:109]
	v_mfma_f32_16x16x32_bf16 v[106:109], v[168:171], v[192:195], v[106:109]
	v_mfma_f32_16x16x32_bf16 v[102:105], v[172:175], v[188:191], v[102:105]
	v_mfma_f32_16x16x32_bf16 v[102:105], v[176:179], v[192:195], v[102:105]
	v_mfma_f32_16x16x32_bf16 v[90:93], v[164:167], v[196:199], v[90:93]
	v_mfma_f32_16x16x32_bf16 v[90:93], v[168:171], v[200:203], v[90:93]
	v_mfma_f32_16x16x32_bf16 v[86:89], v[172:175], v[196:199], v[86:89]
	v_mfma_f32_16x16x32_bf16 v[86:89], v[176:179], v[200:203], v[86:89]
	v_mfma_f32_16x16x32_bf16 v[74:77], v[164:167], v[204:207], v[74:77]
	v_mfma_f32_16x16x32_bf16 v[74:77], v[168:171], v[208:211], v[74:77]
	v_mfma_f32_16x16x32_bf16 v[70:73], v[172:175], v[204:207], v[70:73]
	v_mfma_f32_16x16x32_bf16 v[70:73], v[176:179], v[208:211], v[70:73]
	s_barrier
	s_setprio 0
	ds_read_b128 v[180:183], v149 offset:16384
	ds_read_b128 v[184:187], v149 offset:17408
	ds_read_b128 v[188:191], v149 offset:18432
	ds_read_b128 v[192:195], v149 offset:19456
	ds_read_b128 v[196:199], v149 offset:20480
	ds_read_b128 v[200:203], v149 offset:21504
	ds_read_b128 v[204:207], v149 offset:22528
	ds_read_b128 v[208:211], v149 offset:23552
	s_mov_b32 m0, s45
	s_nop 0
	global_load_lds_dwordx4 v142, s[56:57] offset:0
	s_add_u32 s30, s56, 0x80000
	s_mov_b32 m0, s52
	s_nop 0
	global_load_lds_dwordx4 v144, s[56:57] offset:0
	s_addc_u32 s31, s57, 0
	s_mov_b32 m0, s53
	s_nop 0
	global_load_lds_dwordx4 v142, s[30:31] offset:0
	s_nop 0
	s_mov_b32 m0, s64
	s_nop 0
	global_load_lds_dwordx4 v144, s[30:31] offset:0
	s_nop 0
	s_mov_b32 m0, s33
	s_nop 0
	global_load_lds_dwordx4 v1, s[58:59] offset:0
	s_nop 0
	s_mov_b32 m0, s65
	s_nop 0
	global_load_lds_dwordx4 v143, s[58:59] offset:0
	s_waitcnt vmcnt(8)
	s_waitcnt lgkmcnt(0)
	s_barrier
	s_setprio 1
	v_mfma_f32_16x16x32_bf16 v[66:69], v[138:141], v[180:183], v[66:69]
	v_mfma_f32_16x16x32_bf16 v[66:69], v[152:155], v[184:187], v[66:69]
	v_mfma_f32_16x16x32_bf16 v[62:65], v[156:159], v[180:183], v[62:65]
	v_mfma_f32_16x16x32_bf16 v[62:65], v[160:163], v[184:187], v[62:65]
	v_mfma_f32_16x16x32_bf16 v[50:53], v[138:141], v[188:191], v[50:53]
	v_mfma_f32_16x16x32_bf16 v[50:53], v[152:155], v[192:195], v[50:53]
	v_mfma_f32_16x16x32_bf16 v[46:49], v[156:159], v[188:191], v[46:49]
	v_mfma_f32_16x16x32_bf16 v[46:49], v[160:163], v[192:195], v[46:49]
	v_mfma_f32_16x16x32_bf16 v[34:37], v[138:141], v[196:199], v[34:37]
	v_mfma_f32_16x16x32_bf16 v[34:37], v[152:155], v[200:203], v[34:37]
	v_mfma_f32_16x16x32_bf16 v[30:33], v[156:159], v[196:199], v[30:33]
	v_mfma_f32_16x16x32_bf16 v[30:33], v[160:163], v[200:203], v[30:33]
	v_mfma_f32_16x16x32_bf16 v[18:21], v[138:141], v[204:207], v[18:21]
	v_mfma_f32_16x16x32_bf16 v[18:21], v[152:155], v[208:211], v[18:21]
	v_mfma_f32_16x16x32_bf16 v[14:17], v[156:159], v[204:207], v[14:17]
	v_mfma_f32_16x16x32_bf16 v[14:17], v[160:163], v[208:211], v[14:17]
	s_setprio 0
	s_setprio 1
	v_mfma_f32_16x16x32_bf16 v[58:61], v[164:167], v[180:183], v[58:61]
	v_mfma_f32_16x16x32_bf16 v[54:57], v[172:175], v[180:183], v[54:57]
	v_mfma_f32_16x16x32_bf16 v[42:45], v[164:167], v[188:191], v[42:45]
	v_mfma_f32_16x16x32_bf16 v[38:41], v[172:175], v[188:191], v[38:41]
	v_mfma_f32_16x16x32_bf16 v[26:29], v[164:167], v[196:199], v[26:29]
	v_mfma_f32_16x16x32_bf16 v[22:25], v[172:175], v[196:199], v[22:25]
	v_mfma_f32_16x16x32_bf16 v[10:13], v[164:167], v[204:207], v[10:13]
	v_mfma_f32_16x16x32_bf16 v[4:7], v[172:175], v[204:207], v[6:9]
	v_mfma_f32_16x16x32_bf16 v[58:61], v[168:171], v[184:187], v[58:61]
	v_mfma_f32_16x16x32_bf16 v[54:57], v[176:179], v[184:187], v[54:57]
	v_mfma_f32_16x16x32_bf16 v[42:45], v[168:171], v[192:195], v[42:45]
	v_mfma_f32_16x16x32_bf16 v[38:41], v[176:179], v[192:195], v[38:41]
	v_mfma_f32_16x16x32_bf16 v[26:29], v[168:171], v[200:203], v[26:29]
	v_mfma_f32_16x16x32_bf16 v[22:25], v[176:179], v[200:203], v[22:25]
	v_mfma_f32_16x16x32_bf16 v[10:13], v[168:171], v[208:211], v[10:13]
	v_mfma_f32_16x16x32_bf16 v[4:7], v[176:179], v[208:211], v[4:7]
	s_barrier
; #define PG8_KSETUP() const bool last = (t == nt - 2); const char* a1 = cA + (size_t)(t + 1) * kstep; \
;             const char* a2 = last ? nA : cA + (size_t)(t + 2) * kstep; const char* b2 = last ? nB : cB + (size_t)(t + 2) * kstep; const char* a3 = a2 + kstep; const char* b3 = b2 + kstep; \
;             if (last && has_next) S.a_ready(nxt)
; template <class Epi, class Sched, bool ALIGN_EPI = false, bool SP2 = false>
; __device__ __forceinline__ void gemm_phase(PG8_LAS unsigned char* lds, const Gemm g, const Sched& S, const Epi& E) {
;     ...
;         int t0 = 0;
;         if constexpr (SP2 && Epi::NVM == 16) { if (ui > 0) { const int t = 0; PG8_KSETUP(); PG8_KITER_SP2(24, 24); t0 = 2; } }
;         if constexpr (SP2 && Epi::NVM == 8) { if (ui > 0) { const int t = 0; PG8_KSETUP(); PG8_KITER_SP2(16, 16); t0 = 2; } }
;         for (int t = t0; t < nt; t += 2) {
;             PG8_KSETUP();
;             if constexpr (SP2) {
;             PG8_KITER_SP2(8, 8);
	s_setprio 0
	ds_read_b128 v[138:141], v150
	ds_read_b128 v[152:155], v150 offset:1024
	ds_read_b128 v[156:159], v150 offset:2048
	ds_read_b128 v[160:163], v150 offset:3072
	ds_read_b128 v[164:167], v151
	ds_read_b128 v[168:171], v151 offset:1024
	ds_read_b128 v[172:175], v151 offset:2048
	ds_read_b128 v[176:179], v151 offset:3072
	ds_read_b128 v[180:183], v149 offset:32768
	ds_read_b128 v[184:187], v149 offset:33792
	ds_read_b128 v[188:191], v149 offset:34816
	ds_read_b128 v[192:195], v149 offset:35840
	ds_read_b128 v[196:199], v149 offset:36864
	ds_read_b128 v[200:203], v149 offset:37888
	ds_read_b128 v[204:207], v149 offset:38912
	ds_read_b128 v[208:211], v149 offset:39936
	s_add_u32 s30, s58, 0x80000
	s_addc_u32 s31, s59, 0
	s_mov_b32 m0, s66
	s_nop 0
	global_load_lds_dwordx4 v1, s[30:31] offset:0
	s_nop 0
	s_mov_b32 m0, s67
	s_nop 0
	global_load_lds_dwordx4 v143, s[30:31] offset:0
	s_waitcnt vmcnt(8)
	s_waitcnt lgkmcnt(0)
	s_barrier
	s_setprio 1
	v_mfma_f32_16x16x32_bf16 v[130:133], v[138:141], v[180:183], v[130:133]
	v_mfma_f32_16x16x32_bf16 v[130:133], v[152:155], v[184:187], v[130:133]
	v_mfma_f32_16x16x32_bf16 v[126:129], v[156:159], v[180:183], v[126:129]
	v_mfma_f32_16x16x32_bf16 v[126:129], v[160:163], v[184:187], v[126:129]
	v_mfma_f32_16x16x32_bf16 v[114:117], v[138:141], v[188:191], v[114:117]
	v_mfma_f32_16x16x32_bf16 v[114:117], v[152:155], v[192:195], v[114:117]
	v_mfma_f32_16x16x32_bf16 v[110:113], v[156:159], v[188:191], v[110:113]
	v_mfma_f32_16x16x32_bf16 v[110:113], v[160:163], v[192:195], v[110:113]
	v_mfma_f32_16x16x32_bf16 v[98:101], v[138:141], v[196:199], v[98:101]
	v_mfma_f32_16x16x32_bf16 v[98:101], v[152:155], v[200:203], v[98:101]
	v_mfma_f32_16x16x32_bf16 v[94:97], v[156:159], v[196:199], v[94:97]
	v_mfma_f32_16x16x32_bf16 v[94:97], v[160:163], v[200:203], v[94:97]
	v_mfma_f32_16x16x32_bf16 v[82:85], v[138:141], v[204:207], v[82:85]
	v_mfma_f32_16x16x32_bf16 v[82:85], v[152:155], v[208:211], v[82:85]
	v_mfma_f32_16x16x32_bf16 v[78:81], v[156:159], v[204:207], v[78:81]
	v_mfma_f32_16x16x32_bf16 v[78:81], v[160:163], v[208:211], v[78:81]
	s_setprio 0
	s_setprio 1
	v_mfma_f32_16x16x32_bf16 v[122:125], v[164:167], v[180:183], v[122:125]
	v_mfma_f32_16x16x32_bf16 v[122:125], v[168:171], v[184:187], v[122:125]
	v_mfma_f32_16x16x32_bf16 v[118:121], v[172:175], v[180:183], v[118:121]
	v_mfma_f32_16x16x32_bf16 v[118:121], v[176:179], v[184:187], v[118:121]
	v_mfma_f32_16x16x32_bf16 v[106:109], v[164:167], v[188:191], v[106:109]
	v_mfma_f32_16x16x32_bf16 v[106:109], v[168:171], v[192:195], v[106:109]
	v_mfma_f32_16x16x32_bf16 v[102:105], v[172:175], v[188:191], v[102:105]
	v_mfma_f32_16x16x32_bf16 v[102:105], v[176:179], v[192:195], v[102:105]
	v_mfma_f32_16x16x32_bf16 v[90:93], v[164:167], v[196:199], v[90:93]
	v_mfma_f32_16x16x32_bf16 v[90:93], v[168:171], v[200:203], v[90:93]
	v_mfma_f32_16x16x32_bf16 v[86:89], v[172:175], v[196:199], v[86:89]
	v_mfma_f32_16x16x32_bf16 v[86:89], v[176:179], v[200:203], v[86:89]
	v_mfma_f32_16x16x32_bf16 v[74:77], v[164:167], v[204:207], v[74:77]
	v_mfma_f32_16x16x32_bf16 v[74:77], v[168:171], v[208:211], v[74:77]
	v_mfma_f32_16x16x32_bf16 v[70:73], v[172:175], v[204:207], v[70:73]
	v_mfma_f32_16x16x32_bf16 v[70:73], v[176:179], v[208:211], v[70:73]
	s_barrier
	s_setprio 0
	ds_read_b128 v[180:183], v149 offset:49152
	ds_read_b128 v[184:187], v149 offset:50176
	ds_read_b128 v[188:191], v149 offset:51200
	ds_read_b128 v[192:195], v149 offset:52224
	ds_read_b128 v[196:199], v149 offset:53248
	ds_read_b128 v[200:203], v149 offset:54272
	ds_read_b128 v[204:207], v149 offset:55296
	ds_read_b128 v[208:211], v149 offset:56320
	s_add_u32 s30, s56, 0x80
	s_addc_u32 s31, s57, 0
	s_mov_b32 m0, s71
	s_nop 0
	global_load_lds_dwordx4 v142, s[30:31] offset:0
	s_nop 0
	s_mov_b32 m0, s72
	s_nop 0
	global_load_lds_dwordx4 v144, s[30:31] offset:0
	s_add_u32 s30, s56, 0x80080
	s_addc_u32 s31, s57, 0
	s_mov_b32 m0, s75
	s_nop 0
	global_load_lds_dwordx4 v142, s[30:31] offset:0
	s_nop 0
	s_mov_b32 m0, s76
	s_nop 0
	global_load_lds_dwordx4 v144, s[30:31] offset:0
	s_nop 0
	s_mov_b32 m0, s73
	s_nop 0
	global_load_lds_dwordx4 v1, s[54:55] offset:0
	s_nop 0
	s_mov_b32 m0, s74
	s_nop 0
	global_load_lds_dwordx4 v143, s[54:55] offset:0
	s_waitcnt vmcnt(8)
	s_waitcnt lgkmcnt(0)
	s_barrier
	s_setprio 1
	v_mfma_f32_16x16x32_bf16 v[66:69], v[138:141], v[180:183], v[66:69]
	v_mfma_f32_16x16x32_bf16 v[66:69], v[152:155], v[184:187], v[66:69]
	v_mfma_f32_16x16x32_bf16 v[62:65], v[156:159], v[180:183], v[62:65]
	v_mfma_f32_16x16x32_bf16 v[62:65], v[160:163], v[184:187], v[62:65]
	v_mfma_f32_16x16x32_bf16 v[50:53], v[138:141], v[188:191], v[50:53]
	v_mfma_f32_16x16x32_bf16 v[50:53], v[152:155], v[192:195], v[50:53]
	v_mfma_f32_16x16x32_bf16 v[46:49], v[156:159], v[188:191], v[46:49]
	v_mfma_f32_16x16x32_bf16 v[46:49], v[160:163], v[192:195], v[46:49]
	v_mfma_f32_16x16x32_bf16 v[34:37], v[138:141], v[196:199], v[34:37]
	v_mfma_f32_16x16x32_bf16 v[34:37], v[152:155], v[200:203], v[34:37]
	v_mfma_f32_16x16x32_bf16 v[30:33], v[156:159], v[196:199], v[30:33]
	v_mfma_f32_16x16x32_bf16 v[30:33], v[160:163], v[200:203], v[30:33]
	v_mfma_f32_16x16x32_bf16 v[18:21], v[138:141], v[204:207], v[18:21]
	v_mfma_f32_16x16x32_bf16 v[18:21], v[152:155], v[208:211], v[18:21]
	v_mfma_f32_16x16x32_bf16 v[14:17], v[156:159], v[204:207], v[14:17]
	v_mfma_f32_16x16x32_bf16 v[14:17], v[160:163], v[208:211], v[14:17]
	s_setprio 0
	s_setprio 1
	v_mfma_f32_16x16x32_bf16 v[58:61], v[164:167], v[180:183], v[58:61]
	v_mfma_f32_16x16x32_bf16 v[54:57], v[172:175], v[180:183], v[54:57]
	v_mfma_f32_16x16x32_bf16 v[42:45], v[164:167], v[188:191], v[42:45]
	v_mfma_f32_16x16x32_bf16 v[38:41], v[172:175], v[188:191], v[38:41]
	v_mfma_f32_16x16x32_bf16 v[26:29], v[164:167], v[196:199], v[26:29]
	v_mfma_f32_16x16x32_bf16 v[22:25], v[172:175], v[196:199], v[22:25]
	v_mfma_f32_16x16x32_bf16 v[8:11], v[164:167], v[204:207], v[10:13]
	v_mfma_f32_16x16x32_bf16 v[4:7], v[172:175], v[204:207], v[4:7]
	v_mfma_f32_16x16x32_bf16 v[58:61], v[168:171], v[184:187], v[58:61]
	v_mfma_f32_16x16x32_bf16 v[54:57], v[176:179], v[184:187], v[54:57]
	v_mfma_f32_16x16x32_bf16 v[42:45], v[168:171], v[192:195], v[42:45]
	v_mfma_f32_16x16x32_bf16 v[38:41], v[176:179], v[192:195], v[38:41]
	v_mfma_f32_16x16x32_bf16 v[26:29], v[168:171], v[200:203], v[26:29]
	v_mfma_f32_16x16x32_bf16 v[22:25], v[176:179], v[200:203], v[22:25]
	v_mfma_f32_16x16x32_bf16 v[10:13], v[168:171], v[208:211], v[8:11]
	v_mfma_f32_16x16x32_bf16 v[6:9], v[176:179], v[208:211], v[4:7]
	s_barrier
	s_setprio 0
	s_add_i32 s84, s84, 2
	s_add_u32 s85, s85, 0x100
	s_addc_u32 s86, s86, 0
	s_add_u32 s87, s87, 0x100
	s_addc_u32 s88, s88, 0
	s_add_u32 s46, s46, 0x100
	s_addc_u32 s47, s47, 0
	s_cmp_gt_u32 s84, 29
	s_cbranch_scc0 .LBB0_2714
	s_and_b64 vcc, exec, s[18:19]
	s_cbranch_vccz .LBB0_2717
	s_barrier

; #define PG8_KSETUP() const bool last = (t == nt - 2); const char* a1 = cA + (size_t)(t + 1) * kstep; \
;             const char* a2 = last ? nA : cA + (size_t)(t + 2) * kstep; const char* b2 = last ? nB : cB + (size_t)(t + 2) * kstep; const char* a3 = a2 + kstep; const char* b3 = b2 + kstep; \
;             if (last && has_next) S.a_ready(nxt)
; template <class Epi, class Sched, bool ALIGN_EPI = false, bool SP2 = false>
; __device__ __forceinline__ void gemm_phase(PG8_LAS unsigned char* lds, const Gemm g, const Sched& S, const Epi& E) {
;     ...
;         int t0 = 0;
;         if constexpr (SP2 && Epi::NVM == 16) { if (ui > 0) { const int t = 0; PG8_KSETUP(); PG8_KITER_SP2(24, 24); t0 = 2; } }
.LBB0_2869:
	s_cmp_lg_u32 s73, 0
	s_mov_b32 s40, 0
	s_cbranch_scc0 .LBB0_2871
	ds_read_b128 v[4:7], v152
	ds_read_b128 v[8:11], v152 offset:1024
	ds_read_b128 v[12:15], v152 offset:2048
	ds_read_b128 v[16:19], v152 offset:3072
	ds_read_b128 v[20:23], v153
	ds_read_b128 v[24:27], v153 offset:1024
	ds_read_b128 v[28:31], v153 offset:2048
	ds_read_b128 v[32:35], v153 offset:3072
	s_add_u32 s24, s36, 0x100
	s_addc_u32 s25, s37, 0
	s_add_u32 s30, s38, 0x100
	s_addc_u32 s31, s39, 0
	s_add_u32 s22, s36, 0x180
	s_addc_u32 s23, s37, 0
	ds_read_b128 v[36:39], v154
	ds_read_b128 v[40:43], v154 offset:1024
	ds_read_b128 v[44:47], v154 offset:2048
	ds_read_b128 v[48:51], v154 offset:3072
	ds_read_b128 v[52:55], v154 offset:4096
	ds_read_b128 v[56:59], v154 offset:5120
	ds_read_b128 v[60:63], v154 offset:6144
	ds_read_b128 v[64:67], v154 offset:7168
	s_add_u32 s40, s36, 0x80080
	s_addc_u32 s41, s37, 0
	s_mov_b32 m0, s64
	s_nop 0
	global_load_lds_dwordx4 v1, s[40:41] offset:0
	s_nop 0
	s_mov_b32 m0, s65
	s_nop 0
	global_load_lds_dwordx4 v147, s[40:41] offset:0
	s_waitcnt vmcnt(16)
	s_waitcnt lgkmcnt(0)
	s_barrier
	s_setprio 1
	v_mfma_f32_16x16x32_bf16 v[92:95], v[4:7], v[60:63], 0
	v_mfma_f32_16x16x32_bf16 v[68:71], v[4:7], v[36:39], 0
	v_mfma_f32_16x16x32_bf16 v[72:75], v[12:15], v[36:39], 0
	v_mfma_f32_16x16x32_bf16 v[76:79], v[4:7], v[44:47], 0
	v_mfma_f32_16x16x32_bf16 v[80:83], v[12:15], v[44:47], 0
	v_mfma_f32_16x16x32_bf16 v[84:87], v[4:7], v[52:55], 0
	v_mfma_f32_16x16x32_bf16 v[88:91], v[12:15], v[52:55], 0
	v_mfma_f32_16x16x32_bf16 v[102:105], v[8:11], v[64:67], v[92:95]
	v_mfma_f32_16x16x32_bf16 v[92:95], v[12:15], v[60:63], 0
	v_mfma_f32_16x16x32_bf16 v[68:71], v[8:11], v[40:43], v[68:71]
	v_mfma_f32_16x16x32_bf16 v[72:75], v[16:19], v[40:43], v[72:75]
	v_mfma_f32_16x16x32_bf16 v[76:79], v[8:11], v[48:51], v[76:79]
	v_mfma_f32_16x16x32_bf16 v[80:83], v[16:19], v[48:51], v[80:83]
	v_mfma_f32_16x16x32_bf16 v[84:87], v[8:11], v[56:59], v[84:87]
	v_mfma_f32_16x16x32_bf16 v[88:91], v[16:19], v[56:59], v[88:91]
	v_mfma_f32_16x16x32_bf16 v[106:109], v[16:19], v[64:67], v[92:95]
	s_setprio 0
	s_setprio 1
	v_mfma_f32_16x16x32_bf16 v[92:95], v[20:23], v[36:39], 0
	v_mfma_f32_16x16x32_bf16 v[36:39], v[28:31], v[36:39], 0
	v_mfma_f32_16x16x32_bf16 v[118:121], v[24:27], v[40:43], v[92:95]
	v_mfma_f32_16x16x32_bf16 v[36:39], v[32:35], v[40:43], v[36:39]
	v_mfma_f32_16x16x32_bf16 v[40:43], v[20:23], v[44:47], 0
	v_mfma_f32_16x16x32_bf16 v[44:47], v[28:31], v[44:47], 0
	v_mfma_f32_16x16x32_bf16 v[40:43], v[24:27], v[48:51], v[40:43]
	v_mfma_f32_16x16x32_bf16 v[44:47], v[32:35], v[48:51], v[44:47]
	v_mfma_f32_16x16x32_bf16 v[48:51], v[20:23], v[52:55], 0
	v_mfma_f32_16x16x32_bf16 v[52:55], v[28:31], v[52:55], 0
	v_mfma_f32_16x16x32_bf16 v[48:51], v[24:27], v[56:59], v[48:51]
	v_mfma_f32_16x16x32_bf16 v[52:55], v[32:35], v[56:59], v[52:55]
	v_mfma_f32_16x16x32_bf16 v[56:59], v[20:23], v[60:63], 0
	v_mfma_f32_16x16x32_bf16 v[60:63], v[28:31], v[60:63], 0
	v_mfma_f32_16x16x32_bf16 v[56:59], v[24:27], v[64:67], v[56:59]
	v_mfma_f32_16x16x32_bf16 v[60:63], v[32:35], v[64:67], v[60:63]
	s_barrier
	s_setprio 0
	ds_read_b128 v[64:67], v154 offset:16384
	ds_read_b128 v[92:95], v154 offset:17408
	ds_read_b128 v[96:99], v154 offset:18432
	ds_read_b128 v[110:113], v154 offset:19456
	ds_read_b128 v[114:117], v154 offset:20480
	ds_read_b128 v[122:125], v154 offset:21504
	ds_read_b128 v[126:129], v154 offset:22528
	ds_read_b128 v[130:133], v154 offset:23552
	s_mov_b32 m0, s29
	s_nop 0
	global_load_lds_dwordx4 v146, s[30:31] offset:0
	s_nop 0
	s_mov_b32 m0, s44
	s_nop 0
	global_load_lds_dwordx4 v148, s[30:31] offset:0
	s_add_u32 s30, s38, 0x80100
	s_addc_u32 s31, s39, 0
	s_mov_b32 m0, s45
	s_nop 0
	global_load_lds_dwordx4 v146, s[30:31] offset:0
	s_nop 0
	s_mov_b32 m0, s46
	s_nop 0
	global_load_lds_dwordx4 v148, s[30:31] offset:0
	s_nop 0
	s_mov_b32 m0, s21
	s_nop 0
	global_load_lds_dwordx4 v1, s[24:25] offset:0
	s_nop 0
	s_mov_b32 m0, s47
	s_nop 0
	global_load_lds_dwordx4 v147, s[24:25] offset:0
	s_waitcnt vmcnt(16)
	s_waitcnt lgkmcnt(0)
	s_barrier
	s_setprio 1
	v_mfma_f32_16x16x32_bf16 v[138:141], v[4:7], v[64:67], 0
	v_mfma_f32_16x16x32_bf16 v[158:161], v[4:7], v[96:99], 0
	v_mfma_f32_16x16x32_bf16 v[166:169], v[4:7], v[114:117], 0
	v_mfma_f32_16x16x32_bf16 v[4:7], v[4:7], v[126:129], 0
	v_mfma_f32_16x16x32_bf16 v[138:141], v[8:11], v[92:95], v[138:141]
	v_mfma_f32_16x16x32_bf16 v[158:161], v[8:11], v[110:113], v[158:161]
	v_mfma_f32_16x16x32_bf16 v[166:169], v[8:11], v[122:125], v[166:169]
	v_mfma_f32_16x16x32_bf16 v[4:7], v[8:11], v[130:133], v[4:7]
	v_mfma_f32_16x16x32_bf16 v[8:11], v[12:15], v[126:129], 0
	v_mfma_f32_16x16x32_bf16 v[142:145], v[12:15], v[64:67], 0
	v_mfma_f32_16x16x32_bf16 v[162:165], v[12:15], v[96:99], 0
	v_mfma_f32_16x16x32_bf16 v[170:173], v[12:15], v[114:117], 0
	v_mfma_f32_16x16x32_bf16 v[8:11], v[16:19], v[130:133], v[8:11]
	v_mfma_f32_16x16x32_bf16 v[142:145], v[16:19], v[92:95], v[142:145]
	v_mfma_f32_16x16x32_bf16 v[162:165], v[16:19], v[110:113], v[162:165]
	v_mfma_f32_16x16x32_bf16 v[170:173], v[16:19], v[122:125], v[170:173]
	s_setprio 0
	s_setprio 1
	v_mfma_f32_16x16x32_bf16 v[12:15], v[20:23], v[64:67], 0
	v_mfma_f32_16x16x32_bf16 v[174:177], v[24:27], v[92:95], v[12:15]
	v_mfma_f32_16x16x32_bf16 v[12:15], v[28:31], v[64:67], 0
	v_mfma_f32_16x16x32_bf16 v[178:181], v[32:35], v[92:95], v[12:15]
	v_mfma_f32_16x16x32_bf16 v[12:15], v[20:23], v[96:99], 0
	v_mfma_f32_16x16x32_bf16 v[182:185], v[24:27], v[110:113], v[12:15]
	v_mfma_f32_16x16x32_bf16 v[12:15], v[28:31], v[96:99], 0
	v_mfma_f32_16x16x32_bf16 v[186:189], v[32:35], v[110:113], v[12:15]
	v_mfma_f32_16x16x32_bf16 v[12:15], v[20:23], v[114:117], 0
	v_mfma_f32_16x16x32_bf16 v[190:193], v[24:27], v[122:125], v[12:15]
	v_mfma_f32_16x16x32_bf16 v[12:15], v[28:31], v[114:117], 0
	v_mfma_f32_16x16x32_bf16 v[194:197], v[32:35], v[122:125], v[12:15]
	v_mfma_f32_16x16x32_bf16 v[12:15], v[20:23], v[126:129], 0
	v_mfma_f32_16x16x32_bf16 v[198:201], v[24:27], v[130:133], v[12:15]
	v_mfma_f32_16x16x32_bf16 v[12:15], v[28:31], v[126:129], 0
	v_mfma_f32_16x16x32_bf16 v[202:205], v[32:35], v[130:133], v[12:15]
	s_barrier
; #define PG8_KSETUP() const bool last = (t == nt - 2); const char* a1 = cA + (size_t)(t + 1) * kstep; \
;             const char* a2 = last ? nA : cA + (size_t)(t + 2) * kstep; const char* b2 = last ? nB : cB + (size_t)(t + 2) * kstep; const char* a3 = a2 + kstep; const char* b3 = b2 + kstep; \
;             if (last && has_next) S.a_ready(nxt)
; template <class Epi, class Sched, bool ALIGN_EPI = false, bool SP2 = false>
; __device__ __forceinline__ void gemm_phase(PG8_LAS unsigned char* lds, const Gemm g, const Sched& S, const Epi& E) {
;     ...
;         int t0 = 0;
;         if constexpr (SP2 && Epi::NVM == 16) { if (ui > 0) { const int t = 0; PG8_KSETUP(); PG8_KITER_SP2(24, 24); t0 = 2; } }
	s_setprio 0
	s_nop 4
	ds_read_b128 v[12:15], v155
	ds_read_b128 v[16:19], v155 offset:1024
	ds_read_b128 v[22:25], v155 offset:2048
	ds_read_b128 v[26:29], v155 offset:3072
	ds_read_b128 v[206:209], v156
	ds_read_b128 v[210:213], v156 offset:1024
	ds_read_b128 v[214:217], v156 offset:2048
	ds_read_b128 v[218:221], v156 offset:3072
	ds_read_b128 v[30:33], v154 offset:32768
	ds_read_b128 v[64:67], v154 offset:33792
	ds_read_b128 v[222:225], v154 offset:34816
	ds_read_b128 v[226:229], v154 offset:35840
	ds_read_b128 v[230:233], v154 offset:36864
	ds_read_b128 v[234:237], v154 offset:37888
	ds_read_b128 v[238:241], v154 offset:38912
	ds_read_b128 v[242:245], v154 offset:39936
	s_add_u32 s24, s36, 0x80100
	s_addc_u32 s25, s37, 0
	s_mov_b32 m0, s52
	s_nop 0
	global_load_lds_dwordx4 v1, s[24:25] offset:0
	s_nop 0
	s_mov_b32 m0, s53
	s_nop 0
	global_load_lds_dwordx4 v147, s[24:25] offset:0
	s_waitcnt vmcnt(8)
	s_waitcnt lgkmcnt(0)
	s_barrier
	s_setprio 1
	v_mfma_f32_16x16x32_bf16 v[68:71], v[12:15], v[30:33], v[68:71]
	v_mfma_f32_16x16x32_bf16 v[130:133], v[16:19], v[64:67], v[68:71]
	v_mfma_f32_16x16x32_bf16 v[68:71], v[22:25], v[30:33], v[72:75]
	v_mfma_f32_16x16x32_bf16 v[126:129], v[26:29], v[64:67], v[68:71]
	v_mfma_f32_16x16x32_bf16 v[68:71], v[12:15], v[222:225], v[76:79]
	v_mfma_f32_16x16x32_bf16 v[114:117], v[16:19], v[226:229], v[68:71]
	v_mfma_f32_16x16x32_bf16 v[68:71], v[22:25], v[222:225], v[80:83]
	v_mfma_f32_16x16x32_bf16 v[110:113], v[26:29], v[226:229], v[68:71]
	v_mfma_f32_16x16x32_bf16 v[68:71], v[12:15], v[230:233], v[84:87]
	v_mfma_f32_16x16x32_bf16 v[98:101], v[16:19], v[234:237], v[68:71]
	v_mfma_f32_16x16x32_bf16 v[68:71], v[22:25], v[230:233], v[88:91]
	v_mfma_f32_16x16x32_bf16 v[94:97], v[26:29], v[234:237], v[68:71]
	v_mfma_f32_16x16x32_bf16 v[68:71], v[12:15], v[238:241], v[102:105]
	v_mfma_f32_16x16x32_bf16 v[82:85], v[16:19], v[242:245], v[68:71]
	v_mfma_f32_16x16x32_bf16 v[68:71], v[22:25], v[238:241], v[106:109]
	v_mfma_f32_16x16x32_bf16 v[78:81], v[26:29], v[242:245], v[68:71]
	s_setprio 0
	s_setprio 1
	v_mfma_f32_16x16x32_bf16 v[68:71], v[206:209], v[30:33], v[118:121]
	v_mfma_f32_16x16x32_bf16 v[30:33], v[214:217], v[30:33], v[36:39]
	v_mfma_f32_16x16x32_bf16 v[118:121], v[218:221], v[64:67], v[30:33]
	v_mfma_f32_16x16x32_bf16 v[30:33], v[206:209], v[222:225], v[40:43]
	v_mfma_f32_16x16x32_bf16 v[106:109], v[210:213], v[226:229], v[30:33]
	v_mfma_f32_16x16x32_bf16 v[30:33], v[214:217], v[222:225], v[44:47]
	v_mfma_f32_16x16x32_bf16 v[102:105], v[218:221], v[226:229], v[30:33]
	v_mfma_f32_16x16x32_bf16 v[30:33], v[206:209], v[230:233], v[48:51]
	v_mfma_f32_16x16x32_bf16 v[90:93], v[210:213], v[234:237], v[30:33]
	v_mfma_f32_16x16x32_bf16 v[30:33], v[214:217], v[230:233], v[52:55]
	v_mfma_f32_16x16x32_bf16 v[86:89], v[218:221], v[234:237], v[30:33]
	v_mfma_f32_16x16x32_bf16 v[30:33], v[206:209], v[238:241], v[56:59]
	v_mfma_f32_16x16x32_bf16 v[74:77], v[210:213], v[242:245], v[30:33]
	v_mfma_f32_16x16x32_bf16 v[30:33], v[214:217], v[238:241], v[60:63]
	v_mfma_f32_16x16x32_bf16 v[122:125], v[210:213], v[64:67], v[68:71]
	v_mfma_f32_16x16x32_bf16 v[66:69], v[218:221], v[242:245], v[30:33]
	s_barrier
	s_setprio 0
	ds_read_b128 v[38:41], v154 offset:49152
	ds_read_b128 v[42:45], v154 offset:50176
	ds_read_b128 v[222:225], v154 offset:51200
	ds_read_b128 v[226:229], v154 offset:52224
	ds_read_b128 v[230:233], v154 offset:53248
	ds_read_b128 v[234:237], v154 offset:54272
	ds_read_b128 v[238:241], v154 offset:55296
	ds_read_b128 v[242:245], v154 offset:56320
	s_add_u32 s24, s38, 0x180
	s_addc_u32 s25, s39, 0
	s_mov_b32 m0, s54
	s_nop 0
	global_load_lds_dwordx4 v146, s[24:25] offset:0
	s_nop 0
	s_mov_b32 m0, s55
	s_nop 0
	global_load_lds_dwordx4 v148, s[24:25] offset:0
	s_add_u32 s24, s38, 0x80180
	s_addc_u32 s25, s39, 0
	s_mov_b32 m0, s58
	s_nop 0
	global_load_lds_dwordx4 v146, s[24:25] offset:0
	s_nop 0
	s_mov_b32 m0, s59
	s_nop 0
	global_load_lds_dwordx4 v148, s[24:25] offset:0
	s_nop 0
	s_mov_b32 m0, s56
	s_nop 0
	global_load_lds_dwordx4 v1, s[22:23] offset:0
	s_nop 0
	s_mov_b32 m0, s57
	s_nop 0
	global_load_lds_dwordx4 v147, s[22:23] offset:0
	s_waitcnt vmcnt(8)
	s_waitcnt lgkmcnt(0)
	s_barrier
	s_setprio 1
	v_mfma_f32_16x16x32_bf16 v[30:33], v[12:15], v[38:41], v[138:141]
	v_mfma_f32_16x16x32_bf16 v[70:73], v[16:19], v[42:45], v[30:33]
	v_mfma_f32_16x16x32_bf16 v[30:33], v[22:25], v[38:41], v[142:145]
	v_mfma_f32_16x16x32_bf16 v[62:65], v[26:29], v[42:45], v[30:33]
	v_mfma_f32_16x16x32_bf16 v[30:33], v[12:15], v[222:225], v[158:161]
	v_mfma_f32_16x16x32_bf16 v[50:53], v[16:19], v[226:229], v[30:33]
	v_mfma_f32_16x16x32_bf16 v[30:33], v[22:25], v[222:225], v[162:165]
	v_mfma_f32_16x16x32_bf16 v[46:49], v[26:29], v[226:229], v[30:33]
	v_mfma_f32_16x16x32_bf16 v[30:33], v[12:15], v[230:233], v[166:169]
	v_mfma_f32_16x16x32_bf16 v[4:7], v[12:15], v[238:241], v[4:7]
	v_mfma_f32_16x16x32_bf16 v[34:37], v[16:19], v[234:237], v[30:33]
	v_mfma_f32_16x16x32_bf16 v[30:33], v[22:25], v[230:233], v[170:173]
	v_mfma_f32_16x16x32_bf16 v[18:21], v[16:19], v[242:245], v[4:7]
	v_mfma_f32_16x16x32_bf16 v[4:7], v[22:25], v[238:241], v[8:11]
	v_mfma_f32_16x16x32_bf16 v[30:33], v[26:29], v[234:237], v[30:33]
	v_mfma_f32_16x16x32_bf16 v[14:17], v[26:29], v[242:245], v[4:7]
	s_setprio 0
	s_setprio 1
	v_mfma_f32_16x16x32_bf16 v[4:7], v[206:209], v[38:41], v[174:177]
	v_mfma_f32_16x16x32_bf16 v[58:61], v[210:213], v[42:45], v[4:7]
	v_mfma_f32_16x16x32_bf16 v[4:7], v[214:217], v[38:41], v[178:181]
	v_mfma_f32_16x16x32_bf16 v[54:57], v[218:221], v[42:45], v[4:7]
	v_mfma_f32_16x16x32_bf16 v[4:7], v[206:209], v[222:225], v[182:185]
	v_mfma_f32_16x16x32_bf16 v[42:45], v[210:213], v[226:229], v[4:7]
	v_mfma_f32_16x16x32_bf16 v[4:7], v[214:217], v[222:225], v[186:189]
	v_mfma_f32_16x16x32_bf16 v[38:41], v[218:221], v[226:229], v[4:7]
	v_mfma_f32_16x16x32_bf16 v[4:7], v[206:209], v[230:233], v[190:193]
	v_mfma_f32_16x16x32_bf16 v[26:29], v[210:213], v[234:237], v[4:7]
	v_mfma_f32_16x16x32_bf16 v[4:7], v[214:217], v[230:233], v[194:197]
	v_mfma_f32_16x16x32_bf16 v[22:25], v[218:221], v[234:237], v[4:7]
	v_mfma_f32_16x16x32_bf16 v[4:7], v[206:209], v[238:241], v[198:201]
	v_mfma_f32_16x16x32_bf16 v[10:13], v[210:213], v[242:245], v[4:7]
	v_mfma_f32_16x16x32_bf16 v[4:7], v[214:217], v[238:241], v[202:205]
	v_mfma_f32_16x16x32_bf16 v[6:9], v[218:221], v[242:245], v[4:7]
	s_barrier
	s_setprio 0
	s_mov_b32 s40, 2
	s_branch .LBB0_2872

.LBB0_2873:
	ds_read_b128 v[138:141], v152
	ds_read_b128 v[142:145], v152 offset:1024
	ds_read_b128 v[158:161], v152 offset:2048
	ds_read_b128 v[162:165], v152 offset:3072
	ds_read_b128 v[166:169], v153
	ds_read_b128 v[170:173], v153 offset:1024
	ds_read_b128 v[174:177], v153 offset:2048
	ds_read_b128 v[178:181], v153 offset:3072
	s_cmp_eq_u32 s76, 28
	s_cselect_b32 s40, s74, s79
	s_cselect_b32 s41, s19, s80
	s_cselect_b32 s38, s75, s77
	s_cselect_b32 s39, s17, s78
	s_add_u32 s36, s40, 0x80
	s_addc_u32 s37, s41, 0
	ds_read_b128 v[182:185], v154
	ds_read_b128 v[186:189], v154 offset:1024
	ds_read_b128 v[190:193], v154 offset:2048
	ds_read_b128 v[194:197], v154 offset:3072
	ds_read_b128 v[198:201], v154 offset:4096
	ds_read_b128 v[202:205], v154 offset:5120
	ds_read_b128 v[206:209], v154 offset:6144
	ds_read_b128 v[210:213], v154 offset:7168
	s_add_u32 s30, s79, 0x7ff80
	s_addc_u32 s31, s80, 0
	s_mov_b32 m0, s64
	s_nop 0
	global_load_lds_dwordx4 v1, s[30:31] offset:0
	s_nop 0
	s_mov_b32 m0, s65
	s_nop 0
	global_load_lds_dwordx4 v147, s[30:31] offset:0
	s_waitcnt vmcnt(8)
	s_waitcnt lgkmcnt(0)
	s_barrier
	s_setprio 1
	v_mfma_f32_16x16x32_bf16 v[130:133], v[138:141], v[182:185], v[130:133]
	v_mfma_f32_16x16x32_bf16 v[130:133], v[142:145], v[186:189], v[130:133]
	v_mfma_f32_16x16x32_bf16 v[126:129], v[158:161], v[182:185], v[126:129]
	v_mfma_f32_16x16x32_bf16 v[126:129], v[162:165], v[186:189], v[126:129]
	v_mfma_f32_16x16x32_bf16 v[114:117], v[138:141], v[190:193], v[114:117]
	v_mfma_f32_16x16x32_bf16 v[114:117], v[142:145], v[194:197], v[114:117]
	v_mfma_f32_16x16x32_bf16 v[110:113], v[158:161], v[190:193], v[110:113]
	v_mfma_f32_16x16x32_bf16 v[110:113], v[162:165], v[194:197], v[110:113]
	v_mfma_f32_16x16x32_bf16 v[98:101], v[138:141], v[198:201], v[98:101]
	v_mfma_f32_16x16x32_bf16 v[98:101], v[142:145], v[202:205], v[98:101]
	v_mfma_f32_16x16x32_bf16 v[94:97], v[158:161], v[198:201], v[94:97]
	v_mfma_f32_16x16x32_bf16 v[94:97], v[162:165], v[202:205], v[94:97]
	v_mfma_f32_16x16x32_bf16 v[82:85], v[138:141], v[206:209], v[82:85]
	v_mfma_f32_16x16x32_bf16 v[82:85], v[142:145], v[210:213], v[82:85]
	v_mfma_f32_16x16x32_bf16 v[78:81], v[158:161], v[206:209], v[78:81]
	v_mfma_f32_16x16x32_bf16 v[78:81], v[162:165], v[210:213], v[78:81]
	s_setprio 0
	s_setprio 1
	v_mfma_f32_16x16x32_bf16 v[122:125], v[166:169], v[182:185], v[122:125]
	v_mfma_f32_16x16x32_bf16 v[122:125], v[170:173], v[186:189], v[122:125]
	v_mfma_f32_16x16x32_bf16 v[118:121], v[174:177], v[182:185], v[118:121]
	v_mfma_f32_16x16x32_bf16 v[118:121], v[178:181], v[186:189], v[118:121]
	v_mfma_f32_16x16x32_bf16 v[106:109], v[166:169], v[190:193], v[106:109]
	v_mfma_f32_16x16x32_bf16 v[106:109], v[170:173], v[194:197], v[106:109]
	v_mfma_f32_16x16x32_bf16 v[102:105], v[174:177], v[190:193], v[102:105]
	v_mfma_f32_16x16x32_bf16 v[102:105], v[178:181], v[194:197], v[102:105]
	v_mfma_f32_16x16x32_bf16 v[90:93], v[166:169], v[198:201], v[90:93]
	v_mfma_f32_16x16x32_bf16 v[90:93], v[170:173], v[202:205], v[90:93]
	v_mfma_f32_16x16x32_bf16 v[86:89], v[174:177], v[198:201], v[86:89]
	v_mfma_f32_16x16x32_bf16 v[86:89], v[178:181], v[202:205], v[86:89]
	v_mfma_f32_16x16x32_bf16 v[74:77], v[166:169], v[206:209], v[74:77]
	v_mfma_f32_16x16x32_bf16 v[74:77], v[170:173], v[210:213], v[74:77]
	v_mfma_f32_16x16x32_bf16 v[66:69], v[174:177], v[206:209], v[66:69]
	v_mfma_f32_16x16x32_bf16 v[66:69], v[178:181], v[210:213], v[66:69]
	s_barrier
	s_setprio 0
	ds_read_b128 v[182:185], v154 offset:16384
	ds_read_b128 v[186:189], v154 offset:17408
	ds_read_b128 v[190:193], v154 offset:18432
	ds_read_b128 v[194:197], v154 offset:19456
	ds_read_b128 v[198:201], v154 offset:20480
	ds_read_b128 v[202:205], v154 offset:21504
	ds_read_b128 v[206:209], v154 offset:22528
	ds_read_b128 v[210:213], v154 offset:23552
	s_mov_b32 m0, s29
	s_nop 0
	global_load_lds_dwordx4 v146, s[38:39] offset:0
	s_add_u32 s30, s38, 0x80000
	s_mov_b32 m0, s44
	s_nop 0
	global_load_lds_dwordx4 v148, s[38:39] offset:0
	s_addc_u32 s31, s39, 0
	s_mov_b32 m0, s45
	s_nop 0
	global_load_lds_dwordx4 v146, s[30:31] offset:0
	s_nop 0
	s_mov_b32 m0, s46
	s_nop 0
	global_load_lds_dwordx4 v148, s[30:31] offset:0
	s_nop 0
	s_mov_b32 m0, s21
	s_nop 0
	global_load_lds_dwordx4 v1, s[40:41] offset:0
	s_nop 0
	s_mov_b32 m0, s47
	s_nop 0
	global_load_lds_dwordx4 v147, s[40:41] offset:0
	s_waitcnt vmcnt(8)
	s_waitcnt lgkmcnt(0)
	s_barrier
	s_setprio 1
	v_mfma_f32_16x16x32_bf16 v[70:73], v[138:141], v[182:185], v[70:73]
	v_mfma_f32_16x16x32_bf16 v[70:73], v[142:145], v[186:189], v[70:73]
	v_mfma_f32_16x16x32_bf16 v[62:65], v[158:161], v[182:185], v[62:65]
	v_mfma_f32_16x16x32_bf16 v[62:65], v[162:165], v[186:189], v[62:65]
	v_mfma_f32_16x16x32_bf16 v[50:53], v[138:141], v[190:193], v[50:53]
	v_mfma_f32_16x16x32_bf16 v[50:53], v[142:145], v[194:197], v[50:53]
	v_mfma_f32_16x16x32_bf16 v[46:49], v[158:161], v[190:193], v[46:49]
	v_mfma_f32_16x16x32_bf16 v[46:49], v[162:165], v[194:197], v[46:49]
	v_mfma_f32_16x16x32_bf16 v[34:37], v[138:141], v[198:201], v[34:37]
	v_mfma_f32_16x16x32_bf16 v[34:37], v[142:145], v[202:205], v[34:37]
	v_mfma_f32_16x16x32_bf16 v[30:33], v[158:161], v[198:201], v[30:33]
	v_mfma_f32_16x16x32_bf16 v[30:33], v[162:165], v[202:205], v[30:33]
	v_mfma_f32_16x16x32_bf16 v[18:21], v[138:141], v[206:209], v[18:21]
	v_mfma_f32_16x16x32_bf16 v[18:21], v[142:145], v[210:213], v[18:21]
	v_mfma_f32_16x16x32_bf16 v[14:17], v[158:161], v[206:209], v[14:17]
	v_mfma_f32_16x16x32_bf16 v[14:17], v[162:165], v[210:213], v[14:17]
	s_setprio 0
	s_setprio 1
	v_mfma_f32_16x16x32_bf16 v[58:61], v[166:169], v[182:185], v[58:61]
	v_mfma_f32_16x16x32_bf16 v[54:57], v[174:177], v[182:185], v[54:57]
	v_mfma_f32_16x16x32_bf16 v[42:45], v[166:169], v[190:193], v[42:45]
	v_mfma_f32_16x16x32_bf16 v[38:41], v[174:177], v[190:193], v[38:41]
	v_mfma_f32_16x16x32_bf16 v[26:29], v[166:169], v[198:201], v[26:29]
	v_mfma_f32_16x16x32_bf16 v[22:25], v[174:177], v[198:201], v[22:25]
	v_mfma_f32_16x16x32_bf16 v[10:13], v[166:169], v[206:209], v[10:13]
	v_mfma_f32_16x16x32_bf16 v[4:7], v[174:177], v[206:209], v[6:9]
	v_mfma_f32_16x16x32_bf16 v[58:61], v[170:173], v[186:189], v[58:61]
	v_mfma_f32_16x16x32_bf16 v[54:57], v[178:181], v[186:189], v[54:57]
	v_mfma_f32_16x16x32_bf16 v[42:45], v[170:173], v[194:197], v[42:45]
	v_mfma_f32_16x16x32_bf16 v[38:41], v[178:181], v[194:197], v[38:41]
	v_mfma_f32_16x16x32_bf16 v[26:29], v[170:173], v[202:205], v[26:29]
	v_mfma_f32_16x16x32_bf16 v[22:25], v[178:181], v[202:205], v[22:25]
	v_mfma_f32_16x16x32_bf16 v[10:13], v[170:173], v[210:213], v[10:13]
	v_mfma_f32_16x16x32_bf16 v[4:7], v[178:181], v[210:213], v[4:7]
	s_barrier
; #define PG8_KSETUP() const bool last = (t == nt - 2); const char* a1 = cA + (size_t)(t + 1) * kstep; \
;             const char* a2 = last ? nA : cA + (size_t)(t + 2) * kstep; const char* b2 = last ? nB : cB + (size_t)(t + 2) * kstep; const char* a3 = a2 + kstep; const char* b3 = b2 + kstep; \
;             if (last && has_next) S.a_ready(nxt)
; template <class Epi, class Sched, bool ALIGN_EPI = false, bool SP2 = false>
; __device__ __forceinline__ void gemm_phase(PG8_LAS unsigned char* lds, const Gemm g, const Sched& S, const Epi& E) {
;     ...
;         int t0 = 0;
;         if constexpr (SP2 && Epi::NVM == 16) { if (ui > 0) { const int t = 0; PG8_KSETUP(); PG8_KITER_SP2(24, 24); t0 = 2; } }
;         if constexpr (SP2 && Epi::NVM == 8) { if (ui > 0) { const int t = 0; PG8_KSETUP(); PG8_KITER_SP2(16, 16); t0 = 2; } }
;         for (int t = t0; t < nt; t += 2) {
	s_setprio 0
	ds_read_b128 v[138:141], v155
	ds_read_b128 v[142:145], v155 offset:1024
	ds_read_b128 v[158:161], v155 offset:2048
	ds_read_b128 v[162:165], v155 offset:3072
	ds_read_b128 v[166:169], v156
	ds_read_b128 v[170:173], v156 offset:1024
	ds_read_b128 v[174:177], v156 offset:2048
	ds_read_b128 v[178:181], v156 offset:3072
	ds_read_b128 v[182:185], v154 offset:32768
	ds_read_b128 v[186:189], v154 offset:33792
	ds_read_b128 v[190:193], v154 offset:34816
	ds_read_b128 v[194:197], v154 offset:35840
	ds_read_b128 v[198:201], v154 offset:36864
	ds_read_b128 v[202:205], v154 offset:37888
	ds_read_b128 v[206:209], v154 offset:38912
	ds_read_b128 v[210:213], v154 offset:39936
	s_add_u32 s30, s40, 0x80000
	s_addc_u32 s31, s41, 0
	s_mov_b32 m0, s52
	s_nop 0
	global_load_lds_dwordx4 v1, s[30:31] offset:0
	s_nop 0
	s_mov_b32 m0, s53
	s_nop 0
	global_load_lds_dwordx4 v147, s[30:31] offset:0
	s_waitcnt vmcnt(8)
	s_waitcnt lgkmcnt(0)
	s_barrier
	s_setprio 1
	v_mfma_f32_16x16x32_bf16 v[130:133], v[138:141], v[182:185], v[130:133]
	v_mfma_f32_16x16x32_bf16 v[130:133], v[142:145], v[186:189], v[130:133]
	v_mfma_f32_16x16x32_bf16 v[126:129], v[158:161], v[182:185], v[126:129]
	v_mfma_f32_16x16x32_bf16 v[126:129], v[162:165], v[186:189], v[126:129]
	v_mfma_f32_16x16x32_bf16 v[114:117], v[138:141], v[190:193], v[114:117]
	v_mfma_f32_16x16x32_bf16 v[114:117], v[142:145], v[194:197], v[114:117]
	v_mfma_f32_16x16x32_bf16 v[110:113], v[158:161], v[190:193], v[110:113]
	v_mfma_f32_16x16x32_bf16 v[110:113], v[162:165], v[194:197], v[110:113]
	v_mfma_f32_16x16x32_bf16 v[98:101], v[138:141], v[198:201], v[98:101]
	v_mfma_f32_16x16x32_bf16 v[98:101], v[142:145], v[202:205], v[98:101]
	v_mfma_f32_16x16x32_bf16 v[94:97], v[158:161], v[198:201], v[94:97]
	v_mfma_f32_16x16x32_bf16 v[94:97], v[162:165], v[202:205], v[94:97]
	v_mfma_f32_16x16x32_bf16 v[82:85], v[138:141], v[206:209], v[82:85]
	v_mfma_f32_16x16x32_bf16 v[82:85], v[142:145], v[210:213], v[82:85]
	v_mfma_f32_16x16x32_bf16 v[78:81], v[158:161], v[206:209], v[78:81]
	v_mfma_f32_16x16x32_bf16 v[78:81], v[162:165], v[210:213], v[78:81]
	s_setprio 0
	s_setprio 1
	v_mfma_f32_16x16x32_bf16 v[122:125], v[166:169], v[182:185], v[122:125]
	v_mfma_f32_16x16x32_bf16 v[122:125], v[170:173], v[186:189], v[122:125]
	v_mfma_f32_16x16x32_bf16 v[118:121], v[174:177], v[182:185], v[118:121]
	v_mfma_f32_16x16x32_bf16 v[118:121], v[178:181], v[186:189], v[118:121]
	v_mfma_f32_16x16x32_bf16 v[106:109], v[166:169], v[190:193], v[106:109]
	v_mfma_f32_16x16x32_bf16 v[106:109], v[170:173], v[194:197], v[106:109]
	v_mfma_f32_16x16x32_bf16 v[102:105], v[174:177], v[190:193], v[102:105]
	v_mfma_f32_16x16x32_bf16 v[102:105], v[178:181], v[194:197], v[102:105]
	v_mfma_f32_16x16x32_bf16 v[90:93], v[166:169], v[198:201], v[90:93]
	v_mfma_f32_16x16x32_bf16 v[90:93], v[170:173], v[202:205], v[90:93]
	v_mfma_f32_16x16x32_bf16 v[86:89], v[174:177], v[198:201], v[86:89]
	v_mfma_f32_16x16x32_bf16 v[86:89], v[178:181], v[202:205], v[86:89]
	v_mfma_f32_16x16x32_bf16 v[74:77], v[166:169], v[206:209], v[74:77]
	v_mfma_f32_16x16x32_bf16 v[74:77], v[170:173], v[210:213], v[74:77]
	v_mfma_f32_16x16x32_bf16 v[66:69], v[174:177], v[206:209], v[66:69]
	v_mfma_f32_16x16x32_bf16 v[66:69], v[178:181], v[210:213], v[66:69]
	s_barrier
	s_setprio 0
	ds_read_b128 v[182:185], v154 offset:49152
	ds_read_b128 v[186:189], v154 offset:50176
	ds_read_b128 v[190:193], v154 offset:51200
	ds_read_b128 v[194:197], v154 offset:52224
	ds_read_b128 v[198:201], v154 offset:53248
	ds_read_b128 v[202:205], v154 offset:54272
	ds_read_b128 v[206:209], v154 offset:55296
	ds_read_b128 v[210:213], v154 offset:56320
	s_add_u32 s30, s38, 0x80
	s_addc_u32 s31, s39, 0
	s_mov_b32 m0, s54
	s_nop 0
	global_load_lds_dwordx4 v146, s[30:31] offset:0
	s_nop 0
	s_mov_b32 m0, s55
	s_nop 0
	global_load_lds_dwordx4 v148, s[30:31] offset:0
	s_add_u32 s30, s38, 0x80080
	s_addc_u32 s31, s39, 0
	s_mov_b32 m0, s58
	s_nop 0
	global_load_lds_dwordx4 v146, s[30:31] offset:0
	s_nop 0
	s_mov_b32 m0, s59
	s_nop 0
	global_load_lds_dwordx4 v148, s[30:31] offset:0
	s_nop 0
	s_mov_b32 m0, s56
	s_nop 0
	global_load_lds_dwordx4 v1, s[36:37] offset:0
	s_nop 0
	s_mov_b32 m0, s57
	s_nop 0
	global_load_lds_dwordx4 v147, s[36:37] offset:0
	s_waitcnt vmcnt(8)
	s_waitcnt lgkmcnt(0)
	s_barrier
	s_setprio 1
	v_mfma_f32_16x16x32_bf16 v[70:73], v[138:141], v[182:185], v[70:73]
	v_mfma_f32_16x16x32_bf16 v[70:73], v[142:145], v[186:189], v[70:73]
	v_mfma_f32_16x16x32_bf16 v[62:65], v[158:161], v[182:185], v[62:65]
	v_mfma_f32_16x16x32_bf16 v[62:65], v[162:165], v[186:189], v[62:65]
	v_mfma_f32_16x16x32_bf16 v[50:53], v[138:141], v[190:193], v[50:53]
	v_mfma_f32_16x16x32_bf16 v[50:53], v[142:145], v[194:197], v[50:53]
	v_mfma_f32_16x16x32_bf16 v[46:49], v[158:161], v[190:193], v[46:49]
	v_mfma_f32_16x16x32_bf16 v[46:49], v[162:165], v[194:197], v[46:49]
	v_mfma_f32_16x16x32_bf16 v[34:37], v[138:141], v[198:201], v[34:37]
	v_mfma_f32_16x16x32_bf16 v[34:37], v[142:145], v[202:205], v[34:37]
	v_mfma_f32_16x16x32_bf16 v[30:33], v[158:161], v[198:201], v[30:33]
	v_mfma_f32_16x16x32_bf16 v[30:33], v[162:165], v[202:205], v[30:33]
	v_mfma_f32_16x16x32_bf16 v[18:21], v[138:141], v[206:209], v[18:21]
	v_mfma_f32_16x16x32_bf16 v[18:21], v[142:145], v[210:213], v[18:21]
	v_mfma_f32_16x16x32_bf16 v[14:17], v[158:161], v[206:209], v[14:17]
	v_mfma_f32_16x16x32_bf16 v[14:17], v[162:165], v[210:213], v[14:17]
	s_setprio 0
	s_setprio 1
	v_mfma_f32_16x16x32_bf16 v[58:61], v[166:169], v[182:185], v[58:61]
	v_mfma_f32_16x16x32_bf16 v[54:57], v[174:177], v[182:185], v[54:57]
	v_mfma_f32_16x16x32_bf16 v[42:45], v[166:169], v[190:193], v[42:45]
	v_mfma_f32_16x16x32_bf16 v[38:41], v[174:177], v[190:193], v[38:41]
	v_mfma_f32_16x16x32_bf16 v[26:29], v[166:169], v[198:201], v[26:29]
	v_mfma_f32_16x16x32_bf16 v[22:25], v[174:177], v[198:201], v[22:25]
	v_mfma_f32_16x16x32_bf16 v[8:11], v[166:169], v[206:209], v[10:13]
	v_mfma_f32_16x16x32_bf16 v[4:7], v[174:177], v[206:209], v[4:7]
	v_mfma_f32_16x16x32_bf16 v[58:61], v[170:173], v[186:189], v[58:61]
	v_mfma_f32_16x16x32_bf16 v[54:57], v[178:181], v[186:189], v[54:57]
	v_mfma_f32_16x16x32_bf16 v[42:45], v[170:173], v[194:197], v[42:45]
	v_mfma_f32_16x16x32_bf16 v[38:41], v[178:181], v[194:197], v[38:41]
	v_mfma_f32_16x16x32_bf16 v[26:29], v[170:173], v[202:205], v[26:29]
	v_mfma_f32_16x16x32_bf16 v[22:25], v[178:181], v[202:205], v[22:25]
	v_mfma_f32_16x16x32_bf16 v[10:13], v[170:173], v[210:213], v[8:11]
	v_mfma_f32_16x16x32_bf16 v[6:9], v[178:181], v[210:213], v[4:7]
	s_barrier
	s_setprio 0
	s_add_i32 s76, s76, 2
	s_add_u32 s77, s77, 0x100
	s_addc_u32 s78, s78, 0
	s_add_u32 s79, s79, 0x100
	s_addc_u32 s80, s80, 0
	s_cmp_gt_u32 s76, 29
	s_cbranch_scc0 .LBB0_2873
	s_and_b64 vcc, exec, s[14:15]
	s_cbranch_vccz .LBB0_2876
	s_barrier

; #define PG8_KSETUP() const bool last = (t == nt - 2); const char* a1 = cA + (size_t)(t + 1) * kstep; \
;             const char* a2 = last ? nA : cA + (size_t)(t + 2) * kstep; const char* b2 = last ? nB : cB + (size_t)(t + 2) * kstep; const char* a3 = a2 + kstep; const char* b3 = b2 + kstep; \
;             if (last && has_next) S.a_ready(nxt)
; template <class Epi, class Sched, bool ALIGN_EPI = false, bool SP2 = false>
; __device__ __forceinline__ void gemm_phase(PG8_LAS unsigned char* lds, const Gemm g, const Sched& S, const Epi& E) {
;     ...
;         if constexpr (SP2 && Epi::NVM == 16) { if (ui > 0) { const int t = 0; PG8_KSETUP(); PG8_KITER_SP2(24, 24); t0 = 2; } }
.LBB0_2955:
	ds_read_b128 v[4:7], v147
	ds_read_b128 v[8:11], v147 offset:1024
	ds_read_b128 v[12:15], v147 offset:2048
	ds_read_b128 v[16:19], v147 offset:3072
	ds_read_b128 v[20:23], v148
	ds_read_b128 v[24:27], v148 offset:1024
	ds_read_b128 v[28:31], v148 offset:2048
	ds_read_b128 v[32:35], v148 offset:3072
	s_add_u32 s42, s36, 0x100
	s_addc_u32 s43, s37, 0
	s_add_u32 s30, s38, 0x100
	s_addc_u32 s31, s39, 0
	s_add_u32 s40, s36, 0x180
	s_addc_u32 s41, s37, 0
	ds_read_b128 v[36:39], v149
	ds_read_b128 v[40:43], v149 offset:1024
	ds_read_b128 v[44:47], v149 offset:2048
	ds_read_b128 v[48:51], v149 offset:3072
	ds_read_b128 v[52:55], v149 offset:4096
	ds_read_b128 v[56:59], v149 offset:5120
	ds_read_b128 v[60:63], v149 offset:6144
	ds_read_b128 v[64:67], v149 offset:7168
	s_add_u32 s48, s36, 0x160080
	s_addc_u32 s49, s37, 0
	s_mov_b32 m0, s70
	s_nop 0
	global_load_lds_dwordx4 v1, s[48:49] offset:0
	s_nop 0
	s_mov_b32 m0, s71
	s_nop 0
	global_load_lds_dwordx4 v143, s[48:49] offset:0
	s_waitcnt vmcnt(24)
	s_waitcnt lgkmcnt(0)
	s_barrier
	s_setprio 1
	v_mfma_f32_16x16x32_bf16 v[92:95], v[4:7], v[60:63], 0
	v_mfma_f32_16x16x32_bf16 v[68:71], v[4:7], v[36:39], 0
	v_mfma_f32_16x16x32_bf16 v[72:75], v[12:15], v[36:39], 0
	v_mfma_f32_16x16x32_bf16 v[76:79], v[4:7], v[44:47], 0
	v_mfma_f32_16x16x32_bf16 v[80:83], v[12:15], v[44:47], 0
	v_mfma_f32_16x16x32_bf16 v[84:87], v[4:7], v[52:55], 0
	v_mfma_f32_16x16x32_bf16 v[88:91], v[12:15], v[52:55], 0
	v_mfma_f32_16x16x32_bf16 v[102:105], v[8:11], v[64:67], v[92:95]
	v_mfma_f32_16x16x32_bf16 v[92:95], v[12:15], v[60:63], 0
	v_mfma_f32_16x16x32_bf16 v[68:71], v[8:11], v[40:43], v[68:71]
	v_mfma_f32_16x16x32_bf16 v[72:75], v[16:19], v[40:43], v[72:75]
	v_mfma_f32_16x16x32_bf16 v[76:79], v[8:11], v[48:51], v[76:79]
	v_mfma_f32_16x16x32_bf16 v[80:83], v[16:19], v[48:51], v[80:83]
	v_mfma_f32_16x16x32_bf16 v[84:87], v[8:11], v[56:59], v[84:87]
	v_mfma_f32_16x16x32_bf16 v[88:91], v[16:19], v[56:59], v[88:91]
	v_mfma_f32_16x16x32_bf16 v[106:109], v[16:19], v[64:67], v[92:95]
	s_setprio 0
	s_setprio 1
	v_mfma_f32_16x16x32_bf16 v[92:95], v[20:23], v[36:39], 0
	v_mfma_f32_16x16x32_bf16 v[36:39], v[28:31], v[36:39], 0
	v_mfma_f32_16x16x32_bf16 v[118:121], v[24:27], v[40:43], v[92:95]
	v_mfma_f32_16x16x32_bf16 v[36:39], v[32:35], v[40:43], v[36:39]
	v_mfma_f32_16x16x32_bf16 v[40:43], v[20:23], v[44:47], 0
	v_mfma_f32_16x16x32_bf16 v[44:47], v[28:31], v[44:47], 0
	v_mfma_f32_16x16x32_bf16 v[40:43], v[24:27], v[48:51], v[40:43]
	v_mfma_f32_16x16x32_bf16 v[44:47], v[32:35], v[48:51], v[44:47]
	v_mfma_f32_16x16x32_bf16 v[48:51], v[20:23], v[52:55], 0
	v_mfma_f32_16x16x32_bf16 v[52:55], v[28:31], v[52:55], 0
	v_mfma_f32_16x16x32_bf16 v[48:51], v[24:27], v[56:59], v[48:51]
	v_mfma_f32_16x16x32_bf16 v[52:55], v[32:35], v[56:59], v[52:55]
	v_mfma_f32_16x16x32_bf16 v[56:59], v[20:23], v[60:63], 0
	v_mfma_f32_16x16x32_bf16 v[60:63], v[28:31], v[60:63], 0
	v_mfma_f32_16x16x32_bf16 v[56:59], v[24:27], v[64:67], v[56:59]
	v_mfma_f32_16x16x32_bf16 v[60:63], v[32:35], v[64:67], v[60:63]
	s_barrier
	s_setprio 0
	ds_read_b128 v[64:67], v149 offset:16384
	ds_read_b128 v[92:95], v149 offset:17408
	ds_read_b128 v[96:99], v149 offset:18432
	ds_read_b128 v[110:113], v149 offset:19456
	ds_read_b128 v[114:117], v149 offset:20480
	ds_read_b128 v[122:125], v149 offset:21504
	ds_read_b128 v[126:129], v149 offset:22528
	ds_read_b128 v[130:133], v149 offset:23552
	s_mov_b32 m0, s46
	s_nop 0
	global_load_lds_dwordx4 v142, s[30:31] offset:0
	s_nop 0
	s_mov_b32 m0, s47
	s_nop 0
	global_load_lds_dwordx4 v144, s[30:31] offset:0
	s_add_u32 s30, s38, 0x160100
	s_addc_u32 s31, s39, 0
	s_mov_b32 m0, s52
	s_nop 0
	global_load_lds_dwordx4 v142, s[30:31] offset:0
	s_nop 0
	s_mov_b32 m0, s53
	s_nop 0
	global_load_lds_dwordx4 v144, s[30:31] offset:0
	s_nop 0
	s_mov_b32 m0, s45
	s_nop 0
	global_load_lds_dwordx4 v1, s[42:43] offset:0
	s_nop 0
	s_mov_b32 m0, s54
	s_nop 0
	global_load_lds_dwordx4 v143, s[42:43] offset:0
	s_waitcnt vmcnt(24)
	s_waitcnt lgkmcnt(0)
	s_barrier
	s_setprio 1
	v_mfma_f32_16x16x32_bf16 v[138:141], v[4:7], v[64:67], 0
	v_mfma_f32_16x16x32_bf16 v[156:159], v[4:7], v[96:99], 0
	v_mfma_f32_16x16x32_bf16 v[164:167], v[4:7], v[114:117], 0
	v_mfma_f32_16x16x32_bf16 v[4:7], v[4:7], v[126:129], 0
	v_mfma_f32_16x16x32_bf16 v[138:141], v[8:11], v[92:95], v[138:141]
	v_mfma_f32_16x16x32_bf16 v[156:159], v[8:11], v[110:113], v[156:159]
	v_mfma_f32_16x16x32_bf16 v[164:167], v[8:11], v[122:125], v[164:167]
	v_mfma_f32_16x16x32_bf16 v[4:7], v[8:11], v[130:133], v[4:7]
	v_mfma_f32_16x16x32_bf16 v[8:11], v[12:15], v[126:129], 0
	v_mfma_f32_16x16x32_bf16 v[152:155], v[12:15], v[64:67], 0
	v_mfma_f32_16x16x32_bf16 v[160:163], v[12:15], v[96:99], 0
	v_mfma_f32_16x16x32_bf16 v[168:171], v[12:15], v[114:117], 0
	v_mfma_f32_16x16x32_bf16 v[8:11], v[16:19], v[130:133], v[8:11]
	v_mfma_f32_16x16x32_bf16 v[152:155], v[16:19], v[92:95], v[152:155]
	v_mfma_f32_16x16x32_bf16 v[160:163], v[16:19], v[110:113], v[160:163]
	v_mfma_f32_16x16x32_bf16 v[168:171], v[16:19], v[122:125], v[168:171]
	s_setprio 0
	s_setprio 1
	v_mfma_f32_16x16x32_bf16 v[12:15], v[20:23], v[64:67], 0
	v_mfma_f32_16x16x32_bf16 v[172:175], v[24:27], v[92:95], v[12:15]
	v_mfma_f32_16x16x32_bf16 v[12:15], v[28:31], v[64:67], 0
	v_mfma_f32_16x16x32_bf16 v[176:179], v[32:35], v[92:95], v[12:15]
	v_mfma_f32_16x16x32_bf16 v[12:15], v[20:23], v[96:99], 0
	v_mfma_f32_16x16x32_bf16 v[180:183], v[24:27], v[110:113], v[12:15]
	v_mfma_f32_16x16x32_bf16 v[12:15], v[28:31], v[96:99], 0
	v_mfma_f32_16x16x32_bf16 v[184:187], v[32:35], v[110:113], v[12:15]
	v_mfma_f32_16x16x32_bf16 v[12:15], v[20:23], v[114:117], 0
	v_mfma_f32_16x16x32_bf16 v[188:191], v[24:27], v[122:125], v[12:15]
	v_mfma_f32_16x16x32_bf16 v[12:15], v[28:31], v[114:117], 0
	v_mfma_f32_16x16x32_bf16 v[192:195], v[32:35], v[122:125], v[12:15]
	v_mfma_f32_16x16x32_bf16 v[12:15], v[20:23], v[126:129], 0
	v_mfma_f32_16x16x32_bf16 v[196:199], v[24:27], v[130:133], v[12:15]
	v_mfma_f32_16x16x32_bf16 v[12:15], v[28:31], v[126:129], 0
	v_mfma_f32_16x16x32_bf16 v[200:203], v[32:35], v[130:133], v[12:15]
	s_barrier
; #define PG8_KSETUP() const bool last = (t == nt - 2); const char* a1 = cA + (size_t)(t + 1) * kstep; \
;             const char* a2 = last ? nA : cA + (size_t)(t + 2) * kstep; const char* b2 = last ? nB : cB + (size_t)(t + 2) * kstep; const char* a3 = a2 + kstep; const char* b3 = b2 + kstep; \
;             if (last && has_next) S.a_ready(nxt)
; template <class Epi, class Sched, bool ALIGN_EPI = false, bool SP2 = false>
; __device__ __forceinline__ void gemm_phase(PG8_LAS unsigned char* lds, const Gemm g, const Sched& S, const Epi& E) {
;     ...
;         int t0 = 0;
;         if constexpr (SP2 && Epi::NVM == 16) { if (ui > 0) { const int t = 0; PG8_KSETUP(); PG8_KITER_SP2(24, 24); t0 = 2; } }
	s_setprio 0
	s_nop 4
	ds_read_b128 v[12:15], v150
	ds_read_b128 v[16:19], v150 offset:1024
	ds_read_b128 v[22:25], v150 offset:2048
	ds_read_b128 v[26:29], v150 offset:3072
	ds_read_b128 v[204:207], v151
	ds_read_b128 v[208:211], v151 offset:1024
	ds_read_b128 v[212:215], v151 offset:2048
	ds_read_b128 v[216:219], v151 offset:3072
	ds_read_b128 v[30:33], v149 offset:32768
	ds_read_b128 v[64:67], v149 offset:33792
	ds_read_b128 v[220:223], v149 offset:34816
	ds_read_b128 v[224:227], v149 offset:35840
	ds_read_b128 v[228:231], v149 offset:36864
	ds_read_b128 v[232:235], v149 offset:37888
	ds_read_b128 v[236:239], v149 offset:38912
	ds_read_b128 v[240:243], v149 offset:39936
	s_add_u32 s30, s36, 0x160100
	s_addc_u32 s31, s37, 0
	s_mov_b32 m0, s55
	s_nop 0
	global_load_lds_dwordx4 v1, s[30:31] offset:0
	s_nop 0
	s_mov_b32 m0, s56
	s_nop 0
	global_load_lds_dwordx4 v143, s[30:31] offset:0
	s_waitcnt vmcnt(8)
	s_waitcnt lgkmcnt(0)
	s_barrier
	s_setprio 1
	v_mfma_f32_16x16x32_bf16 v[68:71], v[12:15], v[30:33], v[68:71]
	v_mfma_f32_16x16x32_bf16 v[130:133], v[16:19], v[64:67], v[68:71]
	v_mfma_f32_16x16x32_bf16 v[68:71], v[22:25], v[30:33], v[72:75]
	v_mfma_f32_16x16x32_bf16 v[126:129], v[26:29], v[64:67], v[68:71]
	v_mfma_f32_16x16x32_bf16 v[68:71], v[12:15], v[220:223], v[76:79]
	v_mfma_f32_16x16x32_bf16 v[114:117], v[16:19], v[224:227], v[68:71]
	v_mfma_f32_16x16x32_bf16 v[68:71], v[22:25], v[220:223], v[80:83]
	v_mfma_f32_16x16x32_bf16 v[110:113], v[26:29], v[224:227], v[68:71]
	v_mfma_f32_16x16x32_bf16 v[68:71], v[12:15], v[228:231], v[84:87]
	v_mfma_f32_16x16x32_bf16 v[98:101], v[16:19], v[232:235], v[68:71]
	v_mfma_f32_16x16x32_bf16 v[68:71], v[22:25], v[228:231], v[88:91]
	v_mfma_f32_16x16x32_bf16 v[94:97], v[26:29], v[232:235], v[68:71]
	v_mfma_f32_16x16x32_bf16 v[68:71], v[12:15], v[236:239], v[102:105]
	v_mfma_f32_16x16x32_bf16 v[82:85], v[16:19], v[240:243], v[68:71]
	v_mfma_f32_16x16x32_bf16 v[68:71], v[22:25], v[236:239], v[106:109]
	v_mfma_f32_16x16x32_bf16 v[78:81], v[26:29], v[240:243], v[68:71]
	s_setprio 0
	s_setprio 1
	v_mfma_f32_16x16x32_bf16 v[68:71], v[204:207], v[30:33], v[118:121]
	v_mfma_f32_16x16x32_bf16 v[30:33], v[212:215], v[30:33], v[36:39]
	v_mfma_f32_16x16x32_bf16 v[118:121], v[216:219], v[64:67], v[30:33]
	v_mfma_f32_16x16x32_bf16 v[30:33], v[204:207], v[220:223], v[40:43]
	v_mfma_f32_16x16x32_bf16 v[106:109], v[208:211], v[224:227], v[30:33]
	v_mfma_f32_16x16x32_bf16 v[30:33], v[212:215], v[220:223], v[44:47]
	v_mfma_f32_16x16x32_bf16 v[102:105], v[216:219], v[224:227], v[30:33]
	v_mfma_f32_16x16x32_bf16 v[30:33], v[204:207], v[228:231], v[48:51]
	v_mfma_f32_16x16x32_bf16 v[90:93], v[208:211], v[232:235], v[30:33]
	v_mfma_f32_16x16x32_bf16 v[30:33], v[212:215], v[228:231], v[52:55]
	v_mfma_f32_16x16x32_bf16 v[86:89], v[216:219], v[232:235], v[30:33]
	v_mfma_f32_16x16x32_bf16 v[30:33], v[204:207], v[236:239], v[56:59]
	v_mfma_f32_16x16x32_bf16 v[74:77], v[208:211], v[240:243], v[30:33]
	v_mfma_f32_16x16x32_bf16 v[30:33], v[212:215], v[236:239], v[60:63]
	v_mfma_f32_16x16x32_bf16 v[122:125], v[208:211], v[64:67], v[68:71]
	v_mfma_f32_16x16x32_bf16 v[70:73], v[216:219], v[240:243], v[30:33]
	s_barrier
	s_setprio 0
	ds_read_b128 v[38:41], v149 offset:49152
	ds_read_b128 v[42:45], v149 offset:50176
	ds_read_b128 v[220:223], v149 offset:51200
	ds_read_b128 v[224:227], v149 offset:52224
	ds_read_b128 v[228:231], v149 offset:53248
	ds_read_b128 v[232:235], v149 offset:54272
	ds_read_b128 v[236:239], v149 offset:55296
	ds_read_b128 v[240:243], v149 offset:56320
	s_add_u32 s30, s38, 0x180
	s_addc_u32 s31, s39, 0
	s_mov_b32 m0, s64
	s_nop 0
	global_load_lds_dwordx4 v142, s[30:31] offset:0
	s_nop 0
	s_mov_b32 m0, s65
	s_nop 0
	global_load_lds_dwordx4 v144, s[30:31] offset:0
	s_add_u32 s30, s38, 0x160180
	s_addc_u32 s31, s39, 0
	s_mov_b32 m0, s68
	s_nop 0
	global_load_lds_dwordx4 v142, s[30:31] offset:0
	s_nop 0
	s_mov_b32 m0, s69
	s_nop 0
	global_load_lds_dwordx4 v144, s[30:31] offset:0
	s_nop 0
	s_mov_b32 m0, s66
	s_nop 0
	global_load_lds_dwordx4 v1, s[40:41] offset:0
	s_nop 0
	s_mov_b32 m0, s67
	s_nop 0
	global_load_lds_dwordx4 v143, s[40:41] offset:0
	s_waitcnt vmcnt(8)
	s_waitcnt lgkmcnt(0)
	s_barrier
	s_setprio 1
	v_mfma_f32_16x16x32_bf16 v[30:33], v[12:15], v[38:41], v[138:141]
	v_mfma_f32_16x16x32_bf16 v[66:69], v[16:19], v[42:45], v[30:33]
	v_mfma_f32_16x16x32_bf16 v[30:33], v[22:25], v[38:41], v[152:155]
	v_mfma_f32_16x16x32_bf16 v[62:65], v[26:29], v[42:45], v[30:33]
	v_mfma_f32_16x16x32_bf16 v[30:33], v[12:15], v[220:223], v[156:159]
	v_mfma_f32_16x16x32_bf16 v[50:53], v[16:19], v[224:227], v[30:33]
	v_mfma_f32_16x16x32_bf16 v[30:33], v[22:25], v[220:223], v[160:163]
	v_mfma_f32_16x16x32_bf16 v[46:49], v[26:29], v[224:227], v[30:33]
	v_mfma_f32_16x16x32_bf16 v[30:33], v[12:15], v[228:231], v[164:167]
	v_mfma_f32_16x16x32_bf16 v[4:7], v[12:15], v[236:239], v[4:7]
	v_mfma_f32_16x16x32_bf16 v[34:37], v[16:19], v[232:235], v[30:33]
	v_mfma_f32_16x16x32_bf16 v[30:33], v[22:25], v[228:231], v[168:171]
	v_mfma_f32_16x16x32_bf16 v[18:21], v[16:19], v[240:243], v[4:7]
	v_mfma_f32_16x16x32_bf16 v[4:7], v[22:25], v[236:239], v[8:11]
	v_mfma_f32_16x16x32_bf16 v[30:33], v[26:29], v[232:235], v[30:33]
	v_mfma_f32_16x16x32_bf16 v[14:17], v[26:29], v[240:243], v[4:7]
	s_setprio 0
	s_setprio 1
	v_mfma_f32_16x16x32_bf16 v[4:7], v[204:207], v[38:41], v[172:175]
	v_mfma_f32_16x16x32_bf16 v[58:61], v[208:211], v[42:45], v[4:7]
	v_mfma_f32_16x16x32_bf16 v[4:7], v[212:215], v[38:41], v[176:179]
	v_mfma_f32_16x16x32_bf16 v[54:57], v[216:219], v[42:45], v[4:7]
	v_mfma_f32_16x16x32_bf16 v[4:7], v[204:207], v[220:223], v[180:183]
	v_mfma_f32_16x16x32_bf16 v[42:45], v[208:211], v[224:227], v[4:7]
	v_mfma_f32_16x16x32_bf16 v[4:7], v[212:215], v[220:223], v[184:187]
	v_mfma_f32_16x16x32_bf16 v[38:41], v[216:219], v[224:227], v[4:7]
	v_mfma_f32_16x16x32_bf16 v[4:7], v[204:207], v[228:231], v[188:191]
	v_mfma_f32_16x16x32_bf16 v[26:29], v[208:211], v[232:235], v[4:7]
	v_mfma_f32_16x16x32_bf16 v[4:7], v[212:215], v[228:231], v[192:195]
	v_mfma_f32_16x16x32_bf16 v[22:25], v[216:219], v[232:235], v[4:7]
	v_mfma_f32_16x16x32_bf16 v[4:7], v[204:207], v[236:239], v[196:199]
	v_mfma_f32_16x16x32_bf16 v[10:13], v[208:211], v[240:243], v[4:7]
	v_mfma_f32_16x16x32_bf16 v[4:7], v[212:215], v[236:239], v[200:203]
	v_mfma_f32_16x16x32_bf16 v[6:9], v[216:219], v[240:243], v[4:7]
	s_barrier
	s_setprio 0
	s_mov_b32 s40, 2
	s_branch .LBB0_2959

.LBB0_2960:
	ds_read_b128 v[138:141], v147
	ds_read_b128 v[152:155], v147 offset:1024
	ds_read_b128 v[156:159], v147 offset:2048
	ds_read_b128 v[160:163], v147 offset:3072
	ds_read_b128 v[164:167], v148
	ds_read_b128 v[168:171], v148 offset:1024
	ds_read_b128 v[172:175], v148 offset:2048
	ds_read_b128 v[176:179], v148 offset:3072
	s_cmpk_eq_i32 s80, 0x54
	s_cselect_b32 s42, s8, s83
	s_cselect_b32 s43, s9, s84
	s_cselect_b32 s40, s28, s81
	s_cselect_b32 s41, s29, s82
	s_add_u32 s38, s42, 0x80
	s_addc_u32 s39, s43, 0
	ds_read_b128 v[180:183], v149
	ds_read_b128 v[184:187], v149 offset:1024
	ds_read_b128 v[188:191], v149 offset:2048
	ds_read_b128 v[192:195], v149 offset:3072
	ds_read_b128 v[196:199], v149 offset:4096
	ds_read_b128 v[200:203], v149 offset:5120
	ds_read_b128 v[204:207], v149 offset:6144
	ds_read_b128 v[208:211], v149 offset:7168
	s_mov_b32 m0, s70
	s_nop 0
	global_load_lds_dwordx4 v1, s[36:37] offset:0
	s_nop 0
	s_mov_b32 m0, s71
	s_nop 0
	global_load_lds_dwordx4 v143, s[36:37] offset:0
	s_waitcnt vmcnt(8)
	s_waitcnt lgkmcnt(0)
	s_barrier
	s_setprio 1
	v_mfma_f32_16x16x32_bf16 v[130:133], v[138:141], v[180:183], v[130:133]
	v_mfma_f32_16x16x32_bf16 v[130:133], v[152:155], v[184:187], v[130:133]
	v_mfma_f32_16x16x32_bf16 v[126:129], v[156:159], v[180:183], v[126:129]
	v_mfma_f32_16x16x32_bf16 v[126:129], v[160:163], v[184:187], v[126:129]
	v_mfma_f32_16x16x32_bf16 v[114:117], v[138:141], v[188:191], v[114:117]
	v_mfma_f32_16x16x32_bf16 v[114:117], v[152:155], v[192:195], v[114:117]
	v_mfma_f32_16x16x32_bf16 v[110:113], v[156:159], v[188:191], v[110:113]
	v_mfma_f32_16x16x32_bf16 v[110:113], v[160:163], v[192:195], v[110:113]
	v_mfma_f32_16x16x32_bf16 v[98:101], v[138:141], v[196:199], v[98:101]
	v_mfma_f32_16x16x32_bf16 v[98:101], v[152:155], v[200:203], v[98:101]
	v_mfma_f32_16x16x32_bf16 v[94:97], v[156:159], v[196:199], v[94:97]
	v_mfma_f32_16x16x32_bf16 v[94:97], v[160:163], v[200:203], v[94:97]
	v_mfma_f32_16x16x32_bf16 v[82:85], v[138:141], v[204:207], v[82:85]
	v_mfma_f32_16x16x32_bf16 v[82:85], v[152:155], v[208:211], v[82:85]
	v_mfma_f32_16x16x32_bf16 v[78:81], v[156:159], v[204:207], v[78:81]
	v_mfma_f32_16x16x32_bf16 v[78:81], v[160:163], v[208:211], v[78:81]
	s_setprio 0
	s_setprio 1
	v_mfma_f32_16x16x32_bf16 v[122:125], v[164:167], v[180:183], v[122:125]
	v_mfma_f32_16x16x32_bf16 v[122:125], v[168:171], v[184:187], v[122:125]
	v_mfma_f32_16x16x32_bf16 v[118:121], v[172:175], v[180:183], v[118:121]
	v_mfma_f32_16x16x32_bf16 v[118:121], v[176:179], v[184:187], v[118:121]
	v_mfma_f32_16x16x32_bf16 v[106:109], v[164:167], v[188:191], v[106:109]
	v_mfma_f32_16x16x32_bf16 v[106:109], v[168:171], v[192:195], v[106:109]
	v_mfma_f32_16x16x32_bf16 v[102:105], v[172:175], v[188:191], v[102:105]
	v_mfma_f32_16x16x32_bf16 v[102:105], v[176:179], v[192:195], v[102:105]
	v_mfma_f32_16x16x32_bf16 v[90:93], v[164:167], v[196:199], v[90:93]
	v_mfma_f32_16x16x32_bf16 v[90:93], v[168:171], v[200:203], v[90:93]
	v_mfma_f32_16x16x32_bf16 v[86:89], v[172:175], v[196:199], v[86:89]
	v_mfma_f32_16x16x32_bf16 v[86:89], v[176:179], v[200:203], v[86:89]
	v_mfma_f32_16x16x32_bf16 v[74:77], v[164:167], v[204:207], v[74:77]
	v_mfma_f32_16x16x32_bf16 v[74:77], v[168:171], v[208:211], v[74:77]
	v_mfma_f32_16x16x32_bf16 v[70:73], v[172:175], v[204:207], v[70:73]
	v_mfma_f32_16x16x32_bf16 v[70:73], v[176:179], v[208:211], v[70:73]
	s_barrier
	s_setprio 0
	ds_read_b128 v[180:183], v149 offset:16384
	ds_read_b128 v[184:187], v149 offset:17408
	ds_read_b128 v[188:191], v149 offset:18432
	ds_read_b128 v[192:195], v149 offset:19456
	ds_read_b128 v[196:199], v149 offset:20480
	ds_read_b128 v[200:203], v149 offset:21504
	ds_read_b128 v[204:207], v149 offset:22528
	ds_read_b128 v[208:211], v149 offset:23552
	s_mov_b32 m0, s46
	s_nop 0
	global_load_lds_dwordx4 v142, s[40:41] offset:0
	s_add_u32 s30, s40, 0x160000
	s_mov_b32 m0, s47
	s_nop 0
	global_load_lds_dwordx4 v144, s[40:41] offset:0
	s_addc_u32 s31, s41, 0
	s_mov_b32 m0, s52
	s_nop 0
	global_load_lds_dwordx4 v142, s[30:31] offset:0
	s_nop 0
	s_mov_b32 m0, s53
	s_nop 0
	global_load_lds_dwordx4 v144, s[30:31] offset:0
	s_nop 0
	s_mov_b32 m0, s45
	s_nop 0
	global_load_lds_dwordx4 v1, s[42:43] offset:0
	s_nop 0
	s_mov_b32 m0, s54
	s_nop 0
	global_load_lds_dwordx4 v143, s[42:43] offset:0
	s_waitcnt vmcnt(8)
	s_waitcnt lgkmcnt(0)
	s_barrier
	s_setprio 1
	v_mfma_f32_16x16x32_bf16 v[66:69], v[138:141], v[180:183], v[66:69]
	v_mfma_f32_16x16x32_bf16 v[66:69], v[152:155], v[184:187], v[66:69]
	v_mfma_f32_16x16x32_bf16 v[62:65], v[156:159], v[180:183], v[62:65]
	v_mfma_f32_16x16x32_bf16 v[62:65], v[160:163], v[184:187], v[62:65]
	v_mfma_f32_16x16x32_bf16 v[50:53], v[138:141], v[188:191], v[50:53]
	v_mfma_f32_16x16x32_bf16 v[50:53], v[152:155], v[192:195], v[50:53]
	v_mfma_f32_16x16x32_bf16 v[46:49], v[156:159], v[188:191], v[46:49]
	v_mfma_f32_16x16x32_bf16 v[46:49], v[160:163], v[192:195], v[46:49]
	v_mfma_f32_16x16x32_bf16 v[34:37], v[138:141], v[196:199], v[34:37]
	v_mfma_f32_16x16x32_bf16 v[34:37], v[152:155], v[200:203], v[34:37]
	v_mfma_f32_16x16x32_bf16 v[30:33], v[156:159], v[196:199], v[30:33]
	v_mfma_f32_16x16x32_bf16 v[30:33], v[160:163], v[200:203], v[30:33]
	v_mfma_f32_16x16x32_bf16 v[18:21], v[138:141], v[204:207], v[18:21]
	v_mfma_f32_16x16x32_bf16 v[18:21], v[152:155], v[208:211], v[18:21]
	v_mfma_f32_16x16x32_bf16 v[14:17], v[156:159], v[204:207], v[14:17]
	v_mfma_f32_16x16x32_bf16 v[14:17], v[160:163], v[208:211], v[14:17]
	s_setprio 0
	s_setprio 1
	v_mfma_f32_16x16x32_bf16 v[58:61], v[164:167], v[180:183], v[58:61]
	v_mfma_f32_16x16x32_bf16 v[54:57], v[172:175], v[180:183], v[54:57]
	v_mfma_f32_16x16x32_bf16 v[42:45], v[164:167], v[188:191], v[42:45]
	v_mfma_f32_16x16x32_bf16 v[38:41], v[172:175], v[188:191], v[38:41]
	v_mfma_f32_16x16x32_bf16 v[26:29], v[164:167], v[196:199], v[26:29]
	v_mfma_f32_16x16x32_bf16 v[22:25], v[172:175], v[196:199], v[22:25]
	v_mfma_f32_16x16x32_bf16 v[10:13], v[164:167], v[204:207], v[10:13]
	v_mfma_f32_16x16x32_bf16 v[4:7], v[172:175], v[204:207], v[6:9]
	v_mfma_f32_16x16x32_bf16 v[58:61], v[168:171], v[184:187], v[58:61]
	v_mfma_f32_16x16x32_bf16 v[54:57], v[176:179], v[184:187], v[54:57]
	v_mfma_f32_16x16x32_bf16 v[42:45], v[168:171], v[192:195], v[42:45]
	v_mfma_f32_16x16x32_bf16 v[38:41], v[176:179], v[192:195], v[38:41]
	v_mfma_f32_16x16x32_bf16 v[26:29], v[168:171], v[200:203], v[26:29]
	v_mfma_f32_16x16x32_bf16 v[22:25], v[176:179], v[200:203], v[22:25]
	v_mfma_f32_16x16x32_bf16 v[10:13], v[168:171], v[208:211], v[10:13]
	v_mfma_f32_16x16x32_bf16 v[4:7], v[176:179], v[208:211], v[4:7]
	s_barrier
; #define PG8_KSETUP() const bool last = (t == nt - 2); const char* a1 = cA + (size_t)(t + 1) * kstep; \
;             const char* a2 = last ? nA : cA + (size_t)(t + 2) * kstep; const char* b2 = last ? nB : cB + (size_t)(t + 2) * kstep; const char* a3 = a2 + kstep; const char* b3 = b2 + kstep; \
;             if (last && has_next) S.a_ready(nxt)
; template <class Epi, class Sched, bool ALIGN_EPI = false, bool SP2 = false>
; __device__ __forceinline__ void gemm_phase(PG8_LAS unsigned char* lds, const Gemm g, const Sched& S, const Epi& E) {
;     ...
;         int t0 = 0;
;         if constexpr (SP2 && Epi::NVM == 16) { if (ui > 0) { const int t = 0; PG8_KSETUP(); PG8_KITER_SP2(24, 24); t0 = 2; } }
;         if constexpr (SP2 && Epi::NVM == 8) { if (ui > 0) { const int t = 0; PG8_KSETUP(); PG8_KITER_SP2(16, 16); t0 = 2; } }
;         for (int t = t0; t < nt; t += 2) {
	s_setprio 0
	ds_read_b128 v[138:141], v150
	ds_read_b128 v[152:155], v150 offset:1024
	ds_read_b128 v[156:159], v150 offset:2048
	ds_read_b128 v[160:163], v150 offset:3072
	ds_read_b128 v[164:167], v151
	ds_read_b128 v[168:171], v151 offset:1024
	ds_read_b128 v[172:175], v151 offset:2048
	ds_read_b128 v[176:179], v151 offset:3072
	ds_read_b128 v[180:183], v149 offset:32768
	ds_read_b128 v[184:187], v149 offset:33792
	ds_read_b128 v[188:191], v149 offset:34816
	ds_read_b128 v[192:195], v149 offset:35840
	ds_read_b128 v[196:199], v149 offset:36864
	ds_read_b128 v[200:203], v149 offset:37888
	ds_read_b128 v[204:207], v149 offset:38912
	ds_read_b128 v[208:211], v149 offset:39936
	s_add_u32 s30, s42, 0x160000
	s_addc_u32 s31, s43, 0
	s_mov_b32 m0, s55
	s_nop 0
	global_load_lds_dwordx4 v1, s[30:31] offset:0
	s_nop 0
	s_mov_b32 m0, s56
	s_nop 0
	global_load_lds_dwordx4 v143, s[30:31] offset:0
	s_waitcnt vmcnt(8)
	s_waitcnt lgkmcnt(0)
	s_barrier
	s_setprio 1
	v_mfma_f32_16x16x32_bf16 v[130:133], v[138:141], v[180:183], v[130:133]
	v_mfma_f32_16x16x32_bf16 v[130:133], v[152:155], v[184:187], v[130:133]
	v_mfma_f32_16x16x32_bf16 v[126:129], v[156:159], v[180:183], v[126:129]
	v_mfma_f32_16x16x32_bf16 v[126:129], v[160:163], v[184:187], v[126:129]
	v_mfma_f32_16x16x32_bf16 v[114:117], v[138:141], v[188:191], v[114:117]
	v_mfma_f32_16x16x32_bf16 v[114:117], v[152:155], v[192:195], v[114:117]
	v_mfma_f32_16x16x32_bf16 v[110:113], v[156:159], v[188:191], v[110:113]
	v_mfma_f32_16x16x32_bf16 v[110:113], v[160:163], v[192:195], v[110:113]
	v_mfma_f32_16x16x32_bf16 v[98:101], v[138:141], v[196:199], v[98:101]
	v_mfma_f32_16x16x32_bf16 v[98:101], v[152:155], v[200:203], v[98:101]
	v_mfma_f32_16x16x32_bf16 v[94:97], v[156:159], v[196:199], v[94:97]
	v_mfma_f32_16x16x32_bf16 v[94:97], v[160:163], v[200:203], v[94:97]
	v_mfma_f32_16x16x32_bf16 v[82:85], v[138:141], v[204:207], v[82:85]
	v_mfma_f32_16x16x32_bf16 v[82:85], v[152:155], v[208:211], v[82:85]
	v_mfma_f32_16x16x32_bf16 v[78:81], v[156:159], v[204:207], v[78:81]
	v_mfma_f32_16x16x32_bf16 v[78:81], v[160:163], v[208:211], v[78:81]
	s_setprio 0
	s_setprio 1
	v_mfma_f32_16x16x32_bf16 v[122:125], v[164:167], v[180:183], v[122:125]
	v_mfma_f32_16x16x32_bf16 v[122:125], v[168:171], v[184:187], v[122:125]
	v_mfma_f32_16x16x32_bf16 v[118:121], v[172:175], v[180:183], v[118:121]
	v_mfma_f32_16x16x32_bf16 v[118:121], v[176:179], v[184:187], v[118:121]
	v_mfma_f32_16x16x32_bf16 v[106:109], v[164:167], v[188:191], v[106:109]
	v_mfma_f32_16x16x32_bf16 v[106:109], v[168:171], v[192:195], v[106:109]
	v_mfma_f32_16x16x32_bf16 v[102:105], v[172:175], v[188:191], v[102:105]
	v_mfma_f32_16x16x32_bf16 v[102:105], v[176:179], v[192:195], v[102:105]
	v_mfma_f32_16x16x32_bf16 v[90:93], v[164:167], v[196:199], v[90:93]
	v_mfma_f32_16x16x32_bf16 v[90:93], v[168:171], v[200:203], v[90:93]
	v_mfma_f32_16x16x32_bf16 v[86:89], v[172:175], v[196:199], v[86:89]
	v_mfma_f32_16x16x32_bf16 v[86:89], v[176:179], v[200:203], v[86:89]
	v_mfma_f32_16x16x32_bf16 v[74:77], v[164:167], v[204:207], v[74:77]
	v_mfma_f32_16x16x32_bf16 v[74:77], v[168:171], v[208:211], v[74:77]
	v_mfma_f32_16x16x32_bf16 v[70:73], v[172:175], v[204:207], v[70:73]
	v_mfma_f32_16x16x32_bf16 v[70:73], v[176:179], v[208:211], v[70:73]
	s_barrier
	s_setprio 0
	ds_read_b128 v[180:183], v149 offset:49152
	ds_read_b128 v[184:187], v149 offset:50176
	ds_read_b128 v[188:191], v149 offset:51200
	ds_read_b128 v[192:195], v149 offset:52224
	ds_read_b128 v[196:199], v149 offset:53248
	ds_read_b128 v[200:203], v149 offset:54272
	ds_read_b128 v[204:207], v149 offset:55296
	ds_read_b128 v[208:211], v149 offset:56320
	s_add_u32 s30, s40, 0x80
	s_addc_u32 s31, s41, 0
	s_mov_b32 m0, s64
	s_nop 0
	global_load_lds_dwordx4 v142, s[30:31] offset:0
	s_nop 0
	s_mov_b32 m0, s65
	s_nop 0
	global_load_lds_dwordx4 v144, s[30:31] offset:0
	s_add_u32 s30, s40, 0x160080
	s_addc_u32 s31, s41, 0
	s_mov_b32 m0, s68
	s_nop 0
	global_load_lds_dwordx4 v142, s[30:31] offset:0
	s_nop 0
	s_mov_b32 m0, s69
	s_nop 0
	global_load_lds_dwordx4 v144, s[30:31] offset:0
	s_nop 0
	s_mov_b32 m0, s66
	s_nop 0
	global_load_lds_dwordx4 v1, s[38:39] offset:0
	s_nop 0
	s_mov_b32 m0, s67
	s_nop 0
	global_load_lds_dwordx4 v143, s[38:39] offset:0
	s_waitcnt vmcnt(8)
	s_waitcnt lgkmcnt(0)
	s_barrier
	s_setprio 1
	v_mfma_f32_16x16x32_bf16 v[66:69], v[138:141], v[180:183], v[66:69]
	v_mfma_f32_16x16x32_bf16 v[66:69], v[152:155], v[184:187], v[66:69]
	v_mfma_f32_16x16x32_bf16 v[62:65], v[156:159], v[180:183], v[62:65]
	v_mfma_f32_16x16x32_bf16 v[62:65], v[160:163], v[184:187], v[62:65]
	v_mfma_f32_16x16x32_bf16 v[50:53], v[138:141], v[188:191], v[50:53]
	v_mfma_f32_16x16x32_bf16 v[50:53], v[152:155], v[192:195], v[50:53]
	v_mfma_f32_16x16x32_bf16 v[46:49], v[156:159], v[188:191], v[46:49]
	v_mfma_f32_16x16x32_bf16 v[46:49], v[160:163], v[192:195], v[46:49]
	v_mfma_f32_16x16x32_bf16 v[34:37], v[138:141], v[196:199], v[34:37]
	v_mfma_f32_16x16x32_bf16 v[34:37], v[152:155], v[200:203], v[34:37]
	v_mfma_f32_16x16x32_bf16 v[30:33], v[156:159], v[196:199], v[30:33]
	v_mfma_f32_16x16x32_bf16 v[30:33], v[160:163], v[200:203], v[30:33]
	v_mfma_f32_16x16x32_bf16 v[18:21], v[138:141], v[204:207], v[18:21]
	v_mfma_f32_16x16x32_bf16 v[18:21], v[152:155], v[208:211], v[18:21]
	v_mfma_f32_16x16x32_bf16 v[14:17], v[156:159], v[204:207], v[14:17]
	v_mfma_f32_16x16x32_bf16 v[14:17], v[160:163], v[208:211], v[14:17]
	s_setprio 0
	s_setprio 1
	v_mfma_f32_16x16x32_bf16 v[58:61], v[164:167], v[180:183], v[58:61]
	v_mfma_f32_16x16x32_bf16 v[54:57], v[172:175], v[180:183], v[54:57]
	v_mfma_f32_16x16x32_bf16 v[42:45], v[164:167], v[188:191], v[42:45]
	v_mfma_f32_16x16x32_bf16 v[38:41], v[172:175], v[188:191], v[38:41]
	v_mfma_f32_16x16x32_bf16 v[26:29], v[164:167], v[196:199], v[26:29]
	v_mfma_f32_16x16x32_bf16 v[22:25], v[172:175], v[196:199], v[22:25]
	v_mfma_f32_16x16x32_bf16 v[8:11], v[164:167], v[204:207], v[10:13]
	v_mfma_f32_16x16x32_bf16 v[4:7], v[172:175], v[204:207], v[4:7]
	v_mfma_f32_16x16x32_bf16 v[58:61], v[168:171], v[184:187], v[58:61]
	v_mfma_f32_16x16x32_bf16 v[54:57], v[176:179], v[184:187], v[54:57]
	v_mfma_f32_16x16x32_bf16 v[42:45], v[168:171], v[192:195], v[42:45]
	v_mfma_f32_16x16x32_bf16 v[38:41], v[176:179], v[192:195], v[38:41]
	v_mfma_f32_16x16x32_bf16 v[26:29], v[168:171], v[200:203], v[26:29]
	v_mfma_f32_16x16x32_bf16 v[22:25], v[176:179], v[200:203], v[22:25]
	v_mfma_f32_16x16x32_bf16 v[10:13], v[168:171], v[208:211], v[8:11]
	v_mfma_f32_16x16x32_bf16 v[6:9], v[176:179], v[208:211], v[4:7]
	s_barrier
	s_setprio 0
	s_add_i32 s80, s80, 2
	s_add_u32 s81, s81, 0x100
	s_addc_u32 s82, s82, 0
	s_add_u32 s83, s83, 0x100
	s_addc_u32 s84, s84, 0
	s_add_u32 s36, s36, 0x100
	s_addc_u32 s37, s37, 0
	s_cmpk_gt_u32 s80, 0x55
	s_cbranch_scc0 .LBB0_2960
	s_and_b64 vcc, exec, s[16:17]
	s_cbranch_vccz .LBB0_2963
	s_barrier

.LBB0_3114:
	ds_read_b128 v[136:139], v149
	ds_read_b128 v[154:157], v149 offset:1024
	ds_read_b128 v[158:161], v149 offset:2048
	ds_read_b128 v[162:165], v149 offset:3072
	ds_read_b128 v[166:169], v150
	ds_read_b128 v[170:173], v150 offset:1024
	ds_read_b128 v[174:177], v150 offset:2048
	ds_read_b128 v[178:181], v150 offset:3072
	s_cmp_eq_u32 s78, 28
	s_cselect_b32 s40, s72, s76
	s_cselect_b32 s41, s19, s77
	s_cselect_b32 s38, s73, s74
	s_cselect_b32 s39, s17, s75
	s_add_u32 s36, s40, 0x80
	s_addc_u32 s37, s41, 0
	ds_read_b128 v[182:185], v151
	ds_read_b128 v[186:189], v151 offset:1024
	ds_read_b128 v[190:193], v151 offset:2048
	ds_read_b128 v[194:197], v151 offset:3072
	ds_read_b128 v[198:201], v151 offset:4096
	ds_read_b128 v[202:205], v151 offset:5120
	ds_read_b128 v[206:209], v151 offset:6144
	ds_read_b128 v[210:213], v151 offset:7168
	s_mov_b32 m0, s67
	s_nop 0
	global_load_lds_dwordx4 v1, s[28:29] offset:0
	s_nop 0
	s_mov_b32 m0, s68
	s_nop 0
	global_load_lds_dwordx4 v143, s[28:29] offset:0
	s_waitcnt vmcnt(8)
	s_waitcnt lgkmcnt(0)
	s_barrier
	s_setprio 1
	v_mfma_f32_16x16x32_bf16 v[126:129], v[136:139], v[182:185], v[126:129]
	v_mfma_f32_16x16x32_bf16 v[126:129], v[154:157], v[186:189], v[126:129]
	v_mfma_f32_16x16x32_bf16 v[122:125], v[158:161], v[182:185], v[122:125]
	v_mfma_f32_16x16x32_bf16 v[122:125], v[162:165], v[186:189], v[122:125]
	v_mfma_f32_16x16x32_bf16 v[114:117], v[136:139], v[190:193], v[114:117]
	v_mfma_f32_16x16x32_bf16 v[114:117], v[154:157], v[194:197], v[114:117]
	v_mfma_f32_16x16x32_bf16 v[106:109], v[158:161], v[190:193], v[106:109]
	v_mfma_f32_16x16x32_bf16 v[106:109], v[162:165], v[194:197], v[106:109]
	v_mfma_f32_16x16x32_bf16 v[98:101], v[136:139], v[198:201], v[98:101]
	v_mfma_f32_16x16x32_bf16 v[98:101], v[154:157], v[202:205], v[98:101]
	v_mfma_f32_16x16x32_bf16 v[90:93], v[158:161], v[198:201], v[90:93]
	v_mfma_f32_16x16x32_bf16 v[90:93], v[162:165], v[202:205], v[90:93]
	v_mfma_f32_16x16x32_bf16 v[82:85], v[136:139], v[206:209], v[82:85]
	v_mfma_f32_16x16x32_bf16 v[82:85], v[154:157], v[210:213], v[82:85]
	v_mfma_f32_16x16x32_bf16 v[74:77], v[158:161], v[206:209], v[74:77]
	v_mfma_f32_16x16x32_bf16 v[74:77], v[162:165], v[210:213], v[74:77]
	s_setprio 0
	s_setprio 1
	v_mfma_f32_16x16x32_bf16 v[118:121], v[166:169], v[182:185], v[118:121]
	v_mfma_f32_16x16x32_bf16 v[118:121], v[170:173], v[186:189], v[118:121]
	v_mfma_f32_16x16x32_bf16 v[110:113], v[174:177], v[182:185], v[110:113]
	v_mfma_f32_16x16x32_bf16 v[110:113], v[178:181], v[186:189], v[110:113]
	v_mfma_f32_16x16x32_bf16 v[102:105], v[166:169], v[190:193], v[102:105]
	v_mfma_f32_16x16x32_bf16 v[102:105], v[170:173], v[194:197], v[102:105]
	v_mfma_f32_16x16x32_bf16 v[94:97], v[174:177], v[190:193], v[94:97]
	v_mfma_f32_16x16x32_bf16 v[94:97], v[178:181], v[194:197], v[94:97]
	v_mfma_f32_16x16x32_bf16 v[86:89], v[166:169], v[198:201], v[86:89]
	v_mfma_f32_16x16x32_bf16 v[86:89], v[170:173], v[202:205], v[86:89]
	v_mfma_f32_16x16x32_bf16 v[78:81], v[174:177], v[198:201], v[78:81]
	v_mfma_f32_16x16x32_bf16 v[78:81], v[178:181], v[202:205], v[78:81]
	v_mfma_f32_16x16x32_bf16 v[70:73], v[166:169], v[206:209], v[70:73]
	v_mfma_f32_16x16x32_bf16 v[70:73], v[170:173], v[210:213], v[70:73]
	v_mfma_f32_16x16x32_bf16 v[66:69], v[174:177], v[206:209], v[66:69]
	v_mfma_f32_16x16x32_bf16 v[66:69], v[178:181], v[210:213], v[66:69]
	s_barrier
	s_setprio 0
	ds_read_b128 v[182:185], v151 offset:16384
	ds_read_b128 v[186:189], v151 offset:17408
	ds_read_b128 v[190:193], v151 offset:18432
	ds_read_b128 v[194:197], v151 offset:19456
	ds_read_b128 v[198:201], v151 offset:20480
	ds_read_b128 v[202:205], v151 offset:21504
	ds_read_b128 v[206:209], v151 offset:22528
	ds_read_b128 v[210:213], v151 offset:23552
	s_mov_b32 m0, s25
	s_nop 0
	global_load_lds_dwordx4 v135, s[38:39] offset:0
	s_add_u32 s30, s38, 0x80000
	s_mov_b32 m0, s46
	s_nop 0
	global_load_lds_dwordx4 v145, s[38:39] offset:0
	s_addc_u32 s31, s39, 0
	s_mov_b32 m0, s47
	s_nop 0
	global_load_lds_dwordx4 v135, s[30:31] offset:0
	s_nop 0
	s_mov_b32 m0, s52
	s_nop 0
	global_load_lds_dwordx4 v145, s[30:31] offset:0
	s_nop 0
	s_mov_b32 m0, s43
	s_nop 0
	global_load_lds_dwordx4 v1, s[40:41] offset:0
	s_nop 0
	s_mov_b32 m0, s53
	s_nop 0
	global_load_lds_dwordx4 v143, s[40:41] offset:0
	s_waitcnt vmcnt(8)
	s_waitcnt lgkmcnt(0)
	s_barrier
	s_setprio 1
	v_mfma_f32_16x16x32_bf16 v[62:65], v[136:139], v[182:185], v[62:65]
	v_mfma_f32_16x16x32_bf16 v[62:65], v[154:157], v[186:189], v[62:65]
	v_mfma_f32_16x16x32_bf16 v[58:61], v[158:161], v[182:185], v[58:61]
	v_mfma_f32_16x16x32_bf16 v[58:61], v[162:165], v[186:189], v[58:61]
	v_mfma_f32_16x16x32_bf16 v[50:53], v[136:139], v[190:193], v[50:53]
	v_mfma_f32_16x16x32_bf16 v[50:53], v[154:157], v[194:197], v[50:53]
	v_mfma_f32_16x16x32_bf16 v[42:45], v[158:161], v[190:193], v[42:45]
	v_mfma_f32_16x16x32_bf16 v[42:45], v[162:165], v[194:197], v[42:45]
	v_mfma_f32_16x16x32_bf16 v[34:37], v[136:139], v[198:201], v[34:37]
	v_mfma_f32_16x16x32_bf16 v[34:37], v[154:157], v[202:205], v[34:37]
	v_mfma_f32_16x16x32_bf16 v[26:29], v[158:161], v[198:201], v[26:29]
	v_mfma_f32_16x16x32_bf16 v[26:29], v[162:165], v[202:205], v[26:29]
	v_mfma_f32_16x16x32_bf16 v[18:21], v[136:139], v[206:209], v[18:21]
	v_mfma_f32_16x16x32_bf16 v[18:21], v[154:157], v[210:213], v[18:21]
	v_mfma_f32_16x16x32_bf16 v[10:13], v[158:161], v[206:209], v[10:13]
	v_mfma_f32_16x16x32_bf16 v[10:13], v[162:165], v[210:213], v[10:13]
	s_setprio 0
	s_setprio 1
	v_mfma_f32_16x16x32_bf16 v[54:57], v[166:169], v[182:185], v[54:57]
	v_mfma_f32_16x16x32_bf16 v[54:57], v[170:173], v[186:189], v[54:57]
	v_mfma_f32_16x16x32_bf16 v[46:49], v[174:177], v[182:185], v[46:49]
	v_mfma_f32_16x16x32_bf16 v[46:49], v[178:181], v[186:189], v[46:49]
	v_mfma_f32_16x16x32_bf16 v[38:41], v[166:169], v[190:193], v[38:41]
	v_mfma_f32_16x16x32_bf16 v[38:41], v[170:173], v[194:197], v[38:41]
	v_mfma_f32_16x16x32_bf16 v[30:33], v[174:177], v[190:193], v[30:33]
	v_mfma_f32_16x16x32_bf16 v[30:33], v[178:181], v[194:197], v[30:33]
	v_mfma_f32_16x16x32_bf16 v[22:25], v[166:169], v[198:201], v[22:25]
	v_mfma_f32_16x16x32_bf16 v[22:25], v[170:173], v[202:205], v[22:25]
	v_mfma_f32_16x16x32_bf16 v[14:17], v[174:177], v[198:201], v[14:17]
	v_mfma_f32_16x16x32_bf16 v[14:17], v[178:181], v[202:205], v[14:17]
	v_mfma_f32_16x16x32_bf16 v[6:9], v[166:169], v[206:209], v[6:9]
	v_mfma_f32_16x16x32_bf16 v[6:9], v[170:173], v[210:213], v[6:9]
	v_mfma_f32_16x16x32_bf16 v[2:5], v[174:177], v[206:209], v[2:5]
	v_mfma_f32_16x16x32_bf16 v[2:5], v[178:181], v[210:213], v[2:5]
	s_barrier
; #define PG8_KSETUP() const bool last = (t == nt - 2); const char* a1 = cA + (size_t)(t + 1) * kstep; \
;             const char* a2 = last ? nA : cA + (size_t)(t + 2) * kstep; const char* b2 = last ? nB : cB + (size_t)(t + 2) * kstep; const char* a3 = a2 + kstep; const char* b3 = b2 + kstep; \
;             if (last && has_next) S.a_ready(nxt)
; template <class Epi, class Sched, bool ALIGN_EPI = false, bool SP2 = false>
; __device__ __forceinline__ void gemm_phase(PG8_LAS unsigned char* lds, const Gemm g, const Sched& S, const Epi& E) {
;     ...
;         int t0 = 0;
;         if constexpr (SP2 && Epi::NVM == 16) { if (ui > 0) { const int t = 0; PG8_KSETUP(); PG8_KITER_SP2(24, 24); t0 = 2; } }
;         if constexpr (SP2 && Epi::NVM == 8) { if (ui > 0) { const int t = 0; PG8_KSETUP(); PG8_KITER_SP2(16, 16); t0 = 2; } }
;         for (int t = t0; t < nt; t += 2) {
	s_setprio 0
	ds_read_b128 v[136:139], v152
	ds_read_b128 v[154:157], v152 offset:1024
	ds_read_b128 v[158:161], v152 offset:2048
	ds_read_b128 v[162:165], v152 offset:3072
	ds_read_b128 v[166:169], v153
	ds_read_b128 v[170:173], v153 offset:1024
	ds_read_b128 v[174:177], v153 offset:2048
	ds_read_b128 v[178:181], v153 offset:3072
	ds_read_b128 v[182:185], v151 offset:32768
	ds_read_b128 v[186:189], v151 offset:33792
	ds_read_b128 v[190:193], v151 offset:34816
	ds_read_b128 v[194:197], v151 offset:35840
	ds_read_b128 v[198:201], v151 offset:36864
	ds_read_b128 v[202:205], v151 offset:37888
	ds_read_b128 v[206:209], v151 offset:38912
	ds_read_b128 v[210:213], v151 offset:39936
	s_add_u32 s30, s40, 0x80000
	s_addc_u32 s31, s41, 0
	s_mov_b32 m0, s54
	s_nop 0
	global_load_lds_dwordx4 v1, s[30:31] offset:0
	s_nop 0
	s_mov_b32 m0, s55
	s_nop 0
	global_load_lds_dwordx4 v143, s[30:31] offset:0
	s_waitcnt vmcnt(8)
	s_waitcnt lgkmcnt(0)
	s_barrier
	s_setprio 1
	v_mfma_f32_16x16x32_bf16 v[126:129], v[136:139], v[182:185], v[126:129]
	v_mfma_f32_16x16x32_bf16 v[126:129], v[154:157], v[186:189], v[126:129]
	v_mfma_f32_16x16x32_bf16 v[122:125], v[158:161], v[182:185], v[122:125]
	v_mfma_f32_16x16x32_bf16 v[122:125], v[162:165], v[186:189], v[122:125]
	v_mfma_f32_16x16x32_bf16 v[114:117], v[136:139], v[190:193], v[114:117]
	v_mfma_f32_16x16x32_bf16 v[114:117], v[154:157], v[194:197], v[114:117]
	v_mfma_f32_16x16x32_bf16 v[106:109], v[158:161], v[190:193], v[106:109]
	v_mfma_f32_16x16x32_bf16 v[106:109], v[162:165], v[194:197], v[106:109]
	v_mfma_f32_16x16x32_bf16 v[98:101], v[136:139], v[198:201], v[98:101]
	v_mfma_f32_16x16x32_bf16 v[98:101], v[154:157], v[202:205], v[98:101]
	v_mfma_f32_16x16x32_bf16 v[90:93], v[158:161], v[198:201], v[90:93]
	v_mfma_f32_16x16x32_bf16 v[90:93], v[162:165], v[202:205], v[90:93]
	v_mfma_f32_16x16x32_bf16 v[82:85], v[136:139], v[206:209], v[82:85]
	v_mfma_f32_16x16x32_bf16 v[82:85], v[154:157], v[210:213], v[82:85]
	v_mfma_f32_16x16x32_bf16 v[74:77], v[158:161], v[206:209], v[74:77]
	v_mfma_f32_16x16x32_bf16 v[74:77], v[162:165], v[210:213], v[74:77]
	s_setprio 0
	s_setprio 1
	v_mfma_f32_16x16x32_bf16 v[118:121], v[166:169], v[182:185], v[118:121]
	v_mfma_f32_16x16x32_bf16 v[118:121], v[170:173], v[186:189], v[118:121]
	v_mfma_f32_16x16x32_bf16 v[110:113], v[174:177], v[182:185], v[110:113]
	v_mfma_f32_16x16x32_bf16 v[110:113], v[178:181], v[186:189], v[110:113]
	v_mfma_f32_16x16x32_bf16 v[102:105], v[166:169], v[190:193], v[102:105]
	v_mfma_f32_16x16x32_bf16 v[102:105], v[170:173], v[194:197], v[102:105]
	v_mfma_f32_16x16x32_bf16 v[94:97], v[174:177], v[190:193], v[94:97]
	v_mfma_f32_16x16x32_bf16 v[94:97], v[178:181], v[194:197], v[94:97]
	v_mfma_f32_16x16x32_bf16 v[86:89], v[166:169], v[198:201], v[86:89]
	v_mfma_f32_16x16x32_bf16 v[86:89], v[170:173], v[202:205], v[86:89]
	v_mfma_f32_16x16x32_bf16 v[78:81], v[174:177], v[198:201], v[78:81]
	v_mfma_f32_16x16x32_bf16 v[78:81], v[178:181], v[202:205], v[78:81]
	v_mfma_f32_16x16x32_bf16 v[70:73], v[166:169], v[206:209], v[70:73]
	v_mfma_f32_16x16x32_bf16 v[70:73], v[170:173], v[210:213], v[70:73]
	v_mfma_f32_16x16x32_bf16 v[66:69], v[174:177], v[206:209], v[66:69]
	v_mfma_f32_16x16x32_bf16 v[66:69], v[178:181], v[210:213], v[66:69]
	s_barrier
	s_setprio 0
	ds_read_b128 v[182:185], v151 offset:49152
	ds_read_b128 v[186:189], v151 offset:50176
	ds_read_b128 v[190:193], v151 offset:51200
	ds_read_b128 v[194:197], v151 offset:52224
	ds_read_b128 v[198:201], v151 offset:53248
	ds_read_b128 v[202:205], v151 offset:54272
	ds_read_b128 v[206:209], v151 offset:55296
	ds_read_b128 v[210:213], v151 offset:56320
	s_add_u32 s30, s38, 0x80
	s_addc_u32 s31, s39, 0
	s_mov_b32 m0, s57
	s_nop 0
	global_load_lds_dwordx4 v135, s[30:31] offset:0
	s_nop 0
	s_mov_b32 m0, s58
	s_nop 0
	global_load_lds_dwordx4 v145, s[30:31] offset:0
	s_add_u32 s30, s38, 0x80080
	s_addc_u32 s31, s39, 0
	s_mov_b32 m0, s65
	s_nop 0
	global_load_lds_dwordx4 v135, s[30:31] offset:0
	s_nop 0
	s_mov_b32 m0, s66
	s_nop 0
	global_load_lds_dwordx4 v145, s[30:31] offset:0
	s_nop 0
	s_mov_b32 m0, s59
	s_nop 0
	global_load_lds_dwordx4 v1, s[36:37] offset:0
	s_nop 0
	s_mov_b32 m0, s64
	s_nop 0
	global_load_lds_dwordx4 v143, s[36:37] offset:0
	s_waitcnt vmcnt(8)
	s_waitcnt lgkmcnt(0)
	s_barrier
	s_setprio 1
	v_mfma_f32_16x16x32_bf16 v[62:65], v[136:139], v[182:185], v[62:65]
	v_mfma_f32_16x16x32_bf16 v[62:65], v[154:157], v[186:189], v[62:65]
	v_mfma_f32_16x16x32_bf16 v[58:61], v[158:161], v[182:185], v[58:61]
	v_mfma_f32_16x16x32_bf16 v[58:61], v[162:165], v[186:189], v[58:61]
	v_mfma_f32_16x16x32_bf16 v[50:53], v[136:139], v[190:193], v[50:53]
	v_mfma_f32_16x16x32_bf16 v[50:53], v[154:157], v[194:197], v[50:53]
	v_mfma_f32_16x16x32_bf16 v[42:45], v[158:161], v[190:193], v[42:45]
	v_mfma_f32_16x16x32_bf16 v[42:45], v[162:165], v[194:197], v[42:45]
	v_mfma_f32_16x16x32_bf16 v[34:37], v[136:139], v[198:201], v[34:37]
	v_mfma_f32_16x16x32_bf16 v[34:37], v[154:157], v[202:205], v[34:37]
	v_mfma_f32_16x16x32_bf16 v[26:29], v[158:161], v[198:201], v[26:29]
	v_mfma_f32_16x16x32_bf16 v[26:29], v[162:165], v[202:205], v[26:29]
	v_mfma_f32_16x16x32_bf16 v[18:21], v[136:139], v[206:209], v[18:21]
	v_mfma_f32_16x16x32_bf16 v[18:21], v[154:157], v[210:213], v[18:21]
	v_mfma_f32_16x16x32_bf16 v[10:13], v[158:161], v[206:209], v[10:13]
	v_mfma_f32_16x16x32_bf16 v[10:13], v[162:165], v[210:213], v[10:13]
	s_setprio 0
	s_setprio 1
	v_mfma_f32_16x16x32_bf16 v[54:57], v[166:169], v[182:185], v[54:57]
	v_mfma_f32_16x16x32_bf16 v[54:57], v[170:173], v[186:189], v[54:57]
	v_mfma_f32_16x16x32_bf16 v[46:49], v[174:177], v[182:185], v[46:49]
	v_mfma_f32_16x16x32_bf16 v[46:49], v[178:181], v[186:189], v[46:49]
	v_mfma_f32_16x16x32_bf16 v[38:41], v[166:169], v[190:193], v[38:41]
	v_mfma_f32_16x16x32_bf16 v[38:41], v[170:173], v[194:197], v[38:41]
	v_mfma_f32_16x16x32_bf16 v[30:33], v[174:177], v[190:193], v[30:33]
	v_mfma_f32_16x16x32_bf16 v[30:33], v[178:181], v[194:197], v[30:33]
	v_mfma_f32_16x16x32_bf16 v[22:25], v[166:169], v[198:201], v[22:25]
	v_mfma_f32_16x16x32_bf16 v[22:25], v[170:173], v[202:205], v[22:25]
	v_mfma_f32_16x16x32_bf16 v[14:17], v[174:177], v[198:201], v[14:17]
	v_mfma_f32_16x16x32_bf16 v[14:17], v[178:181], v[202:205], v[14:17]
	v_mfma_f32_16x16x32_bf16 v[6:9], v[166:169], v[206:209], v[6:9]
	v_mfma_f32_16x16x32_bf16 v[6:9], v[170:173], v[210:213], v[6:9]
	v_mfma_f32_16x16x32_bf16 v[2:5], v[174:177], v[206:209], v[2:5]
	v_mfma_f32_16x16x32_bf16 v[2:5], v[178:181], v[210:213], v[2:5]
	s_barrier
	s_setprio 0
	s_add_i32 s78, s78, 2
	s_add_u32 s74, s74, 0x100
	s_addc_u32 s75, s75, 0
	s_add_u32 s76, s76, 0x100
	s_addc_u32 s77, s77, 0
	s_add_u32 s28, s28, 0x100
	s_addc_u32 s29, s29, 0
	s_cmp_gt_u32 s78, 29
	s_cbranch_scc0 .LBB0_3114
	s_and_b64 vcc, exec, s[14:15]
	s_cbranch_vccz .LBB0_3117
	s_barrier

; #define PG8_KSETUP() const bool last = (t == nt - 2); const char* a1 = cA + (size_t)(t + 1) * kstep; \
;             const char* a2 = last ? nA : cA + (size_t)(t + 2) * kstep; const char* b2 = last ? nB : cB + (size_t)(t + 2) * kstep; const char* a3 = a2 + kstep; const char* b3 = b2 + kstep; \
;             if (last && has_next) S.a_ready(nxt)
; template <class Epi, class Sched, bool ALIGN_EPI = false, bool SP2 = false>
; __device__ __forceinline__ void gemm_phase(PG8_LAS unsigned char* lds, const Gemm g, const Sched& S, const Epi& E) {
;     ...
;         if constexpr (SP2 && Epi::NVM == 16) { if (ui > 0) { const int t = 0; PG8_KSETUP(); PG8_KITER_SP2(24, 24); t0 = 2; } }
.LBB0_3464:
	s_cmp_eq_u32 s29, 0
	s_mov_b32 s50, 0
	s_cbranch_scc1 .LBB0_3466
	ds_read_b128 v[4:7], v147
	ds_read_b128 v[8:11], v147 offset:1024
	ds_read_b128 v[12:15], v147 offset:2048
	ds_read_b128 v[16:19], v147 offset:3072
	ds_read_b128 v[20:23], v148
	ds_read_b128 v[24:27], v148 offset:1024
	ds_read_b128 v[28:31], v148 offset:2048
	ds_read_b128 v[32:35], v148 offset:3072
	s_add_u32 s40, s46, 0x100
	s_addc_u32 s41, s47, 0
	s_add_u32 s30, s48, 0x100
	s_addc_u32 s31, s49, 0
	s_add_u32 s38, s46, 0x180
	s_addc_u32 s39, s47, 0
	ds_read_b128 v[36:39], v149
	ds_read_b128 v[40:43], v149 offset:1024
	ds_read_b128 v[44:47], v149 offset:2048
	ds_read_b128 v[48:51], v149 offset:3072
	ds_read_b128 v[52:55], v149 offset:4096
	ds_read_b128 v[56:59], v149 offset:5120
	ds_read_b128 v[60:63], v149 offset:6144
	ds_read_b128 v[64:67], v149 offset:7168
	s_add_u32 s50, s46, 0x80080
	s_addc_u32 s51, s47, 0
	s_mov_b32 m0, s73
	s_nop 0
	global_load_lds_dwordx4 v1, s[50:51] offset:0
	s_nop 0
	s_mov_b32 m0, s74
	s_nop 0
	global_load_lds_dwordx4 v143, s[50:51] offset:0
	s_waitcnt vmcnt(24)
	s_waitcnt lgkmcnt(0)
	s_barrier
	s_setprio 1
	v_mfma_f32_16x16x32_bf16 v[92:95], v[4:7], v[60:63], 0
	v_mfma_f32_16x16x32_bf16 v[68:71], v[4:7], v[36:39], 0
	v_mfma_f32_16x16x32_bf16 v[72:75], v[12:15], v[36:39], 0
	v_mfma_f32_16x16x32_bf16 v[76:79], v[4:7], v[44:47], 0
	v_mfma_f32_16x16x32_bf16 v[80:83], v[12:15], v[44:47], 0
	v_mfma_f32_16x16x32_bf16 v[84:87], v[4:7], v[52:55], 0
	v_mfma_f32_16x16x32_bf16 v[88:91], v[12:15], v[52:55], 0
	v_mfma_f32_16x16x32_bf16 v[102:105], v[8:11], v[64:67], v[92:95]
	v_mfma_f32_16x16x32_bf16 v[92:95], v[12:15], v[60:63], 0
	v_mfma_f32_16x16x32_bf16 v[68:71], v[8:11], v[40:43], v[68:71]
	v_mfma_f32_16x16x32_bf16 v[72:75], v[16:19], v[40:43], v[72:75]
	v_mfma_f32_16x16x32_bf16 v[76:79], v[8:11], v[48:51], v[76:79]
	v_mfma_f32_16x16x32_bf16 v[80:83], v[16:19], v[48:51], v[80:83]
	v_mfma_f32_16x16x32_bf16 v[84:87], v[8:11], v[56:59], v[84:87]
	v_mfma_f32_16x16x32_bf16 v[88:91], v[16:19], v[56:59], v[88:91]
	v_mfma_f32_16x16x32_bf16 v[106:109], v[16:19], v[64:67], v[92:95]
	s_setprio 0
	s_setprio 1
	v_mfma_f32_16x16x32_bf16 v[92:95], v[20:23], v[36:39], 0
	v_mfma_f32_16x16x32_bf16 v[36:39], v[28:31], v[36:39], 0
	v_mfma_f32_16x16x32_bf16 v[118:121], v[24:27], v[40:43], v[92:95]
	v_mfma_f32_16x16x32_bf16 v[36:39], v[32:35], v[40:43], v[36:39]
	v_mfma_f32_16x16x32_bf16 v[40:43], v[20:23], v[44:47], 0
	v_mfma_f32_16x16x32_bf16 v[44:47], v[28:31], v[44:47], 0
	v_mfma_f32_16x16x32_bf16 v[40:43], v[24:27], v[48:51], v[40:43]
	v_mfma_f32_16x16x32_bf16 v[44:47], v[32:35], v[48:51], v[44:47]
	v_mfma_f32_16x16x32_bf16 v[48:51], v[20:23], v[52:55], 0
	v_mfma_f32_16x16x32_bf16 v[52:55], v[28:31], v[52:55], 0
	v_mfma_f32_16x16x32_bf16 v[48:51], v[24:27], v[56:59], v[48:51]
	v_mfma_f32_16x16x32_bf16 v[52:55], v[32:35], v[56:59], v[52:55]
	v_mfma_f32_16x16x32_bf16 v[56:59], v[20:23], v[60:63], 0
	v_mfma_f32_16x16x32_bf16 v[60:63], v[28:31], v[60:63], 0
	v_mfma_f32_16x16x32_bf16 v[56:59], v[24:27], v[64:67], v[56:59]
	v_mfma_f32_16x16x32_bf16 v[60:63], v[32:35], v[64:67], v[60:63]
	s_barrier
	s_setprio 0
	ds_read_b128 v[64:67], v149 offset:16384
	ds_read_b128 v[92:95], v149 offset:17408
	ds_read_b128 v[96:99], v149 offset:18432
	ds_read_b128 v[110:113], v149 offset:19456
	ds_read_b128 v[114:117], v149 offset:20480
	ds_read_b128 v[122:125], v149 offset:21504
	ds_read_b128 v[126:129], v149 offset:22528
	ds_read_b128 v[130:133], v149 offset:23552
	s_mov_b32 m0, s45
	s_nop 0
	global_load_lds_dwordx4 v142, s[30:31] offset:0
	s_nop 0
	s_mov_b32 m0, s54
	s_nop 0
	global_load_lds_dwordx4 v144, s[30:31] offset:0
	s_add_u32 s30, s48, 0x80100
	s_addc_u32 s31, s49, 0
	s_mov_b32 m0, s55
	s_nop 0
	global_load_lds_dwordx4 v142, s[30:31] offset:0
	s_nop 0
	s_mov_b32 m0, s56
	s_nop 0
	global_load_lds_dwordx4 v144, s[30:31] offset:0
	s_nop 0
	s_mov_b32 m0, s33
	s_nop 0
	global_load_lds_dwordx4 v1, s[40:41] offset:0
	s_nop 0
	s_mov_b32 m0, s57
	s_nop 0
	global_load_lds_dwordx4 v143, s[40:41] offset:0
	s_waitcnt vmcnt(24)
	s_waitcnt lgkmcnt(0)
	s_barrier
	s_setprio 1
	v_mfma_f32_16x16x32_bf16 v[138:141], v[4:7], v[64:67], 0
	v_mfma_f32_16x16x32_bf16 v[156:159], v[4:7], v[96:99], 0
	v_mfma_f32_16x16x32_bf16 v[164:167], v[4:7], v[114:117], 0
	v_mfma_f32_16x16x32_bf16 v[4:7], v[4:7], v[126:129], 0
	v_mfma_f32_16x16x32_bf16 v[138:141], v[8:11], v[92:95], v[138:141]
	v_mfma_f32_16x16x32_bf16 v[156:159], v[8:11], v[110:113], v[156:159]
	v_mfma_f32_16x16x32_bf16 v[164:167], v[8:11], v[122:125], v[164:167]
	v_mfma_f32_16x16x32_bf16 v[4:7], v[8:11], v[130:133], v[4:7]
	v_mfma_f32_16x16x32_bf16 v[8:11], v[12:15], v[126:129], 0
	v_mfma_f32_16x16x32_bf16 v[152:155], v[12:15], v[64:67], 0
	v_mfma_f32_16x16x32_bf16 v[160:163], v[12:15], v[96:99], 0
	v_mfma_f32_16x16x32_bf16 v[168:171], v[12:15], v[114:117], 0
	v_mfma_f32_16x16x32_bf16 v[8:11], v[16:19], v[130:133], v[8:11]
	v_mfma_f32_16x16x32_bf16 v[152:155], v[16:19], v[92:95], v[152:155]
	v_mfma_f32_16x16x32_bf16 v[160:163], v[16:19], v[110:113], v[160:163]
	v_mfma_f32_16x16x32_bf16 v[168:171], v[16:19], v[122:125], v[168:171]
	s_setprio 0
	s_setprio 1
	v_mfma_f32_16x16x32_bf16 v[12:15], v[20:23], v[64:67], 0
	v_mfma_f32_16x16x32_bf16 v[172:175], v[24:27], v[92:95], v[12:15]
	v_mfma_f32_16x16x32_bf16 v[12:15], v[28:31], v[64:67], 0
	v_mfma_f32_16x16x32_bf16 v[176:179], v[32:35], v[92:95], v[12:15]
	v_mfma_f32_16x16x32_bf16 v[12:15], v[20:23], v[96:99], 0
	v_mfma_f32_16x16x32_bf16 v[180:183], v[24:27], v[110:113], v[12:15]
	v_mfma_f32_16x16x32_bf16 v[12:15], v[28:31], v[96:99], 0
	v_mfma_f32_16x16x32_bf16 v[184:187], v[32:35], v[110:113], v[12:15]
	v_mfma_f32_16x16x32_bf16 v[12:15], v[20:23], v[114:117], 0
	v_mfma_f32_16x16x32_bf16 v[188:191], v[24:27], v[122:125], v[12:15]
	v_mfma_f32_16x16x32_bf16 v[12:15], v[28:31], v[114:117], 0
	v_mfma_f32_16x16x32_bf16 v[192:195], v[32:35], v[122:125], v[12:15]
	v_mfma_f32_16x16x32_bf16 v[12:15], v[20:23], v[126:129], 0
	v_mfma_f32_16x16x32_bf16 v[196:199], v[24:27], v[130:133], v[12:15]
	v_mfma_f32_16x16x32_bf16 v[12:15], v[28:31], v[126:129], 0
	v_mfma_f32_16x16x32_bf16 v[200:203], v[32:35], v[130:133], v[12:15]
	s_barrier
; #define PG8_KSETUP() const bool last = (t == nt - 2); const char* a1 = cA + (size_t)(t + 1) * kstep; \
;             const char* a2 = last ? nA : cA + (size_t)(t + 2) * kstep; const char* b2 = last ? nB : cB + (size_t)(t + 2) * kstep; const char* a3 = a2 + kstep; const char* b3 = b2 + kstep; \
;             if (last && has_next) S.a_ready(nxt)
; template <class Epi, class Sched, bool ALIGN_EPI = false, bool SP2 = false>
; __device__ __forceinline__ void gemm_phase(PG8_LAS unsigned char* lds, const Gemm g, const Sched& S, const Epi& E) {
;     ...
;         int t0 = 0;
;         if constexpr (SP2 && Epi::NVM == 16) { if (ui > 0) { const int t = 0; PG8_KSETUP(); PG8_KITER_SP2(24, 24); t0 = 2; } }
	s_setprio 0
	s_nop 4
	ds_read_b128 v[12:15], v150
	ds_read_b128 v[16:19], v150 offset:1024
	ds_read_b128 v[22:25], v150 offset:2048
	ds_read_b128 v[26:29], v150 offset:3072
	ds_read_b128 v[204:207], v151
	ds_read_b128 v[208:211], v151 offset:1024
	ds_read_b128 v[212:215], v151 offset:2048
	ds_read_b128 v[216:219], v151 offset:3072
	ds_read_b128 v[30:33], v149 offset:32768
	ds_read_b128 v[64:67], v149 offset:33792
	ds_read_b128 v[220:223], v149 offset:34816
	ds_read_b128 v[224:227], v149 offset:35840
	ds_read_b128 v[228:231], v149 offset:36864
	ds_read_b128 v[232:235], v149 offset:37888
	ds_read_b128 v[236:239], v149 offset:38912
	ds_read_b128 v[240:243], v149 offset:39936
	s_add_u32 s30, s46, 0x80100
	s_addc_u32 s31, s47, 0
	s_mov_b32 m0, s58
	s_nop 0
	global_load_lds_dwordx4 v1, s[30:31] offset:0
	s_nop 0
	s_mov_b32 m0, s59
	s_nop 0
	global_load_lds_dwordx4 v143, s[30:31] offset:0
	s_waitcnt vmcnt(8)
	s_waitcnt lgkmcnt(0)
	s_barrier
	s_setprio 1
	v_mfma_f32_16x16x32_bf16 v[68:71], v[12:15], v[30:33], v[68:71]
	v_mfma_f32_16x16x32_bf16 v[130:133], v[16:19], v[64:67], v[68:71]
	v_mfma_f32_16x16x32_bf16 v[68:71], v[22:25], v[30:33], v[72:75]
	v_mfma_f32_16x16x32_bf16 v[126:129], v[26:29], v[64:67], v[68:71]
	v_mfma_f32_16x16x32_bf16 v[68:71], v[12:15], v[220:223], v[76:79]
	v_mfma_f32_16x16x32_bf16 v[114:117], v[16:19], v[224:227], v[68:71]
	v_mfma_f32_16x16x32_bf16 v[68:71], v[22:25], v[220:223], v[80:83]
	v_mfma_f32_16x16x32_bf16 v[110:113], v[26:29], v[224:227], v[68:71]
	v_mfma_f32_16x16x32_bf16 v[68:71], v[12:15], v[228:231], v[84:87]
	v_mfma_f32_16x16x32_bf16 v[98:101], v[16:19], v[232:235], v[68:71]
	v_mfma_f32_16x16x32_bf16 v[68:71], v[22:25], v[228:231], v[88:91]
	v_mfma_f32_16x16x32_bf16 v[94:97], v[26:29], v[232:235], v[68:71]
	v_mfma_f32_16x16x32_bf16 v[68:71], v[12:15], v[236:239], v[102:105]
	v_mfma_f32_16x16x32_bf16 v[82:85], v[16:19], v[240:243], v[68:71]
	v_mfma_f32_16x16x32_bf16 v[68:71], v[22:25], v[236:239], v[106:109]
	v_mfma_f32_16x16x32_bf16 v[78:81], v[26:29], v[240:243], v[68:71]
	s_setprio 0
	s_setprio 1
	v_mfma_f32_16x16x32_bf16 v[68:71], v[204:207], v[30:33], v[118:121]
	v_mfma_f32_16x16x32_bf16 v[30:33], v[212:215], v[30:33], v[36:39]
	v_mfma_f32_16x16x32_bf16 v[118:121], v[216:219], v[64:67], v[30:33]
	v_mfma_f32_16x16x32_bf16 v[30:33], v[204:207], v[220:223], v[40:43]
	v_mfma_f32_16x16x32_bf16 v[106:109], v[208:211], v[224:227], v[30:33]
	v_mfma_f32_16x16x32_bf16 v[30:33], v[212:215], v[220:223], v[44:47]
	v_mfma_f32_16x16x32_bf16 v[102:105], v[216:219], v[224:227], v[30:33]
	v_mfma_f32_16x16x32_bf16 v[30:33], v[204:207], v[228:231], v[48:51]
	v_mfma_f32_16x16x32_bf16 v[90:93], v[208:211], v[232:235], v[30:33]
	v_mfma_f32_16x16x32_bf16 v[30:33], v[212:215], v[228:231], v[52:55]
	v_mfma_f32_16x16x32_bf16 v[86:89], v[216:219], v[232:235], v[30:33]
	v_mfma_f32_16x16x32_bf16 v[30:33], v[204:207], v[236:239], v[56:59]
	v_mfma_f32_16x16x32_bf16 v[74:77], v[208:211], v[240:243], v[30:33]
	v_mfma_f32_16x16x32_bf16 v[30:33], v[212:215], v[236:239], v[60:63]
	v_mfma_f32_16x16x32_bf16 v[122:125], v[208:211], v[64:67], v[68:71]
	v_mfma_f32_16x16x32_bf16 v[70:73], v[216:219], v[240:243], v[30:33]
	s_barrier
	s_setprio 0
	ds_read_b128 v[38:41], v149 offset:49152
	ds_read_b128 v[42:45], v149 offset:50176
	ds_read_b128 v[220:223], v149 offset:51200
	ds_read_b128 v[224:227], v149 offset:52224
	ds_read_b128 v[228:231], v149 offset:53248
	ds_read_b128 v[232:235], v149 offset:54272
	ds_read_b128 v[236:239], v149 offset:55296
	ds_read_b128 v[240:243], v149 offset:56320
	s_add_u32 s30, s48, 0x180
	s_addc_u32 s31, s49, 0
	s_mov_b32 m0, s67
	s_nop 0
	global_load_lds_dwordx4 v142, s[30:31] offset:0
	s_nop 0
	s_mov_b32 m0, s68
	s_nop 0
	global_load_lds_dwordx4 v144, s[30:31] offset:0
	s_add_u32 s30, s48, 0x80180
	s_addc_u32 s31, s49, 0
	s_mov_b32 m0, s71
	s_nop 0
	global_load_lds_dwordx4 v142, s[30:31] offset:0
	s_nop 0
	s_mov_b32 m0, s72
	s_nop 0
	global_load_lds_dwordx4 v144, s[30:31] offset:0
	s_nop 0
	s_mov_b32 m0, s69
	s_nop 0
	global_load_lds_dwordx4 v1, s[38:39] offset:0
	s_nop 0
	s_mov_b32 m0, s70
	s_nop 0
	global_load_lds_dwordx4 v143, s[38:39] offset:0
	s_waitcnt vmcnt(8)
	s_waitcnt lgkmcnt(0)
	s_barrier
	s_setprio 1
	v_mfma_f32_16x16x32_bf16 v[30:33], v[12:15], v[38:41], v[138:141]
	v_mfma_f32_16x16x32_bf16 v[66:69], v[16:19], v[42:45], v[30:33]
	v_mfma_f32_16x16x32_bf16 v[30:33], v[22:25], v[38:41], v[152:155]
	v_mfma_f32_16x16x32_bf16 v[62:65], v[26:29], v[42:45], v[30:33]
	v_mfma_f32_16x16x32_bf16 v[30:33], v[12:15], v[220:223], v[156:159]
	v_mfma_f32_16x16x32_bf16 v[50:53], v[16:19], v[224:227], v[30:33]
	v_mfma_f32_16x16x32_bf16 v[30:33], v[22:25], v[220:223], v[160:163]
	v_mfma_f32_16x16x32_bf16 v[46:49], v[26:29], v[224:227], v[30:33]
	v_mfma_f32_16x16x32_bf16 v[30:33], v[12:15], v[228:231], v[164:167]
	v_mfma_f32_16x16x32_bf16 v[4:7], v[12:15], v[236:239], v[4:7]
	v_mfma_f32_16x16x32_bf16 v[34:37], v[16:19], v[232:235], v[30:33]
	v_mfma_f32_16x16x32_bf16 v[30:33], v[22:25], v[228:231], v[168:171]
	v_mfma_f32_16x16x32_bf16 v[18:21], v[16:19], v[240:243], v[4:7]
	v_mfma_f32_16x16x32_bf16 v[4:7], v[22:25], v[236:239], v[8:11]
	v_mfma_f32_16x16x32_bf16 v[30:33], v[26:29], v[232:235], v[30:33]
	v_mfma_f32_16x16x32_bf16 v[14:17], v[26:29], v[240:243], v[4:7]
	s_setprio 0
	s_setprio 1
	v_mfma_f32_16x16x32_bf16 v[4:7], v[204:207], v[38:41], v[172:175]
	v_mfma_f32_16x16x32_bf16 v[58:61], v[208:211], v[42:45], v[4:7]
	v_mfma_f32_16x16x32_bf16 v[4:7], v[212:215], v[38:41], v[176:179]
	v_mfma_f32_16x16x32_bf16 v[54:57], v[216:219], v[42:45], v[4:7]
	v_mfma_f32_16x16x32_bf16 v[4:7], v[204:207], v[220:223], v[180:183]
	v_mfma_f32_16x16x32_bf16 v[42:45], v[208:211], v[224:227], v[4:7]
	v_mfma_f32_16x16x32_bf16 v[4:7], v[212:215], v[220:223], v[184:187]
	v_mfma_f32_16x16x32_bf16 v[38:41], v[216:219], v[224:227], v[4:7]
	v_mfma_f32_16x16x32_bf16 v[4:7], v[204:207], v[228:231], v[188:191]
	v_mfma_f32_16x16x32_bf16 v[26:29], v[208:211], v[232:235], v[4:7]
	v_mfma_f32_16x16x32_bf16 v[4:7], v[212:215], v[228:231], v[192:195]
	v_mfma_f32_16x16x32_bf16 v[22:25], v[216:219], v[232:235], v[4:7]
	v_mfma_f32_16x16x32_bf16 v[4:7], v[204:207], v[236:239], v[196:199]
	v_mfma_f32_16x16x32_bf16 v[10:13], v[208:211], v[240:243], v[4:7]
	v_mfma_f32_16x16x32_bf16 v[4:7], v[212:215], v[236:239], v[200:203]
	v_mfma_f32_16x16x32_bf16 v[6:9], v[216:219], v[240:243], v[4:7]
	s_barrier
	s_setprio 0
	s_mov_b32 s50, 2
	s_branch .LBB0_3467

.LBB0_3468:
	ds_read_b128 v[138:141], v147
	ds_read_b128 v[152:155], v147 offset:1024
	ds_read_b128 v[156:159], v147 offset:2048
	ds_read_b128 v[160:163], v147 offset:3072
	ds_read_b128 v[164:167], v148
	ds_read_b128 v[168:171], v148 offset:1024
	ds_read_b128 v[172:175], v148 offset:2048
	ds_read_b128 v[176:179], v148 offset:3072
	s_cmp_eq_u32 s80, 28
	s_cselect_b32 s52, s43, s83
	s_cselect_b32 s53, s37, s84
	s_cselect_b32 s50, s79, s81
	s_cselect_b32 s51, s29, s82
	s_add_u32 s48, s52, 0x80
	s_addc_u32 s49, s53, 0
	ds_read_b128 v[180:183], v149
	ds_read_b128 v[184:187], v149 offset:1024
	ds_read_b128 v[188:191], v149 offset:2048
	ds_read_b128 v[192:195], v149 offset:3072
	ds_read_b128 v[196:199], v149 offset:4096
	ds_read_b128 v[200:203], v149 offset:5120
	ds_read_b128 v[204:207], v149 offset:6144
	ds_read_b128 v[208:211], v149 offset:7168
	s_mov_b32 m0, s73
	s_nop 0
	global_load_lds_dwordx4 v1, s[46:47] offset:0
	s_nop 0
	s_mov_b32 m0, s74
	s_nop 0
	global_load_lds_dwordx4 v143, s[46:47] offset:0
	s_waitcnt vmcnt(8)
	s_waitcnt lgkmcnt(0)
	s_barrier
	s_setprio 1
	v_mfma_f32_16x16x32_bf16 v[130:133], v[138:141], v[180:183], v[130:133]
	v_mfma_f32_16x16x32_bf16 v[130:133], v[152:155], v[184:187], v[130:133]
	v_mfma_f32_16x16x32_bf16 v[126:129], v[156:159], v[180:183], v[126:129]
	v_mfma_f32_16x16x32_bf16 v[126:129], v[160:163], v[184:187], v[126:129]
	v_mfma_f32_16x16x32_bf16 v[114:117], v[138:141], v[188:191], v[114:117]
	v_mfma_f32_16x16x32_bf16 v[114:117], v[152:155], v[192:195], v[114:117]
	v_mfma_f32_16x16x32_bf16 v[110:113], v[156:159], v[188:191], v[110:113]
	v_mfma_f32_16x16x32_bf16 v[110:113], v[160:163], v[192:195], v[110:113]
	v_mfma_f32_16x16x32_bf16 v[98:101], v[138:141], v[196:199], v[98:101]
	v_mfma_f32_16x16x32_bf16 v[98:101], v[152:155], v[200:203], v[98:101]
	v_mfma_f32_16x16x32_bf16 v[94:97], v[156:159], v[196:199], v[94:97]
	v_mfma_f32_16x16x32_bf16 v[94:97], v[160:163], v[200:203], v[94:97]
	v_mfma_f32_16x16x32_bf16 v[82:85], v[138:141], v[204:207], v[82:85]
	v_mfma_f32_16x16x32_bf16 v[82:85], v[152:155], v[208:211], v[82:85]
	v_mfma_f32_16x16x32_bf16 v[78:81], v[156:159], v[204:207], v[78:81]
	v_mfma_f32_16x16x32_bf16 v[78:81], v[160:163], v[208:211], v[78:81]
	s_setprio 0
	s_setprio 1
	v_mfma_f32_16x16x32_bf16 v[122:125], v[164:167], v[180:183], v[122:125]
	v_mfma_f32_16x16x32_bf16 v[122:125], v[168:171], v[184:187], v[122:125]
	v_mfma_f32_16x16x32_bf16 v[118:121], v[172:175], v[180:183], v[118:121]
	v_mfma_f32_16x16x32_bf16 v[118:121], v[176:179], v[184:187], v[118:121]
	v_mfma_f32_16x16x32_bf16 v[106:109], v[164:167], v[188:191], v[106:109]
	v_mfma_f32_16x16x32_bf16 v[106:109], v[168:171], v[192:195], v[106:109]
	v_mfma_f32_16x16x32_bf16 v[102:105], v[172:175], v[188:191], v[102:105]
	v_mfma_f32_16x16x32_bf16 v[102:105], v[176:179], v[192:195], v[102:105]
	v_mfma_f32_16x16x32_bf16 v[90:93], v[164:167], v[196:199], v[90:93]
	v_mfma_f32_16x16x32_bf16 v[90:93], v[168:171], v[200:203], v[90:93]
	v_mfma_f32_16x16x32_bf16 v[86:89], v[172:175], v[196:199], v[86:89]
	v_mfma_f32_16x16x32_bf16 v[86:89], v[176:179], v[200:203], v[86:89]
	v_mfma_f32_16x16x32_bf16 v[74:77], v[164:167], v[204:207], v[74:77]
	v_mfma_f32_16x16x32_bf16 v[74:77], v[168:171], v[208:211], v[74:77]
	v_mfma_f32_16x16x32_bf16 v[70:73], v[172:175], v[204:207], v[70:73]
	v_mfma_f32_16x16x32_bf16 v[70:73], v[176:179], v[208:211], v[70:73]
	s_barrier
	s_setprio 0
	ds_read_b128 v[180:183], v149 offset:16384
	ds_read_b128 v[184:187], v149 offset:17408
	ds_read_b128 v[188:191], v149 offset:18432
	ds_read_b128 v[192:195], v149 offset:19456
	ds_read_b128 v[196:199], v149 offset:20480
	ds_read_b128 v[200:203], v149 offset:21504
	ds_read_b128 v[204:207], v149 offset:22528
	ds_read_b128 v[208:211], v149 offset:23552
	s_mov_b32 m0, s45
	s_nop 0
	global_load_lds_dwordx4 v142, s[50:51] offset:0
	s_add_u32 s30, s50, 0x80000
	s_mov_b32 m0, s54
	s_nop 0
	global_load_lds_dwordx4 v144, s[50:51] offset:0
	s_addc_u32 s31, s51, 0
	s_mov_b32 m0, s55
	s_nop 0
	global_load_lds_dwordx4 v142, s[30:31] offset:0
	s_nop 0
	s_mov_b32 m0, s56
	s_nop 0
	global_load_lds_dwordx4 v144, s[30:31] offset:0
	s_nop 0
	s_mov_b32 m0, s33
	s_nop 0
	global_load_lds_dwordx4 v1, s[52:53] offset:0
	s_nop 0
	s_mov_b32 m0, s57
	s_nop 0
	global_load_lds_dwordx4 v143, s[52:53] offset:0
	s_waitcnt vmcnt(8)
	s_waitcnt lgkmcnt(0)
	s_barrier
	s_setprio 1
	v_mfma_f32_16x16x32_bf16 v[66:69], v[138:141], v[180:183], v[66:69]
	v_mfma_f32_16x16x32_bf16 v[66:69], v[152:155], v[184:187], v[66:69]
	v_mfma_f32_16x16x32_bf16 v[62:65], v[156:159], v[180:183], v[62:65]
	v_mfma_f32_16x16x32_bf16 v[62:65], v[160:163], v[184:187], v[62:65]
	v_mfma_f32_16x16x32_bf16 v[50:53], v[138:141], v[188:191], v[50:53]
	v_mfma_f32_16x16x32_bf16 v[50:53], v[152:155], v[192:195], v[50:53]
	v_mfma_f32_16x16x32_bf16 v[46:49], v[156:159], v[188:191], v[46:49]
	v_mfma_f32_16x16x32_bf16 v[46:49], v[160:163], v[192:195], v[46:49]
	v_mfma_f32_16x16x32_bf16 v[34:37], v[138:141], v[196:199], v[34:37]
	v_mfma_f32_16x16x32_bf16 v[34:37], v[152:155], v[200:203], v[34:37]
	v_mfma_f32_16x16x32_bf16 v[30:33], v[156:159], v[196:199], v[30:33]
	v_mfma_f32_16x16x32_bf16 v[30:33], v[160:163], v[200:203], v[30:33]
	v_mfma_f32_16x16x32_bf16 v[18:21], v[138:141], v[204:207], v[18:21]
	v_mfma_f32_16x16x32_bf16 v[18:21], v[152:155], v[208:211], v[18:21]
	v_mfma_f32_16x16x32_bf16 v[14:17], v[156:159], v[204:207], v[14:17]
	v_mfma_f32_16x16x32_bf16 v[14:17], v[160:163], v[208:211], v[14:17]
	s_setprio 0
	s_setprio 1
	v_mfma_f32_16x16x32_bf16 v[58:61], v[164:167], v[180:183], v[58:61]
	v_mfma_f32_16x16x32_bf16 v[54:57], v[172:175], v[180:183], v[54:57]
	v_mfma_f32_16x16x32_bf16 v[42:45], v[164:167], v[188:191], v[42:45]
	v_mfma_f32_16x16x32_bf16 v[38:41], v[172:175], v[188:191], v[38:41]
	v_mfma_f32_16x16x32_bf16 v[26:29], v[164:167], v[196:199], v[26:29]
	v_mfma_f32_16x16x32_bf16 v[22:25], v[172:175], v[196:199], v[22:25]
	v_mfma_f32_16x16x32_bf16 v[10:13], v[164:167], v[204:207], v[10:13]
	v_mfma_f32_16x16x32_bf16 v[4:7], v[172:175], v[204:207], v[6:9]
	v_mfma_f32_16x16x32_bf16 v[58:61], v[168:171], v[184:187], v[58:61]
	v_mfma_f32_16x16x32_bf16 v[54:57], v[176:179], v[184:187], v[54:57]
	v_mfma_f32_16x16x32_bf16 v[42:45], v[168:171], v[192:195], v[42:45]
	v_mfma_f32_16x16x32_bf16 v[38:41], v[176:179], v[192:195], v[38:41]
	v_mfma_f32_16x16x32_bf16 v[26:29], v[168:171], v[200:203], v[26:29]
	v_mfma_f32_16x16x32_bf16 v[22:25], v[176:179], v[200:203], v[22:25]
	v_mfma_f32_16x16x32_bf16 v[10:13], v[168:171], v[208:211], v[10:13]
	v_mfma_f32_16x16x32_bf16 v[4:7], v[176:179], v[208:211], v[4:7]
	s_barrier
; #define PG8_KSETUP() const bool last = (t == nt - 2); const char* a1 = cA + (size_t)(t + 1) * kstep; \
;             const char* a2 = last ? nA : cA + (size_t)(t + 2) * kstep; const char* b2 = last ? nB : cB + (size_t)(t + 2) * kstep; const char* a3 = a2 + kstep; const char* b3 = b2 + kstep; \
;             if (last && has_next) S.a_ready(nxt)
; template <class Epi, class Sched, bool ALIGN_EPI = false, bool SP2 = false>
; __device__ __forceinline__ void gemm_phase(PG8_LAS unsigned char* lds, const Gemm g, const Sched& S, const Epi& E) {
;     ...
;         int t0 = 0;
;         if constexpr (SP2 && Epi::NVM == 16) { if (ui > 0) { const int t = 0; PG8_KSETUP(); PG8_KITER_SP2(24, 24); t0 = 2; } }
;         if constexpr (SP2 && Epi::NVM == 8) { if (ui > 0) { const int t = 0; PG8_KSETUP(); PG8_KITER_SP2(16, 16); t0 = 2; } }
;         for (int t = t0; t < nt; t += 2) {
	s_setprio 0
	ds_read_b128 v[138:141], v150
	ds_read_b128 v[152:155], v150 offset:1024
	ds_read_b128 v[156:159], v150 offset:2048
	ds_read_b128 v[160:163], v150 offset:3072
	ds_read_b128 v[164:167], v151
	ds_read_b128 v[168:171], v151 offset:1024
	ds_read_b128 v[172:175], v151 offset:2048
	ds_read_b128 v[176:179], v151 offset:3072
	ds_read_b128 v[180:183], v149 offset:32768
	ds_read_b128 v[184:187], v149 offset:33792
	ds_read_b128 v[188:191], v149 offset:34816
	ds_read_b128 v[192:195], v149 offset:35840
	ds_read_b128 v[196:199], v149 offset:36864
	ds_read_b128 v[200:203], v149 offset:37888
	ds_read_b128 v[204:207], v149 offset:38912
	ds_read_b128 v[208:211], v149 offset:39936
	s_add_u32 s30, s52, 0x80000
	s_addc_u32 s31, s53, 0
	s_mov_b32 m0, s58
	s_nop 0
	global_load_lds_dwordx4 v1, s[30:31] offset:0
	s_nop 0
	s_mov_b32 m0, s59
	s_nop 0
	global_load_lds_dwordx4 v143, s[30:31] offset:0
	s_waitcnt vmcnt(8)
	s_waitcnt lgkmcnt(0)
	s_barrier
	s_setprio 1
	v_mfma_f32_16x16x32_bf16 v[130:133], v[138:141], v[180:183], v[130:133]
	v_mfma_f32_16x16x32_bf16 v[130:133], v[152:155], v[184:187], v[130:133]
	v_mfma_f32_16x16x32_bf16 v[126:129], v[156:159], v[180:183], v[126:129]
	v_mfma_f32_16x16x32_bf16 v[126:129], v[160:163], v[184:187], v[126:129]
	v_mfma_f32_16x16x32_bf16 v[114:117], v[138:141], v[188:191], v[114:117]
	v_mfma_f32_16x16x32_bf16 v[114:117], v[152:155], v[192:195], v[114:117]
	v_mfma_f32_16x16x32_bf16 v[110:113], v[156:159], v[188:191], v[110:113]
	v_mfma_f32_16x16x32_bf16 v[110:113], v[160:163], v[192:195], v[110:113]
	v_mfma_f32_16x16x32_bf16 v[98:101], v[138:141], v[196:199], v[98:101]
	v_mfma_f32_16x16x32_bf16 v[98:101], v[152:155], v[200:203], v[98:101]
	v_mfma_f32_16x16x32_bf16 v[94:97], v[156:159], v[196:199], v[94:97]
	v_mfma_f32_16x16x32_bf16 v[94:97], v[160:163], v[200:203], v[94:97]
	v_mfma_f32_16x16x32_bf16 v[82:85], v[138:141], v[204:207], v[82:85]
	v_mfma_f32_16x16x32_bf16 v[82:85], v[152:155], v[208:211], v[82:85]
	v_mfma_f32_16x16x32_bf16 v[78:81], v[156:159], v[204:207], v[78:81]
	v_mfma_f32_16x16x32_bf16 v[78:81], v[160:163], v[208:211], v[78:81]
	s_setprio 0
	s_setprio 1
	v_mfma_f32_16x16x32_bf16 v[122:125], v[164:167], v[180:183], v[122:125]
	v_mfma_f32_16x16x32_bf16 v[122:125], v[168:171], v[184:187], v[122:125]
	v_mfma_f32_16x16x32_bf16 v[118:121], v[172:175], v[180:183], v[118:121]
	v_mfma_f32_16x16x32_bf16 v[118:121], v[176:179], v[184:187], v[118:121]
	v_mfma_f32_16x16x32_bf16 v[106:109], v[164:167], v[188:191], v[106:109]
	v_mfma_f32_16x16x32_bf16 v[106:109], v[168:171], v[192:195], v[106:109]
	v_mfma_f32_16x16x32_bf16 v[102:105], v[172:175], v[188:191], v[102:105]
	v_mfma_f32_16x16x32_bf16 v[102:105], v[176:179], v[192:195], v[102:105]
	v_mfma_f32_16x16x32_bf16 v[90:93], v[164:167], v[196:199], v[90:93]
	v_mfma_f32_16x16x32_bf16 v[90:93], v[168:171], v[200:203], v[90:93]
	v_mfma_f32_16x16x32_bf16 v[86:89], v[172:175], v[196:199], v[86:89]
	v_mfma_f32_16x16x32_bf16 v[86:89], v[176:179], v[200:203], v[86:89]
	v_mfma_f32_16x16x32_bf16 v[74:77], v[164:167], v[204:207], v[74:77]
	v_mfma_f32_16x16x32_bf16 v[74:77], v[168:171], v[208:211], v[74:77]
	v_mfma_f32_16x16x32_bf16 v[70:73], v[172:175], v[204:207], v[70:73]
	v_mfma_f32_16x16x32_bf16 v[70:73], v[176:179], v[208:211], v[70:73]
	s_barrier
	s_setprio 0
	ds_read_b128 v[180:183], v149 offset:49152
	ds_read_b128 v[184:187], v149 offset:50176
	ds_read_b128 v[188:191], v149 offset:51200
	ds_read_b128 v[192:195], v149 offset:52224
	ds_read_b128 v[196:199], v149 offset:53248
	ds_read_b128 v[200:203], v149 offset:54272
	ds_read_b128 v[204:207], v149 offset:55296
	ds_read_b128 v[208:211], v149 offset:56320
	s_add_u32 s30, s50, 0x80
	s_addc_u32 s31, s51, 0
	s_mov_b32 m0, s67
	s_nop 0
	global_load_lds_dwordx4 v142, s[30:31] offset:0
	s_nop 0
	s_mov_b32 m0, s68
	s_nop 0
	global_load_lds_dwordx4 v144, s[30:31] offset:0
	s_add_u32 s30, s50, 0x80080
	s_addc_u32 s31, s51, 0
	s_mov_b32 m0, s71
	s_nop 0
	global_load_lds_dwordx4 v142, s[30:31] offset:0
	s_nop 0
	s_mov_b32 m0, s72
	s_nop 0
	global_load_lds_dwordx4 v144, s[30:31] offset:0
	s_nop 0
	s_mov_b32 m0, s69
	s_nop 0
	global_load_lds_dwordx4 v1, s[48:49] offset:0
	s_nop 0
	s_mov_b32 m0, s70
	s_nop 0
	global_load_lds_dwordx4 v143, s[48:49] offset:0
	s_waitcnt vmcnt(8)
	s_waitcnt lgkmcnt(0)
	s_barrier
	s_setprio 1
	v_mfma_f32_16x16x32_bf16 v[66:69], v[138:141], v[180:183], v[66:69]
	v_mfma_f32_16x16x32_bf16 v[66:69], v[152:155], v[184:187], v[66:69]
	v_mfma_f32_16x16x32_bf16 v[62:65], v[156:159], v[180:183], v[62:65]
	v_mfma_f32_16x16x32_bf16 v[62:65], v[160:163], v[184:187], v[62:65]
	v_mfma_f32_16x16x32_bf16 v[50:53], v[138:141], v[188:191], v[50:53]
	v_mfma_f32_16x16x32_bf16 v[50:53], v[152:155], v[192:195], v[50:53]
	v_mfma_f32_16x16x32_bf16 v[46:49], v[156:159], v[188:191], v[46:49]
	v_mfma_f32_16x16x32_bf16 v[46:49], v[160:163], v[192:195], v[46:49]
	v_mfma_f32_16x16x32_bf16 v[34:37], v[138:141], v[196:199], v[34:37]
	v_mfma_f32_16x16x32_bf16 v[34:37], v[152:155], v[200:203], v[34:37]
	v_mfma_f32_16x16x32_bf16 v[30:33], v[156:159], v[196:199], v[30:33]
	v_mfma_f32_16x16x32_bf16 v[30:33], v[160:163], v[200:203], v[30:33]
	v_mfma_f32_16x16x32_bf16 v[18:21], v[138:141], v[204:207], v[18:21]
	v_mfma_f32_16x16x32_bf16 v[18:21], v[152:155], v[208:211], v[18:21]
	v_mfma_f32_16x16x32_bf16 v[14:17], v[156:159], v[204:207], v[14:17]
	v_mfma_f32_16x16x32_bf16 v[14:17], v[160:163], v[208:211], v[14:17]
	s_setprio 0
	s_setprio 1
	v_mfma_f32_16x16x32_bf16 v[58:61], v[164:167], v[180:183], v[58:61]
	v_mfma_f32_16x16x32_bf16 v[54:57], v[172:175], v[180:183], v[54:57]
	v_mfma_f32_16x16x32_bf16 v[42:45], v[164:167], v[188:191], v[42:45]
	v_mfma_f32_16x16x32_bf16 v[38:41], v[172:175], v[188:191], v[38:41]
	v_mfma_f32_16x16x32_bf16 v[26:29], v[164:167], v[196:199], v[26:29]
	v_mfma_f32_16x16x32_bf16 v[22:25], v[172:175], v[196:199], v[22:25]
	v_mfma_f32_16x16x32_bf16 v[8:11], v[164:167], v[204:207], v[10:13]
	v_mfma_f32_16x16x32_bf16 v[4:7], v[172:175], v[204:207], v[4:7]
	v_mfma_f32_16x16x32_bf16 v[58:61], v[168:171], v[184:187], v[58:61]
	v_mfma_f32_16x16x32_bf16 v[54:57], v[176:179], v[184:187], v[54:57]
	v_mfma_f32_16x16x32_bf16 v[42:45], v[168:171], v[192:195], v[42:45]
	v_mfma_f32_16x16x32_bf16 v[38:41], v[176:179], v[192:195], v[38:41]
	v_mfma_f32_16x16x32_bf16 v[26:29], v[168:171], v[200:203], v[26:29]
	v_mfma_f32_16x16x32_bf16 v[22:25], v[176:179], v[200:203], v[22:25]
	v_mfma_f32_16x16x32_bf16 v[10:13], v[168:171], v[208:211], v[8:11]
	v_mfma_f32_16x16x32_bf16 v[6:9], v[176:179], v[208:211], v[4:7]
	s_barrier
	s_setprio 0
	s_add_i32 s80, s80, 2
	s_add_u32 s81, s81, 0x100
	s_addc_u32 s82, s82, 0
	s_add_u32 s83, s83, 0x100
	s_addc_u32 s84, s84, 0
	s_add_u32 s46, s46, 0x100
	s_addc_u32 s47, s47, 0
	s_cmp_gt_u32 s80, 29
	s_cbranch_scc0 .LBB0_3468
	s_and_b64 vcc, exec, s[18:19]
	s_cbranch_vccz .LBB0_3471
	s_barrier

; #define PG8_KSETUP() const bool last = (t == nt - 2); const char* a1 = cA + (size_t)(t + 1) * kstep; \
;             const char* a2 = last ? nA : cA + (size_t)(t + 2) * kstep; const char* b2 = last ? nB : cB + (size_t)(t + 2) * kstep; const char* a3 = a2 + kstep; const char* b3 = b2 + kstep; \
;             if (last && has_next) S.a_ready(nxt)
; template <class Epi, class Sched, bool ALIGN_EPI = false, bool SP2 = false>
; __device__ __forceinline__ void gemm_phase(PG8_LAS unsigned char* lds, const Gemm g, const Sched& S, const Epi& E) {
;     ...
;         if constexpr (SP2 && Epi::NVM == 8) { if (ui > 0) { const int t = 0; PG8_KSETUP(); PG8_KITER_SP2(16, 16); t0 = 2; } }
.LBB0_3617:
	s_cmp_lg_u32 s69, 0
	s_mov_b32 s40, 0
	s_cbranch_scc0 .LBB0_3619
	ds_read_b128 v[4:7], v152
	ds_read_b128 v[8:11], v152 offset:1024
	ds_read_b128 v[12:15], v152 offset:2048
	ds_read_b128 v[16:19], v152 offset:3072
	ds_read_b128 v[20:23], v153
	ds_read_b128 v[24:27], v153 offset:1024
	ds_read_b128 v[28:31], v153 offset:2048
	ds_read_b128 v[32:35], v153 offset:3072
	s_add_u32 s24, s36, 0x100
	s_addc_u32 s25, s37, 0
	s_add_u32 s30, s38, 0x100
	s_addc_u32 s31, s39, 0
	s_add_u32 s22, s36, 0x180
	s_addc_u32 s23, s37, 0
	ds_read_b128 v[36:39], v154
	ds_read_b128 v[40:43], v154 offset:1024
	ds_read_b128 v[44:47], v154 offset:2048
	ds_read_b128 v[48:51], v154 offset:3072
	ds_read_b128 v[52:55], v154 offset:4096
	ds_read_b128 v[56:59], v154 offset:5120
	ds_read_b128 v[60:63], v154 offset:6144
	ds_read_b128 v[64:67], v154 offset:7168
	s_add_u32 s40, s36, 0x80080
	s_addc_u32 s41, s37, 0
	s_mov_b32 m0, s56
	s_nop 0
	global_load_lds_dwordx4 v1, s[40:41] offset:0
	s_nop 0
	s_mov_b32 m0, s57
	s_nop 0
	global_load_lds_dwordx4 v147, s[40:41] offset:0
	s_waitcnt vmcnt(16)
	s_waitcnt lgkmcnt(0)
	s_barrier
	s_setprio 1
	v_mfma_f32_16x16x32_bf16 v[92:95], v[4:7], v[60:63], 0
	v_mfma_f32_16x16x32_bf16 v[68:71], v[4:7], v[36:39], 0
	v_mfma_f32_16x16x32_bf16 v[72:75], v[12:15], v[36:39], 0
	v_mfma_f32_16x16x32_bf16 v[76:79], v[4:7], v[44:47], 0
	v_mfma_f32_16x16x32_bf16 v[80:83], v[12:15], v[44:47], 0
	v_mfma_f32_16x16x32_bf16 v[84:87], v[4:7], v[52:55], 0
	v_mfma_f32_16x16x32_bf16 v[88:91], v[12:15], v[52:55], 0
	v_mfma_f32_16x16x32_bf16 v[102:105], v[8:11], v[64:67], v[92:95]
	v_mfma_f32_16x16x32_bf16 v[92:95], v[12:15], v[60:63], 0
	v_mfma_f32_16x16x32_bf16 v[68:71], v[8:11], v[40:43], v[68:71]
	v_mfma_f32_16x16x32_bf16 v[72:75], v[16:19], v[40:43], v[72:75]
	v_mfma_f32_16x16x32_bf16 v[76:79], v[8:11], v[48:51], v[76:79]
	v_mfma_f32_16x16x32_bf16 v[80:83], v[16:19], v[48:51], v[80:83]
	v_mfma_f32_16x16x32_bf16 v[84:87], v[8:11], v[56:59], v[84:87]
	v_mfma_f32_16x16x32_bf16 v[88:91], v[16:19], v[56:59], v[88:91]
	v_mfma_f32_16x16x32_bf16 v[106:109], v[16:19], v[64:67], v[92:95]
	s_setprio 0
	s_setprio 1
	v_mfma_f32_16x16x32_bf16 v[92:95], v[20:23], v[36:39], 0
	v_mfma_f32_16x16x32_bf16 v[36:39], v[28:31], v[36:39], 0
	v_mfma_f32_16x16x32_bf16 v[118:121], v[24:27], v[40:43], v[92:95]
	v_mfma_f32_16x16x32_bf16 v[36:39], v[32:35], v[40:43], v[36:39]
	v_mfma_f32_16x16x32_bf16 v[40:43], v[20:23], v[44:47], 0
	v_mfma_f32_16x16x32_bf16 v[44:47], v[28:31], v[44:47], 0
	v_mfma_f32_16x16x32_bf16 v[40:43], v[24:27], v[48:51], v[40:43]
	v_mfma_f32_16x16x32_bf16 v[44:47], v[32:35], v[48:51], v[44:47]
	v_mfma_f32_16x16x32_bf16 v[48:51], v[20:23], v[52:55], 0
	v_mfma_f32_16x16x32_bf16 v[52:55], v[28:31], v[52:55], 0
	v_mfma_f32_16x16x32_bf16 v[48:51], v[24:27], v[56:59], v[48:51]
	v_mfma_f32_16x16x32_bf16 v[52:55], v[32:35], v[56:59], v[52:55]
	v_mfma_f32_16x16x32_bf16 v[56:59], v[20:23], v[60:63], 0
	v_mfma_f32_16x16x32_bf16 v[60:63], v[28:31], v[60:63], 0
	v_mfma_f32_16x16x32_bf16 v[56:59], v[24:27], v[64:67], v[56:59]
	v_mfma_f32_16x16x32_bf16 v[60:63], v[32:35], v[64:67], v[60:63]
	s_barrier
	s_setprio 0
	ds_read_b128 v[64:67], v154 offset:16384
	ds_read_b128 v[92:95], v154 offset:17408
	ds_read_b128 v[96:99], v154 offset:18432
	ds_read_b128 v[110:113], v154 offset:19456
	ds_read_b128 v[114:117], v154 offset:20480
	ds_read_b128 v[122:125], v154 offset:21504
	ds_read_b128 v[126:129], v154 offset:22528
	ds_read_b128 v[130:133], v154 offset:23552
	s_mov_b32 m0, s29
	s_nop 0
	global_load_lds_dwordx4 v146, s[30:31] offset:0
	s_nop 0
	s_mov_b32 m0, s44
	s_nop 0
	global_load_lds_dwordx4 v148, s[30:31] offset:0
	s_add_u32 s30, s38, 0x80100
	s_addc_u32 s31, s39, 0
	s_mov_b32 m0, s45
	s_nop 0
	global_load_lds_dwordx4 v146, s[30:31] offset:0
	s_nop 0
	s_mov_b32 m0, s46
	s_nop 0
	global_load_lds_dwordx4 v148, s[30:31] offset:0
	s_nop 0
	s_mov_b32 m0, s21
	s_nop 0
	global_load_lds_dwordx4 v1, s[24:25] offset:0
	s_nop 0
	s_mov_b32 m0, s47
	s_nop 0
	global_load_lds_dwordx4 v147, s[24:25] offset:0
	s_waitcnt vmcnt(16)
	s_waitcnt lgkmcnt(0)
	s_barrier
	s_setprio 1
	v_mfma_f32_16x16x32_bf16 v[138:141], v[4:7], v[64:67], 0
	v_mfma_f32_16x16x32_bf16 v[158:161], v[4:7], v[96:99], 0
	v_mfma_f32_16x16x32_bf16 v[166:169], v[4:7], v[114:117], 0
	v_mfma_f32_16x16x32_bf16 v[4:7], v[4:7], v[126:129], 0
	v_mfma_f32_16x16x32_bf16 v[138:141], v[8:11], v[92:95], v[138:141]
	v_mfma_f32_16x16x32_bf16 v[158:161], v[8:11], v[110:113], v[158:161]
	v_mfma_f32_16x16x32_bf16 v[166:169], v[8:11], v[122:125], v[166:169]
	v_mfma_f32_16x16x32_bf16 v[4:7], v[8:11], v[130:133], v[4:7]
	v_mfma_f32_16x16x32_bf16 v[8:11], v[12:15], v[126:129], 0
	v_mfma_f32_16x16x32_bf16 v[142:145], v[12:15], v[64:67], 0
	v_mfma_f32_16x16x32_bf16 v[162:165], v[12:15], v[96:99], 0
	v_mfma_f32_16x16x32_bf16 v[170:173], v[12:15], v[114:117], 0
	v_mfma_f32_16x16x32_bf16 v[8:11], v[16:19], v[130:133], v[8:11]
	v_mfma_f32_16x16x32_bf16 v[142:145], v[16:19], v[92:95], v[142:145]
	v_mfma_f32_16x16x32_bf16 v[162:165], v[16:19], v[110:113], v[162:165]
	v_mfma_f32_16x16x32_bf16 v[170:173], v[16:19], v[122:125], v[170:173]
	s_setprio 0
	s_setprio 1
	v_mfma_f32_16x16x32_bf16 v[12:15], v[20:23], v[64:67], 0
	v_mfma_f32_16x16x32_bf16 v[174:177], v[24:27], v[92:95], v[12:15]
	v_mfma_f32_16x16x32_bf16 v[12:15], v[28:31], v[64:67], 0
	v_mfma_f32_16x16x32_bf16 v[178:181], v[32:35], v[92:95], v[12:15]
	v_mfma_f32_16x16x32_bf16 v[12:15], v[20:23], v[96:99], 0
	v_mfma_f32_16x16x32_bf16 v[182:185], v[24:27], v[110:113], v[12:15]
	v_mfma_f32_16x16x32_bf16 v[12:15], v[28:31], v[96:99], 0
	v_mfma_f32_16x16x32_bf16 v[186:189], v[32:35], v[110:113], v[12:15]
	v_mfma_f32_16x16x32_bf16 v[12:15], v[20:23], v[114:117], 0
	v_mfma_f32_16x16x32_bf16 v[190:193], v[24:27], v[122:125], v[12:15]
	v_mfma_f32_16x16x32_bf16 v[12:15], v[28:31], v[114:117], 0
	v_mfma_f32_16x16x32_bf16 v[194:197], v[32:35], v[122:125], v[12:15]
	v_mfma_f32_16x16x32_bf16 v[12:15], v[20:23], v[126:129], 0
	v_mfma_f32_16x16x32_bf16 v[198:201], v[24:27], v[130:133], v[12:15]
	v_mfma_f32_16x16x32_bf16 v[12:15], v[28:31], v[126:129], 0
	v_mfma_f32_16x16x32_bf16 v[202:205], v[32:35], v[130:133], v[12:15]
	s_barrier
; #define PG8_KSETUP() const bool last = (t == nt - 2); const char* a1 = cA + (size_t)(t + 1) * kstep; \
;             const char* a2 = last ? nA : cA + (size_t)(t + 2) * kstep; const char* b2 = last ? nB : cB + (size_t)(t + 2) * kstep; const char* a3 = a2 + kstep; const char* b3 = b2 + kstep; \
;             if (last && has_next) S.a_ready(nxt)
; template <class Epi, class Sched, bool ALIGN_EPI = false, bool SP2 = false>
; __device__ __forceinline__ void gemm_phase(PG8_LAS unsigned char* lds, const Gemm g, const Sched& S, const Epi& E) {
;     ...
;         int t0 = 0;
;         if constexpr (SP2 && Epi::NVM == 16) { if (ui > 0) { const int t = 0; PG8_KSETUP(); PG8_KITER_SP2(24, 24); t0 = 2; } }
;         if constexpr (SP2 && Epi::NVM == 8) { if (ui > 0) { const int t = 0; PG8_KSETUP(); PG8_KITER_SP2(16, 16); t0 = 2; } }
	s_setprio 0
	s_nop 4
	ds_read_b128 v[12:15], v155
	ds_read_b128 v[16:19], v155 offset:1024
	ds_read_b128 v[22:25], v155 offset:2048
	ds_read_b128 v[26:29], v155 offset:3072
	ds_read_b128 v[206:209], v156
	ds_read_b128 v[210:213], v156 offset:1024
	ds_read_b128 v[214:217], v156 offset:2048
	ds_read_b128 v[218:221], v156 offset:3072
	ds_read_b128 v[30:33], v154 offset:32768
	ds_read_b128 v[64:67], v154 offset:33792
	ds_read_b128 v[222:225], v154 offset:34816
	ds_read_b128 v[226:229], v154 offset:35840
	ds_read_b128 v[230:233], v154 offset:36864
	ds_read_b128 v[234:237], v154 offset:37888
	ds_read_b128 v[238:241], v154 offset:38912
	ds_read_b128 v[242:245], v154 offset:39936
	s_add_u32 s24, s36, 0x80100
	s_addc_u32 s25, s37, 0
	s_mov_b32 m0, s48
	s_nop 0
	global_load_lds_dwordx4 v1, s[24:25] offset:0
	s_nop 0
	s_mov_b32 m0, s49
	s_nop 0
	global_load_lds_dwordx4 v147, s[24:25] offset:0
	s_waitcnt vmcnt(8)
	s_waitcnt lgkmcnt(0)
	s_barrier
	s_setprio 1
	v_mfma_f32_16x16x32_bf16 v[68:71], v[12:15], v[30:33], v[68:71]
	v_mfma_f32_16x16x32_bf16 v[130:133], v[16:19], v[64:67], v[68:71]
	v_mfma_f32_16x16x32_bf16 v[68:71], v[22:25], v[30:33], v[72:75]
	v_mfma_f32_16x16x32_bf16 v[126:129], v[26:29], v[64:67], v[68:71]
	v_mfma_f32_16x16x32_bf16 v[68:71], v[12:15], v[222:225], v[76:79]
	v_mfma_f32_16x16x32_bf16 v[114:117], v[16:19], v[226:229], v[68:71]
	v_mfma_f32_16x16x32_bf16 v[68:71], v[22:25], v[222:225], v[80:83]
	v_mfma_f32_16x16x32_bf16 v[110:113], v[26:29], v[226:229], v[68:71]
	v_mfma_f32_16x16x32_bf16 v[68:71], v[12:15], v[230:233], v[84:87]
	v_mfma_f32_16x16x32_bf16 v[98:101], v[16:19], v[234:237], v[68:71]
	v_mfma_f32_16x16x32_bf16 v[68:71], v[22:25], v[230:233], v[88:91]
	v_mfma_f32_16x16x32_bf16 v[94:97], v[26:29], v[234:237], v[68:71]
	v_mfma_f32_16x16x32_bf16 v[68:71], v[12:15], v[238:241], v[102:105]
	v_mfma_f32_16x16x32_bf16 v[82:85], v[16:19], v[242:245], v[68:71]
	v_mfma_f32_16x16x32_bf16 v[68:71], v[22:25], v[238:241], v[106:109]
	v_mfma_f32_16x16x32_bf16 v[78:81], v[26:29], v[242:245], v[68:71]
	s_setprio 0
	s_setprio 1
	v_mfma_f32_16x16x32_bf16 v[68:71], v[206:209], v[30:33], v[118:121]
	v_mfma_f32_16x16x32_bf16 v[30:33], v[214:217], v[30:33], v[36:39]
	v_mfma_f32_16x16x32_bf16 v[118:121], v[218:221], v[64:67], v[30:33]
	v_mfma_f32_16x16x32_bf16 v[30:33], v[206:209], v[222:225], v[40:43]
	v_mfma_f32_16x16x32_bf16 v[106:109], v[210:213], v[226:229], v[30:33]
	v_mfma_f32_16x16x32_bf16 v[30:33], v[214:217], v[222:225], v[44:47]
	v_mfma_f32_16x16x32_bf16 v[102:105], v[218:221], v[226:229], v[30:33]
	v_mfma_f32_16x16x32_bf16 v[30:33], v[206:209], v[230:233], v[48:51]
	v_mfma_f32_16x16x32_bf16 v[90:93], v[210:213], v[234:237], v[30:33]
	v_mfma_f32_16x16x32_bf16 v[30:33], v[214:217], v[230:233], v[52:55]
	v_mfma_f32_16x16x32_bf16 v[86:89], v[218:221], v[234:237], v[30:33]
	v_mfma_f32_16x16x32_bf16 v[30:33], v[206:209], v[238:241], v[56:59]
	v_mfma_f32_16x16x32_bf16 v[74:77], v[210:213], v[242:245], v[30:33]
	v_mfma_f32_16x16x32_bf16 v[30:33], v[214:217], v[238:241], v[60:63]
	v_mfma_f32_16x16x32_bf16 v[122:125], v[210:213], v[64:67], v[68:71]
	v_mfma_f32_16x16x32_bf16 v[66:69], v[218:221], v[242:245], v[30:33]
	s_barrier
	s_setprio 0
	ds_read_b128 v[38:41], v154 offset:49152
	ds_read_b128 v[42:45], v154 offset:50176
	ds_read_b128 v[222:225], v154 offset:51200
	ds_read_b128 v[226:229], v154 offset:52224
	ds_read_b128 v[230:233], v154 offset:53248
	ds_read_b128 v[234:237], v154 offset:54272
	ds_read_b128 v[238:241], v154 offset:55296
	ds_read_b128 v[242:245], v154 offset:56320
	s_add_u32 s24, s38, 0x180
	s_addc_u32 s25, s39, 0
	s_mov_b32 m0, s50
	s_nop 0
	global_load_lds_dwordx4 v146, s[24:25] offset:0
	s_nop 0
	s_mov_b32 m0, s51
	s_nop 0
	global_load_lds_dwordx4 v148, s[24:25] offset:0
	s_add_u32 s24, s38, 0x80180
	s_addc_u32 s25, s39, 0
	s_mov_b32 m0, s54
	s_nop 0
	global_load_lds_dwordx4 v146, s[24:25] offset:0
	s_nop 0
	s_mov_b32 m0, s55
	s_nop 0
	global_load_lds_dwordx4 v148, s[24:25] offset:0
	s_nop 0
	s_mov_b32 m0, s52
	s_nop 0
	global_load_lds_dwordx4 v1, s[22:23] offset:0
	s_nop 0
	s_mov_b32 m0, s53
	s_nop 0
	global_load_lds_dwordx4 v147, s[22:23] offset:0
	s_waitcnt vmcnt(8)
	s_waitcnt lgkmcnt(0)
	s_barrier
	s_setprio 1
	v_mfma_f32_16x16x32_bf16 v[30:33], v[12:15], v[38:41], v[138:141]
	v_mfma_f32_16x16x32_bf16 v[70:73], v[16:19], v[42:45], v[30:33]
	v_mfma_f32_16x16x32_bf16 v[30:33], v[22:25], v[38:41], v[142:145]
	v_mfma_f32_16x16x32_bf16 v[62:65], v[26:29], v[42:45], v[30:33]
	v_mfma_f32_16x16x32_bf16 v[30:33], v[12:15], v[222:225], v[158:161]
	v_mfma_f32_16x16x32_bf16 v[50:53], v[16:19], v[226:229], v[30:33]
	v_mfma_f32_16x16x32_bf16 v[30:33], v[22:25], v[222:225], v[162:165]
	v_mfma_f32_16x16x32_bf16 v[46:49], v[26:29], v[226:229], v[30:33]
	v_mfma_f32_16x16x32_bf16 v[30:33], v[12:15], v[230:233], v[166:169]
	v_mfma_f32_16x16x32_bf16 v[4:7], v[12:15], v[238:241], v[4:7]
	v_mfma_f32_16x16x32_bf16 v[34:37], v[16:19], v[234:237], v[30:33]
	v_mfma_f32_16x16x32_bf16 v[30:33], v[22:25], v[230:233], v[170:173]
	v_mfma_f32_16x16x32_bf16 v[18:21], v[16:19], v[242:245], v[4:7]
	v_mfma_f32_16x16x32_bf16 v[4:7], v[22:25], v[238:241], v[8:11]
	v_mfma_f32_16x16x32_bf16 v[30:33], v[26:29], v[234:237], v[30:33]
	v_mfma_f32_16x16x32_bf16 v[14:17], v[26:29], v[242:245], v[4:7]
	s_setprio 0
	s_setprio 1
	v_mfma_f32_16x16x32_bf16 v[4:7], v[206:209], v[38:41], v[174:177]
	v_mfma_f32_16x16x32_bf16 v[58:61], v[210:213], v[42:45], v[4:7]
	v_mfma_f32_16x16x32_bf16 v[4:7], v[214:217], v[38:41], v[178:181]
	v_mfma_f32_16x16x32_bf16 v[54:57], v[218:221], v[42:45], v[4:7]
	v_mfma_f32_16x16x32_bf16 v[4:7], v[206:209], v[222:225], v[182:185]
	v_mfma_f32_16x16x32_bf16 v[42:45], v[210:213], v[226:229], v[4:7]
	v_mfma_f32_16x16x32_bf16 v[4:7], v[214:217], v[222:225], v[186:189]
	v_mfma_f32_16x16x32_bf16 v[38:41], v[218:221], v[226:229], v[4:7]
	v_mfma_f32_16x16x32_bf16 v[4:7], v[206:209], v[230:233], v[190:193]
	v_mfma_f32_16x16x32_bf16 v[26:29], v[210:213], v[234:237], v[4:7]
	v_mfma_f32_16x16x32_bf16 v[4:7], v[214:217], v[230:233], v[194:197]
	v_mfma_f32_16x16x32_bf16 v[22:25], v[218:221], v[234:237], v[4:7]
	v_mfma_f32_16x16x32_bf16 v[4:7], v[206:209], v[238:241], v[198:201]
	v_mfma_f32_16x16x32_bf16 v[10:13], v[210:213], v[242:245], v[4:7]
	v_mfma_f32_16x16x32_bf16 v[4:7], v[214:217], v[238:241], v[202:205]
	v_mfma_f32_16x16x32_bf16 v[6:9], v[218:221], v[242:245], v[4:7]
	s_barrier
	s_setprio 0
	s_mov_b32 s40, 2
	s_branch .LBB0_3620

.LBB0_3621:
	ds_read_b128 v[138:141], v152
	ds_read_b128 v[142:145], v152 offset:1024
	ds_read_b128 v[158:161], v152 offset:2048
	ds_read_b128 v[162:165], v152 offset:3072
	ds_read_b128 v[166:169], v153
	ds_read_b128 v[170:173], v153 offset:1024
	ds_read_b128 v[174:177], v153 offset:2048
	ds_read_b128 v[178:181], v153 offset:3072
	s_cmp_eq_u32 s72, 28
	s_cselect_b32 s40, s70, s75
	s_cselect_b32 s41, s19, s76
	s_cselect_b32 s38, s71, s73
	s_cselect_b32 s39, s17, s74
	s_add_u32 s36, s40, 0x80
	s_addc_u32 s37, s41, 0
	ds_read_b128 v[182:185], v154
	ds_read_b128 v[186:189], v154 offset:1024
	ds_read_b128 v[190:193], v154 offset:2048
	ds_read_b128 v[194:197], v154 offset:3072
	ds_read_b128 v[198:201], v154 offset:4096
	ds_read_b128 v[202:205], v154 offset:5120
	ds_read_b128 v[206:209], v154 offset:6144
	ds_read_b128 v[210:213], v154 offset:7168
	s_add_u32 s30, s75, 0x7ff80
	s_addc_u32 s31, s76, 0
	s_mov_b32 m0, s56
	s_nop 0
	global_load_lds_dwordx4 v1, s[30:31] offset:0
	s_nop 0
	s_mov_b32 m0, s57
	s_nop 0
	global_load_lds_dwordx4 v147, s[30:31] offset:0
	s_waitcnt vmcnt(8)
	s_waitcnt lgkmcnt(0)
	s_barrier
	s_setprio 1
	v_mfma_f32_16x16x32_bf16 v[130:133], v[138:141], v[182:185], v[130:133]
	v_mfma_f32_16x16x32_bf16 v[130:133], v[142:145], v[186:189], v[130:133]
	v_mfma_f32_16x16x32_bf16 v[126:129], v[158:161], v[182:185], v[126:129]
	v_mfma_f32_16x16x32_bf16 v[126:129], v[162:165], v[186:189], v[126:129]
	v_mfma_f32_16x16x32_bf16 v[114:117], v[138:141], v[190:193], v[114:117]
	v_mfma_f32_16x16x32_bf16 v[114:117], v[142:145], v[194:197], v[114:117]
	v_mfma_f32_16x16x32_bf16 v[110:113], v[158:161], v[190:193], v[110:113]
	v_mfma_f32_16x16x32_bf16 v[110:113], v[162:165], v[194:197], v[110:113]
	v_mfma_f32_16x16x32_bf16 v[98:101], v[138:141], v[198:201], v[98:101]
	v_mfma_f32_16x16x32_bf16 v[98:101], v[142:145], v[202:205], v[98:101]
	v_mfma_f32_16x16x32_bf16 v[94:97], v[158:161], v[198:201], v[94:97]
	v_mfma_f32_16x16x32_bf16 v[94:97], v[162:165], v[202:205], v[94:97]
	v_mfma_f32_16x16x32_bf16 v[82:85], v[138:141], v[206:209], v[82:85]
	v_mfma_f32_16x16x32_bf16 v[82:85], v[142:145], v[210:213], v[82:85]
	v_mfma_f32_16x16x32_bf16 v[78:81], v[158:161], v[206:209], v[78:81]
	v_mfma_f32_16x16x32_bf16 v[78:81], v[162:165], v[210:213], v[78:81]
	s_setprio 0
	s_setprio 1
	v_mfma_f32_16x16x32_bf16 v[122:125], v[166:169], v[182:185], v[122:125]
	v_mfma_f32_16x16x32_bf16 v[122:125], v[170:173], v[186:189], v[122:125]
	v_mfma_f32_16x16x32_bf16 v[118:121], v[174:177], v[182:185], v[118:121]
	v_mfma_f32_16x16x32_bf16 v[118:121], v[178:181], v[186:189], v[118:121]
	v_mfma_f32_16x16x32_bf16 v[106:109], v[166:169], v[190:193], v[106:109]
	v_mfma_f32_16x16x32_bf16 v[106:109], v[170:173], v[194:197], v[106:109]
	v_mfma_f32_16x16x32_bf16 v[102:105], v[174:177], v[190:193], v[102:105]
	v_mfma_f32_16x16x32_bf16 v[102:105], v[178:181], v[194:197], v[102:105]
	v_mfma_f32_16x16x32_bf16 v[90:93], v[166:169], v[198:201], v[90:93]
	v_mfma_f32_16x16x32_bf16 v[90:93], v[170:173], v[202:205], v[90:93]
	v_mfma_f32_16x16x32_bf16 v[86:89], v[174:177], v[198:201], v[86:89]
	v_mfma_f32_16x16x32_bf16 v[86:89], v[178:181], v[202:205], v[86:89]
	v_mfma_f32_16x16x32_bf16 v[74:77], v[166:169], v[206:209], v[74:77]
	v_mfma_f32_16x16x32_bf16 v[74:77], v[170:173], v[210:213], v[74:77]
	v_mfma_f32_16x16x32_bf16 v[66:69], v[174:177], v[206:209], v[66:69]
	v_mfma_f32_16x16x32_bf16 v[66:69], v[178:181], v[210:213], v[66:69]
	s_barrier
	s_setprio 0
	ds_read_b128 v[182:185], v154 offset:16384
	ds_read_b128 v[186:189], v154 offset:17408
	ds_read_b128 v[190:193], v154 offset:18432
	ds_read_b128 v[194:197], v154 offset:19456
	ds_read_b128 v[198:201], v154 offset:20480
	ds_read_b128 v[202:205], v154 offset:21504
	ds_read_b128 v[206:209], v154 offset:22528
	ds_read_b128 v[210:213], v154 offset:23552
	s_mov_b32 m0, s29
	s_nop 0
	global_load_lds_dwordx4 v146, s[38:39] offset:0
	s_add_u32 s30, s38, 0x80000
	s_mov_b32 m0, s44
	s_nop 0
	global_load_lds_dwordx4 v148, s[38:39] offset:0
	s_addc_u32 s31, s39, 0
	s_mov_b32 m0, s45
	s_nop 0
	global_load_lds_dwordx4 v146, s[30:31] offset:0
	s_nop 0
	s_mov_b32 m0, s46
	s_nop 0
	global_load_lds_dwordx4 v148, s[30:31] offset:0
	s_nop 0
	s_mov_b32 m0, s21
	s_nop 0
	global_load_lds_dwordx4 v1, s[40:41] offset:0
	s_nop 0
	s_mov_b32 m0, s47
	s_nop 0
	global_load_lds_dwordx4 v147, s[40:41] offset:0
	s_waitcnt vmcnt(8)
	s_waitcnt lgkmcnt(0)
	s_barrier
	s_setprio 1
	v_mfma_f32_16x16x32_bf16 v[70:73], v[138:141], v[182:185], v[70:73]
	v_mfma_f32_16x16x32_bf16 v[70:73], v[142:145], v[186:189], v[70:73]
	v_mfma_f32_16x16x32_bf16 v[62:65], v[158:161], v[182:185], v[62:65]
	v_mfma_f32_16x16x32_bf16 v[62:65], v[162:165], v[186:189], v[62:65]
	v_mfma_f32_16x16x32_bf16 v[50:53], v[138:141], v[190:193], v[50:53]
	v_mfma_f32_16x16x32_bf16 v[50:53], v[142:145], v[194:197], v[50:53]
	v_mfma_f32_16x16x32_bf16 v[46:49], v[158:161], v[190:193], v[46:49]
	v_mfma_f32_16x16x32_bf16 v[46:49], v[162:165], v[194:197], v[46:49]
	v_mfma_f32_16x16x32_bf16 v[34:37], v[138:141], v[198:201], v[34:37]
	v_mfma_f32_16x16x32_bf16 v[34:37], v[142:145], v[202:205], v[34:37]
	v_mfma_f32_16x16x32_bf16 v[30:33], v[158:161], v[198:201], v[30:33]
	v_mfma_f32_16x16x32_bf16 v[30:33], v[162:165], v[202:205], v[30:33]
	v_mfma_f32_16x16x32_bf16 v[18:21], v[138:141], v[206:209], v[18:21]
	v_mfma_f32_16x16x32_bf16 v[18:21], v[142:145], v[210:213], v[18:21]
	v_mfma_f32_16x16x32_bf16 v[14:17], v[158:161], v[206:209], v[14:17]
	v_mfma_f32_16x16x32_bf16 v[14:17], v[162:165], v[210:213], v[14:17]
	s_setprio 0
	s_setprio 1
	v_mfma_f32_16x16x32_bf16 v[58:61], v[166:169], v[182:185], v[58:61]
	v_mfma_f32_16x16x32_bf16 v[54:57], v[174:177], v[182:185], v[54:57]
	v_mfma_f32_16x16x32_bf16 v[42:45], v[166:169], v[190:193], v[42:45]
	v_mfma_f32_16x16x32_bf16 v[38:41], v[174:177], v[190:193], v[38:41]
	v_mfma_f32_16x16x32_bf16 v[26:29], v[166:169], v[198:201], v[26:29]
	v_mfma_f32_16x16x32_bf16 v[22:25], v[174:177], v[198:201], v[22:25]
	v_mfma_f32_16x16x32_bf16 v[10:13], v[166:169], v[206:209], v[10:13]
	v_mfma_f32_16x16x32_bf16 v[4:7], v[174:177], v[206:209], v[6:9]
	v_mfma_f32_16x16x32_bf16 v[58:61], v[170:173], v[186:189], v[58:61]
	v_mfma_f32_16x16x32_bf16 v[54:57], v[178:181], v[186:189], v[54:57]
	v_mfma_f32_16x16x32_bf16 v[42:45], v[170:173], v[194:197], v[42:45]
	v_mfma_f32_16x16x32_bf16 v[38:41], v[178:181], v[194:197], v[38:41]
	v_mfma_f32_16x16x32_bf16 v[26:29], v[170:173], v[202:205], v[26:29]
	v_mfma_f32_16x16x32_bf16 v[22:25], v[178:181], v[202:205], v[22:25]
	v_mfma_f32_16x16x32_bf16 v[10:13], v[170:173], v[210:213], v[10:13]
	v_mfma_f32_16x16x32_bf16 v[4:7], v[178:181], v[210:213], v[4:7]
	s_barrier
; #define PG8_KSETUP() const bool last = (t == nt - 2); const char* a1 = cA + (size_t)(t + 1) * kstep; \
;             const char* a2 = last ? nA : cA + (size_t)(t + 2) * kstep; const char* b2 = last ? nB : cB + (size_t)(t + 2) * kstep; const char* a3 = a2 + kstep; const char* b3 = b2 + kstep; \
;             if (last && has_next) S.a_ready(nxt)
; template <class Epi, class Sched, bool ALIGN_EPI = false, bool SP2 = false>
; __device__ __forceinline__ void gemm_phase(PG8_LAS unsigned char* lds, const Gemm g, const Sched& S, const Epi& E) {
;     ...
;         int t0 = 0;
;         if constexpr (SP2 && Epi::NVM == 16) { if (ui > 0) { const int t = 0; PG8_KSETUP(); PG8_KITER_SP2(24, 24); t0 = 2; } }
;         if constexpr (SP2 && Epi::NVM == 8) { if (ui > 0) { const int t = 0; PG8_KSETUP(); PG8_KITER_SP2(16, 16); t0 = 2; } }
;         for (int t = t0; t < nt; t += 2) {
	s_setprio 0
	ds_read_b128 v[138:141], v155
	ds_read_b128 v[142:145], v155 offset:1024
	ds_read_b128 v[158:161], v155 offset:2048
	ds_read_b128 v[162:165], v155 offset:3072
	ds_read_b128 v[166:169], v156
	ds_read_b128 v[170:173], v156 offset:1024
	ds_read_b128 v[174:177], v156 offset:2048
	ds_read_b128 v[178:181], v156 offset:3072
	ds_read_b128 v[182:185], v154 offset:32768
	ds_read_b128 v[186:189], v154 offset:33792
	ds_read_b128 v[190:193], v154 offset:34816
	ds_read_b128 v[194:197], v154 offset:35840
	ds_read_b128 v[198:201], v154 offset:36864
	ds_read_b128 v[202:205], v154 offset:37888
	ds_read_b128 v[206:209], v154 offset:38912
	ds_read_b128 v[210:213], v154 offset:39936
	s_add_u32 s30, s40, 0x80000
	s_addc_u32 s31, s41, 0
	s_mov_b32 m0, s48
	s_nop 0
	global_load_lds_dwordx4 v1, s[30:31] offset:0
	s_nop 0
	s_mov_b32 m0, s49
	s_nop 0
	global_load_lds_dwordx4 v147, s[30:31] offset:0
	s_waitcnt vmcnt(8)
	s_waitcnt lgkmcnt(0)
	s_barrier
	s_setprio 1
	v_mfma_f32_16x16x32_bf16 v[130:133], v[138:141], v[182:185], v[130:133]
	v_mfma_f32_16x16x32_bf16 v[130:133], v[142:145], v[186:189], v[130:133]
	v_mfma_f32_16x16x32_bf16 v[126:129], v[158:161], v[182:185], v[126:129]
	v_mfma_f32_16x16x32_bf16 v[126:129], v[162:165], v[186:189], v[126:129]
	v_mfma_f32_16x16x32_bf16 v[114:117], v[138:141], v[190:193], v[114:117]
	v_mfma_f32_16x16x32_bf16 v[114:117], v[142:145], v[194:197], v[114:117]
	v_mfma_f32_16x16x32_bf16 v[110:113], v[158:161], v[190:193], v[110:113]
	v_mfma_f32_16x16x32_bf16 v[110:113], v[162:165], v[194:197], v[110:113]
	v_mfma_f32_16x16x32_bf16 v[98:101], v[138:141], v[198:201], v[98:101]
	v_mfma_f32_16x16x32_bf16 v[98:101], v[142:145], v[202:205], v[98:101]
	v_mfma_f32_16x16x32_bf16 v[94:97], v[158:161], v[198:201], v[94:97]
	v_mfma_f32_16x16x32_bf16 v[94:97], v[162:165], v[202:205], v[94:97]
	v_mfma_f32_16x16x32_bf16 v[82:85], v[138:141], v[206:209], v[82:85]
	v_mfma_f32_16x16x32_bf16 v[82:85], v[142:145], v[210:213], v[82:85]
	v_mfma_f32_16x16x32_bf16 v[78:81], v[158:161], v[206:209], v[78:81]
	v_mfma_f32_16x16x32_bf16 v[78:81], v[162:165], v[210:213], v[78:81]
	s_setprio 0
	s_setprio 1
	v_mfma_f32_16x16x32_bf16 v[122:125], v[166:169], v[182:185], v[122:125]
	v_mfma_f32_16x16x32_bf16 v[122:125], v[170:173], v[186:189], v[122:125]
	v_mfma_f32_16x16x32_bf16 v[118:121], v[174:177], v[182:185], v[118:121]
	v_mfma_f32_16x16x32_bf16 v[118:121], v[178:181], v[186:189], v[118:121]
	v_mfma_f32_16x16x32_bf16 v[106:109], v[166:169], v[190:193], v[106:109]
	v_mfma_f32_16x16x32_bf16 v[106:109], v[170:173], v[194:197], v[106:109]
	v_mfma_f32_16x16x32_bf16 v[102:105], v[174:177], v[190:193], v[102:105]
	v_mfma_f32_16x16x32_bf16 v[102:105], v[178:181], v[194:197], v[102:105]
	v_mfma_f32_16x16x32_bf16 v[90:93], v[166:169], v[198:201], v[90:93]
	v_mfma_f32_16x16x32_bf16 v[90:93], v[170:173], v[202:205], v[90:93]
	v_mfma_f32_16x16x32_bf16 v[86:89], v[174:177], v[198:201], v[86:89]
	v_mfma_f32_16x16x32_bf16 v[86:89], v[178:181], v[202:205], v[86:89]
	v_mfma_f32_16x16x32_bf16 v[74:77], v[166:169], v[206:209], v[74:77]
	v_mfma_f32_16x16x32_bf16 v[74:77], v[170:173], v[210:213], v[74:77]
	v_mfma_f32_16x16x32_bf16 v[66:69], v[174:177], v[206:209], v[66:69]
	v_mfma_f32_16x16x32_bf16 v[66:69], v[178:181], v[210:213], v[66:69]
	s_barrier
	s_setprio 0
	ds_read_b128 v[182:185], v154 offset:49152
	ds_read_b128 v[186:189], v154 offset:50176
	ds_read_b128 v[190:193], v154 offset:51200
	ds_read_b128 v[194:197], v154 offset:52224
	ds_read_b128 v[198:201], v154 offset:53248
	ds_read_b128 v[202:205], v154 offset:54272
	ds_read_b128 v[206:209], v154 offset:55296
	ds_read_b128 v[210:213], v154 offset:56320
	s_add_u32 s30, s38, 0x80
	s_addc_u32 s31, s39, 0
	s_mov_b32 m0, s50
	s_nop 0
	global_load_lds_dwordx4 v146, s[30:31] offset:0
	s_nop 0
	s_mov_b32 m0, s51
	s_nop 0
	global_load_lds_dwordx4 v148, s[30:31] offset:0
	s_add_u32 s30, s38, 0x80080
	s_addc_u32 s31, s39, 0
	s_mov_b32 m0, s54
	s_nop 0
	global_load_lds_dwordx4 v146, s[30:31] offset:0
	s_nop 0
	s_mov_b32 m0, s55
	s_nop 0
	global_load_lds_dwordx4 v148, s[30:31] offset:0
	s_nop 0
	s_mov_b32 m0, s52
	s_nop 0
	global_load_lds_dwordx4 v1, s[36:37] offset:0
	s_nop 0
	s_mov_b32 m0, s53
	s_nop 0
	global_load_lds_dwordx4 v147, s[36:37] offset:0
	s_waitcnt vmcnt(8)
	s_waitcnt lgkmcnt(0)
	s_barrier
	s_setprio 1
	v_mfma_f32_16x16x32_bf16 v[70:73], v[138:141], v[182:185], v[70:73]
	v_mfma_f32_16x16x32_bf16 v[70:73], v[142:145], v[186:189], v[70:73]
	v_mfma_f32_16x16x32_bf16 v[62:65], v[158:161], v[182:185], v[62:65]
	v_mfma_f32_16x16x32_bf16 v[62:65], v[162:165], v[186:189], v[62:65]
	v_mfma_f32_16x16x32_bf16 v[50:53], v[138:141], v[190:193], v[50:53]
	v_mfma_f32_16x16x32_bf16 v[50:53], v[142:145], v[194:197], v[50:53]
	v_mfma_f32_16x16x32_bf16 v[46:49], v[158:161], v[190:193], v[46:49]
	v_mfma_f32_16x16x32_bf16 v[46:49], v[162:165], v[194:197], v[46:49]
	v_mfma_f32_16x16x32_bf16 v[34:37], v[138:141], v[198:201], v[34:37]
	v_mfma_f32_16x16x32_bf16 v[34:37], v[142:145], v[202:205], v[34:37]
	v_mfma_f32_16x16x32_bf16 v[30:33], v[158:161], v[198:201], v[30:33]
	v_mfma_f32_16x16x32_bf16 v[30:33], v[162:165], v[202:205], v[30:33]
	v_mfma_f32_16x16x32_bf16 v[18:21], v[138:141], v[206:209], v[18:21]
	v_mfma_f32_16x16x32_bf16 v[18:21], v[142:145], v[210:213], v[18:21]
	v_mfma_f32_16x16x32_bf16 v[14:17], v[158:161], v[206:209], v[14:17]
	v_mfma_f32_16x16x32_bf16 v[14:17], v[162:165], v[210:213], v[14:17]
	s_setprio 0
	s_setprio 1
	v_mfma_f32_16x16x32_bf16 v[58:61], v[166:169], v[182:185], v[58:61]
	v_mfma_f32_16x16x32_bf16 v[54:57], v[174:177], v[182:185], v[54:57]
	v_mfma_f32_16x16x32_bf16 v[42:45], v[166:169], v[190:193], v[42:45]
	v_mfma_f32_16x16x32_bf16 v[38:41], v[174:177], v[190:193], v[38:41]
	v_mfma_f32_16x16x32_bf16 v[26:29], v[166:169], v[198:201], v[26:29]
	v_mfma_f32_16x16x32_bf16 v[22:25], v[174:177], v[198:201], v[22:25]
	v_mfma_f32_16x16x32_bf16 v[8:11], v[166:169], v[206:209], v[10:13]
	v_mfma_f32_16x16x32_bf16 v[4:7], v[174:177], v[206:209], v[4:7]
	v_mfma_f32_16x16x32_bf16 v[58:61], v[170:173], v[186:189], v[58:61]
	v_mfma_f32_16x16x32_bf16 v[54:57], v[178:181], v[186:189], v[54:57]
	v_mfma_f32_16x16x32_bf16 v[42:45], v[170:173], v[194:197], v[42:45]
	v_mfma_f32_16x16x32_bf16 v[38:41], v[178:181], v[194:197], v[38:41]
	v_mfma_f32_16x16x32_bf16 v[26:29], v[170:173], v[202:205], v[26:29]
	v_mfma_f32_16x16x32_bf16 v[22:25], v[178:181], v[202:205], v[22:25]
	v_mfma_f32_16x16x32_bf16 v[10:13], v[170:173], v[210:213], v[8:11]
	v_mfma_f32_16x16x32_bf16 v[6:9], v[178:181], v[210:213], v[4:7]
	s_barrier
	s_setprio 0
	s_add_i32 s72, s72, 2
	s_add_u32 s73, s73, 0x100
	s_addc_u32 s74, s74, 0
	s_add_u32 s75, s75, 0x100
	s_addc_u32 s76, s76, 0
	s_cmp_gt_u32 s72, 29
	s_cbranch_scc0 .LBB0_3621
	s_and_b64 vcc, exec, s[14:15]
	s_cbranch_vccz .LBB0_3624
	s_barrier

; #define PG8_KSETUP() const bool last = (t == nt - 2); const char* a1 = cA + (size_t)(t + 1) * kstep; \
;             const char* a2 = last ? nA : cA + (size_t)(t + 2) * kstep; const char* b2 = last ? nB : cB + (size_t)(t + 2) * kstep; const char* a3 = a2 + kstep; const char* b3 = b2 + kstep; \
;             if (last && has_next) S.a_ready(nxt)
; template <class Epi, class Sched, bool ALIGN_EPI = false, bool SP2 = false>
; __device__ __forceinline__ void gemm_phase(PG8_LAS unsigned char* lds, const Gemm g, const Sched& S, const Epi& E) {
;     ...
;         if constexpr (SP2 && Epi::NVM == 16) { if (ui > 0) { const int t = 0; PG8_KSETUP(); PG8_KITER_SP2(24, 24); t0 = 2; } }
.LBB0_3696:
	ds_read_b128 v[2:5], v150
	ds_read_b128 v[6:9], v150 offset:1024
	ds_read_b128 v[10:13], v150 offset:2048
	ds_read_b128 v[14:17], v150 offset:3072
	ds_read_b128 v[18:21], v151
	ds_read_b128 v[22:25], v151 offset:1024
	ds_read_b128 v[26:29], v151 offset:2048
	ds_read_b128 v[30:33], v151 offset:3072
	s_add_u32 s22, s16, 0x100
	s_addc_u32 s23, s17, 0
	s_add_u32 s30, s18, 0x100
	s_addc_u32 s31, s19, 0
	s_add_u32 s20, s16, 0x180
	s_addc_u32 s21, s17, 0
	ds_read_b128 v[34:37], v152
	ds_read_b128 v[38:41], v152 offset:1024
	ds_read_b128 v[42:45], v152 offset:2048
	ds_read_b128 v[46:49], v152 offset:3072
	ds_read_b128 v[50:53], v152 offset:4096
	ds_read_b128 v[54:57], v152 offset:5120
	ds_read_b128 v[58:61], v152 offset:6144
	ds_read_b128 v[62:65], v152 offset:7168
	s_add_u32 s56, s16, 0x160080
	s_addc_u32 s57, s17, 0
	s_mov_b32 m0, s48
	s_nop 0
	global_load_lds_dwordx4 v144, s[56:57] offset:0
	s_nop 0
	s_mov_b32 m0, s49
	s_nop 0
	global_load_lds_dwordx4 v146, s[56:57] offset:0
	s_waitcnt vmcnt(24)
	s_waitcnt lgkmcnt(0)
	s_barrier
	s_setprio 1
	v_mfma_f32_16x16x32_bf16 v[90:93], v[2:5], v[58:61], 0
	v_mfma_f32_16x16x32_bf16 v[66:69], v[2:5], v[34:37], 0
	v_mfma_f32_16x16x32_bf16 v[70:73], v[10:13], v[34:37], 0
	v_mfma_f32_16x16x32_bf16 v[74:77], v[2:5], v[42:45], 0
	v_mfma_f32_16x16x32_bf16 v[78:81], v[10:13], v[42:45], 0
	v_mfma_f32_16x16x32_bf16 v[82:85], v[2:5], v[50:53], 0
	v_mfma_f32_16x16x32_bf16 v[86:89], v[10:13], v[50:53], 0
	v_mfma_f32_16x16x32_bf16 v[100:103], v[6:9], v[62:65], v[90:93]
	v_mfma_f32_16x16x32_bf16 v[90:93], v[10:13], v[58:61], 0
	v_mfma_f32_16x16x32_bf16 v[66:69], v[6:9], v[38:41], v[66:69]
	v_mfma_f32_16x16x32_bf16 v[70:73], v[14:17], v[38:41], v[70:73]
	v_mfma_f32_16x16x32_bf16 v[74:77], v[6:9], v[46:49], v[74:77]
	v_mfma_f32_16x16x32_bf16 v[78:81], v[14:17], v[46:49], v[78:81]
	v_mfma_f32_16x16x32_bf16 v[82:85], v[6:9], v[54:57], v[82:85]
	v_mfma_f32_16x16x32_bf16 v[86:89], v[14:17], v[54:57], v[86:89]
	v_mfma_f32_16x16x32_bf16 v[104:107], v[14:17], v[62:65], v[90:93]
	s_setprio 0
	s_setprio 1
	v_mfma_f32_16x16x32_bf16 v[90:93], v[18:21], v[34:37], 0
	v_mfma_f32_16x16x32_bf16 v[34:37], v[26:29], v[34:37], 0
	v_mfma_f32_16x16x32_bf16 v[116:119], v[22:25], v[38:41], v[90:93]
	v_mfma_f32_16x16x32_bf16 v[34:37], v[30:33], v[38:41], v[34:37]
	v_mfma_f32_16x16x32_bf16 v[38:41], v[18:21], v[42:45], 0
	v_mfma_f32_16x16x32_bf16 v[42:45], v[26:29], v[42:45], 0
	v_mfma_f32_16x16x32_bf16 v[38:41], v[22:25], v[46:49], v[38:41]
	v_mfma_f32_16x16x32_bf16 v[42:45], v[30:33], v[46:49], v[42:45]
	v_mfma_f32_16x16x32_bf16 v[46:49], v[18:21], v[50:53], 0
	v_mfma_f32_16x16x32_bf16 v[50:53], v[26:29], v[50:53], 0
	v_mfma_f32_16x16x32_bf16 v[46:49], v[22:25], v[54:57], v[46:49]
	v_mfma_f32_16x16x32_bf16 v[50:53], v[30:33], v[54:57], v[50:53]
	v_mfma_f32_16x16x32_bf16 v[54:57], v[18:21], v[58:61], 0
	v_mfma_f32_16x16x32_bf16 v[58:61], v[26:29], v[58:61], 0
	v_mfma_f32_16x16x32_bf16 v[54:57], v[22:25], v[62:65], v[54:57]
	v_mfma_f32_16x16x32_bf16 v[58:61], v[30:33], v[62:65], v[58:61]
	s_barrier
	s_setprio 0
	ds_read_b128 v[62:65], v152 offset:16384
	ds_read_b128 v[90:93], v152 offset:17408
	ds_read_b128 v[94:97], v152 offset:18432
	ds_read_b128 v[108:111], v152 offset:19456
	ds_read_b128 v[112:115], v152 offset:20480
	ds_read_b128 v[120:123], v152 offset:21504
	ds_read_b128 v[124:127], v152 offset:22528
	ds_read_b128 v[128:131], v152 offset:23552
	s_mov_b32 m0, s34
	s_nop 0
	global_load_lds_dwordx4 v145, s[30:31] offset:0
	s_nop 0
	s_mov_b32 m0, s36
	s_nop 0
	global_load_lds_dwordx4 v147, s[30:31] offset:0
	s_add_u32 s30, s18, 0x160100
	s_addc_u32 s31, s19, 0
	s_mov_b32 m0, s37
	s_nop 0
	global_load_lds_dwordx4 v145, s[30:31] offset:0
	s_nop 0
	s_mov_b32 m0, s38
	s_nop 0
	global_load_lds_dwordx4 v147, s[30:31] offset:0
	s_nop 0
	s_mov_b32 m0, s28
	s_nop 0
	global_load_lds_dwordx4 v144, s[22:23] offset:0
	s_nop 0
	s_mov_b32 m0, s39
	s_nop 0
	global_load_lds_dwordx4 v146, s[22:23] offset:0
	s_waitcnt vmcnt(24)
	s_waitcnt lgkmcnt(0)
	s_barrier
	s_setprio 1
	v_mfma_f32_16x16x32_bf16 v[132:135], v[2:5], v[62:65], 0
	v_mfma_f32_16x16x32_bf16 v[156:159], v[2:5], v[94:97], 0
	v_mfma_f32_16x16x32_bf16 v[164:167], v[2:5], v[112:115], 0
	v_mfma_f32_16x16x32_bf16 v[2:5], v[2:5], v[124:127], 0
	v_mfma_f32_16x16x32_bf16 v[132:135], v[6:9], v[90:93], v[132:135]
	v_mfma_f32_16x16x32_bf16 v[156:159], v[6:9], v[108:111], v[156:159]
	v_mfma_f32_16x16x32_bf16 v[164:167], v[6:9], v[120:123], v[164:167]
	v_mfma_f32_16x16x32_bf16 v[2:5], v[6:9], v[128:131], v[2:5]
	v_mfma_f32_16x16x32_bf16 v[6:9], v[10:13], v[124:127], 0
	v_mfma_f32_16x16x32_bf16 v[140:143], v[10:13], v[62:65], 0
	v_mfma_f32_16x16x32_bf16 v[160:163], v[10:13], v[94:97], 0
	v_mfma_f32_16x16x32_bf16 v[168:171], v[10:13], v[112:115], 0
	v_mfma_f32_16x16x32_bf16 v[6:9], v[14:17], v[128:131], v[6:9]
	v_mfma_f32_16x16x32_bf16 v[140:143], v[14:17], v[90:93], v[140:143]
	v_mfma_f32_16x16x32_bf16 v[160:163], v[14:17], v[108:111], v[160:163]
	v_mfma_f32_16x16x32_bf16 v[168:171], v[14:17], v[120:123], v[168:171]
	s_setprio 0
	s_setprio 1
	v_mfma_f32_16x16x32_bf16 v[10:13], v[18:21], v[62:65], 0
	v_mfma_f32_16x16x32_bf16 v[172:175], v[22:25], v[90:93], v[10:13]
	v_mfma_f32_16x16x32_bf16 v[10:13], v[26:29], v[62:65], 0
	v_mfma_f32_16x16x32_bf16 v[176:179], v[30:33], v[90:93], v[10:13]
	v_mfma_f32_16x16x32_bf16 v[10:13], v[18:21], v[94:97], 0
	v_mfma_f32_16x16x32_bf16 v[180:183], v[22:25], v[108:111], v[10:13]
	v_mfma_f32_16x16x32_bf16 v[10:13], v[26:29], v[94:97], 0
	v_mfma_f32_16x16x32_bf16 v[184:187], v[30:33], v[108:111], v[10:13]
	v_mfma_f32_16x16x32_bf16 v[10:13], v[18:21], v[112:115], 0
	v_mfma_f32_16x16x32_bf16 v[188:191], v[22:25], v[120:123], v[10:13]
	v_mfma_f32_16x16x32_bf16 v[10:13], v[26:29], v[112:115], 0
	v_mfma_f32_16x16x32_bf16 v[192:195], v[30:33], v[120:123], v[10:13]
	v_mfma_f32_16x16x32_bf16 v[10:13], v[18:21], v[124:127], 0
	v_mfma_f32_16x16x32_bf16 v[196:199], v[22:25], v[128:131], v[10:13]
	v_mfma_f32_16x16x32_bf16 v[10:13], v[26:29], v[124:127], 0
	v_mfma_f32_16x16x32_bf16 v[200:203], v[30:33], v[128:131], v[10:13]
	s_barrier
; #define PG8_KSETUP() const bool last = (t == nt - 2); const char* a1 = cA + (size_t)(t + 1) * kstep; \
;             const char* a2 = last ? nA : cA + (size_t)(t + 2) * kstep; const char* b2 = last ? nB : cB + (size_t)(t + 2) * kstep; const char* a3 = a2 + kstep; const char* b3 = b2 + kstep; \
;             if (last && has_next) S.a_ready(nxt)
; template <class Epi, class Sched, bool ALIGN_EPI = false, bool SP2 = false>
; __device__ __forceinline__ void gemm_phase(PG8_LAS unsigned char* lds, const Gemm g, const Sched& S, const Epi& E) {
;     ...
;         int t0 = 0;
;         if constexpr (SP2 && Epi::NVM == 16) { if (ui > 0) { const int t = 0; PG8_KSETUP(); PG8_KITER_SP2(24, 24); t0 = 2; } }
	s_setprio 0
	s_nop 4
	ds_read_b128 v[10:13], v153
	ds_read_b128 v[14:17], v153 offset:1024
	ds_read_b128 v[20:23], v153 offset:2048
	ds_read_b128 v[24:27], v153 offset:3072
	ds_read_b128 v[204:207], v154
	ds_read_b128 v[208:211], v154 offset:1024
	ds_read_b128 v[212:215], v154 offset:2048
	ds_read_b128 v[216:219], v154 offset:3072
	ds_read_b128 v[28:31], v152 offset:32768
	ds_read_b128 v[62:65], v152 offset:33792
	ds_read_b128 v[220:223], v152 offset:34816
	ds_read_b128 v[224:227], v152 offset:35840
	ds_read_b128 v[228:231], v152 offset:36864
	ds_read_b128 v[232:235], v152 offset:37888
	ds_read_b128 v[236:239], v152 offset:38912
	ds_read_b128 v[240:243], v152 offset:39936
	s_add_u32 s22, s16, 0x160100
	s_addc_u32 s23, s17, 0
	s_mov_b32 m0, s40
	s_nop 0
	global_load_lds_dwordx4 v144, s[22:23] offset:0
	s_nop 0
	s_mov_b32 m0, s41
	s_nop 0
	global_load_lds_dwordx4 v146, s[22:23] offset:0
	s_waitcnt vmcnt(8)
	s_waitcnt lgkmcnt(0)
	s_barrier
	s_setprio 1
	v_mfma_f32_16x16x32_bf16 v[66:69], v[10:13], v[28:31], v[66:69]
	v_mfma_f32_16x16x32_bf16 v[128:131], v[14:17], v[62:65], v[66:69]
	v_mfma_f32_16x16x32_bf16 v[66:69], v[20:23], v[28:31], v[70:73]
	v_mfma_f32_16x16x32_bf16 v[124:127], v[24:27], v[62:65], v[66:69]
	v_mfma_f32_16x16x32_bf16 v[66:69], v[10:13], v[220:223], v[74:77]
	v_mfma_f32_16x16x32_bf16 v[112:115], v[14:17], v[224:227], v[66:69]
	v_mfma_f32_16x16x32_bf16 v[66:69], v[20:23], v[220:223], v[78:81]
	v_mfma_f32_16x16x32_bf16 v[108:111], v[24:27], v[224:227], v[66:69]
	v_mfma_f32_16x16x32_bf16 v[66:69], v[10:13], v[228:231], v[82:85]
	v_mfma_f32_16x16x32_bf16 v[96:99], v[14:17], v[232:235], v[66:69]
	v_mfma_f32_16x16x32_bf16 v[66:69], v[20:23], v[228:231], v[86:89]
	v_mfma_f32_16x16x32_bf16 v[92:95], v[24:27], v[232:235], v[66:69]
	v_mfma_f32_16x16x32_bf16 v[66:69], v[10:13], v[236:239], v[100:103]
	v_mfma_f32_16x16x32_bf16 v[80:83], v[14:17], v[240:243], v[66:69]
	v_mfma_f32_16x16x32_bf16 v[66:69], v[20:23], v[236:239], v[104:107]
	v_mfma_f32_16x16x32_bf16 v[76:79], v[24:27], v[240:243], v[66:69]
	s_setprio 0
	s_setprio 1
	v_mfma_f32_16x16x32_bf16 v[66:69], v[204:207], v[28:31], v[116:119]
	v_mfma_f32_16x16x32_bf16 v[28:31], v[212:215], v[28:31], v[34:37]
	v_mfma_f32_16x16x32_bf16 v[116:119], v[216:219], v[62:65], v[28:31]
	v_mfma_f32_16x16x32_bf16 v[28:31], v[204:207], v[220:223], v[38:41]
	v_mfma_f32_16x16x32_bf16 v[104:107], v[208:211], v[224:227], v[28:31]
	v_mfma_f32_16x16x32_bf16 v[28:31], v[212:215], v[220:223], v[42:45]
	v_mfma_f32_16x16x32_bf16 v[100:103], v[216:219], v[224:227], v[28:31]
	v_mfma_f32_16x16x32_bf16 v[28:31], v[204:207], v[228:231], v[46:49]
	v_mfma_f32_16x16x32_bf16 v[88:91], v[208:211], v[232:235], v[28:31]
	v_mfma_f32_16x16x32_bf16 v[28:31], v[212:215], v[228:231], v[50:53]
	v_mfma_f32_16x16x32_bf16 v[84:87], v[216:219], v[232:235], v[28:31]
	v_mfma_f32_16x16x32_bf16 v[28:31], v[204:207], v[236:239], v[54:57]
	v_mfma_f32_16x16x32_bf16 v[72:75], v[208:211], v[240:243], v[28:31]
	v_mfma_f32_16x16x32_bf16 v[28:31], v[212:215], v[236:239], v[58:61]
	v_mfma_f32_16x16x32_bf16 v[120:123], v[208:211], v[62:65], v[66:69]
	v_mfma_f32_16x16x32_bf16 v[68:71], v[216:219], v[240:243], v[28:31]
	s_barrier
	s_setprio 0
	ds_read_b128 v[36:39], v152 offset:49152
	ds_read_b128 v[40:43], v152 offset:50176
	ds_read_b128 v[220:223], v152 offset:51200
	ds_read_b128 v[224:227], v152 offset:52224
	ds_read_b128 v[228:231], v152 offset:53248
	ds_read_b128 v[232:235], v152 offset:54272
	ds_read_b128 v[236:239], v152 offset:55296
	ds_read_b128 v[240:243], v152 offset:56320
	s_add_u32 s22, s18, 0x180
	s_addc_u32 s23, s19, 0
	s_mov_b32 m0, s42
	s_nop 0
	global_load_lds_dwordx4 v145, s[22:23] offset:0
	s_nop 0
	s_mov_b32 m0, s43
	s_nop 0
	global_load_lds_dwordx4 v147, s[22:23] offset:0
	s_add_u32 s22, s18, 0x160180
	s_addc_u32 s23, s19, 0
	s_mov_b32 m0, s46
	s_nop 0
	global_load_lds_dwordx4 v145, s[22:23] offset:0
	s_nop 0
	s_mov_b32 m0, s47
	s_nop 0
	global_load_lds_dwordx4 v147, s[22:23] offset:0
	s_nop 0
	s_mov_b32 m0, s44
	s_nop 0
	global_load_lds_dwordx4 v144, s[20:21] offset:0
	s_nop 0
	s_mov_b32 m0, s45
	s_nop 0
	global_load_lds_dwordx4 v146, s[20:21] offset:0
	s_waitcnt vmcnt(8)
	s_waitcnt lgkmcnt(0)
	s_barrier
	s_setprio 1
	v_mfma_f32_16x16x32_bf16 v[28:31], v[10:13], v[36:39], v[132:135]
	v_mfma_f32_16x16x32_bf16 v[64:67], v[14:17], v[40:43], v[28:31]
	v_mfma_f32_16x16x32_bf16 v[28:31], v[20:23], v[36:39], v[140:143]
	v_mfma_f32_16x16x32_bf16 v[60:63], v[24:27], v[40:43], v[28:31]
	v_mfma_f32_16x16x32_bf16 v[28:31], v[10:13], v[220:223], v[156:159]
	v_mfma_f32_16x16x32_bf16 v[48:51], v[14:17], v[224:227], v[28:31]
	v_mfma_f32_16x16x32_bf16 v[28:31], v[20:23], v[220:223], v[160:163]
	v_mfma_f32_16x16x32_bf16 v[44:47], v[24:27], v[224:227], v[28:31]
	v_mfma_f32_16x16x32_bf16 v[28:31], v[10:13], v[228:231], v[164:167]
	v_mfma_f32_16x16x32_bf16 v[2:5], v[10:13], v[236:239], v[2:5]
	v_mfma_f32_16x16x32_bf16 v[32:35], v[14:17], v[232:235], v[28:31]
	v_mfma_f32_16x16x32_bf16 v[28:31], v[20:23], v[228:231], v[168:171]
	v_mfma_f32_16x16x32_bf16 v[16:19], v[14:17], v[240:243], v[2:5]
	v_mfma_f32_16x16x32_bf16 v[2:5], v[20:23], v[236:239], v[6:9]
	v_mfma_f32_16x16x32_bf16 v[28:31], v[24:27], v[232:235], v[28:31]
	v_mfma_f32_16x16x32_bf16 v[12:15], v[24:27], v[240:243], v[2:5]
	s_setprio 0
	s_setprio 1
	v_mfma_f32_16x16x32_bf16 v[2:5], v[204:207], v[36:39], v[172:175]
	v_mfma_f32_16x16x32_bf16 v[56:59], v[208:211], v[40:43], v[2:5]
	v_mfma_f32_16x16x32_bf16 v[2:5], v[212:215], v[36:39], v[176:179]
	v_mfma_f32_16x16x32_bf16 v[52:55], v[216:219], v[40:43], v[2:5]
	v_mfma_f32_16x16x32_bf16 v[2:5], v[204:207], v[220:223], v[180:183]
	v_mfma_f32_16x16x32_bf16 v[40:43], v[208:211], v[224:227], v[2:5]
	v_mfma_f32_16x16x32_bf16 v[2:5], v[212:215], v[220:223], v[184:187]
	v_mfma_f32_16x16x32_bf16 v[36:39], v[216:219], v[224:227], v[2:5]
	v_mfma_f32_16x16x32_bf16 v[2:5], v[204:207], v[228:231], v[188:191]
	v_mfma_f32_16x16x32_bf16 v[24:27], v[208:211], v[232:235], v[2:5]
	v_mfma_f32_16x16x32_bf16 v[2:5], v[212:215], v[228:231], v[192:195]
	v_mfma_f32_16x16x32_bf16 v[20:23], v[216:219], v[232:235], v[2:5]
	v_mfma_f32_16x16x32_bf16 v[2:5], v[204:207], v[236:239], v[196:199]
	v_mfma_f32_16x16x32_bf16 v[8:11], v[208:211], v[240:243], v[2:5]
	v_mfma_f32_16x16x32_bf16 v[2:5], v[212:215], v[236:239], v[200:203]
	v_mfma_f32_16x16x32_bf16 v[4:7], v[216:219], v[240:243], v[2:5]
	s_barrier
	s_setprio 0
	s_mov_b32 s20, 2
	s_branch .LBB0_3700

; #define PG8_KSETUP() const bool last = (t == nt - 2); const char* a1 = cA + (size_t)(t + 1) * kstep; \
;             const char* a2 = last ? nA : cA + (size_t)(t + 2) * kstep; const char* b2 = last ? nB : cB + (size_t)(t + 2) * kstep; const char* a3 = a2 + kstep; const char* b3 = b2 + kstep; \
;             if (last && has_next) S.a_ready(nxt)
; template <class Epi, class Sched, bool ALIGN_EPI = false, bool SP2 = false>
; __device__ __forceinline__ void gemm_phase(PG8_LAS unsigned char* lds, const Gemm g, const Sched& S, const Epi& E) {
;     ...
;         int t0 = 0;
;         if constexpr (SP2 && Epi::NVM == 16) { if (ui > 0) { const int t = 0; PG8_KSETUP(); PG8_KITER_SP2(24, 24); t0 = 2; } }
;         if constexpr (SP2 && Epi::NVM == 8) { if (ui > 0) { const int t = 0; PG8_KSETUP(); PG8_KITER_SP2(16, 16); t0 = 2; } }
;         for (int t = t0; t < nt; t += 2) {
;             PG8_KSETUP();
;             if constexpr (SP2) {
;             PG8_KITER_SP2(8, 8);
.LBB0_3701:
	ds_read_b128 v[132:135], v150
	ds_read_b128 v[140:143], v150 offset:1024
	ds_read_b128 v[156:159], v150 offset:2048
	ds_read_b128 v[160:163], v150 offset:3072
	ds_read_b128 v[164:167], v151
	ds_read_b128 v[168:171], v151 offset:1024
	ds_read_b128 v[172:175], v151 offset:2048
	ds_read_b128 v[176:179], v151 offset:3072
	s_cmpk_eq_i32 s22, 0x54
	s_cselect_b32 s20, s4, s57
	s_cselect_b32 s21, s5, s58
	s_cselect_b32 s18, s14, s23
	s_cselect_b32 s19, s15, s56
	s_add_u32 s16, s20, 0x80
	s_addc_u32 s17, s21, 0
	ds_read_b128 v[180:183], v152
	ds_read_b128 v[184:187], v152 offset:1024
	ds_read_b128 v[188:191], v152 offset:2048
	ds_read_b128 v[192:195], v152 offset:3072
	ds_read_b128 v[196:199], v152 offset:4096
	ds_read_b128 v[200:203], v152 offset:5120
	ds_read_b128 v[204:207], v152 offset:6144
	ds_read_b128 v[208:211], v152 offset:7168
	s_add_u32 s30, s57, 0x15ff80
	s_addc_u32 s31, s58, 0
	s_mov_b32 m0, s48
	s_nop 0
	global_load_lds_dwordx4 v144, s[30:31] offset:0
	s_nop 0
	s_mov_b32 m0, s49
	s_nop 0
	global_load_lds_dwordx4 v146, s[30:31] offset:0
	s_waitcnt vmcnt(8)
	s_waitcnt lgkmcnt(0)
	s_barrier
	s_setprio 1
	v_mfma_f32_16x16x32_bf16 v[128:131], v[132:135], v[180:183], v[128:131]
	v_mfma_f32_16x16x32_bf16 v[128:131], v[140:143], v[184:187], v[128:131]
	v_mfma_f32_16x16x32_bf16 v[124:127], v[156:159], v[180:183], v[124:127]
	v_mfma_f32_16x16x32_bf16 v[124:127], v[160:163], v[184:187], v[124:127]
	v_mfma_f32_16x16x32_bf16 v[112:115], v[132:135], v[188:191], v[112:115]
	v_mfma_f32_16x16x32_bf16 v[112:115], v[140:143], v[192:195], v[112:115]
	v_mfma_f32_16x16x32_bf16 v[108:111], v[156:159], v[188:191], v[108:111]
	v_mfma_f32_16x16x32_bf16 v[108:111], v[160:163], v[192:195], v[108:111]
	v_mfma_f32_16x16x32_bf16 v[96:99], v[132:135], v[196:199], v[96:99]
	v_mfma_f32_16x16x32_bf16 v[96:99], v[140:143], v[200:203], v[96:99]
	v_mfma_f32_16x16x32_bf16 v[92:95], v[156:159], v[196:199], v[92:95]
	v_mfma_f32_16x16x32_bf16 v[92:95], v[160:163], v[200:203], v[92:95]
	v_mfma_f32_16x16x32_bf16 v[80:83], v[132:135], v[204:207], v[80:83]
	v_mfma_f32_16x16x32_bf16 v[80:83], v[140:143], v[208:211], v[80:83]
	v_mfma_f32_16x16x32_bf16 v[76:79], v[156:159], v[204:207], v[76:79]
	v_mfma_f32_16x16x32_bf16 v[76:79], v[160:163], v[208:211], v[76:79]
	s_setprio 0
	s_setprio 1
	v_mfma_f32_16x16x32_bf16 v[120:123], v[164:167], v[180:183], v[120:123]
	v_mfma_f32_16x16x32_bf16 v[120:123], v[168:171], v[184:187], v[120:123]
	v_mfma_f32_16x16x32_bf16 v[116:119], v[172:175], v[180:183], v[116:119]
	v_mfma_f32_16x16x32_bf16 v[116:119], v[176:179], v[184:187], v[116:119]
	v_mfma_f32_16x16x32_bf16 v[104:107], v[164:167], v[188:191], v[104:107]
	v_mfma_f32_16x16x32_bf16 v[104:107], v[168:171], v[192:195], v[104:107]
	v_mfma_f32_16x16x32_bf16 v[100:103], v[172:175], v[188:191], v[100:103]
	v_mfma_f32_16x16x32_bf16 v[100:103], v[176:179], v[192:195], v[100:103]
	v_mfma_f32_16x16x32_bf16 v[88:91], v[164:167], v[196:199], v[88:91]
	v_mfma_f32_16x16x32_bf16 v[88:91], v[168:171], v[200:203], v[88:91]
	v_mfma_f32_16x16x32_bf16 v[84:87], v[172:175], v[196:199], v[84:87]
	v_mfma_f32_16x16x32_bf16 v[84:87], v[176:179], v[200:203], v[84:87]
	v_mfma_f32_16x16x32_bf16 v[72:75], v[164:167], v[204:207], v[72:75]
	v_mfma_f32_16x16x32_bf16 v[72:75], v[168:171], v[208:211], v[72:75]
	v_mfma_f32_16x16x32_bf16 v[68:71], v[172:175], v[204:207], v[68:71]
	v_mfma_f32_16x16x32_bf16 v[68:71], v[176:179], v[208:211], v[68:71]
	s_barrier
	s_setprio 0
	ds_read_b128 v[180:183], v152 offset:16384
	ds_read_b128 v[184:187], v152 offset:17408
	ds_read_b128 v[188:191], v152 offset:18432
	ds_read_b128 v[192:195], v152 offset:19456
	ds_read_b128 v[196:199], v152 offset:20480
	ds_read_b128 v[200:203], v152 offset:21504
	ds_read_b128 v[204:207], v152 offset:22528
	ds_read_b128 v[208:211], v152 offset:23552
	s_mov_b32 m0, s34
	s_nop 0
	global_load_lds_dwordx4 v145, s[18:19] offset:0
	s_add_u32 s30, s18, 0x160000
	s_mov_b32 m0, s36
	s_nop 0
	global_load_lds_dwordx4 v147, s[18:19] offset:0
	s_addc_u32 s31, s19, 0
	s_mov_b32 m0, s37
	s_nop 0
	global_load_lds_dwordx4 v145, s[30:31] offset:0
	s_nop 0
	s_mov_b32 m0, s38
	s_nop 0
	global_load_lds_dwordx4 v147, s[30:31] offset:0
	s_nop 0
	s_mov_b32 m0, s28
	s_nop 0
	global_load_lds_dwordx4 v144, s[20:21] offset:0
	s_nop 0
	s_mov_b32 m0, s39
	s_nop 0
	global_load_lds_dwordx4 v146, s[20:21] offset:0
	s_waitcnt vmcnt(8)
	s_waitcnt lgkmcnt(0)
	s_barrier
	s_setprio 1
	v_mfma_f32_16x16x32_bf16 v[64:67], v[132:135], v[180:183], v[64:67]
	v_mfma_f32_16x16x32_bf16 v[64:67], v[140:143], v[184:187], v[64:67]
	v_mfma_f32_16x16x32_bf16 v[60:63], v[156:159], v[180:183], v[60:63]
	v_mfma_f32_16x16x32_bf16 v[60:63], v[160:163], v[184:187], v[60:63]
	v_mfma_f32_16x16x32_bf16 v[48:51], v[132:135], v[188:191], v[48:51]
	v_mfma_f32_16x16x32_bf16 v[48:51], v[140:143], v[192:195], v[48:51]
	v_mfma_f32_16x16x32_bf16 v[44:47], v[156:159], v[188:191], v[44:47]
	v_mfma_f32_16x16x32_bf16 v[44:47], v[160:163], v[192:195], v[44:47]
	v_mfma_f32_16x16x32_bf16 v[32:35], v[132:135], v[196:199], v[32:35]
	v_mfma_f32_16x16x32_bf16 v[32:35], v[140:143], v[200:203], v[32:35]
	v_mfma_f32_16x16x32_bf16 v[28:31], v[156:159], v[196:199], v[28:31]
	v_mfma_f32_16x16x32_bf16 v[28:31], v[160:163], v[200:203], v[28:31]
	v_mfma_f32_16x16x32_bf16 v[16:19], v[132:135], v[204:207], v[16:19]
	v_mfma_f32_16x16x32_bf16 v[16:19], v[140:143], v[208:211], v[16:19]
	v_mfma_f32_16x16x32_bf16 v[12:15], v[156:159], v[204:207], v[12:15]
	v_mfma_f32_16x16x32_bf16 v[12:15], v[160:163], v[208:211], v[12:15]
	s_setprio 0
	s_setprio 1
	v_mfma_f32_16x16x32_bf16 v[56:59], v[164:167], v[180:183], v[56:59]
	v_mfma_f32_16x16x32_bf16 v[52:55], v[172:175], v[180:183], v[52:55]
	v_mfma_f32_16x16x32_bf16 v[40:43], v[164:167], v[188:191], v[40:43]
	v_mfma_f32_16x16x32_bf16 v[36:39], v[172:175], v[188:191], v[36:39]
	v_mfma_f32_16x16x32_bf16 v[24:27], v[164:167], v[196:199], v[24:27]
	v_mfma_f32_16x16x32_bf16 v[20:23], v[172:175], v[196:199], v[20:23]
	v_mfma_f32_16x16x32_bf16 v[8:11], v[164:167], v[204:207], v[8:11]
	v_mfma_f32_16x16x32_bf16 v[2:5], v[172:175], v[204:207], v[4:7]
	v_mfma_f32_16x16x32_bf16 v[56:59], v[168:171], v[184:187], v[56:59]
	v_mfma_f32_16x16x32_bf16 v[52:55], v[176:179], v[184:187], v[52:55]
	v_mfma_f32_16x16x32_bf16 v[40:43], v[168:171], v[192:195], v[40:43]
	v_mfma_f32_16x16x32_bf16 v[36:39], v[176:179], v[192:195], v[36:39]
	v_mfma_f32_16x16x32_bf16 v[24:27], v[168:171], v[200:203], v[24:27]
	v_mfma_f32_16x16x32_bf16 v[20:23], v[176:179], v[200:203], v[20:23]
	v_mfma_f32_16x16x32_bf16 v[8:11], v[168:171], v[208:211], v[8:11]
	v_mfma_f32_16x16x32_bf16 v[2:5], v[176:179], v[208:211], v[2:5]
	s_barrier
; #define PG8_STAGE(bufoff, gbase, voff) PG8_STAGEI(bufoff, gbase, 0, voff)
; #define PG8_LDA(dst, b, h) do { _Pragma("unroll") for (int m = 0; m < 4; ++m) _Pragma("unroll") for (int k = 0; k < 2; ++k) dst[m][k] = *(const PG8_LAS bf16x8*)(lds + PG8_SA(b, h) + aoff + m * 2048 + k * 1024); } while (0)
; #define PG8_WAIT_V(n) asm volatile("s_waitcnt vmcnt(" #n ")" ::: "memory")
; #define PG8_BAR __builtin_amdgcn_s_barrier()
; template <class Epi, class Sched, bool ALIGN_EPI = false, bool SP2 = false>
; __device__ __forceinline__ void gemm_phase(PG8_LAS unsigned char* lds, const Gemm g, const Sched& S, const Epi& E) {
;     ...
;         int t0 = 0;
;         if constexpr (SP2 && Epi::NVM == 16) { if (ui > 0) { const int t = 0; PG8_KSETUP(); PG8_KITER_SP2(24, 24); t0 = 2; } }
;         if constexpr (SP2 && Epi::NVM == 8) { if (ui > 0) { const int t = 0; PG8_KSETUP(); PG8_KITER_SP2(16, 16); t0 = 2; } }
;         for (int t = t0; t < nt; t += 2) {
;             PG8_KSETUP();
;             if constexpr (SP2) {
;             PG8_KITER_SP2(8, 8);
;             } else {
;             PG8_LDB(B0, 0, 0); PG8_SCHED; PG8_LDA(At, 0, 0); PG8_STAGE(PG8_SA(1, 1), a1 + hstep, voffA);
;             PG8_WAIT_L(8); PG8_BAR; PG8_WAIT_L(0); PG8_MMA(0, 0, At, B0); PG8_BAR; PG8_SCHED;
;             PG8_LDB(B1, 0, 1); PG8_STAGE(PG8_SB(0, 0), b2, voffB);
;             PG8_BAR; PG8_WAIT_L(0); PG8_MMA(0, 1, At, B1); PG8_BAR;
;             PG8_LDA(At, 0, 1); PG8_STAGE(PG8_SA(0, 0), a2, voffA);
;             PG8_BAR; PG8_WAIT_L(0); PG8_MMA(1, 0, At, B0); PG8_BAR; PG8_SCHED;
;             PG8_STAGE(PG8_SB(0, 1), b2 + hstep, voffB);
;             PG8_WAIT_V(6); PG8_BAR; PG8_MMA(1, 1, At, B1); PG8_BAR;
;             PG8_LDB(B0, 1, 0); PG8_SCHED; PG8_LDA(At, 1, 0); PG8_STAGE(PG8_SA(0, 1), a2 + hstep, voffA);
;             PG8_WAIT_L(8); PG8_BAR; PG8_WAIT_L(0); PG8_MMA(0, 0, At, B0); PG8_BAR; PG8_SCHED;
;             PG8_LDB(B1, 1, 1); PG8_STAGE(PG8_SB(1, 0), b3, voffB);
;             PG8_BAR; PG8_WAIT_L(0); PG8_MMA(0, 1, At, B1); PG8_BAR;
;             PG8_LDA(At, 1, 1); PG8_STAGE(PG8_SA(1, 0), a3, voffA);
;             PG8_BAR; PG8_WAIT_L(0); PG8_MMA(1, 0, At, B0); PG8_BAR; PG8_SCHED;
;             PG8_STAGE(PG8_SB(1, 1), b3 + hstep, voffB);
;             PG8_WAIT_V(6); PG8_BAR; PG8_MMA(1, 1, At, B1); PG8_BAR;
;             }
;         }
;     ...
;         if constexpr (ALIGN_EPI) { if (wr == 0) PG8_BAR; }
	s_setprio 0
	ds_read_b128 v[132:135], v153
	ds_read_b128 v[140:143], v153 offset:1024
	ds_read_b128 v[156:159], v153 offset:2048
	ds_read_b128 v[160:163], v153 offset:3072
	ds_read_b128 v[164:167], v154
	ds_read_b128 v[168:171], v154 offset:1024
	ds_read_b128 v[172:175], v154 offset:2048
	ds_read_b128 v[176:179], v154 offset:3072
	ds_read_b128 v[180:183], v152 offset:32768
	ds_read_b128 v[184:187], v152 offset:33792
	ds_read_b128 v[188:191], v152 offset:34816
	ds_read_b128 v[192:195], v152 offset:35840
	ds_read_b128 v[196:199], v152 offset:36864
	ds_read_b128 v[200:203], v152 offset:37888
	ds_read_b128 v[204:207], v152 offset:38912
	ds_read_b128 v[208:211], v152 offset:39936
	s_add_u32 s20, s20, 0x160000
	s_addc_u32 s21, s21, 0
	s_mov_b32 m0, s40
	s_nop 0
	global_load_lds_dwordx4 v144, s[20:21] offset:0
	s_nop 0
	s_mov_b32 m0, s41
	s_nop 0
	global_load_lds_dwordx4 v146, s[20:21] offset:0
	s_waitcnt vmcnt(8)
	s_waitcnt lgkmcnt(0)
	s_barrier
	s_setprio 1
	v_mfma_f32_16x16x32_bf16 v[128:131], v[132:135], v[180:183], v[128:131]
	v_mfma_f32_16x16x32_bf16 v[128:131], v[140:143], v[184:187], v[128:131]
	v_mfma_f32_16x16x32_bf16 v[124:127], v[156:159], v[180:183], v[124:127]
	v_mfma_f32_16x16x32_bf16 v[124:127], v[160:163], v[184:187], v[124:127]
	v_mfma_f32_16x16x32_bf16 v[112:115], v[132:135], v[188:191], v[112:115]
	v_mfma_f32_16x16x32_bf16 v[112:115], v[140:143], v[192:195], v[112:115]
	v_mfma_f32_16x16x32_bf16 v[108:111], v[156:159], v[188:191], v[108:111]
	v_mfma_f32_16x16x32_bf16 v[108:111], v[160:163], v[192:195], v[108:111]
	v_mfma_f32_16x16x32_bf16 v[96:99], v[132:135], v[196:199], v[96:99]
	v_mfma_f32_16x16x32_bf16 v[96:99], v[140:143], v[200:203], v[96:99]
	v_mfma_f32_16x16x32_bf16 v[92:95], v[156:159], v[196:199], v[92:95]
	v_mfma_f32_16x16x32_bf16 v[92:95], v[160:163], v[200:203], v[92:95]
	v_mfma_f32_16x16x32_bf16 v[80:83], v[132:135], v[204:207], v[80:83]
	v_mfma_f32_16x16x32_bf16 v[80:83], v[140:143], v[208:211], v[80:83]
	v_mfma_f32_16x16x32_bf16 v[76:79], v[156:159], v[204:207], v[76:79]
	v_mfma_f32_16x16x32_bf16 v[76:79], v[160:163], v[208:211], v[76:79]
	s_setprio 0
	s_setprio 1
	v_mfma_f32_16x16x32_bf16 v[120:123], v[164:167], v[180:183], v[120:123]
	v_mfma_f32_16x16x32_bf16 v[120:123], v[168:171], v[184:187], v[120:123]
	v_mfma_f32_16x16x32_bf16 v[116:119], v[172:175], v[180:183], v[116:119]
	v_mfma_f32_16x16x32_bf16 v[116:119], v[176:179], v[184:187], v[116:119]
	v_mfma_f32_16x16x32_bf16 v[104:107], v[164:167], v[188:191], v[104:107]
	v_mfma_f32_16x16x32_bf16 v[104:107], v[168:171], v[192:195], v[104:107]
	v_mfma_f32_16x16x32_bf16 v[100:103], v[172:175], v[188:191], v[100:103]
	v_mfma_f32_16x16x32_bf16 v[100:103], v[176:179], v[192:195], v[100:103]
	v_mfma_f32_16x16x32_bf16 v[88:91], v[164:167], v[196:199], v[88:91]
	v_mfma_f32_16x16x32_bf16 v[88:91], v[168:171], v[200:203], v[88:91]
	v_mfma_f32_16x16x32_bf16 v[84:87], v[172:175], v[196:199], v[84:87]
	v_mfma_f32_16x16x32_bf16 v[84:87], v[176:179], v[200:203], v[84:87]
	v_mfma_f32_16x16x32_bf16 v[72:75], v[164:167], v[204:207], v[72:75]
	v_mfma_f32_16x16x32_bf16 v[72:75], v[168:171], v[208:211], v[72:75]
	v_mfma_f32_16x16x32_bf16 v[68:71], v[172:175], v[204:207], v[68:71]
	v_mfma_f32_16x16x32_bf16 v[68:71], v[176:179], v[208:211], v[68:71]
	s_barrier
	s_setprio 0
	ds_read_b128 v[180:183], v152 offset:49152
	ds_read_b128 v[184:187], v152 offset:50176
	ds_read_b128 v[188:191], v152 offset:51200
	ds_read_b128 v[192:195], v152 offset:52224
	ds_read_b128 v[196:199], v152 offset:53248
	ds_read_b128 v[200:203], v152 offset:54272
	ds_read_b128 v[204:207], v152 offset:55296
	ds_read_b128 v[208:211], v152 offset:56320
	s_add_u32 s20, s18, 0x80
	s_addc_u32 s21, s19, 0
	s_mov_b32 m0, s42
	s_nop 0
	global_load_lds_dwordx4 v145, s[20:21] offset:0
	s_add_u32 s18, s18, 0x160080
	s_mov_b32 m0, s43
	s_nop 0
	global_load_lds_dwordx4 v147, s[20:21] offset:0
	s_addc_u32 s19, s19, 0
	s_mov_b32 m0, s46
	s_nop 0
	global_load_lds_dwordx4 v145, s[18:19] offset:0
	s_nop 0
	s_mov_b32 m0, s47
	s_nop 0
	global_load_lds_dwordx4 v147, s[18:19] offset:0
	s_nop 0
	s_mov_b32 m0, s44
	s_nop 0
	global_load_lds_dwordx4 v144, s[16:17] offset:0
	s_nop 0
	s_mov_b32 m0, s45
	s_nop 0
	global_load_lds_dwordx4 v146, s[16:17] offset:0
	s_waitcnt vmcnt(8)
	s_waitcnt lgkmcnt(0)
	s_barrier
	s_setprio 1
	v_mfma_f32_16x16x32_bf16 v[64:67], v[132:135], v[180:183], v[64:67]
	v_mfma_f32_16x16x32_bf16 v[64:67], v[140:143], v[184:187], v[64:67]
	v_mfma_f32_16x16x32_bf16 v[60:63], v[156:159], v[180:183], v[60:63]
	v_mfma_f32_16x16x32_bf16 v[60:63], v[160:163], v[184:187], v[60:63]
	v_mfma_f32_16x16x32_bf16 v[48:51], v[132:135], v[188:191], v[48:51]
	v_mfma_f32_16x16x32_bf16 v[48:51], v[140:143], v[192:195], v[48:51]
	v_mfma_f32_16x16x32_bf16 v[44:47], v[156:159], v[188:191], v[44:47]
	v_mfma_f32_16x16x32_bf16 v[44:47], v[160:163], v[192:195], v[44:47]
	v_mfma_f32_16x16x32_bf16 v[32:35], v[132:135], v[196:199], v[32:35]
	v_mfma_f32_16x16x32_bf16 v[32:35], v[140:143], v[200:203], v[32:35]
	v_mfma_f32_16x16x32_bf16 v[28:31], v[156:159], v[196:199], v[28:31]
	v_mfma_f32_16x16x32_bf16 v[28:31], v[160:163], v[200:203], v[28:31]
	v_mfma_f32_16x16x32_bf16 v[16:19], v[132:135], v[204:207], v[16:19]
	v_mfma_f32_16x16x32_bf16 v[16:19], v[140:143], v[208:211], v[16:19]
	v_mfma_f32_16x16x32_bf16 v[12:15], v[156:159], v[204:207], v[12:15]
	v_mfma_f32_16x16x32_bf16 v[12:15], v[160:163], v[208:211], v[12:15]
	s_setprio 0
	s_setprio 1
	v_mfma_f32_16x16x32_bf16 v[56:59], v[164:167], v[180:183], v[56:59]
	v_mfma_f32_16x16x32_bf16 v[52:55], v[172:175], v[180:183], v[52:55]
	v_mfma_f32_16x16x32_bf16 v[40:43], v[164:167], v[188:191], v[40:43]
	v_mfma_f32_16x16x32_bf16 v[36:39], v[172:175], v[188:191], v[36:39]
	v_mfma_f32_16x16x32_bf16 v[24:27], v[164:167], v[196:199], v[24:27]
	v_mfma_f32_16x16x32_bf16 v[20:23], v[172:175], v[196:199], v[20:23]
	v_mfma_f32_16x16x32_bf16 v[6:9], v[164:167], v[204:207], v[8:11]
	v_mfma_f32_16x16x32_bf16 v[2:5], v[172:175], v[204:207], v[2:5]
	v_mfma_f32_16x16x32_bf16 v[56:59], v[168:171], v[184:187], v[56:59]
	v_mfma_f32_16x16x32_bf16 v[52:55], v[176:179], v[184:187], v[52:55]
	v_mfma_f32_16x16x32_bf16 v[40:43], v[168:171], v[192:195], v[40:43]
	v_mfma_f32_16x16x32_bf16 v[36:39], v[176:179], v[192:195], v[36:39]
	v_mfma_f32_16x16x32_bf16 v[24:27], v[168:171], v[200:203], v[24:27]
	v_mfma_f32_16x16x32_bf16 v[20:23], v[176:179], v[200:203], v[20:23]
	v_mfma_f32_16x16x32_bf16 v[8:11], v[168:171], v[208:211], v[6:9]
	v_mfma_f32_16x16x32_bf16 v[4:7], v[176:179], v[208:211], v[2:5]
	s_barrier
	s_setprio 0
	s_add_i32 s22, s22, 2
	s_add_u32 s23, s23, 0x100
	s_addc_u32 s56, s56, 0
	s_add_u32 s57, s57, 0x100
	s_addc_u32 s58, s58, 0
	s_cmpk_gt_u32 s22, 0x55
	s_cbranch_scc0 .LBB0_3701
	s_and_b64 vcc, exec, s[12:13]
	s_cbranch_vccz .LBB0_3704
	s_barrier
